# GEMM load segments: first m0 write hoisted into preceding MFMA shadow; s_nop after second m0 write replaced by the segment's last LDS read
# baseline (speedup 1.0000x reference)
; #define PG8_STAGE(bufoff, gbase, voff) do { _Pragma("unroll") for (int _i = 0; _i < 2; ++_i) \
;         __builtin_amdgcn_global_load_lds((const unsigned*)((const char*)(gbase) + (voff)[_i]), (LAS unsigned*)(lds + (bufoff) + ldsw + _i * 8192), 16, 0, 0); } while (0)
; #define PG8_LDA(dst, b, h) do { _Pragma("unroll") for (int m = 0; m < 4; ++m) _Pragma("unroll") for (int k = 0; k < 2; ++k) dst[m][k] = *(const LAS bf16x8*)(lds + PG8_SA(b, h) + aoff + m * 2048 + k * 1024); } while (0)
; #define PG8_LDB(dst, b, h) do { _Pragma("unroll") for (int n = 0; n < 2; ++n) _Pragma("unroll") for (int k = 0; k < 2; ++k) dst[n][k] = *(const LAS bf16x8*)(lds + PG8_SB(b, h) + boff + n * 2048 + k * 1024); } while (0)
; #define PG8_WAIT_V(n) asm volatile("s_waitcnt vmcnt(" #n ")" ::: "memory")
; #define PG8_WAIT_L(n) asm volatile("s_waitcnt lgkmcnt(" #n ")" ::: "memory")
; #define PG8_BAR __builtin_amdgcn_s_barrier()
; #define PG8_SCHED __builtin_amdgcn_sched_barrier(0)
; template <class Map, class Epi>
; DI void gemm_phase(LAS unsigned char* lds, const Map& MP, const Epi& E, const int nM, const int nN, const int K, const int lda, const int ldb) {
;     ...
;             const bool last = (t == nt - 2);
;             const char* a1 = cA + (size_t)(t + 1) * kstep;
;             const char* a2 = last ? nA : cA + (size_t)(t + 2) * kstep; const char* b2 = last ? nB : cB + (size_t)(t + 2) * kstep;
;             const char* a3 = a2 + kstep; const char* b3 = b2 + kstep;
;             PG8_LDB(B0, 0, 0); PG8_SCHED; PG8_LDA(At, 0, 0); PG8_STAGE(PG8_SA(1, 1), a1 + hstepA, voffA);
;             PG8_WAIT_L(8); PG8_BAR; PG8_WAIT_L(0); PG8_MMA(0, 0, At, B0); PG8_BAR; PG8_SCHED;
;             PG8_LDB(B1, 0, 1); PG8_STAGE(PG8_SB(0, 0), b2, voffB);
;             PG8_BAR; PG8_WAIT_L(0); PG8_MMA(0, 1, At, B1); PG8_BAR;
;             PG8_LDA(At, 0, 1); PG8_STAGE(PG8_SA(0, 0), a2, voffA);
;             PG8_BAR; PG8_WAIT_L(0); PG8_MMA(1, 0, At, B0); PG8_BAR; PG8_SCHED;
;             PG8_STAGE(PG8_SB(0, 1), b2 + hstepB, voffB);
;             PG8_WAIT_V(6); PG8_BAR; PG8_MMA(1, 1, At, B1); PG8_BAR;
;             PG8_LDB(B0, 1, 0); PG8_SCHED; PG8_LDA(At, 1, 0); PG8_STAGE(PG8_SA(0, 1), a2 + hstepA, voffA);
;             PG8_WAIT_L(8); PG8_BAR; PG8_WAIT_L(0); PG8_MMA(0, 0, At, B0); PG8_BAR; PG8_SCHED;
.LBB1_229:
	s_add_u32 s26, s24, 0xfff80080
	s_addc_u32 s27, s25, -1
	s_cmp_eq_u32 s57, 4
	s_cselect_b32 s29, s17, s27
	s_cselect_b32 s28, s43, s26
	s_cselect_b32 s27, s53, s56
	s_cselect_b32 s26, s54, s55
	s_add_i32 m0, s2, 0xc000
	ds_read_b128 v[160:163], v168
	ds_read_b128 v[170:173], v168 offset:1024
	ds_read_b128 v[174:177], v168 offset:2048
	ds_read_b128 v[178:181], v168 offset:3072
	ds_read_b128 v[182:185], v168 offset:4096
	ds_read_b128 v[186:189], v168 offset:5120
	ds_read_b128 v[190:193], v168 offset:6144
	ds_read_b128 v[198:201], v168 offset:7168
	global_load_lds_dwordx4 v154, s[24:25]
	s_add_i32 m0, s2, 0xe000
	s_nop 0
	global_load_lds_dwordx4 v152, s[24:25]
	s_waitcnt lgkmcnt(8)
	s_setprio 1
	s_barrier
	s_waitcnt lgkmcnt(7)
	v_mfma_f32_16x16x32_bf16 v[140:143], v[72:75], v[160:163], v[140:143]
	v_mfma_f32_16x16x32_bf16 v[136:139], v[80:83], v[160:163], v[136:139]
	s_waitcnt lgkmcnt(5)
	v_mfma_f32_16x16x32_bf16 v[124:127], v[72:75], v[174:177], v[124:127]
	v_mfma_f32_16x16x32_bf16 v[120:123], v[80:83], v[174:177], v[120:123]
	s_waitcnt lgkmcnt(3)
	v_mfma_f32_16x16x32_bf16 v[108:111], v[72:75], v[182:185], v[108:111]
	v_mfma_f32_16x16x32_bf16 v[104:107], v[80:83], v[182:185], v[104:107]
	s_waitcnt lgkmcnt(1)
	v_mfma_f32_16x16x32_bf16 v[92:95], v[72:75], v[190:193], v[92:95]
	v_mfma_f32_16x16x32_bf16 v[88:91], v[80:83], v[190:193], v[88:91]
	v_mfma_f32_16x16x32_bf16 v[140:143], v[76:79], v[170:173], v[140:143]
	s_add_i32 s58, s48, s34
	v_mfma_f32_16x16x32_bf16 v[136:139], v[84:87], v[170:173], v[136:139]
	v_lshl_add_u64 v[194:195], s[26:27], 0, v[148:149]
	v_mfma_f32_16x16x32_bf16 v[124:127], v[76:79], v[178:181], v[124:127]
	v_lshl_add_u64 v[218:219], s[26:27], 0, v[144:145]
	v_mfma_f32_16x16x32_bf16 v[120:123], v[84:87], v[178:181], v[120:123]
	v_mfma_f32_16x16x32_bf16 v[108:111], v[76:79], v[186:189], v[108:111]
	v_mfma_f32_16x16x32_bf16 v[104:107], v[84:87], v[186:189], v[104:107]
	s_waitcnt lgkmcnt(0)
	v_mfma_f32_16x16x32_bf16 v[92:95], v[76:79], v[198:201], v[92:95]
	s_mov_b32 m0, s58
	v_mfma_f32_16x16x32_bf16 v[88:91], v[84:87], v[198:201], v[88:91]
	s_barrier
	s_setprio 0
	ds_read_b128 v[202:205], v169
	ds_read_b128 v[206:209], v169 offset:1024
	ds_read_b128 v[210:213], v169 offset:2048
	global_load_lds_dwordx4 v[194:195], off
	s_add_i32 m0, s58, 0x2000
	ds_read_b128 v[214:217], v169 offset:3072
	global_load_lds_dwordx4 v[218:219], off
	s_setprio 1
	s_barrier
	s_waitcnt lgkmcnt(3)
	v_mfma_f32_16x16x32_bf16 v[132:135], v[202:205], v[160:163], v[132:135]
	s_waitcnt lgkmcnt(1)
	v_mfma_f32_16x16x32_bf16 v[128:131], v[210:213], v[160:163], v[128:131]
	v_mfma_f32_16x16x32_bf16 v[116:119], v[202:205], v[174:177], v[116:119]
	v_mfma_f32_16x16x32_bf16 v[112:115], v[210:213], v[174:177], v[112:115]
	v_mfma_f32_16x16x32_bf16 v[100:103], v[202:205], v[182:185], v[100:103]
	v_mfma_f32_16x16x32_bf16 v[96:99], v[210:213], v[182:185], v[96:99]
	v_mfma_f32_16x16x32_bf16 v[68:71], v[202:205], v[190:193], v[68:71]
	v_mfma_f32_16x16x32_bf16 v[64:67], v[210:213], v[190:193], v[64:67]
	v_mfma_f32_16x16x32_bf16 v[132:135], v[206:209], v[170:173], v[132:135]
	v_lshl_add_u64 v[222:223], s[28:29], 0, v[146:147]
	s_mov_b32 m0, s2
	s_waitcnt lgkmcnt(0)
	v_mfma_f32_16x16x32_bf16 v[128:131], v[214:217], v[170:173], v[128:131]
	v_lshl_add_u64 v[220:221], s[28:29], 0, v[150:151]
	v_mfma_f32_16x16x32_bf16 v[116:119], v[206:209], v[178:181], v[116:119]
	v_mfma_f32_16x16x32_bf16 v[112:115], v[214:217], v[178:181], v[112:115]
	v_mfma_f32_16x16x32_bf16 v[100:103], v[206:209], v[186:189], v[100:103]
	v_mfma_f32_16x16x32_bf16 v[96:99], v[214:217], v[186:189], v[96:99]
	v_mfma_f32_16x16x32_bf16 v[68:71], v[206:209], v[198:201], v[68:71]
	v_mfma_f32_16x16x32_bf16 v[64:67], v[214:217], v[198:201], v[64:67]
	s_barrier
	s_setprio 0
	ds_read_b128 v[160:163], v168 offset:16384
	ds_read_b128 v[170:173], v168 offset:17408
	ds_read_b128 v[174:177], v168 offset:18432
	ds_read_b128 v[178:181], v168 offset:19456
	ds_read_b128 v[182:185], v168 offset:20480
	ds_read_b128 v[186:189], v168 offset:21504
	ds_read_b128 v[190:193], v168 offset:22528
	global_load_lds_dwordx4 v[220:221], off
	s_mov_b32 m0, s4
	ds_read_b128 v[198:201], v168 offset:23552
	global_load_lds_dwordx4 v[222:223], off
	s_waitcnt vmcnt(10)
	s_setprio 1
	s_barrier
	s_waitcnt lgkmcnt(7)
	v_mfma_f32_16x16x32_bf16 v[60:63], v[72:75], v[160:163], v[60:63]
	v_mfma_f32_16x16x32_bf16 v[56:59], v[80:83], v[160:163], v[56:59]
	s_waitcnt lgkmcnt(5)
	v_mfma_f32_16x16x32_bf16 v[44:47], v[72:75], v[174:177], v[44:47]
	v_mfma_f32_16x16x32_bf16 v[40:43], v[80:83], v[174:177], v[40:43]
	s_waitcnt lgkmcnt(3)
	v_mfma_f32_16x16x32_bf16 v[28:31], v[72:75], v[182:185], v[28:31]
	v_mfma_f32_16x16x32_bf16 v[24:27], v[80:83], v[182:185], v[24:27]
	s_waitcnt lgkmcnt(1)
	v_mfma_f32_16x16x32_bf16 v[12:15], v[72:75], v[190:193], v[12:15]
	v_mfma_f32_16x16x32_bf16 v[8:11], v[80:83], v[190:193], v[8:11]
	v_mfma_f32_16x16x32_bf16 v[60:63], v[76:79], v[170:173], v[60:63]
	s_add_u32 s58, s26, 0x20000
	s_addc_u32 s59, s27, 0
	v_mfma_f32_16x16x32_bf16 v[56:59], v[84:87], v[170:173], v[56:59]
	s_add_i32 s60, s49, s34
	v_mfma_f32_16x16x32_bf16 v[44:47], v[76:79], v[178:181], v[44:47]
	v_mfma_f32_16x16x32_bf16 v[40:43], v[84:87], v[178:181], v[40:43]
	v_mfma_f32_16x16x32_bf16 v[28:31], v[76:79], v[186:189], v[28:31]
	v_mfma_f32_16x16x32_bf16 v[24:27], v[84:87], v[186:189], v[24:27]
	s_waitcnt lgkmcnt(0)
	v_mfma_f32_16x16x32_bf16 v[12:15], v[76:79], v[198:201], v[12:15]
	s_mov_b32 m0, s60
	v_mfma_f32_16x16x32_bf16 v[8:11], v[84:87], v[198:201], v[8:11]
	s_barrier
; #define PG8_STAGE(bufoff, gbase, voff) do { _Pragma("unroll") for (int _i = 0; _i < 2; ++_i) \
;         __builtin_amdgcn_global_load_lds((const unsigned*)((const char*)(gbase) + (voff)[_i]), (LAS unsigned*)(lds + (bufoff) + ldsw + _i * 8192), 16, 0, 0); } while (0)
; #define PG8_LDA(dst, b, h) do { _Pragma("unroll") for (int m = 0; m < 4; ++m) _Pragma("unroll") for (int k = 0; k < 2; ++k) dst[m][k] = *(const LAS bf16x8*)(lds + PG8_SA(b, h) + aoff + m * 2048 + k * 1024); } while (0)
; #define PG8_LDB(dst, b, h) do { _Pragma("unroll") for (int n = 0; n < 2; ++n) _Pragma("unroll") for (int k = 0; k < 2; ++k) dst[n][k] = *(const LAS bf16x8*)(lds + PG8_SB(b, h) + boff + n * 2048 + k * 1024); } while (0)
; #define PG8_MMA(ai, bj, At, Bt) do { __builtin_amdgcn_s_setprio(1); _Pragma("unroll") for (int m = 0; m < 4; ++m) _Pragma("unroll") for (int n = 0; n < 2; ++n) _Pragma("unroll") for (int k = 0; k < 2; ++k) \
;         acc[ai][bj][m][n] = __builtin_amdgcn_mfma_f32_16x16x32_bf16(Bt[n][k], At[m][k], acc[ai][bj][m][n], 0, 0, 0); __builtin_amdgcn_s_setprio(0); } while (0)
; #define PG8_WAIT_V(n) asm volatile("s_waitcnt vmcnt(" #n ")" ::: "memory")
; #define PG8_WAIT_L(n) asm volatile("s_waitcnt lgkmcnt(" #n ")" ::: "memory")
; #define PG8_BAR __builtin_amdgcn_s_barrier()
; #define PG8_SCHED __builtin_amdgcn_sched_barrier(0)
; template <class Map, class Epi>
; DI void gemm_phase(LAS unsigned char* lds, const Map& MP, const Epi& E, const int nM, const int nN, const int K, const int lda, const int ldb) {
;     ...
;             PG8_WAIT_V(6); PG8_BAR; PG8_MMA(1, 1, At, B1); PG8_BAR;
;             PG8_LDB(B0, 1, 0); PG8_SCHED; PG8_LDA(At, 1, 0); PG8_STAGE(PG8_SA(0, 1), a2 + hstepA, voffA);
;             PG8_WAIT_L(8); PG8_BAR; PG8_WAIT_L(0); PG8_MMA(0, 0, At, B0); PG8_BAR; PG8_SCHED;
;             PG8_LDB(B1, 1, 1); PG8_STAGE(PG8_SB(1, 0), b3, voffB);
;             PG8_BAR; PG8_WAIT_L(0); PG8_MMA(0, 1, At, B1); PG8_BAR;
;             PG8_LDA(At, 1, 1); PG8_STAGE(PG8_SA(1, 0), a3, voffA);
;             PG8_BAR; PG8_WAIT_L(0); PG8_MMA(1, 0, At, B0); PG8_BAR; PG8_SCHED;
	s_setprio 0
	global_load_lds_dwordx4 v148, s[58:59]
	s_add_i32 m0, s60, 0x2000
	s_nop 0
	global_load_lds_dwordx4 v144, s[58:59]
	s_waitcnt vmcnt(6)
	s_setprio 1
	s_barrier
	v_mfma_f32_16x16x32_bf16 v[52:55], v[202:205], v[160:163], v[52:55]
	v_mfma_f32_16x16x32_bf16 v[48:51], v[210:213], v[160:163], v[48:51]
	s_add_i32 s58, 0, 0x18000
	v_add_u32_e32 v84, s58, v166
	ds_read_b128 v[72:75], v84
	v_mfma_f32_16x16x32_bf16 v[36:39], v[202:205], v[174:177], v[36:39]
	v_mfma_f32_16x16x32_bf16 v[32:35], v[210:213], v[174:177], v[32:35]
	ds_read_b128 v[76:79], v84 offset:1024
	v_mfma_f32_16x16x32_bf16 v[20:23], v[202:205], v[182:185], v[20:23]
	v_mfma_f32_16x16x32_bf16 v[16:19], v[210:213], v[182:185], v[16:19]
	ds_read_b128 v[80:83], v84 offset:2048
	v_mfma_f32_16x16x32_bf16 v[4:7], v[202:205], v[190:193], v[4:7]
	v_mfma_f32_16x16x32_bf16 v[0:3], v[210:213], v[190:193], v[0:3]
	ds_read_b128 v[84:87], v84 offset:3072
	v_mfma_f32_16x16x32_bf16 v[52:55], v[206:209], v[170:173], v[52:55]
	s_add_u32 s28, s28, 0x80000
	s_addc_u32 s29, s29, 0
	v_mfma_f32_16x16x32_bf16 v[48:51], v[214:217], v[170:173], v[48:51]
	v_mfma_f32_16x16x32_bf16 v[36:39], v[206:209], v[178:181], v[36:39]
	v_mfma_f32_16x16x32_bf16 v[32:35], v[214:217], v[178:181], v[32:35]
	v_mfma_f32_16x16x32_bf16 v[20:23], v[206:209], v[186:189], v[20:23]
	v_mfma_f32_16x16x32_bf16 v[16:19], v[214:217], v[186:189], v[16:19]
	v_mfma_f32_16x16x32_bf16 v[4:7], v[206:209], v[198:201], v[4:7]
	s_mov_b32 m0, s5
	v_mfma_f32_16x16x32_bf16 v[0:3], v[214:217], v[198:201], v[0:3]
	s_barrier
	s_setprio 0
	ds_read_b128 v[160:163], v168 offset:32768
	ds_read_b128 v[170:173], v168 offset:33792
	ds_read_b128 v[174:177], v168 offset:34816
	ds_read_b128 v[178:181], v168 offset:35840
	ds_read_b128 v[182:185], v168 offset:36864
	ds_read_b128 v[186:189], v168 offset:37888
	ds_read_b128 v[190:193], v168 offset:38912
	global_load_lds_dwordx4 v150, s[28:29]
	s_mov_b32 m0, s23
	ds_read_b128 v[198:201], v168 offset:39936
	global_load_lds_dwordx4 v146, s[28:29]
	s_waitcnt lgkmcnt(8)
	s_setprio 1
	s_barrier
	s_waitcnt lgkmcnt(7)
	v_mfma_f32_16x16x32_bf16 v[140:143], v[72:75], v[160:163], v[140:143]
	v_mfma_f32_16x16x32_bf16 v[136:139], v[80:83], v[160:163], v[136:139]
	s_waitcnt lgkmcnt(5)
	v_mfma_f32_16x16x32_bf16 v[124:127], v[72:75], v[174:177], v[124:127]
	v_mfma_f32_16x16x32_bf16 v[120:123], v[80:83], v[174:177], v[120:123]
	s_waitcnt lgkmcnt(3)
	v_mfma_f32_16x16x32_bf16 v[108:111], v[72:75], v[182:185], v[108:111]
	v_mfma_f32_16x16x32_bf16 v[104:107], v[80:83], v[182:185], v[104:107]
	s_waitcnt lgkmcnt(1)
	v_mfma_f32_16x16x32_bf16 v[92:95], v[72:75], v[190:193], v[92:95]
	v_mfma_f32_16x16x32_bf16 v[88:91], v[80:83], v[190:193], v[88:91]
	v_mfma_f32_16x16x32_bf16 v[140:143], v[76:79], v[170:173], v[140:143]
	s_add_i32 s28, 0, 0x1c000
	v_mfma_f32_16x16x32_bf16 v[136:139], v[84:87], v[170:173], v[136:139]
	s_add_i32 s29, s58, s34
	v_mfma_f32_16x16x32_bf16 v[124:127], v[76:79], v[178:181], v[124:127]
	v_add_u32_e32 v196, s28, v166
	v_mfma_f32_16x16x32_bf16 v[120:123], v[84:87], v[178:181], v[120:123]
	v_lshl_add_u64 v[194:195], v[194:195], 0, s[12:13]
	v_mfma_f32_16x16x32_bf16 v[108:111], v[76:79], v[186:189], v[108:111]
	v_mfma_f32_16x16x32_bf16 v[104:107], v[84:87], v[186:189], v[104:107]
	s_waitcnt lgkmcnt(0)
	v_mfma_f32_16x16x32_bf16 v[92:95], v[76:79], v[198:201], v[92:95]
	s_mov_b32 m0, s29
	v_mfma_f32_16x16x32_bf16 v[88:91], v[84:87], v[198:201], v[88:91]
	s_barrier
	s_setprio 0
	ds_read_b128 v[202:205], v196
	ds_read_b128 v[206:209], v196 offset:1024
	ds_read_b128 v[210:213], v196 offset:2048
	global_load_lds_dwordx4 v[194:195], off
	v_lshl_add_u64 v[194:195], v[218:219], 0, s[12:13]
	s_add_i32 m0, s29, 0x2000
	ds_read_b128 v[214:217], v196 offset:3072
	global_load_lds_dwordx4 v[194:195], off
	s_setprio 1
	s_barrier
	s_waitcnt lgkmcnt(3)
	v_mfma_f32_16x16x32_bf16 v[132:135], v[202:205], v[160:163], v[132:135]
	s_waitcnt lgkmcnt(1)
	v_mfma_f32_16x16x32_bf16 v[128:131], v[210:213], v[160:163], v[128:131]
	v_mfma_f32_16x16x32_bf16 v[116:119], v[202:205], v[174:177], v[116:119]
	v_mfma_f32_16x16x32_bf16 v[112:115], v[210:213], v[174:177], v[112:115]
	v_mfma_f32_16x16x32_bf16 v[100:103], v[202:205], v[182:185], v[100:103]
	v_mfma_f32_16x16x32_bf16 v[96:99], v[210:213], v[182:185], v[96:99]
	v_mfma_f32_16x16x32_bf16 v[68:71], v[202:205], v[190:193], v[68:71]
	v_mfma_f32_16x16x32_bf16 v[64:67], v[210:213], v[190:193], v[64:67]
	v_mfma_f32_16x16x32_bf16 v[132:135], v[206:209], v[170:173], v[132:135]
	s_mov_b32 m0, s39
	s_waitcnt lgkmcnt(0)
	v_mfma_f32_16x16x32_bf16 v[128:131], v[214:217], v[170:173], v[128:131]
	v_lshl_add_u64 v[194:195], v[220:221], 0, s[12:13]
	v_mfma_f32_16x16x32_bf16 v[116:119], v[206:209], v[178:181], v[116:119]
	v_mfma_f32_16x16x32_bf16 v[112:115], v[214:217], v[178:181], v[112:115]
	v_mfma_f32_16x16x32_bf16 v[100:103], v[206:209], v[186:189], v[100:103]
	v_mfma_f32_16x16x32_bf16 v[96:99], v[214:217], v[186:189], v[96:99]
	v_mfma_f32_16x16x32_bf16 v[68:71], v[206:209], v[198:201], v[68:71]
	v_mfma_f32_16x16x32_bf16 v[64:67], v[214:217], v[198:201], v[64:67]
	s_barrier
; #define PG8_STAGE(bufoff, gbase, voff) do { _Pragma("unroll") for (int _i = 0; _i < 2; ++_i) \
;         __builtin_amdgcn_global_load_lds((const unsigned*)((const char*)(gbase) + (voff)[_i]), (LAS unsigned*)(lds + (bufoff) + ldsw + _i * 8192), 16, 0, 0); } while (0)
; #define PG8_LDA(dst, b, h) do { _Pragma("unroll") for (int m = 0; m < 4; ++m) _Pragma("unroll") for (int k = 0; k < 2; ++k) dst[m][k] = *(const LAS bf16x8*)(lds + PG8_SA(b, h) + aoff + m * 2048 + k * 1024); } while (0)
; #define PG8_LDB(dst, b, h) do { _Pragma("unroll") for (int n = 0; n < 2; ++n) _Pragma("unroll") for (int k = 0; k < 2; ++k) dst[n][k] = *(const LAS bf16x8*)(lds + PG8_SB(b, h) + boff + n * 2048 + k * 1024); } while (0)
; #define PG8_MMA(ai, bj, At, Bt) do { __builtin_amdgcn_s_setprio(1); _Pragma("unroll") for (int m = 0; m < 4; ++m) _Pragma("unroll") for (int n = 0; n < 2; ++n) _Pragma("unroll") for (int k = 0; k < 2; ++k) \
;         acc[ai][bj][m][n] = __builtin_amdgcn_mfma_f32_16x16x32_bf16(Bt[n][k], At[m][k], acc[ai][bj][m][n], 0, 0, 0); __builtin_amdgcn_s_setprio(0); } while (0)
; #define PG8_WAIT_V(n) asm volatile("s_waitcnt vmcnt(" #n ")" ::: "memory")
; #define PG8_WAIT_L(n) asm volatile("s_waitcnt lgkmcnt(" #n ")" ::: "memory")
;     DI void operator()(const f32x4 (&acc)[2][2][4][2], const Unit& u, int wr, int wc, int fr, int fq) const {
;         const int row0 = u.pm * BM + wr * 64 + fr, col0 = u.pn * BM + wc * 32 + 8 * fq;
;         f32x4 sc[2][2];
; #pragma unroll
;         for (int bj = 0; bj < 2; ++bj)
; #pragma unroll
;             for (int n = 0; n < 2; ++n) sc[bj][n] = scale ? *(const f32x4*)(scale + col0 + bj * HALF + 4 * n) : (f32x4){1.f, 1.f, 1.f, 1.f};
; template <class Map, class Epi>
; DI void gemm_phase(LAS unsigned char* lds, const Map& MP, const Epi& E, const int nM, const int nN, const int K, const int lda, const int ldb) {
;     ...
;             PG8_WAIT_L(8); PG8_BAR; PG8_WAIT_L(0); PG8_MMA(0, 0, At, B0); PG8_BAR; PG8_SCHED;
;             PG8_LDB(B1, 1, 1); PG8_STAGE(PG8_SB(1, 0), b3, voffB);
;             PG8_BAR; PG8_WAIT_L(0); PG8_MMA(0, 1, At, B1); PG8_BAR;
;             PG8_LDA(At, 1, 1); PG8_STAGE(PG8_SA(1, 0), a3, voffA);
;             PG8_BAR; PG8_WAIT_L(0); PG8_MMA(1, 0, At, B0); PG8_BAR; PG8_SCHED;
;             PG8_STAGE(PG8_SB(1, 1), b3 + hstepB, voffB);
;             PG8_WAIT_V(6); PG8_BAR; PG8_MMA(1, 1, At, B1); PG8_BAR;
	s_setprio 0
	ds_read_b128 v[160:163], v168 offset:49152
	ds_read_b128 v[170:173], v168 offset:50176
	ds_read_b128 v[174:177], v168 offset:51200
	ds_read_b128 v[178:181], v168 offset:52224
	ds_read_b128 v[182:185], v168 offset:53248
	ds_read_b128 v[186:189], v168 offset:54272
	ds_read_b128 v[190:193], v168 offset:55296
	global_load_lds_dwordx4 v[194:195], off
	v_lshl_add_u64 v[194:195], v[222:223], 0, s[12:13]
	s_mov_b32 m0, s46
	ds_read_b128 v[198:201], v168 offset:56320
	global_load_lds_dwordx4 v[194:195], off
	s_waitcnt vmcnt(10)
	s_setprio 1
	s_barrier
	s_waitcnt lgkmcnt(7)
	v_mfma_f32_16x16x32_bf16 v[60:63], v[72:75], v[160:163], v[60:63]
	v_mfma_f32_16x16x32_bf16 v[56:59], v[80:83], v[160:163], v[56:59]
	s_waitcnt lgkmcnt(5)
	v_mfma_f32_16x16x32_bf16 v[44:47], v[72:75], v[174:177], v[44:47]
	v_mfma_f32_16x16x32_bf16 v[40:43], v[80:83], v[174:177], v[40:43]
	s_waitcnt lgkmcnt(3)
	v_mfma_f32_16x16x32_bf16 v[28:31], v[72:75], v[182:185], v[28:31]
	v_mfma_f32_16x16x32_bf16 v[24:27], v[80:83], v[182:185], v[24:27]
	s_waitcnt lgkmcnt(1)
	v_mfma_f32_16x16x32_bf16 v[12:15], v[72:75], v[190:193], v[12:15]
	v_mfma_f32_16x16x32_bf16 v[8:11], v[80:83], v[190:193], v[8:11]
	v_mfma_f32_16x16x32_bf16 v[60:63], v[76:79], v[170:173], v[60:63]
	s_add_u32 s26, s26, 0x20080
	s_addc_u32 s27, s27, 0
	v_mfma_f32_16x16x32_bf16 v[56:59], v[84:87], v[170:173], v[56:59]
	s_add_i32 s28, s28, s34
	v_mfma_f32_16x16x32_bf16 v[44:47], v[76:79], v[178:181], v[44:47]
	v_mfma_f32_16x16x32_bf16 v[40:43], v[84:87], v[178:181], v[40:43]
	v_mfma_f32_16x16x32_bf16 v[28:31], v[76:79], v[186:189], v[28:31]
	v_mfma_f32_16x16x32_bf16 v[24:27], v[84:87], v[186:189], v[24:27]
	s_waitcnt lgkmcnt(0)
	v_mfma_f32_16x16x32_bf16 v[12:15], v[76:79], v[198:201], v[12:15]
	s_mov_b32 m0, s28
	v_mfma_f32_16x16x32_bf16 v[8:11], v[84:87], v[198:201], v[8:11]
	s_barrier
	s_setprio 0
	global_load_lds_dwordx4 v148, s[26:27]
	s_add_i32 m0, s28, 0x2000
	s_nop 0
	global_load_lds_dwordx4 v144, s[26:27]
	s_waitcnt vmcnt(6)
	s_setprio 1
	s_barrier
	v_mfma_f32_16x16x32_bf16 v[52:55], v[202:205], v[160:163], v[52:55]
	v_mfma_f32_16x16x32_bf16 v[48:51], v[210:213], v[160:163], v[48:51]
	ds_read_b128 v[72:75], v167
	v_mfma_f32_16x16x32_bf16 v[36:39], v[202:205], v[174:177], v[36:39]
	v_mfma_f32_16x16x32_bf16 v[32:35], v[210:213], v[174:177], v[32:35]
	ds_read_b128 v[76:79], v167 offset:1024
	v_mfma_f32_16x16x32_bf16 v[20:23], v[202:205], v[182:185], v[20:23]
	v_mfma_f32_16x16x32_bf16 v[16:19], v[210:213], v[182:185], v[16:19]
	ds_read_b128 v[80:83], v167 offset:2048
	v_mfma_f32_16x16x32_bf16 v[4:7], v[202:205], v[190:193], v[4:7]
	v_mfma_f32_16x16x32_bf16 v[0:3], v[210:213], v[190:193], v[0:3]
	ds_read_b128 v[84:87], v167 offset:3072
	v_mfma_f32_16x16x32_bf16 v[52:55], v[206:209], v[170:173], v[52:55]
	s_add_i32 s57, s57, 2
	v_mfma_f32_16x16x32_bf16 v[48:51], v[214:217], v[170:173], v[48:51]
	s_add_u32 s55, s55, 0x100
	s_addc_u32 s56, s56, 0
	v_mfma_f32_16x16x32_bf16 v[36:39], v[206:209], v[178:181], v[36:39]
	s_add_u32 s24, s24, 0x100
	s_addc_u32 s25, s25, 0
	v_mfma_f32_16x16x32_bf16 v[32:35], v[214:217], v[178:181], v[32:35]
	s_cmp_gt_u32 s57, 5
	v_mfma_f32_16x16x32_bf16 v[20:23], v[206:209], v[186:189], v[20:23]
	v_mfma_f32_16x16x32_bf16 v[16:19], v[214:217], v[186:189], v[16:19]
	v_mfma_f32_16x16x32_bf16 v[4:7], v[206:209], v[198:201], v[4:7]
	v_mfma_f32_16x16x32_bf16 v[0:3], v[214:217], v[198:201], v[0:3]
	s_barrier
	s_setprio 0
	s_cbranch_scc0 .LBB1_229
	s_waitcnt lgkmcnt(0)
	s_lshl_b32 s17, s42, 8
	v_mov_b32_e32 v170, v164
	v_mov_b32_e32 v72, v165
	s_or_b32 s17, s17, s38
	v_mov_b32_e32 v80, 1.0
	v_lshl_add_u32 v160, v72, 3, s17
	v_ashrrev_i32_e32 v161, 31, v160
	v_cndmask_b32_e64 v72, 0, 1, s[14:15]
	v_lshl_add_u64 v[162:163], v[160:161], 2, s[8:9]
	v_cmp_ne_u32_e64 s[42:43], 1, v72
	s_andn2_b64 vcc, exec, s[14:15]
	v_mov_b32_e32 v84, 1.0
	v_mov_b32_e32 v85, 1.0
	v_mov_b32_e32 v86, 1.0
	v_mov_b32_e32 v87, 1.0
	s_cbranch_vccnz .LBB1_232
	global_load_dwordx4 v[84:87], v[162:163], off

; #define PG8_STAGE(bufoff, gbase, voff) do { _Pragma("unroll") for (int _i = 0; _i < 2; ++_i) \
;         __builtin_amdgcn_global_load_lds((const unsigned*)((const char*)(gbase) + (voff)[_i]), (LAS unsigned*)(lds + (bufoff) + ldsw + _i * 8192), 16, 0, 0); } while (0)
; #define PG8_LDA(dst, b, h) do { _Pragma("unroll") for (int m = 0; m < 4; ++m) _Pragma("unroll") for (int k = 0; k < 2; ++k) dst[m][k] = *(const LAS bf16x8*)(lds + PG8_SA(b, h) + aoff + m * 2048 + k * 1024); } while (0)
; #define PG8_LDB(dst, b, h) do { _Pragma("unroll") for (int n = 0; n < 2; ++n) _Pragma("unroll") for (int k = 0; k < 2; ++k) dst[n][k] = *(const LAS bf16x8*)(lds + PG8_SB(b, h) + boff + n * 2048 + k * 1024); } while (0)
; #define PG8_MMA(ai, bj, At, Bt) do { __builtin_amdgcn_s_setprio(1); _Pragma("unroll") for (int m = 0; m < 4; ++m) _Pragma("unroll") for (int n = 0; n < 2; ++n) _Pragma("unroll") for (int k = 0; k < 2; ++k) \
;         acc[ai][bj][m][n] = __builtin_amdgcn_mfma_f32_16x16x32_bf16(Bt[n][k], At[m][k], acc[ai][bj][m][n], 0, 0, 0); __builtin_amdgcn_s_setprio(0); } while (0)
; #define PG8_WAIT_V(n) asm volatile("s_waitcnt vmcnt(" #n ")" ::: "memory")
; #define PG8_WAIT_L(n) asm volatile("s_waitcnt lgkmcnt(" #n ")" ::: "memory")
; template <class Map, class Epi>
; DI void gemm_phase(LAS unsigned char* lds, const Map& MP, const Epi& E, const int nM, const int nN, const int K, const int lda, const int ldb) {
;     ...
;             const bool last = (t == nt - 2);
;             const char* a1 = cA + (size_t)(t + 1) * kstep;
;             const char* a2 = last ? nA : cA + (size_t)(t + 2) * kstep; const char* b2 = last ? nB : cB + (size_t)(t + 2) * kstep;
;             const char* a3 = a2 + kstep; const char* b3 = b2 + kstep;
;             PG8_LDB(B0, 0, 0); PG8_SCHED; PG8_LDA(At, 0, 0); PG8_STAGE(PG8_SA(1, 1), a1 + hstepA, voffA);
;             PG8_WAIT_L(8); PG8_BAR; PG8_WAIT_L(0); PG8_MMA(0, 0, At, B0); PG8_BAR; PG8_SCHED;
;             PG8_LDB(B1, 0, 1); PG8_STAGE(PG8_SB(0, 0), b2, voffB);
;             PG8_BAR; PG8_WAIT_L(0); PG8_MMA(0, 1, At, B1); PG8_BAR;
;             PG8_LDA(At, 0, 1); PG8_STAGE(PG8_SA(0, 0), a2, voffA);
;             PG8_BAR; PG8_WAIT_L(0); PG8_MMA(1, 0, At, B0); PG8_BAR; PG8_SCHED;
;             PG8_STAGE(PG8_SB(0, 1), b2 + hstepB, voffB);
;             PG8_WAIT_V(6); PG8_BAR; PG8_MMA(1, 1, At, B1); PG8_BAR;
.LBB1_380:
	s_add_u32 s28, s44, 0xfff80080
	s_addc_u32 s29, s45, -1
	s_cmp_eq_u32 vcc_hi, 28
	s_cselect_b32 s47, s23, s29
	s_cselect_b32 s46, s61, s28
	s_cselect_b32 s29, s21, vcc_lo
	s_cselect_b32 s28, s58, s59
	s_add_i32 m0, s38, 0xc000
	ds_read_b128 v[96:99], v190
	ds_read_b128 v[100:103], v190 offset:1024
	ds_read_b128 v[108:111], v190 offset:2048
	ds_read_b128 v[112:115], v190 offset:3072
	ds_read_b128 v[160:163], v190 offset:4096
	ds_read_b128 v[164:167], v190 offset:5120
	ds_read_b128 v[198:201], v190 offset:6144
	ds_read_b128 v[202:205], v190 offset:7168
	global_load_lds_dwordx4 v178, s[44:45]
	s_add_i32 m0, s38, 0xe000
	s_nop 0
	global_load_lds_dwordx4 v176, s[44:45]
	s_waitcnt lgkmcnt(8)
	s_setprio 1
	s_barrier
	s_waitcnt lgkmcnt(7)
	v_mfma_f32_16x16x32_bf16 v[148:151], v[80:83], v[96:99], v[148:151]
	v_mfma_f32_16x16x32_bf16 v[144:147], v[88:91], v[96:99], v[144:147]
	s_waitcnt lgkmcnt(5)
	v_mfma_f32_16x16x32_bf16 v[136:139], v[80:83], v[108:111], v[136:139]
	v_mfma_f32_16x16x32_bf16 v[128:131], v[88:91], v[108:111], v[128:131]
	s_waitcnt lgkmcnt(3)
	v_mfma_f32_16x16x32_bf16 v[120:123], v[80:83], v[160:163], v[120:123]
	v_mfma_f32_16x16x32_bf16 v[104:107], v[88:91], v[160:163], v[104:107]
	s_waitcnt lgkmcnt(1)
	v_mfma_f32_16x16x32_bf16 v[76:79], v[80:83], v[198:201], v[76:79]
	v_mfma_f32_16x16x32_bf16 v[72:75], v[88:91], v[198:201], v[72:75]
	v_mfma_f32_16x16x32_bf16 v[148:151], v[84:87], v[100:103], v[148:151]
	s_add_i32 s68, s5, s37
	v_mfma_f32_16x16x32_bf16 v[144:147], v[92:95], v[100:103], v[144:147]
	v_lshl_add_u64 v[184:185], s[28:29], 0, v[172:173]
	v_mfma_f32_16x16x32_bf16 v[136:139], v[84:87], v[112:115], v[136:139]
	v_lshl_add_u64 v[194:195], s[28:29], 0, v[168:169]
	v_mfma_f32_16x16x32_bf16 v[128:131], v[92:95], v[112:115], v[128:131]
	v_mfma_f32_16x16x32_bf16 v[120:123], v[84:87], v[164:167], v[120:123]
	v_mfma_f32_16x16x32_bf16 v[104:107], v[92:95], v[164:167], v[104:107]
	s_waitcnt lgkmcnt(0)
	v_mfma_f32_16x16x32_bf16 v[76:79], v[84:87], v[202:205], v[76:79]
	s_mov_b32 m0, s68
	v_mfma_f32_16x16x32_bf16 v[72:75], v[92:95], v[202:205], v[72:75]
	s_barrier
	s_setprio 0
	ds_read_b128 v[206:209], v191
	ds_read_b128 v[210:213], v191 offset:1024
	ds_read_b128 v[214:217], v191 offset:2048
	global_load_lds_dwordx4 v[184:185], off
	s_add_i32 m0, s68, 0x2000
	ds_read_b128 v[218:221], v191 offset:3072
	global_load_lds_dwordx4 v[194:195], off
	s_setprio 1
	s_barrier
	s_waitcnt lgkmcnt(3)
	v_mfma_f32_16x16x32_bf16 v[156:159], v[206:209], v[96:99], v[156:159]
	s_waitcnt lgkmcnt(1)
	v_mfma_f32_16x16x32_bf16 v[96:99], v[214:217], v[96:99], v[152:155]
	v_mfma_f32_16x16x32_bf16 v[156:159], v[210:213], v[100:103], v[156:159]
	s_waitcnt lgkmcnt(0)
	v_mfma_f32_16x16x32_bf16 v[96:99], v[218:221], v[100:103], v[96:99]
	v_mfma_f32_16x16x32_bf16 v[100:103], v[206:209], v[108:111], v[140:143]
	v_mfma_f32_16x16x32_bf16 v[108:111], v[214:217], v[108:111], v[132:135]
	v_mfma_f32_16x16x32_bf16 v[116:119], v[214:217], v[160:163], v[116:119]
	v_mfma_f32_16x16x32_bf16 v[68:71], v[206:209], v[198:201], v[68:71]
	v_mfma_f32_16x16x32_bf16 v[64:67], v[214:217], v[198:201], v[64:67]
	v_lshl_add_u64 v[234:235], s[46:47], 0, v[170:171]
	s_mov_b32 m0, s38
	v_mfma_f32_16x16x32_bf16 v[100:103], v[210:213], v[112:115], v[100:103]
	v_lshl_add_u64 v[226:227], s[46:47], 0, v[174:175]
	v_mfma_f32_16x16x32_bf16 v[108:111], v[218:221], v[112:115], v[108:111]
	v_mfma_f32_16x16x32_bf16 v[112:115], v[206:209], v[160:163], v[124:127]
	v_mfma_f32_16x16x32_bf16 v[116:119], v[218:221], v[164:167], v[116:119]
	v_mfma_f32_16x16x32_bf16 v[68:71], v[210:213], v[202:205], v[68:71]
	v_mfma_f32_16x16x32_bf16 v[64:67], v[218:221], v[202:205], v[64:67]
	v_mfma_f32_16x16x32_bf16 v[112:115], v[210:213], v[164:167], v[112:115]
	s_barrier
	s_setprio 0
	ds_read_b128 v[124:127], v190 offset:16384
	ds_read_b128 v[132:135], v190 offset:17408
	ds_read_b128 v[140:143], v190 offset:18432
	ds_read_b128 v[152:155], v190 offset:19456
	ds_read_b128 v[160:163], v190 offset:20480
	ds_read_b128 v[164:167], v190 offset:21504
	ds_read_b128 v[198:201], v190 offset:22528
	global_load_lds_dwordx4 v[226:227], off
	s_mov_b32 m0, s39
	ds_read_b128 v[202:205], v190 offset:23552
	global_load_lds_dwordx4 v[234:235], off
	s_waitcnt vmcnt(10)
	s_setprio 1
	s_barrier
	s_waitcnt lgkmcnt(7)
	v_mfma_f32_16x16x32_bf16 v[60:63], v[80:83], v[124:127], v[60:63]
	v_mfma_f32_16x16x32_bf16 v[48:51], v[88:91], v[124:127], v[48:51]
	s_waitcnt lgkmcnt(5)
	v_mfma_f32_16x16x32_bf16 v[40:43], v[80:83], v[140:143], v[40:43]
	v_mfma_f32_16x16x32_bf16 v[32:35], v[88:91], v[140:143], v[32:35]
	s_waitcnt lgkmcnt(3)
	v_mfma_f32_16x16x32_bf16 v[24:27], v[80:83], v[160:163], v[24:27]
	v_mfma_f32_16x16x32_bf16 v[16:19], v[88:91], v[160:163], v[16:19]
	s_waitcnt lgkmcnt(1)
	v_mfma_f32_16x16x32_bf16 v[12:15], v[80:83], v[198:201], v[12:15]
	v_mfma_f32_16x16x32_bf16 v[8:11], v[88:91], v[198:201], v[8:11]
	v_mfma_f32_16x16x32_bf16 v[60:63], v[84:87], v[132:135], v[60:63]
	s_add_u32 s68, s28, 0x80000
	s_addc_u32 s69, s29, 0
	v_mfma_f32_16x16x32_bf16 v[48:51], v[92:95], v[132:135], v[48:51]
	s_add_i32 s70, s2, s37
	v_mfma_f32_16x16x32_bf16 v[40:43], v[84:87], v[152:155], v[40:43]
	v_mfma_f32_16x16x32_bf16 v[32:35], v[92:95], v[152:155], v[32:35]
	v_mfma_f32_16x16x32_bf16 v[24:27], v[84:87], v[164:167], v[24:27]
	v_mfma_f32_16x16x32_bf16 v[16:19], v[92:95], v[164:167], v[16:19]
	s_waitcnt lgkmcnt(0)
	v_mfma_f32_16x16x32_bf16 v[12:15], v[84:87], v[202:205], v[12:15]
	s_mov_b32 m0, s70
	v_mfma_f32_16x16x32_bf16 v[8:11], v[92:95], v[202:205], v[8:11]
	s_barrier
; #define PG8_STAGE(bufoff, gbase, voff) do { _Pragma("unroll") for (int _i = 0; _i < 2; ++_i) \
;         __builtin_amdgcn_global_load_lds((const unsigned*)((const char*)(gbase) + (voff)[_i]), (LAS unsigned*)(lds + (bufoff) + ldsw + _i * 8192), 16, 0, 0); } while (0)
; #define PG8_LDA(dst, b, h) do { _Pragma("unroll") for (int m = 0; m < 4; ++m) _Pragma("unroll") for (int k = 0; k < 2; ++k) dst[m][k] = *(const LAS bf16x8*)(lds + PG8_SA(b, h) + aoff + m * 2048 + k * 1024); } while (0)
; #define PG8_LDB(dst, b, h) do { _Pragma("unroll") for (int n = 0; n < 2; ++n) _Pragma("unroll") for (int k = 0; k < 2; ++k) dst[n][k] = *(const LAS bf16x8*)(lds + PG8_SB(b, h) + boff + n * 2048 + k * 1024); } while (0)
; #define PG8_MMA(ai, bj, At, Bt) do { __builtin_amdgcn_s_setprio(1); _Pragma("unroll") for (int m = 0; m < 4; ++m) _Pragma("unroll") for (int n = 0; n < 2; ++n) _Pragma("unroll") for (int k = 0; k < 2; ++k) \
;         acc[ai][bj][m][n] = __builtin_amdgcn_mfma_f32_16x16x32_bf16(Bt[n][k], At[m][k], acc[ai][bj][m][n], 0, 0, 0); __builtin_amdgcn_s_setprio(0); } while (0)
; #define PG8_WAIT_V(n) asm volatile("s_waitcnt vmcnt(" #n ")" ::: "memory")
; #define PG8_WAIT_L(n) asm volatile("s_waitcnt lgkmcnt(" #n ")" ::: "memory")
; #define PG8_BAR __builtin_amdgcn_s_barrier()
; #define PG8_SCHED __builtin_amdgcn_sched_barrier(0)
; template <class Map, class Epi>
; DI void gemm_phase(LAS unsigned char* lds, const Map& MP, const Epi& E, const int nM, const int nN, const int K, const int lda, const int ldb) {
;     ...
;             PG8_WAIT_V(6); PG8_BAR; PG8_MMA(1, 1, At, B1); PG8_BAR;
;             PG8_LDB(B0, 1, 0); PG8_SCHED; PG8_LDA(At, 1, 0); PG8_STAGE(PG8_SA(0, 1), a2 + hstepA, voffA);
;             PG8_WAIT_L(8); PG8_BAR; PG8_WAIT_L(0); PG8_MMA(0, 0, At, B0); PG8_BAR; PG8_SCHED;
;             PG8_LDB(B1, 1, 1); PG8_STAGE(PG8_SB(1, 0), b3, voffB);
;             PG8_BAR; PG8_WAIT_L(0); PG8_MMA(0, 1, At, B1); PG8_BAR;
;             PG8_LDA(At, 1, 1); PG8_STAGE(PG8_SA(1, 0), a3, voffA);
;             PG8_BAR; PG8_WAIT_L(0); PG8_MMA(1, 0, At, B0); PG8_BAR; PG8_SCHED;
	s_setprio 0
	global_load_lds_dwordx4 v172, s[68:69]
	s_add_i32 m0, s70, 0x2000
	s_nop 0
	global_load_lds_dwordx4 v168, s[68:69]
	s_waitcnt vmcnt(6)
	s_setprio 1
	s_barrier
	v_mfma_f32_16x16x32_bf16 v[56:59], v[206:209], v[124:127], v[56:59]
	v_mfma_f32_16x16x32_bf16 v[52:55], v[214:217], v[124:127], v[52:55]
	s_add_i32 s68, 0, 0x18000
	v_add_u32_e32 v92, s68, v188
	ds_read_b128 v[80:83], v92
	v_mfma_f32_16x16x32_bf16 v[44:47], v[206:209], v[140:143], v[44:47]
	v_mfma_f32_16x16x32_bf16 v[36:39], v[214:217], v[140:143], v[36:39]
	ds_read_b128 v[84:87], v92 offset:1024
	v_mfma_f32_16x16x32_bf16 v[28:31], v[206:209], v[160:163], v[28:31]
	v_mfma_f32_16x16x32_bf16 v[20:23], v[214:217], v[160:163], v[20:23]
	ds_read_b128 v[88:91], v92 offset:2048
	v_mfma_f32_16x16x32_bf16 v[4:7], v[206:209], v[198:201], v[4:7]
	v_mfma_f32_16x16x32_bf16 v[0:3], v[214:217], v[198:201], v[0:3]
	ds_read_b128 v[92:95], v92 offset:3072
	v_mfma_f32_16x16x32_bf16 v[56:59], v[210:213], v[132:135], v[56:59]
	s_add_u32 s46, s46, 0x80000
	s_addc_u32 s47, s47, 0
	v_mfma_f32_16x16x32_bf16 v[52:55], v[218:221], v[132:135], v[52:55]
	v_mfma_f32_16x16x32_bf16 v[44:47], v[210:213], v[152:155], v[44:47]
	v_mfma_f32_16x16x32_bf16 v[36:39], v[218:221], v[152:155], v[36:39]
	v_mfma_f32_16x16x32_bf16 v[28:31], v[210:213], v[164:167], v[28:31]
	v_mfma_f32_16x16x32_bf16 v[20:23], v[218:221], v[164:167], v[20:23]
	v_mfma_f32_16x16x32_bf16 v[4:7], v[210:213], v[202:205], v[4:7]
	s_mov_b32 m0, s56
	v_mfma_f32_16x16x32_bf16 v[0:3], v[218:221], v[202:205], v[0:3]
	s_barrier
	s_setprio 0
	ds_read_b128 v[124:127], v190 offset:32768
	ds_read_b128 v[132:135], v190 offset:33792
	ds_read_b128 v[160:163], v190 offset:34816
	ds_read_b128 v[164:167], v190 offset:35840
	ds_read_b128 v[198:201], v190 offset:36864
	ds_read_b128 v[202:205], v190 offset:37888
	ds_read_b128 v[206:209], v190 offset:38912
	global_load_lds_dwordx4 v174, s[46:47]
	s_mov_b32 m0, s57
	ds_read_b128 v[210:213], v190 offset:39936
	global_load_lds_dwordx4 v170, s[46:47]
	s_waitcnt lgkmcnt(8)
	s_setprio 1
	s_barrier
	s_waitcnt lgkmcnt(7)
	v_mfma_f32_16x16x32_bf16 v[140:143], v[80:83], v[124:127], v[148:151]
	s_waitcnt lgkmcnt(6)
	v_mfma_f32_16x16x32_bf16 v[148:151], v[84:87], v[132:135], v[140:143]
	v_mfma_f32_16x16x32_bf16 v[140:143], v[88:91], v[124:127], v[144:147]
	s_waitcnt lgkmcnt(5)
	v_mfma_f32_16x16x32_bf16 v[136:139], v[80:83], v[160:163], v[136:139]
	v_mfma_f32_16x16x32_bf16 v[128:131], v[88:91], v[160:163], v[128:131]
	s_waitcnt lgkmcnt(3)
	v_mfma_f32_16x16x32_bf16 v[120:123], v[80:83], v[198:201], v[120:123]
	v_mfma_f32_16x16x32_bf16 v[104:107], v[88:91], v[198:201], v[104:107]
	s_waitcnt lgkmcnt(1)
	v_mfma_f32_16x16x32_bf16 v[76:79], v[80:83], v[206:209], v[76:79]
	v_mfma_f32_16x16x32_bf16 v[72:75], v[88:91], v[206:209], v[72:75]
	s_add_i32 s46, 0, 0x1c000
	v_mfma_f32_16x16x32_bf16 v[144:147], v[92:95], v[132:135], v[140:143]
	v_add_u32_e32 v140, s46, v188
	v_mfma_f32_16x16x32_bf16 v[136:139], v[84:87], v[164:167], v[136:139]
	s_add_i32 s47, s68, s37
	v_mfma_f32_16x16x32_bf16 v[128:131], v[92:95], v[164:167], v[128:131]
	v_mfma_f32_16x16x32_bf16 v[120:123], v[84:87], v[202:205], v[120:123]
	v_mfma_f32_16x16x32_bf16 v[104:107], v[92:95], v[202:205], v[104:107]
	s_waitcnt lgkmcnt(0)
	v_mfma_f32_16x16x32_bf16 v[76:79], v[84:87], v[210:213], v[76:79]
	s_mov_b32 m0, s47
	v_mfma_f32_16x16x32_bf16 v[72:75], v[92:95], v[210:213], v[72:75]
	s_barrier
	s_setprio 0
	ds_read_b128 v[214:217], v140
	ds_read_b128 v[218:221], v140 offset:1024
	ds_read_b128 v[222:225], v140 offset:2048
	ds_read_b128 v[230:233], v140 offset:3072
	v_lshl_add_u64 v[140:141], v[184:185], 0, s[14:15]
	global_load_lds_dwordx4 v[140:141], off
	v_lshl_add_u64 v[140:141], v[194:195], 0, s[14:15]
	s_add_i32 m0, s47, 0x2000
	s_nop 0
	global_load_lds_dwordx4 v[140:141], off
	s_setprio 1
	s_barrier
	s_waitcnt lgkmcnt(1)
	v_mfma_f32_16x16x32_bf16 v[96:99], v[222:225], v[124:127], v[96:99]
	v_mfma_f32_16x16x32_bf16 v[140:143], v[214:217], v[124:127], v[156:159]
	s_waitcnt lgkmcnt(0)
	v_mfma_f32_16x16x32_bf16 v[152:155], v[230:233], v[132:135], v[96:99]
	v_mfma_f32_16x16x32_bf16 v[96:99], v[214:217], v[160:163], v[100:103]
	v_mfma_f32_16x16x32_bf16 v[156:159], v[218:221], v[132:135], v[140:143]
	v_mfma_f32_16x16x32_bf16 v[140:143], v[218:221], v[164:167], v[96:99]
	v_mfma_f32_16x16x32_bf16 v[96:99], v[222:225], v[160:163], v[108:111]
	v_mfma_f32_16x16x32_bf16 v[132:135], v[230:233], v[164:167], v[96:99]
	v_mfma_f32_16x16x32_bf16 v[96:99], v[214:217], v[198:201], v[112:115]
	s_mov_b32 m0, s62
	v_mfma_f32_16x16x32_bf16 v[124:127], v[218:221], v[202:205], v[96:99]
	v_lshl_add_u64 v[184:185], v[226:227], 0, s[14:15]
	v_mfma_f32_16x16x32_bf16 v[96:99], v[222:225], v[198:201], v[116:119]
	v_mfma_f32_16x16x32_bf16 v[68:71], v[214:217], v[206:209], v[68:71]
	v_mfma_f32_16x16x32_bf16 v[64:67], v[222:225], v[206:209], v[64:67]
	v_mfma_f32_16x16x32_bf16 v[116:119], v[230:233], v[202:205], v[96:99]
	v_mfma_f32_16x16x32_bf16 v[68:71], v[218:221], v[210:213], v[68:71]
	v_mfma_f32_16x16x32_bf16 v[64:67], v[230:233], v[210:213], v[64:67]
	s_barrier
	s_setprio 0
	ds_read_b128 v[96:99], v190 offset:49152
	ds_read_b128 v[100:103], v190 offset:50176
	ds_read_b128 v[108:111], v190 offset:51200
	ds_read_b128 v[112:115], v190 offset:52224
	ds_read_b128 v[160:163], v190 offset:53248
	ds_read_b128 v[164:167], v190 offset:54272
	ds_read_b128 v[198:201], v190 offset:55296
	global_load_lds_dwordx4 v[184:185], off
	v_lshl_add_u64 v[184:185], v[234:235], 0, s[14:15]
	s_mov_b32 m0, s63
	ds_read_b128 v[202:205], v190 offset:56320
	global_load_lds_dwordx4 v[184:185], off
	s_waitcnt vmcnt(10)
	s_setprio 1
	s_barrier
; #define PG8_STAGE(bufoff, gbase, voff) do { _Pragma("unroll") for (int _i = 0; _i < 2; ++_i) \
;         __builtin_amdgcn_global_load_lds((const unsigned*)((const char*)(gbase) + (voff)[_i]), (LAS unsigned*)(lds + (bufoff) + ldsw + _i * 8192), 16, 0, 0); } while (0)
; #define PG8_MMA(ai, bj, At, Bt) do { __builtin_amdgcn_s_setprio(1); _Pragma("unroll") for (int m = 0; m < 4; ++m) _Pragma("unroll") for (int n = 0; n < 2; ++n) _Pragma("unroll") for (int k = 0; k < 2; ++k) \
;         acc[ai][bj][m][n] = __builtin_amdgcn_mfma_f32_16x16x32_bf16(Bt[n][k], At[m][k], acc[ai][bj][m][n], 0, 0, 0); __builtin_amdgcn_s_setprio(0); } while (0)
; #define PG8_WAIT_V(n) asm volatile("s_waitcnt vmcnt(" #n ")" ::: "memory")
; #define PG8_WAIT_L(n) asm volatile("s_waitcnt lgkmcnt(" #n ")" ::: "memory")
; #define PG8_BAR __builtin_amdgcn_s_barrier()
; #define PG8_SCHED __builtin_amdgcn_sched_barrier(0)
; template <class Map, class Epi>
; DI void gemm_phase(LAS unsigned char* lds, const Map& MP, const Epi& E, const int nM, const int nN, const int K, const int lda, const int ldb) {
;     ...
;             PG8_BAR; PG8_WAIT_L(0); PG8_MMA(1, 0, At, B0); PG8_BAR; PG8_SCHED;
;             PG8_STAGE(PG8_SB(1, 1), b3 + hstepB, voffB);
;             PG8_WAIT_V(6); PG8_BAR; PG8_MMA(1, 1, At, B1); PG8_BAR;
	s_waitcnt lgkmcnt(7)
	v_mfma_f32_16x16x32_bf16 v[60:63], v[80:83], v[96:99], v[60:63]
	v_mfma_f32_16x16x32_bf16 v[48:51], v[88:91], v[96:99], v[48:51]
	s_waitcnt lgkmcnt(5)
	v_mfma_f32_16x16x32_bf16 v[40:43], v[80:83], v[108:111], v[40:43]
	v_mfma_f32_16x16x32_bf16 v[32:35], v[88:91], v[108:111], v[32:35]
	s_waitcnt lgkmcnt(3)
	v_mfma_f32_16x16x32_bf16 v[24:27], v[80:83], v[160:163], v[24:27]
	v_mfma_f32_16x16x32_bf16 v[16:19], v[88:91], v[160:163], v[16:19]
	s_waitcnt lgkmcnt(1)
	v_mfma_f32_16x16x32_bf16 v[12:15], v[80:83], v[198:201], v[12:15]
	v_mfma_f32_16x16x32_bf16 v[8:11], v[88:91], v[198:201], v[8:11]
	v_mfma_f32_16x16x32_bf16 v[60:63], v[84:87], v[100:103], v[60:63]
	s_add_u32 s28, s28, 0x80080
	s_addc_u32 s29, s29, 0
	v_mfma_f32_16x16x32_bf16 v[48:51], v[92:95], v[100:103], v[48:51]
	s_add_i32 s46, s46, s37
	v_mfma_f32_16x16x32_bf16 v[40:43], v[84:87], v[112:115], v[40:43]
	v_mfma_f32_16x16x32_bf16 v[32:35], v[92:95], v[112:115], v[32:35]
	v_mfma_f32_16x16x32_bf16 v[24:27], v[84:87], v[164:167], v[24:27]
	v_mfma_f32_16x16x32_bf16 v[16:19], v[92:95], v[164:167], v[16:19]
	s_waitcnt lgkmcnt(0)
	v_mfma_f32_16x16x32_bf16 v[12:15], v[84:87], v[202:205], v[12:15]
	s_mov_b32 m0, s46
	v_mfma_f32_16x16x32_bf16 v[8:11], v[92:95], v[202:205], v[8:11]
	s_barrier
	s_setprio 0
	global_load_lds_dwordx4 v172, s[28:29]
	s_add_i32 m0, s46, 0x2000
	s_nop 0
	global_load_lds_dwordx4 v168, s[28:29]
	s_waitcnt vmcnt(6)
	s_setprio 1
	s_barrier
	v_mfma_f32_16x16x32_bf16 v[56:59], v[214:217], v[96:99], v[56:59]
	v_mfma_f32_16x16x32_bf16 v[52:55], v[222:225], v[96:99], v[52:55]
	ds_read_b128 v[80:83], v189
	v_mfma_f32_16x16x32_bf16 v[44:47], v[214:217], v[108:111], v[44:47]
	v_mfma_f32_16x16x32_bf16 v[36:39], v[222:225], v[108:111], v[36:39]
	ds_read_b128 v[84:87], v189 offset:1024
	v_mfma_f32_16x16x32_bf16 v[28:31], v[214:217], v[160:163], v[28:31]
	v_mfma_f32_16x16x32_bf16 v[20:23], v[222:225], v[160:163], v[20:23]
	ds_read_b128 v[88:91], v189 offset:2048
	v_mfma_f32_16x16x32_bf16 v[4:7], v[214:217], v[198:201], v[4:7]
	v_mfma_f32_16x16x32_bf16 v[0:3], v[222:225], v[198:201], v[0:3]
	ds_read_b128 v[92:95], v189 offset:3072
	v_mfma_f32_16x16x32_bf16 v[56:59], v[218:221], v[100:103], v[56:59]
	s_add_i32 vcc_hi, vcc_hi, 2
	v_mfma_f32_16x16x32_bf16 v[52:55], v[230:233], v[100:103], v[52:55]
	s_add_u32 s59, s59, 0x100
	s_addc_u32 vcc_lo, vcc_lo, 0
	v_mfma_f32_16x16x32_bf16 v[44:47], v[218:221], v[112:115], v[44:47]
	s_add_u32 s44, s44, 0x100
	s_addc_u32 s45, s45, 0
	v_mfma_f32_16x16x32_bf16 v[36:39], v[230:233], v[112:115], v[36:39]
	s_cmp_gt_u32 vcc_hi, 29
	v_mfma_f32_16x16x32_bf16 v[28:31], v[218:221], v[164:167], v[28:31]
	v_mfma_f32_16x16x32_bf16 v[20:23], v[230:233], v[164:167], v[20:23]
	v_mfma_f32_16x16x32_bf16 v[4:7], v[218:221], v[202:205], v[4:7]
	v_mfma_f32_16x16x32_bf16 v[0:3], v[230:233], v[202:205], v[0:3]
	s_barrier
	s_setprio 0
	s_cbranch_scc0 .LBB1_380
; DI float silu_mul(float g, float v) { return g * v * __builtin_amdgcn_rcpf(1.0f + __builtin_amdgcn_exp2f(-LOG2E * g)); }
;     DI void operator()(const f32x4 (&acc)[2][2][4][2], const Unit& u, int wr, int wc, int fr, int fq) const {
;         const int row0 = u.pm * BM + wr * 64 + fr, ch0 = u.pn * 128 + wc * 32 + 8 * fq;
;         f32x4 w0[2], w1[2], w2[2], bb[2];
; #pragma unroll
;         for (int n = 0; n < 2; ++n) { w0[n] = *(const f32x4*)(cw + ch0 + 4 * n); w1[n] = *(const f32x4*)(cw + DFF + ch0 + 4 * n); w2[n] = *(const f32x4*)(cw + 2 * DFF + ch0 + 4 * n); bb[n] = *(const f32x4*)(cb + ch0 + 4 * n); }
; #pragma unroll
;         for (int ai = 0; ai < 2; ++ai)
; #pragma unroll
;             for (int m = 0; m < 4; ++m) {
;                 const bool efirst = (m == 0) && (fr == 0), elast = (m == 3) && (fr == 15);
;                 const int row = row0 + ai * HALF + m * 16;
;                 f32x4 gc[2];
; #pragma unroll
;                 for (int n = 0; n < 2; ++n) {
;                     const f32x4 g = acc[ai][0][m][n];
;                     const f32x4 gprev = acc[ai][0][m > 0 ? m - 1 : 0][n], gnext = acc[ai][0][m < 3 ? m + 1 : 3][n];
;                     f32x4 up, dn;
; #pragma unroll
;                     for (int e = 0; e < 4; ++e) {
;                         const float pu = (m > 0 && fr == 15) ? gprev[e] : g[e];
;                         const float pd = (m < 3 && fr == 0) ? gnext[e] : g[e];
;                         up[e] = dpp_ror1(pu); dn[e] = dpp_ror15(pd);
;                     }
;                     if (efirst) up = (f32x4){0.f, 0.f, 0.f, 0.f};
;                     if (elast) dn = (f32x4){0.f, 0.f, 0.f, 0.f};
;                     gc[n] = w0[n] * up + w1[n] * g + w2[n] * dn + bb[n];
;                 }
;                 if (efirst || elast) {
;                     const size_t eo = (size_t)((row >> 6) * 2 + (elast ? 1 : 0)) * DFF + ch0;
; #pragma unroll
;                     for (int n = 0; n < 2; ++n) { *(f32x4*)(EP + eo + 4 * n) = gc[n]; *(f32x4*)(ER + eo + 4 * n) = acc[ai][0][m][n]; *(f32x4*)(EV + eo + 4 * n) = acc[ai][1][m][n]; }
;                 } else {
;                     const f32x4 v0 = acc[ai][1][m][0], v1 = acc[ai][1][m][1];
;                     u32x4 o;
;                     o[0] = pack2(silu_mul(gc[0][0], v0[0]), silu_mul(gc[0][1], v0[1])); o[1] = pack2(silu_mul(gc[0][2], v0[2]), silu_mul(gc[0][3], v0[3]));
	s_waitcnt lgkmcnt(0)
	s_lshl_b32 s23, s43, 7
	v_mov_b32_e32 v194, v186
	v_mov_b32_e32 v80, v187
	s_or_b32 s23, s23, s67
	v_lshl_add_u32 v184, v80, 3, s23
	v_ashrrev_i32_e32 v185, 31, v184
	v_lshlrev_b64 v[80:81], 2, v[184:185]
	v_lshl_add_u64 v[84:85], s[52:53], 0, v[80:81]
	v_lshl_add_u64 v[88:89], s[16:17], 0, v[80:81]
	v_lshl_add_u64 v[92:93], s[18:19], 0, v[80:81]
	v_lshl_add_u64 v[112:113], s[54:55], 0, v[80:81]
	global_load_dwordx4 v[80:83], v[84:85], off offset:16
	global_load_dwordx4 v[96:99], v[84:85], off
	s_nop 0
	global_load_dwordx4 v[84:87], v[88:89], off offset:16
	global_load_dwordx4 v[100:103], v[88:89], off
	s_nop 0
	global_load_dwordx4 v[88:91], v[92:93], off offset:16
	global_load_dwordx4 v[108:111], v[92:93], off
	s_nop 0
	global_load_dwordx4 v[92:95], v[112:113], off offset:16
	s_nop 0
	global_load_dwordx4 v[112:115], v[112:113], off
	v_cmp_eq_u32_e32 vcc, 0, v194
	s_nop 0
	s_nop 0
	v_cndmask_b32_e32 v161, v148, v136, vcc
	v_cndmask_b32_e32 v162, v149, v137, vcc
	v_cndmask_b32_e32 v163, v150, v138, vcc
	v_mov_b32_dpp v160, v161 row_ror:15 row_mask:0xf bank_mask:0xf
	s_nop 0
	s_nop 0
	v_mov_b32_dpp v161, v162 row_ror:15 row_mask:0xf bank_mask:0xf
	v_mov_b32_dpp v164, v150 row_ror:1 row_mask:0xf bank_mask:0xf
	v_cndmask_b32_e32 v165, v151, v139, vcc
	v_mov_b32_dpp v162, v163 row_ror:15 row_mask:0xf bank_mask:0xf
	v_mov_b32_dpp v195, v151 row_ror:1 row_mask:0xf bank_mask:0xf
	v_mov_b32_dpp v166, v148 row_ror:1 row_mask:0xf bank_mask:0xf
	v_mov_b32_dpp v167, v149 row_ror:1 row_mask:0xf bank_mask:0xf
	v_mov_b32_dpp v163, v165 row_ror:15 row_mask:0xf bank_mask:0xf
	v_cndmask_b32_e64 v165, v195, 0, vcc
	v_cndmask_b32_e64 v164, v164, 0, vcc
	v_cndmask_b32_e64 v167, v167, 0, vcc
	v_cndmask_b32_e64 v166, v166, 0, vcc
	s_nop 0
	s_nop 0
	v_mov_b32_dpp v195, v144 row_ror:1 row_mask:0xf bank_mask:0xf
	v_mov_b32_dpp v196, v145 row_ror:1 row_mask:0xf bank_mask:0xf
	v_mov_b32_dpp v198, v146 row_ror:1 row_mask:0xf bank_mask:0xf
	v_cndmask_b32_e32 v199, v147, v131, vcc
	v_mov_b32_dpp v200, v147 row_ror:1 row_mask:0xf bank_mask:0xf
	v_cndmask_b32_e64 v198, v198, 0, vcc
	v_cndmask_b32_e64 v201, v196, 0, vcc
	s_lshl_b32 s21, s42, 8
	s_add_i32 s21, s21, s49
	v_add_u32_e32 v193, s21, v194
	v_cmp_ne_u32_e64 s[46:47], 0, v194
	s_waitcnt vmcnt(0)
	v_pk_mul_f32 v[164:165], v[98:99], v[164:165]
	v_pk_mul_f32 v[166:167], v[96:97], v[166:167]
	v_pk_fma_f32 v[164:165], v[150:151], v[102:103], v[164:165]
	v_pk_fma_f32 v[166:167], v[148:149], v[100:101], v[166:167]
	v_pk_fma_f32 v[162:163], v[110:111], v[162:163], v[164:165]
	v_cndmask_b32_e32 v165, v144, v128, vcc
	v_pk_fma_f32 v[160:161], v[108:109], v[160:161], v[166:167]
	v_cndmask_b32_e32 v166, v145, v129, vcc
	v_mov_b32_dpp v164, v165 row_ror:15 row_mask:0xf bank_mask:0xf
	v_cndmask_b32_e32 v167, v146, v130, vcc
	v_pk_add_f32 v[162:163], v[114:115], v[162:163]
	v_mov_b32_dpp v165, v166 row_ror:15 row_mask:0xf bank_mask:0xf
	v_pk_add_f32 v[160:161], v[112:113], v[160:161]
	s_nop 0
	v_mov_b32_dpp v166, v167 row_ror:15 row_mask:0xf bank_mask:0xf
	s_nop 1
	v_mov_b32_dpp v167, v199 row_ror:15 row_mask:0xf bank_mask:0xf
	v_cndmask_b32_e64 v199, v200, 0, vcc
	v_cndmask_b32_e64 v200, v195, 0, vcc
	v_pk_mul_f32 v[200:201], v[80:81], v[200:201]
	v_pk_mul_f32 v[198:199], v[82:83], v[198:199]
	v_pk_fma_f32 v[200:201], v[144:145], v[84:85], v[200:201]
	v_pk_fma_f32 v[198:199], v[146:147], v[86:87], v[198:199]
	v_pk_fma_f32 v[164:165], v[88:89], v[164:165], v[200:201]
	v_pk_fma_f32 v[166:167], v[90:91], v[166:167], v[198:199]
	v_pk_add_f32 v[164:165], v[92:93], v[164:165]
	v_pk_add_f32 v[166:167], v[94:95], v[166:167]
	s_and_saveexec_b64 s[28:29], s[46:47]
	s_xor_b64 s[28:29], exec, s[28:29]
	s_cbranch_execz .LBB1_383
	v_mul_f32_e32 v195, 0xbfb8aa3b, v160
	v_exp_f32_e32 v195, v195
	v_mul_f32_e32 v196, 0xbfb8aa3b, v161
	v_exp_f32_e32 v196, v196
	v_pk_mul_f32 v[160:161], v[156:157], v[160:161]
	v_add_f32_e32 v195, 1.0, v195
	v_rcp_f32_e32 v198, v195
	v_add_f32_e32 v196, 1.0, v196
	v_mul_f32_e32 v195, 0xbfb8aa3b, v162
	v_rcp_f32_e32 v199, v196
	v_exp_f32_e32 v195, v195
	v_mul_f32_e32 v196, 0xbfb8aa3b, v163
	v_exp_f32_e32 v196, v196
	v_pk_mul_f32 v[160:161], v[160:161], v[198:199]
	v_add_f32_e32 v195, 1.0, v195
	v_rcp_f32_e32 v200, v195
	v_add_f32_e32 v195, 1.0, v196
	v_rcp_f32_e32 v201, v195
	v_cvt_pk_bf16_f32 v160, v160, v161
	v_mul_f32_e32 v161, 0xbfb8aa3b, v164
	v_exp_f32_e32 v195, v161
	v_mul_f32_e32 v161, 0xbfb8aa3b, v165
	v_exp_f32_e32 v196, v161
	v_pk_mul_f32 v[162:163], v[158:159], v[162:163]
	v_pk_mul_f32 v[164:165], v[152:153], v[164:165]
	v_pk_mul_f32 v[162:163], v[162:163], v[200:201]
	s_nop 0
	v_cvt_pk_bf16_f32 v161, v162, v163
	v_add_f32_e32 v162, 1.0, v195
	v_mul_f32_e32 v195, 0xbfb8aa3b, v166
	v_add_f32_e32 v163, 1.0, v196
	v_exp_f32_e32 v195, v195
	v_mul_f32_e32 v196, 0xbfb8aa3b, v167
	v_exp_f32_e32 v196, v196
	v_rcp_f32_e32 v162, v162
	v_add_f32_e32 v195, 1.0, v195
	v_rcp_f32_e32 v198, v195
	v_add_f32_e32 v195, 1.0, v196
	v_rcp_f32_e32 v163, v163
	v_rcp_f32_e32 v199, v195
	v_pk_mul_f32 v[166:167], v[154:155], v[166:167]
	v_pk_mul_f32 v[162:163], v[164:165], v[162:163]
	v_pk_mul_f32 v[164:165], v[166:167], v[198:199]
	v_cvt_pk_bf16_f32 v162, v162, v163
	v_cvt_pk_bf16_f32 v163, v164, v165
	v_mov_b64_e32 v[164:165], s[6:7]
	v_mad_i64_i32 v[164:165], s[42:43], v193, s30, v[164:165]
	v_lshl_add_u64 v[164:165], v[184:185], 1, v[164:165]
	global_store_dwordx4 v[164:165], v[160:163], off

;     DI const char* a(const Unit& u) const { return (const char*)(A + (size_t)u.pm * BM * lda); }
;     DI const char* a(const Unit& u) const { return (const char*)(A + (size_t)u.pm * BM * 2048 + (u.pn >> 1) * 512); }
;     DI const char* a(const Unit& u) const { return (const char*)((u.pn < 12 ? A1 : A2) + (size_t)u.pm * BM * 512); }
; #define PG8_STAGE(bufoff, gbase, voff) do { _Pragma("unroll") for (int _i = 0; _i < 2; ++_i) \
;         __builtin_amdgcn_global_load_lds((const unsigned*)((const char*)(gbase) + (voff)[_i]), (LAS unsigned*)(lds + (bufoff) + ldsw + _i * 8192), 16, 0, 0); } while (0)
; #define PG8_LDA(dst, b, h) do { _Pragma("unroll") for (int m = 0; m < 4; ++m) _Pragma("unroll") for (int k = 0; k < 2; ++k) dst[m][k] = *(const LAS bf16x8*)(lds + PG8_SA(b, h) + aoff + m * 2048 + k * 1024); } while (0)
; #define PG8_LDB(dst, b, h) do { _Pragma("unroll") for (int n = 0; n < 2; ++n) _Pragma("unroll") for (int k = 0; k < 2; ++k) dst[n][k] = *(const LAS bf16x8*)(lds + PG8_SB(b, h) + boff + n * 2048 + k * 1024); } while (0)
; template <class Map, class Epi>
; DI void gemm_phase(LAS unsigned char* lds, const Map& MP, const Epi& E, const int nM, const int nN, const int K, const int lda, const int ldb) {
;     ...
;     for (;;) {
;         const bool has_next = sched_next(ui + 1, nM, nN, G, cblk, nxt);
;         const char* nA = has_next ? MP.a(nxt) : cA; const char* nB = has_next ? MP.b(nxt) : cB;
;         for (int t = 0; t < nt; t += 2) {
;             const bool last = (t == nt - 2);
;             const char* a1 = cA + (size_t)(t + 1) * kstep;
;             const char* a2 = last ? nA : cA + (size_t)(t + 2) * kstep; const char* b2 = last ? nB : cB + (size_t)(t + 2) * kstep;
;             const char* a3 = a2 + kstep; const char* b3 = b2 + kstep;
;             PG8_LDB(B0, 0, 0); PG8_SCHED; PG8_LDA(At, 0, 0); PG8_STAGE(PG8_SA(1, 1), a1 + hstepA, voffA);
;             PG8_WAIT_L(8); PG8_BAR; PG8_WAIT_L(0); PG8_MMA(0, 0, At, B0); PG8_BAR; PG8_SCHED;
;             PG8_LDB(B1, 0, 1); PG8_STAGE(PG8_SB(0, 0), b2, voffB);
;             PG8_BAR; PG8_WAIT_L(0); PG8_MMA(0, 1, At, B1); PG8_BAR;
;             PG8_LDA(At, 0, 1); PG8_STAGE(PG8_SA(0, 0), a2, voffA);
;             PG8_BAR; PG8_WAIT_L(0); PG8_MMA(1, 0, At, B0); PG8_BAR; PG8_SCHED;
;             PG8_STAGE(PG8_SB(0, 1), b2 + hstepB, voffB);
;             PG8_WAIT_V(6); PG8_BAR; PG8_MMA(1, 1, At, B1); PG8_BAR;
.LBB1_550:
	s_add_u32 s10, s8, 0x100
	s_addc_u32 s11, s9, 0
	s_cmpk_eq_i32 s3, 0x54
	s_cselect_b32 s15, s43, s11
	s_cselect_b32 s14, s42, s10
	s_cselect_b32 s13, s7, s38
	s_cselect_b32 s12, s6, s5
	s_add_i32 m0, s24, 0xc000
	ds_read_b128 v[168:171], v150
	ds_read_b128 v[172:175], v150 offset:1024
	ds_read_b128 v[176:179], v150 offset:2048
	ds_read_b128 v[180:183], v150 offset:3072
	ds_read_b128 v[184:187], v150 offset:4096
	ds_read_b128 v[188:191], v150 offset:5120
	ds_read_b128 v[192:195], v150 offset:6144
	ds_read_b128 v[198:201], v150 offset:7168
	global_load_lds_dwordx4 v138, s[8:9]
	s_add_i32 m0, s24, 0xe000
	s_nop 0
	global_load_lds_dwordx4 v136, s[8:9]
	s_waitcnt lgkmcnt(8)
	s_setprio 1
	s_barrier
	s_waitcnt lgkmcnt(7)
	v_mfma_f32_16x16x32_bf16 v[124:127], v[152:155], v[168:171], v[124:127]
	v_mfma_f32_16x16x32_bf16 v[120:123], v[160:163], v[168:171], v[120:123]
	s_waitcnt lgkmcnt(5)
	v_mfma_f32_16x16x32_bf16 v[108:111], v[152:155], v[176:179], v[108:111]
	v_mfma_f32_16x16x32_bf16 v[104:107], v[160:163], v[176:179], v[104:107]
	s_waitcnt lgkmcnt(3)
	v_mfma_f32_16x16x32_bf16 v[92:95], v[152:155], v[184:187], v[92:95]
	v_mfma_f32_16x16x32_bf16 v[88:91], v[160:163], v[184:187], v[88:91]
	s_waitcnt lgkmcnt(1)
	v_mfma_f32_16x16x32_bf16 v[76:79], v[152:155], v[192:195], v[76:79]
	v_mfma_f32_16x16x32_bf16 v[72:75], v[160:163], v[192:195], v[72:75]
	v_mfma_f32_16x16x32_bf16 v[124:127], v[156:159], v[172:175], v[124:127]
	s_add_i32 s8, s35, s22
	v_mfma_f32_16x16x32_bf16 v[120:123], v[164:167], v[172:175], v[120:123]
	v_lshl_add_u64 v[144:145], s[12:13], 0, v[132:133]
	v_mfma_f32_16x16x32_bf16 v[108:111], v[156:159], v[180:183], v[108:111]
	v_lshl_add_u64 v[218:219], s[12:13], 0, v[128:129]
	v_mfma_f32_16x16x32_bf16 v[104:107], v[164:167], v[180:183], v[104:107]
	v_mfma_f32_16x16x32_bf16 v[92:95], v[156:159], v[188:191], v[92:95]
	v_mfma_f32_16x16x32_bf16 v[88:91], v[164:167], v[188:191], v[88:91]
	s_waitcnt lgkmcnt(0)
	v_mfma_f32_16x16x32_bf16 v[76:79], v[156:159], v[198:201], v[76:79]
	s_mov_b32 m0, s8
	v_mfma_f32_16x16x32_bf16 v[72:75], v[164:167], v[198:201], v[72:75]
	s_barrier
	s_setprio 0
	ds_read_b128 v[202:205], v151
	ds_read_b128 v[206:209], v151 offset:1024
	ds_read_b128 v[210:213], v151 offset:2048
	global_load_lds_dwordx4 v[144:145], off
	s_add_i32 m0, s8, 0x2000
	ds_read_b128 v[214:217], v151 offset:3072
	global_load_lds_dwordx4 v[218:219], off
	s_setprio 1
	s_barrier
	s_waitcnt lgkmcnt(3)
	v_mfma_f32_16x16x32_bf16 v[116:119], v[202:205], v[168:171], v[116:119]
	s_waitcnt lgkmcnt(1)
	v_mfma_f32_16x16x32_bf16 v[112:115], v[210:213], v[168:171], v[112:115]
	v_mfma_f32_16x16x32_bf16 v[100:103], v[202:205], v[176:179], v[100:103]
	v_mfma_f32_16x16x32_bf16 v[96:99], v[210:213], v[176:179], v[96:99]
	v_mfma_f32_16x16x32_bf16 v[84:87], v[202:205], v[184:187], v[84:87]
	v_mfma_f32_16x16x32_bf16 v[80:83], v[210:213], v[184:187], v[80:83]
	v_mfma_f32_16x16x32_bf16 v[68:71], v[202:205], v[192:195], v[68:71]
	v_mfma_f32_16x16x32_bf16 v[64:67], v[210:213], v[192:195], v[64:67]
	v_mfma_f32_16x16x32_bf16 v[116:119], v[206:209], v[172:175], v[116:119]
	v_lshl_add_u64 v[222:223], s[14:15], 0, v[130:131]
	s_mov_b32 m0, s24
	s_waitcnt lgkmcnt(0)
	v_mfma_f32_16x16x32_bf16 v[112:115], v[214:217], v[172:175], v[112:115]
	v_lshl_add_u64 v[220:221], s[14:15], 0, v[134:135]
	v_mfma_f32_16x16x32_bf16 v[100:103], v[206:209], v[180:183], v[100:103]
	v_mfma_f32_16x16x32_bf16 v[96:99], v[214:217], v[180:183], v[96:99]
	v_mfma_f32_16x16x32_bf16 v[84:87], v[206:209], v[188:191], v[84:87]
	v_mfma_f32_16x16x32_bf16 v[80:83], v[214:217], v[188:191], v[80:83]
	v_mfma_f32_16x16x32_bf16 v[68:71], v[206:209], v[198:201], v[68:71]
	v_mfma_f32_16x16x32_bf16 v[64:67], v[214:217], v[198:201], v[64:67]
	s_barrier
	s_setprio 0
	ds_read_b128 v[168:171], v150 offset:16384
	ds_read_b128 v[172:175], v150 offset:17408
	ds_read_b128 v[176:179], v150 offset:18432
	ds_read_b128 v[180:183], v150 offset:19456
	ds_read_b128 v[184:187], v150 offset:20480
	ds_read_b128 v[188:191], v150 offset:21504
	ds_read_b128 v[192:195], v150 offset:22528
	global_load_lds_dwordx4 v[220:221], off
	s_mov_b32 m0, s25
	ds_read_b128 v[198:201], v150 offset:23552
	global_load_lds_dwordx4 v[222:223], off
	s_waitcnt vmcnt(10)
	s_setprio 1
	s_barrier
	s_waitcnt lgkmcnt(7)
	v_mfma_f32_16x16x32_bf16 v[60:63], v[152:155], v[168:171], v[60:63]
	v_mfma_f32_16x16x32_bf16 v[56:59], v[160:163], v[168:171], v[56:59]
	s_waitcnt lgkmcnt(5)
	v_mfma_f32_16x16x32_bf16 v[44:47], v[152:155], v[176:179], v[44:47]
	v_mfma_f32_16x16x32_bf16 v[40:43], v[160:163], v[176:179], v[40:43]
	s_waitcnt lgkmcnt(3)
	v_mfma_f32_16x16x32_bf16 v[28:31], v[152:155], v[184:187], v[28:31]
	v_mfma_f32_16x16x32_bf16 v[24:27], v[160:163], v[184:187], v[24:27]
	s_waitcnt lgkmcnt(1)
	v_mfma_f32_16x16x32_bf16 v[12:15], v[152:155], v[192:195], v[12:15]
	v_mfma_f32_16x16x32_bf16 v[8:11], v[160:163], v[192:195], v[8:11]
	v_mfma_f32_16x16x32_bf16 v[60:63], v[156:159], v[172:175], v[60:63]
	s_add_u32 s8, s12, 0x160000
	s_addc_u32 s9, s13, 0
	v_mfma_f32_16x16x32_bf16 v[56:59], v[164:167], v[172:175], v[56:59]
	s_add_i32 s39, s36, s22
	v_mfma_f32_16x16x32_bf16 v[44:47], v[156:159], v[180:183], v[44:47]
	v_mfma_f32_16x16x32_bf16 v[40:43], v[164:167], v[180:183], v[40:43]
	v_mfma_f32_16x16x32_bf16 v[28:31], v[156:159], v[188:191], v[28:31]
	v_mfma_f32_16x16x32_bf16 v[24:27], v[164:167], v[188:191], v[24:27]
	s_waitcnt lgkmcnt(0)
	v_mfma_f32_16x16x32_bf16 v[12:15], v[156:159], v[198:201], v[12:15]
	s_mov_b32 m0, s39
	v_mfma_f32_16x16x32_bf16 v[8:11], v[164:167], v[198:201], v[8:11]
	s_barrier
; #define PG8_STAGE(bufoff, gbase, voff) do { _Pragma("unroll") for (int _i = 0; _i < 2; ++_i) \
;         __builtin_amdgcn_global_load_lds((const unsigned*)((const char*)(gbase) + (voff)[_i]), (LAS unsigned*)(lds + (bufoff) + ldsw + _i * 8192), 16, 0, 0); } while (0)
; #define PG8_LDA(dst, b, h) do { _Pragma("unroll") for (int m = 0; m < 4; ++m) _Pragma("unroll") for (int k = 0; k < 2; ++k) dst[m][k] = *(const LAS bf16x8*)(lds + PG8_SA(b, h) + aoff + m * 2048 + k * 1024); } while (0)
; #define PG8_LDB(dst, b, h) do { _Pragma("unroll") for (int n = 0; n < 2; ++n) _Pragma("unroll") for (int k = 0; k < 2; ++k) dst[n][k] = *(const LAS bf16x8*)(lds + PG8_SB(b, h) + boff + n * 2048 + k * 1024); } while (0)
; #define PG8_MMA(ai, bj, At, Bt) do { __builtin_amdgcn_s_setprio(1); _Pragma("unroll") for (int m = 0; m < 4; ++m) _Pragma("unroll") for (int n = 0; n < 2; ++n) _Pragma("unroll") for (int k = 0; k < 2; ++k) \
;         acc[ai][bj][m][n] = __builtin_amdgcn_mfma_f32_16x16x32_bf16(Bt[n][k], At[m][k], acc[ai][bj][m][n], 0, 0, 0); __builtin_amdgcn_s_setprio(0); } while (0)
; #define PG8_WAIT_V(n) asm volatile("s_waitcnt vmcnt(" #n ")" ::: "memory")
; #define PG8_WAIT_L(n) asm volatile("s_waitcnt lgkmcnt(" #n ")" ::: "memory")
; #define PG8_BAR __builtin_amdgcn_s_barrier()
; #define PG8_SCHED __builtin_amdgcn_sched_barrier(0)
; template <class Map, class Epi>
; DI void gemm_phase(LAS unsigned char* lds, const Map& MP, const Epi& E, const int nM, const int nN, const int K, const int lda, const int ldb) {
;     ...
;             PG8_BAR; PG8_WAIT_L(0); PG8_MMA(1, 0, At, B0); PG8_BAR; PG8_SCHED;
;             PG8_STAGE(PG8_SB(0, 1), b2 + hstepB, voffB);
;             PG8_WAIT_V(6); PG8_BAR; PG8_MMA(1, 1, At, B1); PG8_BAR;
;             PG8_LDB(B0, 1, 0); PG8_SCHED; PG8_LDA(At, 1, 0); PG8_STAGE(PG8_SA(0, 1), a2 + hstepA, voffA);
;             PG8_WAIT_L(8); PG8_BAR; PG8_WAIT_L(0); PG8_MMA(0, 0, At, B0); PG8_BAR; PG8_SCHED;
;             PG8_LDB(B1, 1, 1); PG8_STAGE(PG8_SB(1, 0), b3, voffB);
;             PG8_BAR; PG8_WAIT_L(0); PG8_MMA(0, 1, At, B1); PG8_BAR;
;             PG8_LDA(At, 1, 1); PG8_STAGE(PG8_SA(1, 0), a3, voffA);
;             PG8_BAR; PG8_WAIT_L(0); PG8_MMA(1, 0, At, B0); PG8_BAR; PG8_SCHED;
;             PG8_STAGE(PG8_SB(1, 1), b3 + hstepB, voffB);
;             PG8_WAIT_V(6); PG8_BAR; PG8_MMA(1, 1, At, B1); PG8_BAR;
	s_setprio 0
	global_load_lds_dwordx4 v132, s[8:9]
	s_add_i32 m0, s39, 0x2000
	s_nop 0
	global_load_lds_dwordx4 v128, s[8:9]
	s_waitcnt vmcnt(6)
	s_setprio 1
	s_barrier
	v_mfma_f32_16x16x32_bf16 v[52:55], v[202:205], v[168:171], v[52:55]
	v_mfma_f32_16x16x32_bf16 v[48:51], v[210:213], v[168:171], v[48:51]
	s_add_i32 s39, 0, 0x18000
	v_add_u32_e32 v164, s39, v148
	ds_read_b128 v[152:155], v164
	v_mfma_f32_16x16x32_bf16 v[36:39], v[202:205], v[176:179], v[36:39]
	v_mfma_f32_16x16x32_bf16 v[32:35], v[210:213], v[176:179], v[32:35]
	ds_read_b128 v[156:159], v164 offset:1024
	v_mfma_f32_16x16x32_bf16 v[20:23], v[202:205], v[184:187], v[20:23]
	v_mfma_f32_16x16x32_bf16 v[16:19], v[210:213], v[184:187], v[16:19]
	ds_read_b128 v[160:163], v164 offset:2048
	v_mfma_f32_16x16x32_bf16 v[4:7], v[202:205], v[192:195], v[4:7]
	v_mfma_f32_16x16x32_bf16 v[0:3], v[210:213], v[192:195], v[0:3]
	ds_read_b128 v[164:167], v164 offset:3072
	v_mfma_f32_16x16x32_bf16 v[52:55], v[206:209], v[172:175], v[52:55]
	s_add_u32 s8, s14, 0x160000
	s_addc_u32 s9, s15, 0
	v_mfma_f32_16x16x32_bf16 v[48:51], v[214:217], v[172:175], v[48:51]
	v_mfma_f32_16x16x32_bf16 v[36:39], v[206:209], v[180:183], v[36:39]
	v_mfma_f32_16x16x32_bf16 v[32:35], v[214:217], v[180:183], v[32:35]
	v_mfma_f32_16x16x32_bf16 v[20:23], v[206:209], v[188:191], v[20:23]
	v_mfma_f32_16x16x32_bf16 v[16:19], v[214:217], v[188:191], v[16:19]
	v_mfma_f32_16x16x32_bf16 v[4:7], v[206:209], v[198:201], v[4:7]
	s_mov_b32 m0, s26
	v_mfma_f32_16x16x32_bf16 v[0:3], v[214:217], v[198:201], v[0:3]
	s_barrier
	s_setprio 0
	ds_read_b128 v[168:171], v150 offset:32768
	ds_read_b128 v[172:175], v150 offset:33792
	ds_read_b128 v[176:179], v150 offset:34816
	ds_read_b128 v[180:183], v150 offset:35840
	ds_read_b128 v[184:187], v150 offset:36864
	ds_read_b128 v[188:191], v150 offset:37888
	ds_read_b128 v[192:195], v150 offset:38912
	global_load_lds_dwordx4 v134, s[8:9]
	s_mov_b32 m0, s27
	ds_read_b128 v[198:201], v150 offset:39936
	global_load_lds_dwordx4 v130, s[8:9]
	s_waitcnt lgkmcnt(8)
	s_setprio 1
	s_barrier
	s_waitcnt lgkmcnt(7)
	v_mfma_f32_16x16x32_bf16 v[124:127], v[152:155], v[168:171], v[124:127]
	v_mfma_f32_16x16x32_bf16 v[120:123], v[160:163], v[168:171], v[120:123]
	s_waitcnt lgkmcnt(5)
	v_mfma_f32_16x16x32_bf16 v[108:111], v[152:155], v[176:179], v[108:111]
	v_mfma_f32_16x16x32_bf16 v[104:107], v[160:163], v[176:179], v[104:107]
	s_waitcnt lgkmcnt(3)
	v_mfma_f32_16x16x32_bf16 v[92:95], v[152:155], v[184:187], v[92:95]
	v_mfma_f32_16x16x32_bf16 v[88:91], v[160:163], v[184:187], v[88:91]
	s_waitcnt lgkmcnt(1)
	v_mfma_f32_16x16x32_bf16 v[76:79], v[152:155], v[192:195], v[76:79]
	v_mfma_f32_16x16x32_bf16 v[72:75], v[160:163], v[192:195], v[72:75]
	v_mfma_f32_16x16x32_bf16 v[124:127], v[156:159], v[172:175], v[124:127]
	s_add_i32 s14, 0, 0x1c000
	v_mfma_f32_16x16x32_bf16 v[120:123], v[164:167], v[172:175], v[120:123]
	s_add_i32 s8, s39, s22
	v_mfma_f32_16x16x32_bf16 v[108:111], v[156:159], v[180:183], v[108:111]
	v_add_u32_e32 v196, s14, v148
	v_mfma_f32_16x16x32_bf16 v[104:107], v[164:167], v[180:183], v[104:107]
	v_lshl_add_u64 v[144:145], v[144:145], 0, s[52:53]
	v_mfma_f32_16x16x32_bf16 v[92:95], v[156:159], v[188:191], v[92:95]
	v_mfma_f32_16x16x32_bf16 v[88:91], v[164:167], v[188:191], v[88:91]
	s_waitcnt lgkmcnt(0)
	v_mfma_f32_16x16x32_bf16 v[76:79], v[156:159], v[198:201], v[76:79]
	s_mov_b32 m0, s8
	v_mfma_f32_16x16x32_bf16 v[72:75], v[164:167], v[198:201], v[72:75]
	s_barrier
	s_setprio 0
	ds_read_b128 v[202:205], v196
	ds_read_b128 v[206:209], v196 offset:1024
	ds_read_b128 v[210:213], v196 offset:2048
	global_load_lds_dwordx4 v[144:145], off
	v_lshl_add_u64 v[144:145], v[218:219], 0, s[52:53]
	s_add_i32 m0, s8, 0x2000
	ds_read_b128 v[214:217], v196 offset:3072
	global_load_lds_dwordx4 v[144:145], off
	s_setprio 1
	s_barrier
	s_waitcnt lgkmcnt(3)
	v_mfma_f32_16x16x32_bf16 v[116:119], v[202:205], v[168:171], v[116:119]
	s_waitcnt lgkmcnt(1)
	v_mfma_f32_16x16x32_bf16 v[112:115], v[210:213], v[168:171], v[112:115]
	v_mfma_f32_16x16x32_bf16 v[100:103], v[202:205], v[176:179], v[100:103]
	v_mfma_f32_16x16x32_bf16 v[96:99], v[210:213], v[176:179], v[96:99]
	v_mfma_f32_16x16x32_bf16 v[84:87], v[202:205], v[184:187], v[84:87]
	v_mfma_f32_16x16x32_bf16 v[80:83], v[210:213], v[184:187], v[80:83]
	v_mfma_f32_16x16x32_bf16 v[68:71], v[202:205], v[192:195], v[68:71]
	v_mfma_f32_16x16x32_bf16 v[64:67], v[210:213], v[192:195], v[64:67]
	v_mfma_f32_16x16x32_bf16 v[116:119], v[206:209], v[172:175], v[116:119]
	s_mov_b32 m0, s30
	s_waitcnt lgkmcnt(0)
	v_mfma_f32_16x16x32_bf16 v[112:115], v[214:217], v[172:175], v[112:115]
	v_lshl_add_u64 v[144:145], v[220:221], 0, s[52:53]
	v_mfma_f32_16x16x32_bf16 v[100:103], v[206:209], v[180:183], v[100:103]
	v_mfma_f32_16x16x32_bf16 v[96:99], v[214:217], v[180:183], v[96:99]
	v_mfma_f32_16x16x32_bf16 v[84:87], v[206:209], v[188:191], v[84:87]
	v_mfma_f32_16x16x32_bf16 v[80:83], v[214:217], v[188:191], v[80:83]
	v_mfma_f32_16x16x32_bf16 v[68:71], v[206:209], v[198:201], v[68:71]
	v_mfma_f32_16x16x32_bf16 v[64:67], v[214:217], v[198:201], v[64:67]
	s_barrier
	s_setprio 0
	ds_read_b128 v[168:171], v150 offset:49152
	ds_read_b128 v[172:175], v150 offset:50176
	ds_read_b128 v[176:179], v150 offset:51200
	ds_read_b128 v[180:183], v150 offset:52224
	ds_read_b128 v[184:187], v150 offset:53248
	ds_read_b128 v[188:191], v150 offset:54272
	ds_read_b128 v[192:195], v150 offset:55296
	global_load_lds_dwordx4 v[144:145], off
	v_lshl_add_u64 v[144:145], v[222:223], 0, s[52:53]
	s_mov_b32 m0, s31
	ds_read_b128 v[198:201], v150 offset:56320
	global_load_lds_dwordx4 v[144:145], off
	s_waitcnt vmcnt(10)
	s_setprio 1
	s_barrier
; DI unsigned pack2(float a, float b) { f32x2 v = {a, b}; hwbf16x2 r = __builtin_convertvector(v, hwbf16x2); return __builtin_bit_cast(unsigned, r); }
; DI float bflo(unsigned w) { return __uint_as_float(w << 16); }
; DI float bfhi(unsigned w) { return __uint_as_float(w & 0xffff0000u); }
; #define PG8_WAIT_V(n) asm volatile("s_waitcnt vmcnt(" #n ")" ::: "memory")
;     DI void operator()(const f32x4 (&acc)[2][2][4][2], const Unit& u, int wr, int wc, int fr, int fq) const {
;         const int row0 = u.pm * BM + wr * 64 + fr, col0 = u.pn * BM + wc * 32 + 8 * fq;
;         f32x4 sc[2][2];
; #pragma unroll
;         for (int bj = 0; bj < 2; ++bj)
; #pragma unroll
;             for (int n = 0; n < 2; ++n) sc[bj][n] = scale ? *(const f32x4*)(scale + col0 + bj * HALF + 4 * n) : (f32x4){1.f, 1.f, 1.f, 1.f};
; #pragma unroll
;         for (int ai = 0; ai < 2; ++ai)
; #pragma unroll
;             for (int m = 0; m < 4; ++m) { const size_t ro = (size_t)(row0 + ai * HALF + m * 16) * D + col0;
; #pragma unroll
;                 for (int bj = 0; bj < 2; ++bj) {
;                     f32x4 x0, x1;
;                     if constexpr (IB) { const u32x4 w = *(const u32x4*)((const bf16_t*)Xin + ro + bj * HALF);
;                         x0 = (f32x4){bflo(w[0]), bfhi(w[0]), bflo(w[1]), bfhi(w[1])}; x1 = (f32x4){bflo(w[2]), bfhi(w[2]), bflo(w[3]), bfhi(w[3])}; }
;                     else { x0 = *(const f32x4*)((const float*)Xin + ro + bj * HALF); x1 = *(const f32x4*)((const float*)Xin + ro + bj * HALF + 4); }
;                     x0 += acc[ai][bj][m][0] * sc[bj][0]; x1 += acc[ai][bj][m][1] * sc[bj][1];
;                     if constexpr (OB) { u32x4 o; o[0] = pack2(x0[0], x0[1]); o[1] = pack2(x0[2], x0[3]); o[2] = pack2(x1[0], x1[1]); o[3] = pack2(x1[2], x1[3]);
;                         *(u32x4*)((bf16_t*)Xout + ro + bj * HALF) = o; }
;                     else { *(f32x4*)((float*)Xout + ro + bj * HALF) = x0; *(f32x4*)((float*)Xout + ro + bj * HALF + 4) = x1; } } }
; template <class Map, class Epi>
; DI void gemm_phase(LAS unsigned char* lds, const Map& MP, const Epi& E, const int nM, const int nN, const int K, const int lda, const int ldb) {
;     ...
;             PG8_BAR; PG8_WAIT_L(0); PG8_MMA(1, 0, At, B0); PG8_BAR; PG8_SCHED;
;             PG8_STAGE(PG8_SB(1, 1), b3 + hstepB, voffB);
;             PG8_WAIT_V(6); PG8_BAR; PG8_MMA(1, 1, At, B1); PG8_BAR;
;         }
	s_waitcnt lgkmcnt(7)
	v_mfma_f32_16x16x32_bf16 v[60:63], v[152:155], v[168:171], v[60:63]
	v_mfma_f32_16x16x32_bf16 v[56:59], v[160:163], v[168:171], v[56:59]
	s_waitcnt lgkmcnt(5)
	v_mfma_f32_16x16x32_bf16 v[44:47], v[152:155], v[176:179], v[44:47]
	v_mfma_f32_16x16x32_bf16 v[40:43], v[160:163], v[176:179], v[40:43]
	s_waitcnt lgkmcnt(3)
	v_mfma_f32_16x16x32_bf16 v[28:31], v[152:155], v[184:187], v[28:31]
	v_mfma_f32_16x16x32_bf16 v[24:27], v[160:163], v[184:187], v[24:27]
	s_waitcnt lgkmcnt(1)
	v_mfma_f32_16x16x32_bf16 v[12:15], v[152:155], v[192:195], v[12:15]
	v_mfma_f32_16x16x32_bf16 v[8:11], v[160:163], v[192:195], v[8:11]
	v_mfma_f32_16x16x32_bf16 v[60:63], v[156:159], v[172:175], v[60:63]
	s_add_u32 s8, s12, 0x160080
	s_addc_u32 s9, s13, 0
	v_mfma_f32_16x16x32_bf16 v[56:59], v[164:167], v[172:175], v[56:59]
	s_add_i32 s12, s14, s22
	v_mfma_f32_16x16x32_bf16 v[44:47], v[156:159], v[180:183], v[44:47]
	v_mfma_f32_16x16x32_bf16 v[40:43], v[164:167], v[180:183], v[40:43]
	v_mfma_f32_16x16x32_bf16 v[28:31], v[156:159], v[188:191], v[28:31]
	v_mfma_f32_16x16x32_bf16 v[24:27], v[164:167], v[188:191], v[24:27]
	s_waitcnt lgkmcnt(0)
	v_mfma_f32_16x16x32_bf16 v[12:15], v[156:159], v[198:201], v[12:15]
	s_mov_b32 m0, s12
	v_mfma_f32_16x16x32_bf16 v[8:11], v[164:167], v[198:201], v[8:11]
	s_barrier
	s_setprio 0
	global_load_lds_dwordx4 v132, s[8:9]
	s_add_i32 m0, s12, 0x2000
	s_nop 0
	global_load_lds_dwordx4 v128, s[8:9]
	s_waitcnt vmcnt(6)
	s_setprio 1
	s_barrier
	v_mfma_f32_16x16x32_bf16 v[52:55], v[202:205], v[168:171], v[52:55]
	v_mfma_f32_16x16x32_bf16 v[48:51], v[210:213], v[168:171], v[48:51]
	ds_read_b128 v[152:155], v149
	v_mfma_f32_16x16x32_bf16 v[36:39], v[202:205], v[176:179], v[36:39]
	v_mfma_f32_16x16x32_bf16 v[32:35], v[210:213], v[176:179], v[32:35]
	ds_read_b128 v[156:159], v149 offset:1024
	v_mfma_f32_16x16x32_bf16 v[20:23], v[202:205], v[184:187], v[20:23]
	v_mfma_f32_16x16x32_bf16 v[16:19], v[210:213], v[184:187], v[16:19]
	ds_read_b128 v[160:163], v149 offset:2048
	v_mfma_f32_16x16x32_bf16 v[4:7], v[202:205], v[192:195], v[4:7]
	v_mfma_f32_16x16x32_bf16 v[0:3], v[210:213], v[192:195], v[0:3]
	ds_read_b128 v[164:167], v149 offset:3072
	v_mfma_f32_16x16x32_bf16 v[52:55], v[206:209], v[172:175], v[52:55]
	s_add_i32 s3, s3, 2
	v_mfma_f32_16x16x32_bf16 v[48:51], v[214:217], v[172:175], v[48:51]
	s_add_u32 s5, s5, 0x100
	s_addc_u32 s38, s38, 0
	v_mfma_f32_16x16x32_bf16 v[36:39], v[206:209], v[180:183], v[36:39]
	s_cmpk_gt_u32 s3, 0x55
	v_mfma_f32_16x16x32_bf16 v[32:35], v[214:217], v[180:183], v[32:35]
	s_mov_b64 s[8:9], s[10:11]
	v_mfma_f32_16x16x32_bf16 v[20:23], v[206:209], v[188:191], v[20:23]
	v_mfma_f32_16x16x32_bf16 v[16:19], v[214:217], v[188:191], v[16:19]
	v_mfma_f32_16x16x32_bf16 v[4:7], v[206:209], v[198:201], v[4:7]
	v_mfma_f32_16x16x32_bf16 v[0:3], v[214:217], v[198:201], v[0:3]
	s_barrier
	s_setprio 0
	s_cbranch_scc0 .LBB1_550
	s_waitcnt lgkmcnt(0)
	v_mov_b32_e32 v144, v146
	v_mov_b32_e32 v152, v147
	s_lshl_b32 s2, s2, 8
	s_add_i32 s2, s2, s29
	s_lshl_b32 s3, s4, 8
	v_add_u32_e32 v152, s2, v152
	s_or_b32 s3, s3, s54
	v_ashrrev_i32_e32 v153, 31, v152
	v_lshl_add_u32 v144, v144, 3, s3
	v_lshlrev_b64 v[152:153], 12, v[152:153]
	v_ashrrev_i32_e32 v145, 31, v144
	v_lshl_add_u64 v[152:153], s[46:47], 0, v[152:153]
	v_lshl_add_u64 v[144:145], v[144:145], 1, v[152:153]
	global_load_dwordx4 v[160:163], v[144:145], off
	global_load_dwordx4 v[164:167], v[144:145], off offset:256
	s_mov_b64 s[98:99], 0x10000
	v_lshl_add_u64 v[154:155], v[144:145], 0, s[98:99]
	global_load_dwordx4 v[168:171], v[154:155], off
	global_load_dwordx4 v[172:175], v[154:155], off offset:256
	s_mov_b64 s[98:99], 0x20000
	v_lshl_add_u64 v[154:155], v[144:145], 0, s[98:99]
	global_load_dwordx4 v[176:179], v[154:155], off
	global_load_dwordx4 v[180:183], v[154:155], off offset:256
	s_mov_b64 s[98:99], 0x30000
	v_lshl_add_u64 v[154:155], v[144:145], 0, s[98:99]
	global_load_dwordx4 v[184:187], v[154:155], off
	global_load_dwordx4 v[188:191], v[154:155], off offset:256
	s_mov_b64 s[98:99], 0x80000
	v_lshl_add_u64 v[154:155], v[144:145], 0, s[98:99]
	global_load_dwordx4 v[192:195], v[154:155], off
	global_load_dwordx4 v[198:201], v[154:155], off offset:256
	s_mov_b64 s[98:99], 0x90000
	v_lshl_add_u64 v[154:155], v[144:145], 0, s[98:99]
	global_load_dwordx4 v[202:205], v[154:155], off
	global_load_dwordx4 v[206:209], v[154:155], off offset:256
	s_mov_b64 s[98:99], 0xa0000
	v_lshl_add_u64 v[154:155], v[144:145], 0, s[98:99]
	global_load_dwordx4 v[210:213], v[154:155], off
	global_load_dwordx4 v[214:217], v[154:155], off offset:256
	s_mov_b64 s[98:99], 0xb0000
	v_lshl_add_u64 v[154:155], v[144:145], 0, s[98:99]
	global_load_dwordx4 v[248:251], v[154:155], off
	global_load_dwordx4 v[252:255], v[154:155], off offset:256
	s_waitcnt vmcnt(15)
	s_nop 1
	v_mov_b32_e32 v152, v160
	v_mov_b32_e32 v153, v161
	v_mov_b32_e32 v154, v162
	v_mov_b32_e32 v155, v163
	s_mov_b64 s[2:3], 0x10000
	s_mov_b32 s4, s37
	s_mov_b64 s[10:11], s[6:7]
	s_mov_b64 s[8:9], s[42:43]
	s_waitcnt lgkmcnt(0)
	v_lshlrev_b32_e32 v156, 16, v152
	v_and_b32_e32 v157, 0xffff0000, v152
	v_lshlrev_b32_e32 v152, 16, v153
	v_and_b32_e32 v153, 0xffff0000, v153
	v_lshlrev_b32_e32 v158, 16, v154
	v_and_b32_e32 v159, 0xffff0000, v154
	v_lshlrev_b32_e32 v154, 16, v155
	v_and_b32_e32 v155, 0xffff0000, v155
	v_pk_add_f32 v[126:127], v[126:127], v[152:153]
	v_pk_add_f32 v[124:125], v[124:125], v[156:157]
	v_pk_add_f32 v[152:153], v[122:123], v[154:155]
	v_pk_add_f32 v[122:123], v[120:121], v[158:159]
	v_cvt_pk_bf16_f32 v120, v124, v125
	v_cvt_pk_bf16_f32 v121, v126, v127
	v_cvt_pk_bf16_f32 v122, v122, v123
	v_cvt_pk_bf16_f32 v123, v152, v153
	global_store_dwordx4 v[144:145], v[120:123], off
	s_waitcnt vmcnt(15)
; DI unsigned pack2(float a, float b) { f32x2 v = {a, b}; hwbf16x2 r = __builtin_convertvector(v, hwbf16x2); return __builtin_bit_cast(unsigned, r); }
; DI float bflo(unsigned w) { return __uint_as_float(w << 16); }
; DI float bfhi(unsigned w) { return __uint_as_float(w & 0xffff0000u); }
;     DI void operator()(const f32x4 (&acc)[2][2][4][2], const Unit& u, int wr, int wc, int fr, int fq) const {
;     ...
;         for (int ai = 0; ai < 2; ++ai)
; #pragma unroll
;             for (int m = 0; m < 4; ++m) { const size_t ro = (size_t)(row0 + ai * HALF + m * 16) * D + col0;
; #pragma unroll
;                 for (int bj = 0; bj < 2; ++bj) {
;                     f32x4 x0, x1;
;                     if constexpr (IB) { const u32x4 w = *(const u32x4*)((const bf16_t*)Xin + ro + bj * HALF);
;                         x0 = (f32x4){bflo(w[0]), bfhi(w[0]), bflo(w[1]), bfhi(w[1])}; x1 = (f32x4){bflo(w[2]), bfhi(w[2]), bflo(w[3]), bfhi(w[3])}; }
;                     else { x0 = *(const f32x4*)((const float*)Xin + ro + bj * HALF); x1 = *(const f32x4*)((const float*)Xin + ro + bj * HALF + 4); }
;                     x0 += acc[ai][bj][m][0] * sc[bj][0]; x1 += acc[ai][bj][m][1] * sc[bj][1];
;                     if constexpr (OB) { u32x4 o; o[0] = pack2(x0[0], x0[1]); o[1] = pack2(x0[2], x0[3]); o[2] = pack2(x1[0], x1[1]); o[3] = pack2(x1[2], x1[3]);
;                         *(u32x4*)((bf16_t*)Xout + ro + bj * HALF) = o; }
;                     else { *(f32x4*)((float*)Xout + ro + bj * HALF) = x0; *(f32x4*)((float*)Xout + ro + bj * HALF + 4) = x1; } } }
	s_nop 1
	v_mov_b32_e32 v120, v164
	v_mov_b32_e32 v121, v165
	v_mov_b32_e32 v122, v166
	v_mov_b32_e32 v123, v167
	s_waitcnt lgkmcnt(0)
	v_lshlrev_b32_e32 v124, 16, v120
	v_and_b32_e32 v125, 0xffff0000, v120
	v_lshlrev_b32_e32 v120, 16, v121
	v_and_b32_e32 v121, 0xffff0000, v121
	v_lshlrev_b32_e32 v126, 16, v122
	v_and_b32_e32 v127, 0xffff0000, v122
	v_lshlrev_b32_e32 v122, 16, v123
	v_and_b32_e32 v123, 0xffff0000, v123
	v_pk_add_f32 v[116:117], v[116:117], v[124:125]
	v_pk_add_f32 v[118:119], v[118:119], v[120:121]
	v_pk_add_f32 v[120:121], v[114:115], v[122:123]
	v_pk_add_f32 v[114:115], v[112:113], v[126:127]
	v_cvt_pk_bf16_f32 v112, v116, v117
	v_lshl_add_u64 v[116:117], v[144:145], 0, s[2:3]
	s_mov_b32 s2, 0x10000
	v_cvt_pk_bf16_f32 v113, v118, v119
	v_add_co_u32_e32 v118, vcc, s2, v144
	v_cvt_pk_bf16_f32 v114, v114, v115
	v_cvt_pk_bf16_f32 v115, v120, v121
	v_addc_co_u32_e32 v119, vcc, 0, v145, vcc
	global_store_dwordx4 v[144:145], v[112:115], off offset:256
	s_waitcnt vmcnt(15)
	s_nop 1
	v_mov_b32_e32 v112, v168
	v_mov_b32_e32 v113, v169
	v_mov_b32_e32 v114, v170
	v_mov_b32_e32 v115, v171
	s_mov_b64 s[2:3], 0x20000
	s_waitcnt lgkmcnt(0)
	v_lshlrev_b32_e32 v120, 16, v112
	v_and_b32_e32 v121, 0xffff0000, v112
	v_lshlrev_b32_e32 v112, 16, v113
	v_and_b32_e32 v113, 0xffff0000, v113
	v_lshlrev_b32_e32 v122, 16, v114
	v_and_b32_e32 v123, 0xffff0000, v114
	v_lshlrev_b32_e32 v114, 16, v115
	v_and_b32_e32 v115, 0xffff0000, v115
	v_pk_add_f32 v[110:111], v[110:111], v[112:113]
	v_pk_add_f32 v[108:109], v[108:109], v[120:121]
	v_pk_add_f32 v[112:113], v[106:107], v[114:115]
	v_pk_add_f32 v[106:107], v[104:105], v[122:123]
	v_cvt_pk_bf16_f32 v104, v108, v109
	v_cvt_pk_bf16_f32 v105, v110, v111
	v_cvt_pk_bf16_f32 v106, v106, v107
	v_cvt_pk_bf16_f32 v107, v112, v113
	global_store_dwordx4 v[118:119], v[104:107], off
	s_waitcnt vmcnt(15)
	s_nop 1
	v_mov_b32_e32 v104, v172
	v_mov_b32_e32 v105, v173
	v_mov_b32_e32 v106, v174
	v_mov_b32_e32 v107, v175
	s_waitcnt lgkmcnt(0)
	v_lshlrev_b32_e32 v108, 16, v104
	v_and_b32_e32 v109, 0xffff0000, v104
	v_lshlrev_b32_e32 v104, 16, v105
	v_and_b32_e32 v105, 0xffff0000, v105
	v_lshlrev_b32_e32 v110, 16, v106
	v_and_b32_e32 v111, 0xffff0000, v106
	v_lshlrev_b32_e32 v106, 16, v107
	v_and_b32_e32 v107, 0xffff0000, v107
	v_pk_add_f32 v[100:101], v[100:101], v[108:109]
	v_pk_add_f32 v[102:103], v[102:103], v[104:105]
	v_pk_add_f32 v[104:105], v[98:99], v[106:107]
	v_pk_add_f32 v[98:99], v[96:97], v[110:111]
	v_cvt_pk_bf16_f32 v96, v100, v101
	v_lshl_add_u64 v[100:101], v[144:145], 0, s[2:3]
	s_mov_b32 s2, 0x20000
	v_cvt_pk_bf16_f32 v97, v102, v103
	v_add_co_u32_e32 v102, vcc, s2, v144
	v_cvt_pk_bf16_f32 v98, v98, v99
	v_cvt_pk_bf16_f32 v99, v104, v105
	v_addc_co_u32_e32 v103, vcc, 0, v145, vcc
	global_store_dwordx4 v[116:117], v[96:99], off offset:256
	s_waitcnt vmcnt(15)
	s_nop 1
	v_mov_b32_e32 v96, v176
	v_mov_b32_e32 v97, v177
	v_mov_b32_e32 v98, v178
	v_mov_b32_e32 v99, v179
	s_mov_b64 s[2:3], 0x30000
	s_waitcnt lgkmcnt(0)
	v_lshlrev_b32_e32 v104, 16, v96
	v_and_b32_e32 v105, 0xffff0000, v96
	v_lshlrev_b32_e32 v96, 16, v97
	v_and_b32_e32 v97, 0xffff0000, v97
	v_lshlrev_b32_e32 v106, 16, v98
	v_and_b32_e32 v107, 0xffff0000, v98
	v_lshlrev_b32_e32 v98, 16, v99
	v_and_b32_e32 v99, 0xffff0000, v99
	v_pk_add_f32 v[94:95], v[94:95], v[96:97]
	v_pk_add_f32 v[92:93], v[92:93], v[104:105]
	v_pk_add_f32 v[96:97], v[90:91], v[98:99]
	v_pk_add_f32 v[90:91], v[88:89], v[106:107]
	v_cvt_pk_bf16_f32 v88, v92, v93
	v_cvt_pk_bf16_f32 v89, v94, v95
	v_cvt_pk_bf16_f32 v90, v90, v91
	v_cvt_pk_bf16_f32 v91, v96, v97
	global_store_dwordx4 v[102:103], v[88:91], off
	s_waitcnt vmcnt(15)
	s_nop 1
	v_mov_b32_e32 v88, v180
	v_mov_b32_e32 v89, v181
	v_mov_b32_e32 v90, v182
	v_mov_b32_e32 v91, v183
	s_waitcnt lgkmcnt(0)
	v_lshlrev_b32_e32 v92, 16, v88
	v_and_b32_e32 v93, 0xffff0000, v88
	v_lshlrev_b32_e32 v88, 16, v89
	v_and_b32_e32 v89, 0xffff0000, v89
	v_lshlrev_b32_e32 v94, 16, v90
	v_and_b32_e32 v95, 0xffff0000, v90
	v_lshlrev_b32_e32 v90, 16, v91
	v_and_b32_e32 v91, 0xffff0000, v91
	v_pk_add_f32 v[86:87], v[86:87], v[88:89]
	v_pk_add_f32 v[84:85], v[84:85], v[92:93]
	v_pk_add_f32 v[88:89], v[82:83], v[90:91]
	v_pk_add_f32 v[82:83], v[80:81], v[94:95]
	v_cvt_pk_bf16_f32 v80, v84, v85
	v_cvt_pk_bf16_f32 v81, v86, v87
	v_cvt_pk_bf16_f32 v82, v82, v83
	v_cvt_pk_bf16_f32 v83, v88, v89
	global_store_dwordx4 v[100:101], v[80:83], off offset:256
	s_nop 1
	v_lshl_add_u64 v[80:81], v[144:145], 0, s[2:3]
	s_mov_b32 s2, 0x30000
	v_add_co_u32_e32 v86, vcc, s2, v144
	s_mov_b64 s[2:3], 0x80000
	s_nop 0
	v_addc_co_u32_e32 v87, vcc, 0, v145, vcc
	s_waitcnt vmcnt(15)
	s_nop 1
	v_mov_b32_e32 v82, v184
	v_mov_b32_e32 v83, v185
	v_mov_b32_e32 v84, v186
	v_mov_b32_e32 v85, v187
	s_waitcnt lgkmcnt(0)
	v_lshlrev_b32_e32 v88, 16, v82
	v_and_b32_e32 v89, 0xffff0000, v82
	v_lshlrev_b32_e32 v82, 16, v83
	v_and_b32_e32 v83, 0xffff0000, v83
	v_lshlrev_b32_e32 v90, 16, v84
	v_and_b32_e32 v91, 0xffff0000, v84
	v_lshlrev_b32_e32 v84, 16, v85
	v_and_b32_e32 v85, 0xffff0000, v85
	v_pk_add_f32 v[78:79], v[78:79], v[82:83]
	v_pk_add_f32 v[76:77], v[76:77], v[88:89]
	v_pk_add_f32 v[82:83], v[74:75], v[84:85]
	v_pk_add_f32 v[74:75], v[72:73], v[90:91]
	v_cvt_pk_bf16_f32 v72, v76, v77
	v_cvt_pk_bf16_f32 v73, v78, v79
	v_cvt_pk_bf16_f32 v74, v74, v75
	v_cvt_pk_bf16_f32 v75, v82, v83
	global_store_dwordx4 v[86:87], v[72:75], off
	s_waitcnt vmcnt(15)
	s_nop 1
	v_mov_b32_e32 v72, v188
	v_mov_b32_e32 v73, v189
	v_mov_b32_e32 v74, v190
	v_mov_b32_e32 v75, v191
	s_waitcnt lgkmcnt(0)
; DI unsigned pack2(float a, float b) { f32x2 v = {a, b}; hwbf16x2 r = __builtin_convertvector(v, hwbf16x2); return __builtin_bit_cast(unsigned, r); }
; DI float bflo(unsigned w) { return __uint_as_float(w << 16); }
; DI float bfhi(unsigned w) { return __uint_as_float(w & 0xffff0000u); }
;     DI void operator()(const f32x4 (&acc)[2][2][4][2], const Unit& u, int wr, int wc, int fr, int fq) const {
;     ...
;         for (int ai = 0; ai < 2; ++ai)
; #pragma unroll
;             for (int m = 0; m < 4; ++m) { const size_t ro = (size_t)(row0 + ai * HALF + m * 16) * D + col0;
; #pragma unroll
;                 for (int bj = 0; bj < 2; ++bj) {
;                     f32x4 x0, x1;
;                     if constexpr (IB) { const u32x4 w = *(const u32x4*)((const bf16_t*)Xin + ro + bj * HALF);
;                         x0 = (f32x4){bflo(w[0]), bfhi(w[0]), bflo(w[1]), bfhi(w[1])}; x1 = (f32x4){bflo(w[2]), bfhi(w[2]), bflo(w[3]), bfhi(w[3])}; }
;                     else { x0 = *(const f32x4*)((const float*)Xin + ro + bj * HALF); x1 = *(const f32x4*)((const float*)Xin + ro + bj * HALF + 4); }
;                     x0 += acc[ai][bj][m][0] * sc[bj][0]; x1 += acc[ai][bj][m][1] * sc[bj][1];
;                     if constexpr (OB) { u32x4 o; o[0] = pack2(x0[0], x0[1]); o[1] = pack2(x0[2], x0[3]); o[2] = pack2(x1[0], x1[1]); o[3] = pack2(x1[2], x1[3]);
;                         *(u32x4*)((bf16_t*)Xout + ro + bj * HALF) = o; }
;                     else { *(f32x4*)((float*)Xout + ro + bj * HALF) = x0; *(f32x4*)((float*)Xout + ro + bj * HALF + 4) = x1; } } }
	v_lshlrev_b32_e32 v76, 16, v72
	v_and_b32_e32 v77, 0xffff0000, v72
	v_lshlrev_b32_e32 v72, 16, v73
	v_and_b32_e32 v73, 0xffff0000, v73
	v_lshlrev_b32_e32 v78, 16, v74
	v_and_b32_e32 v79, 0xffff0000, v74
	v_lshlrev_b32_e32 v74, 16, v75
	v_and_b32_e32 v75, 0xffff0000, v75
	v_pk_add_f32 v[70:71], v[70:71], v[72:73]
	v_pk_add_f32 v[68:69], v[68:69], v[76:77]
	v_pk_add_f32 v[72:73], v[66:67], v[74:75]
	v_pk_add_f32 v[66:67], v[64:65], v[78:79]
	v_cvt_pk_bf16_f32 v64, v68, v69
	v_cvt_pk_bf16_f32 v65, v70, v71
	v_cvt_pk_bf16_f32 v66, v66, v67
	v_cvt_pk_bf16_f32 v67, v72, v73
	global_store_dwordx4 v[80:81], v[64:67], off offset:256
	s_nop 1
	v_lshl_add_u64 v[64:65], v[144:145], 0, s[2:3]
	s_mov_b32 s2, 0x80000
	v_add_co_u32_e32 v70, vcc, s2, v144
	s_mov_b64 s[2:3], 0x90000
	s_nop 0
	v_addc_co_u32_e32 v71, vcc, 0, v145, vcc
	s_waitcnt vmcnt(15)
	s_nop 1
	v_mov_b32_e32 v66, v192
	v_mov_b32_e32 v67, v193
	v_mov_b32_e32 v68, v194
	v_mov_b32_e32 v69, v195
	s_waitcnt lgkmcnt(0)
	v_lshlrev_b32_e32 v72, 16, v66
	v_and_b32_e32 v73, 0xffff0000, v66
	v_lshlrev_b32_e32 v66, 16, v67
	v_and_b32_e32 v67, 0xffff0000, v67
	v_lshlrev_b32_e32 v74, 16, v68
	v_and_b32_e32 v75, 0xffff0000, v68
	v_lshlrev_b32_e32 v68, 16, v69
	v_and_b32_e32 v69, 0xffff0000, v69
	v_pk_add_f32 v[62:63], v[62:63], v[66:67]
	v_pk_add_f32 v[60:61], v[60:61], v[72:73]
	v_pk_add_f32 v[66:67], v[58:59], v[68:69]
	v_pk_add_f32 v[58:59], v[56:57], v[74:75]
	v_cvt_pk_bf16_f32 v56, v60, v61
	v_cvt_pk_bf16_f32 v57, v62, v63
	v_cvt_pk_bf16_f32 v58, v58, v59
	v_cvt_pk_bf16_f32 v59, v66, v67
	global_store_dwordx4 v[70:71], v[56:59], off
	s_waitcnt vmcnt(15)
	s_nop 1
	v_mov_b32_e32 v56, v198
	v_mov_b32_e32 v57, v199
	v_mov_b32_e32 v58, v200
	v_mov_b32_e32 v59, v201
	s_waitcnt lgkmcnt(0)
	v_lshlrev_b32_e32 v60, 16, v56
	v_and_b32_e32 v61, 0xffff0000, v56
	v_lshlrev_b32_e32 v56, 16, v57
	v_and_b32_e32 v57, 0xffff0000, v57
	v_lshlrev_b32_e32 v62, 16, v58
	v_and_b32_e32 v63, 0xffff0000, v58
	v_lshlrev_b32_e32 v58, 16, v59
	v_and_b32_e32 v59, 0xffff0000, v59
	v_pk_add_f32 v[54:55], v[54:55], v[56:57]
	v_pk_add_f32 v[52:53], v[52:53], v[60:61]
	v_pk_add_f32 v[56:57], v[50:51], v[58:59]
	v_pk_add_f32 v[50:51], v[48:49], v[62:63]
	v_cvt_pk_bf16_f32 v48, v52, v53
	v_cvt_pk_bf16_f32 v49, v54, v55
	v_cvt_pk_bf16_f32 v50, v50, v51
	v_cvt_pk_bf16_f32 v51, v56, v57
	global_store_dwordx4 v[64:65], v[48:51], off offset:256
	s_nop 1
	v_lshl_add_u64 v[48:49], v[144:145], 0, s[2:3]
	s_mov_b32 s2, 0x90000
	v_add_co_u32_e32 v54, vcc, s2, v144
	s_mov_b64 s[2:3], 0xa0000
	s_nop 0
	v_addc_co_u32_e32 v55, vcc, 0, v145, vcc
	s_waitcnt vmcnt(15)
	s_nop 1
	v_mov_b32_e32 v50, v202
	v_mov_b32_e32 v51, v203
	v_mov_b32_e32 v52, v204
	v_mov_b32_e32 v53, v205
	s_waitcnt lgkmcnt(0)
	v_lshlrev_b32_e32 v56, 16, v50
	v_and_b32_e32 v57, 0xffff0000, v50
	v_lshlrev_b32_e32 v50, 16, v51
	v_and_b32_e32 v51, 0xffff0000, v51
	v_lshlrev_b32_e32 v58, 16, v52
	v_and_b32_e32 v59, 0xffff0000, v52
	v_lshlrev_b32_e32 v52, 16, v53
	v_and_b32_e32 v53, 0xffff0000, v53
	v_pk_add_f32 v[46:47], v[46:47], v[50:51]
	v_pk_add_f32 v[44:45], v[44:45], v[56:57]
	v_pk_add_f32 v[50:51], v[42:43], v[52:53]
	v_pk_add_f32 v[42:43], v[40:41], v[58:59]
	v_cvt_pk_bf16_f32 v40, v44, v45
	v_cvt_pk_bf16_f32 v41, v46, v47
	v_cvt_pk_bf16_f32 v42, v42, v43
	v_cvt_pk_bf16_f32 v43, v50, v51
	global_store_dwordx4 v[54:55], v[40:43], off
	s_waitcnt vmcnt(15)
	s_nop 1
	v_mov_b32_e32 v40, v206
	v_mov_b32_e32 v41, v207
	v_mov_b32_e32 v42, v208
	v_mov_b32_e32 v43, v209
	s_waitcnt lgkmcnt(0)
; DI unsigned pack2(float a, float b) { f32x2 v = {a, b}; hwbf16x2 r = __builtin_convertvector(v, hwbf16x2); return __builtin_bit_cast(unsigned, r); }
; DI float bflo(unsigned w) { return __uint_as_float(w << 16); }
; DI float bfhi(unsigned w) { return __uint_as_float(w & 0xffff0000u); }
;     DI const char* a(const Unit& u) const { return (const char*)(A + (size_t)u.pm * BM * lda); }
;     DI const char* a(const Unit& u) const { return (const char*)(A + (size_t)u.pm * BM * 2048 + (u.pn >> 1) * 512); }
;     DI void operator()(const f32x4 (&acc)[2][2][4][2], const Unit& u, int wr, int wc, int fr, int fq) const {
;     ...
;         for (int ai = 0; ai < 2; ++ai)
; #pragma unroll
;             for (int m = 0; m < 4; ++m) { const size_t ro = (size_t)(row0 + ai * HALF + m * 16) * D + col0;
; #pragma unroll
;                 for (int bj = 0; bj < 2; ++bj) {
;                     f32x4 x0, x1;
;                     if constexpr (IB) { const u32x4 w = *(const u32x4*)((const bf16_t*)Xin + ro + bj * HALF);
;                         x0 = (f32x4){bflo(w[0]), bfhi(w[0]), bflo(w[1]), bfhi(w[1])}; x1 = (f32x4){bflo(w[2]), bfhi(w[2]), bflo(w[3]), bfhi(w[3])}; }
;                     else { x0 = *(const f32x4*)((const float*)Xin + ro + bj * HALF); x1 = *(const f32x4*)((const float*)Xin + ro + bj * HALF + 4); }
;                     x0 += acc[ai][bj][m][0] * sc[bj][0]; x1 += acc[ai][bj][m][1] * sc[bj][1];
;                     if constexpr (OB) { u32x4 o; o[0] = pack2(x0[0], x0[1]); o[1] = pack2(x0[2], x0[3]); o[2] = pack2(x1[0], x1[1]); o[3] = pack2(x1[2], x1[3]);
;                         *(u32x4*)((bf16_t*)Xout + ro + bj * HALF) = o; }
;                     else { *(f32x4*)((float*)Xout + ro + bj * HALF) = x0; *(f32x4*)((float*)Xout + ro + bj * HALF + 4) = x1; } } }
; template <class Map, class Epi>
; DI void gemm_phase(LAS unsigned char* lds, const Map& MP, const Epi& E, const int nM, const int nN, const int K, const int lda, const int ldb) {
;     ...
;         if (!has_next) break;
; #pragma unroll
;         for (int a = 0; a < 2; ++a)
; #pragma unroll
;             for (int b = 0; b < 2; ++b)
; #pragma unroll
;                 for (int m = 0; m < 4; ++m)
; #pragma unroll
;                     for (int n = 0; n < 2; ++n) acc[a][b][m][n] = (f32x4){0.f, 0.f, 0.f, 0.f};
;         cur = nxt; cA = nA; cB = nB; ++ui;
	v_lshlrev_b32_e32 v44, 16, v40
	v_and_b32_e32 v45, 0xffff0000, v40
	v_lshlrev_b32_e32 v40, 16, v41
	v_and_b32_e32 v41, 0xffff0000, v41
	v_lshlrev_b32_e32 v46, 16, v42
	v_and_b32_e32 v47, 0xffff0000, v42
	v_lshlrev_b32_e32 v42, 16, v43
	v_and_b32_e32 v43, 0xffff0000, v43
	v_pk_add_f32 v[38:39], v[38:39], v[40:41]
	v_pk_add_f32 v[36:37], v[36:37], v[44:45]
	v_pk_add_f32 v[40:41], v[34:35], v[42:43]
	v_pk_add_f32 v[34:35], v[32:33], v[46:47]
	v_cvt_pk_bf16_f32 v32, v36, v37
	v_cvt_pk_bf16_f32 v33, v38, v39
	v_cvt_pk_bf16_f32 v34, v34, v35
	v_cvt_pk_bf16_f32 v35, v40, v41
	global_store_dwordx4 v[48:49], v[32:35], off offset:256
	s_nop 1
	v_lshl_add_u64 v[32:33], v[144:145], 0, s[2:3]
	s_mov_b32 s2, 0xa0000
	v_add_co_u32_e32 v38, vcc, s2, v144
	s_mov_b64 s[2:3], 0xb0000
	s_nop 0
	v_addc_co_u32_e32 v39, vcc, 0, v145, vcc
	s_waitcnt vmcnt(15)
	s_nop 1
	v_mov_b32_e32 v34, v210
	v_mov_b32_e32 v35, v211
	v_mov_b32_e32 v36, v212
	v_mov_b32_e32 v37, v213
	s_waitcnt lgkmcnt(0)
	v_lshlrev_b32_e32 v40, 16, v34
	v_and_b32_e32 v41, 0xffff0000, v34
	v_lshlrev_b32_e32 v34, 16, v35
	v_and_b32_e32 v35, 0xffff0000, v35
	v_lshlrev_b32_e32 v42, 16, v36
	v_and_b32_e32 v43, 0xffff0000, v36
	v_lshlrev_b32_e32 v36, 16, v37
	v_and_b32_e32 v37, 0xffff0000, v37
	v_pk_add_f32 v[30:31], v[30:31], v[34:35]
	v_pk_add_f32 v[28:29], v[28:29], v[40:41]
	v_pk_add_f32 v[34:35], v[26:27], v[36:37]
	v_pk_add_f32 v[26:27], v[24:25], v[42:43]
	v_cvt_pk_bf16_f32 v24, v28, v29
	v_cvt_pk_bf16_f32 v25, v30, v31
	v_cvt_pk_bf16_f32 v26, v26, v27
	v_cvt_pk_bf16_f32 v27, v34, v35
	global_store_dwordx4 v[38:39], v[24:27], off
	s_waitcnt vmcnt(15)
	s_nop 1
	v_mov_b32_e32 v24, v214
	v_mov_b32_e32 v25, v215
	v_mov_b32_e32 v26, v216
	v_mov_b32_e32 v27, v217
	s_waitcnt lgkmcnt(0)
	v_lshlrev_b32_e32 v28, 16, v24
	v_and_b32_e32 v29, 0xffff0000, v24
	v_lshlrev_b32_e32 v24, 16, v25
	v_and_b32_e32 v25, 0xffff0000, v25
	v_lshlrev_b32_e32 v30, 16, v26
	v_and_b32_e32 v31, 0xffff0000, v26
	v_lshlrev_b32_e32 v26, 16, v27
	v_and_b32_e32 v27, 0xffff0000, v27
	v_pk_add_f32 v[22:23], v[22:23], v[24:25]
	v_pk_add_f32 v[20:21], v[20:21], v[28:29]
	v_pk_add_f32 v[24:25], v[18:19], v[26:27]
	v_pk_add_f32 v[18:19], v[16:17], v[30:31]
	v_cvt_pk_bf16_f32 v16, v20, v21
	v_cvt_pk_bf16_f32 v17, v22, v23
	v_cvt_pk_bf16_f32 v18, v18, v19
	v_cvt_pk_bf16_f32 v19, v24, v25
	global_store_dwordx4 v[32:33], v[16:19], off offset:256
	s_nop 1
	v_lshl_add_u64 v[16:17], v[144:145], 0, s[2:3]
	s_mov_b32 s2, 0xb0000
	v_add_co_u32_e32 v22, vcc, s2, v144
	s_mov_b32 s2, s55
	s_nop 0
	v_addc_co_u32_e32 v23, vcc, 0, v145, vcc
	s_waitcnt vmcnt(15)
	s_nop 1
	v_mov_b32_e32 v18, v248
	v_mov_b32_e32 v19, v249
	v_mov_b32_e32 v20, v250
	v_mov_b32_e32 v21, v251
	s_and_b64 vcc, exec, s[40:41]
	s_waitcnt lgkmcnt(0)
	v_lshlrev_b32_e32 v24, 16, v18
	v_and_b32_e32 v25, 0xffff0000, v18
	v_lshlrev_b32_e32 v18, 16, v19
	v_and_b32_e32 v19, 0xffff0000, v19
	v_lshlrev_b32_e32 v26, 16, v20
	v_and_b32_e32 v27, 0xffff0000, v20
	v_lshlrev_b32_e32 v20, 16, v21
	v_and_b32_e32 v21, 0xffff0000, v21
	v_pk_add_f32 v[14:15], v[14:15], v[18:19]
	v_pk_add_f32 v[12:13], v[12:13], v[24:25]
	v_pk_add_f32 v[18:19], v[10:11], v[20:21]
	v_pk_add_f32 v[10:11], v[8:9], v[26:27]
	v_cvt_pk_bf16_f32 v8, v12, v13
	v_cvt_pk_bf16_f32 v9, v14, v15
	v_cvt_pk_bf16_f32 v10, v10, v11
	v_cvt_pk_bf16_f32 v11, v18, v19
	global_store_dwordx4 v[22:23], v[8:11], off
	s_waitcnt vmcnt(15)
	s_nop 1
	v_mov_b32_e32 v8, v252
	v_mov_b32_e32 v9, v253
	v_mov_b32_e32 v10, v254
	v_mov_b32_e32 v11, v255
	s_waitcnt lgkmcnt(0)
	v_lshlrev_b32_e32 v12, 16, v8
	v_and_b32_e32 v13, 0xffff0000, v8
	v_lshlrev_b32_e32 v8, 16, v9
	v_and_b32_e32 v9, 0xffff0000, v9
	v_lshlrev_b32_e32 v14, 16, v10
	v_and_b32_e32 v15, 0xffff0000, v10
	v_lshlrev_b32_e32 v10, 16, v11
	v_and_b32_e32 v11, 0xffff0000, v11
	v_pk_add_f32 v[6:7], v[6:7], v[8:9]
	v_pk_add_f32 v[4:5], v[4:5], v[12:13]
	v_pk_add_f32 v[8:9], v[2:3], v[10:11]
	v_pk_add_f32 v[2:3], v[0:1], v[14:15]
	v_cvt_pk_bf16_f32 v0, v4, v5
	v_cvt_pk_bf16_f32 v1, v6, v7
	v_cvt_pk_bf16_f32 v2, v2, v3
	v_cvt_pk_bf16_f32 v3, v8, v9
	global_store_dwordx4 v[16:17], v[0:3], off offset:256
	s_cbranch_vccz .LBB1_543
	s_waitcnt vmcnt(0)
	s_cmpk_gt_u32 s17, 0xff
	s_cbranch_scc1 .LBB1_554
	s_barrier

;     DI const char* a(const Unit& u) const { return (const char*)(A + (size_t)u.pm * BM * lda); }
;     DI const char* a(const Unit& u) const { return (const char*)(A + (size_t)u.pm * BM * 2048 + (u.pn >> 1) * 512); }
;     DI const char* a(const Unit& u) const { return (const char*)((u.pn < 12 ? A1 : A2) + (size_t)u.pm * BM * 512); }
; #define PG8_STAGE(bufoff, gbase, voff) do { _Pragma("unroll") for (int _i = 0; _i < 2; ++_i) \
;         __builtin_amdgcn_global_load_lds((const unsigned*)((const char*)(gbase) + (voff)[_i]), (LAS unsigned*)(lds + (bufoff) + ldsw + _i * 8192), 16, 0, 0); } while (0)
; #define PG8_LDA(dst, b, h) do { _Pragma("unroll") for (int m = 0; m < 4; ++m) _Pragma("unroll") for (int k = 0; k < 2; ++k) dst[m][k] = *(const LAS bf16x8*)(lds + PG8_SA(b, h) + aoff + m * 2048 + k * 1024); } while (0)
; #define PG8_LDB(dst, b, h) do { _Pragma("unroll") for (int n = 0; n < 2; ++n) _Pragma("unroll") for (int k = 0; k < 2; ++k) dst[n][k] = *(const LAS bf16x8*)(lds + PG8_SB(b, h) + boff + n * 2048 + k * 1024); } while (0)
; template <class Map, class Epi>
; DI void gemm_phase(LAS unsigned char* lds, const Map& MP, const Epi& E, const int nM, const int nN, const int K, const int lda, const int ldb) {
;     ...
;     for (;;) {
;         const bool has_next = sched_next(ui + 1, nM, nN, G, cblk, nxt);
;         const char* nA = has_next ? MP.a(nxt) : cA; const char* nB = has_next ? MP.b(nxt) : cB;
;         for (int t = 0; t < nt; t += 2) {
;             const bool last = (t == nt - 2);
;             const char* a1 = cA + (size_t)(t + 1) * kstep;
;             const char* a2 = last ? nA : cA + (size_t)(t + 2) * kstep; const char* b2 = last ? nB : cB + (size_t)(t + 2) * kstep;
;             const char* a3 = a2 + kstep; const char* b3 = b2 + kstep;
;             PG8_LDB(B0, 0, 0); PG8_SCHED; PG8_LDA(At, 0, 0); PG8_STAGE(PG8_SA(1, 1), a1 + hstepA, voffA);
;             PG8_WAIT_L(8); PG8_BAR; PG8_WAIT_L(0); PG8_MMA(0, 0, At, B0); PG8_BAR; PG8_SCHED;
;             PG8_LDB(B1, 0, 1); PG8_STAGE(PG8_SB(0, 0), b2, voffB);
;             PG8_BAR; PG8_WAIT_L(0); PG8_MMA(0, 1, At, B1); PG8_BAR;
;             PG8_LDA(At, 0, 1); PG8_STAGE(PG8_SA(0, 0), a2, voffA);
;             PG8_BAR; PG8_WAIT_L(0); PG8_MMA(1, 0, At, B0); PG8_BAR; PG8_SCHED;
;             PG8_STAGE(PG8_SB(0, 1), b2 + hstepB, voffB);
;             PG8_WAIT_V(6); PG8_BAR; PG8_MMA(1, 1, At, B1); PG8_BAR;
.LBB1_693:
	s_add_u32 s3, s20, 0xfff80080
	s_addc_u32 s22, s21, -1
	s_cmp_eq_u32 s54, 28
	s_cselect_b32 s25, s15, s22
	s_cselect_b32 s24, s48, s3
	s_cselect_b32 s23, s13, s53
	s_cselect_b32 s22, s49, s52
	s_add_i32 m0, s31, 0xc000
	ds_read_b128 v[166:169], v148
	ds_read_b128 v[170:173], v148 offset:1024
	ds_read_b128 v[174:177], v148 offset:2048
	ds_read_b128 v[178:181], v148 offset:3072
	ds_read_b128 v[182:185], v148 offset:4096
	ds_read_b128 v[186:189], v148 offset:5120
	ds_read_b128 v[190:193], v148 offset:6144
	ds_read_b128 v[198:201], v148 offset:7168
	global_load_lds_dwordx4 v138, s[20:21]
	s_add_i32 m0, s31, 0xe000
	s_nop 0
	global_load_lds_dwordx4 v136, s[20:21]
	s_waitcnt lgkmcnt(8)
	s_setprio 1
	s_barrier
	s_waitcnt lgkmcnt(7)
	v_mfma_f32_16x16x32_bf16 v[124:127], v[150:153], v[166:169], v[124:127]
	v_mfma_f32_16x16x32_bf16 v[120:123], v[158:161], v[166:169], v[120:123]
	s_waitcnt lgkmcnt(5)
	v_mfma_f32_16x16x32_bf16 v[116:119], v[150:153], v[174:177], v[116:119]
	v_mfma_f32_16x16x32_bf16 v[112:115], v[158:161], v[174:177], v[112:115]
	s_waitcnt lgkmcnt(3)
	v_mfma_f32_16x16x32_bf16 v[100:103], v[150:153], v[182:185], v[100:103]
	v_mfma_f32_16x16x32_bf16 v[96:99], v[158:161], v[182:185], v[96:99]
	s_waitcnt lgkmcnt(1)
	v_mfma_f32_16x16x32_bf16 v[84:87], v[150:153], v[190:193], v[84:87]
	v_mfma_f32_16x16x32_bf16 v[80:83], v[158:161], v[190:193], v[80:83]
	v_mfma_f32_16x16x32_bf16 v[124:127], v[154:157], v[170:173], v[124:127]
	s_add_i32 s3, s44, s29
	v_mfma_f32_16x16x32_bf16 v[120:123], v[162:165], v[170:173], v[120:123]
	v_lshl_add_u64 v[194:195], s[22:23], 0, v[132:133]
	v_mfma_f32_16x16x32_bf16 v[116:119], v[154:157], v[178:181], v[116:119]
	v_lshl_add_u64 v[218:219], s[22:23], 0, v[128:129]
	v_mfma_f32_16x16x32_bf16 v[112:115], v[162:165], v[178:181], v[112:115]
	v_mfma_f32_16x16x32_bf16 v[100:103], v[154:157], v[186:189], v[100:103]
	v_mfma_f32_16x16x32_bf16 v[96:99], v[162:165], v[186:189], v[96:99]
	s_waitcnt lgkmcnt(0)
	v_mfma_f32_16x16x32_bf16 v[84:87], v[154:157], v[198:201], v[84:87]
	s_mov_b32 m0, s3
	v_mfma_f32_16x16x32_bf16 v[80:83], v[162:165], v[198:201], v[80:83]
	s_barrier
	s_setprio 0
	ds_read_b128 v[202:205], v149
	ds_read_b128 v[206:209], v149 offset:1024
	ds_read_b128 v[210:213], v149 offset:2048
	global_load_lds_dwordx4 v[194:195], off
	s_add_i32 m0, s3, 0x2000
	ds_read_b128 v[214:217], v149 offset:3072
	global_load_lds_dwordx4 v[218:219], off
	s_setprio 1
	s_barrier
	s_waitcnt lgkmcnt(3)
	v_mfma_f32_16x16x32_bf16 v[108:111], v[202:205], v[166:169], v[108:111]
	s_waitcnt lgkmcnt(1)
	v_mfma_f32_16x16x32_bf16 v[104:107], v[210:213], v[166:169], v[104:107]
	v_mfma_f32_16x16x32_bf16 v[92:95], v[202:205], v[174:177], v[92:95]
	v_mfma_f32_16x16x32_bf16 v[88:91], v[210:213], v[174:177], v[88:91]
	v_mfma_f32_16x16x32_bf16 v[76:79], v[202:205], v[182:185], v[76:79]
	v_mfma_f32_16x16x32_bf16 v[72:75], v[210:213], v[182:185], v[72:75]
	v_mfma_f32_16x16x32_bf16 v[68:71], v[202:205], v[190:193], v[68:71]
	v_mfma_f32_16x16x32_bf16 v[64:67], v[210:213], v[190:193], v[64:67]
	v_mfma_f32_16x16x32_bf16 v[108:111], v[206:209], v[170:173], v[108:111]
	v_lshl_add_u64 v[222:223], s[24:25], 0, v[130:131]
	s_mov_b32 m0, s31
	s_waitcnt lgkmcnt(0)
	v_mfma_f32_16x16x32_bf16 v[104:107], v[214:217], v[170:173], v[104:107]
	v_lshl_add_u64 v[220:221], s[24:25], 0, v[134:135]
	v_mfma_f32_16x16x32_bf16 v[92:95], v[206:209], v[178:181], v[92:95]
	v_mfma_f32_16x16x32_bf16 v[88:91], v[214:217], v[178:181], v[88:91]
	v_mfma_f32_16x16x32_bf16 v[76:79], v[206:209], v[186:189], v[76:79]
	v_mfma_f32_16x16x32_bf16 v[72:75], v[214:217], v[186:189], v[72:75]
	v_mfma_f32_16x16x32_bf16 v[68:71], v[206:209], v[198:201], v[68:71]
	v_mfma_f32_16x16x32_bf16 v[64:67], v[214:217], v[198:201], v[64:67]
	s_barrier
	s_setprio 0
	ds_read_b128 v[166:169], v148 offset:16384
	ds_read_b128 v[170:173], v148 offset:17408
	ds_read_b128 v[174:177], v148 offset:18432
	ds_read_b128 v[178:181], v148 offset:19456
	ds_read_b128 v[182:185], v148 offset:20480
	ds_read_b128 v[186:189], v148 offset:21504
	ds_read_b128 v[190:193], v148 offset:22528
	global_load_lds_dwordx4 v[220:221], off
	s_mov_b32 m0, s11
	ds_read_b128 v[198:201], v148 offset:23552
	global_load_lds_dwordx4 v[222:223], off
	s_waitcnt vmcnt(10)
	s_setprio 1
	s_barrier
	s_waitcnt lgkmcnt(7)
	v_mfma_f32_16x16x32_bf16 v[60:63], v[150:153], v[166:169], v[60:63]
	v_mfma_f32_16x16x32_bf16 v[56:59], v[158:161], v[166:169], v[56:59]
	s_waitcnt lgkmcnt(5)
	v_mfma_f32_16x16x32_bf16 v[52:55], v[150:153], v[174:177], v[52:55]
	v_mfma_f32_16x16x32_bf16 v[48:51], v[158:161], v[174:177], v[48:51]
	s_waitcnt lgkmcnt(3)
	v_mfma_f32_16x16x32_bf16 v[36:39], v[150:153], v[182:185], v[36:39]
	v_mfma_f32_16x16x32_bf16 v[32:35], v[158:161], v[182:185], v[32:35]
	s_waitcnt lgkmcnt(1)
	v_mfma_f32_16x16x32_bf16 v[20:23], v[150:153], v[190:193], v[20:23]
	v_mfma_f32_16x16x32_bf16 v[16:19], v[158:161], v[190:193], v[16:19]
	v_mfma_f32_16x16x32_bf16 v[60:63], v[154:157], v[170:173], v[60:63]
	s_add_u32 s56, s22, 0x80000
	s_addc_u32 s57, s23, 0
	v_mfma_f32_16x16x32_bf16 v[56:59], v[162:165], v[170:173], v[56:59]
	s_add_i32 s3, s45, s29
	v_mfma_f32_16x16x32_bf16 v[52:55], v[154:157], v[178:181], v[52:55]
	v_mfma_f32_16x16x32_bf16 v[48:51], v[162:165], v[178:181], v[48:51]
	v_mfma_f32_16x16x32_bf16 v[36:39], v[154:157], v[186:189], v[36:39]
	v_mfma_f32_16x16x32_bf16 v[32:35], v[162:165], v[186:189], v[32:35]
	s_waitcnt lgkmcnt(0)
	v_mfma_f32_16x16x32_bf16 v[20:23], v[154:157], v[198:201], v[20:23]
	s_mov_b32 m0, s3
	v_mfma_f32_16x16x32_bf16 v[16:19], v[162:165], v[198:201], v[16:19]
	s_barrier
; #define PG8_STAGE(bufoff, gbase, voff) do { _Pragma("unroll") for (int _i = 0; _i < 2; ++_i) \
;         __builtin_amdgcn_global_load_lds((const unsigned*)((const char*)(gbase) + (voff)[_i]), (LAS unsigned*)(lds + (bufoff) + ldsw + _i * 8192), 16, 0, 0); } while (0)
; #define PG8_LDA(dst, b, h) do { _Pragma("unroll") for (int m = 0; m < 4; ++m) _Pragma("unroll") for (int k = 0; k < 2; ++k) dst[m][k] = *(const LAS bf16x8*)(lds + PG8_SA(b, h) + aoff + m * 2048 + k * 1024); } while (0)
; #define PG8_LDB(dst, b, h) do { _Pragma("unroll") for (int n = 0; n < 2; ++n) _Pragma("unroll") for (int k = 0; k < 2; ++k) dst[n][k] = *(const LAS bf16x8*)(lds + PG8_SB(b, h) + boff + n * 2048 + k * 1024); } while (0)
; #define PG8_MMA(ai, bj, At, Bt) do { __builtin_amdgcn_s_setprio(1); _Pragma("unroll") for (int m = 0; m < 4; ++m) _Pragma("unroll") for (int n = 0; n < 2; ++n) _Pragma("unroll") for (int k = 0; k < 2; ++k) \
;         acc[ai][bj][m][n] = __builtin_amdgcn_mfma_f32_16x16x32_bf16(Bt[n][k], At[m][k], acc[ai][bj][m][n], 0, 0, 0); __builtin_amdgcn_s_setprio(0); } while (0)
; #define PG8_WAIT_V(n) asm volatile("s_waitcnt vmcnt(" #n ")" ::: "memory")
; #define PG8_WAIT_L(n) asm volatile("s_waitcnt lgkmcnt(" #n ")" ::: "memory")
; #define PG8_BAR __builtin_amdgcn_s_barrier()
; #define PG8_SCHED __builtin_amdgcn_sched_barrier(0)
; template <class Map, class Epi>
; DI void gemm_phase(LAS unsigned char* lds, const Map& MP, const Epi& E, const int nM, const int nN, const int K, const int lda, const int ldb) {
;     ...
;             PG8_BAR; PG8_WAIT_L(0); PG8_MMA(1, 0, At, B0); PG8_BAR; PG8_SCHED;
;             PG8_STAGE(PG8_SB(0, 1), b2 + hstepB, voffB);
;             PG8_WAIT_V(6); PG8_BAR; PG8_MMA(1, 1, At, B1); PG8_BAR;
;             PG8_LDB(B0, 1, 0); PG8_SCHED; PG8_LDA(At, 1, 0); PG8_STAGE(PG8_SA(0, 1), a2 + hstepA, voffA);
;             PG8_WAIT_L(8); PG8_BAR; PG8_WAIT_L(0); PG8_MMA(0, 0, At, B0); PG8_BAR; PG8_SCHED;
;             PG8_LDB(B1, 1, 1); PG8_STAGE(PG8_SB(1, 0), b3, voffB);
;             PG8_BAR; PG8_WAIT_L(0); PG8_MMA(0, 1, At, B1); PG8_BAR;
;             PG8_LDA(At, 1, 1); PG8_STAGE(PG8_SA(1, 0), a3, voffA);
;             PG8_BAR; PG8_WAIT_L(0); PG8_MMA(1, 0, At, B0); PG8_BAR; PG8_SCHED;
;             PG8_STAGE(PG8_SB(1, 1), b3 + hstepB, voffB);
;             PG8_WAIT_V(6); PG8_BAR; PG8_MMA(1, 1, At, B1); PG8_BAR;
	s_setprio 0
	global_load_lds_dwordx4 v132, s[56:57]
	s_add_i32 m0, s3, 0x2000
	s_nop 0
	global_load_lds_dwordx4 v128, s[56:57]
	s_waitcnt vmcnt(6)
	s_setprio 1
	s_barrier
	v_mfma_f32_16x16x32_bf16 v[44:47], v[202:205], v[166:169], v[44:47]
	v_mfma_f32_16x16x32_bf16 v[40:43], v[210:213], v[166:169], v[40:43]
	s_add_i32 s3, 0, 0x18000
	v_add_u32_e32 v162, s3, v146
	ds_read_b128 v[150:153], v162
	v_mfma_f32_16x16x32_bf16 v[28:31], v[202:205], v[174:177], v[28:31]
	v_mfma_f32_16x16x32_bf16 v[24:27], v[210:213], v[174:177], v[24:27]
	ds_read_b128 v[154:157], v162 offset:1024
	v_mfma_f32_16x16x32_bf16 v[12:15], v[202:205], v[182:185], v[12:15]
	v_mfma_f32_16x16x32_bf16 v[8:11], v[210:213], v[182:185], v[8:11]
	ds_read_b128 v[158:161], v162 offset:2048
	v_mfma_f32_16x16x32_bf16 v[4:7], v[202:205], v[190:193], v[4:7]
	v_mfma_f32_16x16x32_bf16 v[0:3], v[210:213], v[190:193], v[0:3]
	ds_read_b128 v[162:165], v162 offset:3072
	v_mfma_f32_16x16x32_bf16 v[44:47], v[206:209], v[170:173], v[44:47]
	s_add_u32 s24, s24, 0x80000
	s_addc_u32 s25, s25, 0
	v_mfma_f32_16x16x32_bf16 v[40:43], v[214:217], v[170:173], v[40:43]
	v_mfma_f32_16x16x32_bf16 v[28:31], v[206:209], v[178:181], v[28:31]
	v_mfma_f32_16x16x32_bf16 v[24:27], v[214:217], v[178:181], v[24:27]
	v_mfma_f32_16x16x32_bf16 v[12:15], v[206:209], v[186:189], v[12:15]
	v_mfma_f32_16x16x32_bf16 v[8:11], v[214:217], v[186:189], v[8:11]
	v_mfma_f32_16x16x32_bf16 v[4:7], v[206:209], v[198:201], v[4:7]
	s_mov_b32 m0, s34
	v_mfma_f32_16x16x32_bf16 v[0:3], v[214:217], v[198:201], v[0:3]
	s_barrier
	s_setprio 0
	ds_read_b128 v[166:169], v148 offset:32768
	ds_read_b128 v[170:173], v148 offset:33792
	ds_read_b128 v[174:177], v148 offset:34816
	ds_read_b128 v[178:181], v148 offset:35840
	ds_read_b128 v[182:185], v148 offset:36864
	ds_read_b128 v[186:189], v148 offset:37888
	ds_read_b128 v[190:193], v148 offset:38912
	global_load_lds_dwordx4 v134, s[24:25]
	s_mov_b32 m0, s35
	ds_read_b128 v[198:201], v148 offset:39936
	global_load_lds_dwordx4 v130, s[24:25]
	s_waitcnt lgkmcnt(8)
	s_setprio 1
	s_barrier
	s_waitcnt lgkmcnt(7)
	v_mfma_f32_16x16x32_bf16 v[124:127], v[150:153], v[166:169], v[124:127]
	v_mfma_f32_16x16x32_bf16 v[120:123], v[158:161], v[166:169], v[120:123]
	s_waitcnt lgkmcnt(5)
	v_mfma_f32_16x16x32_bf16 v[116:119], v[150:153], v[174:177], v[116:119]
	v_mfma_f32_16x16x32_bf16 v[112:115], v[158:161], v[174:177], v[112:115]
	s_waitcnt lgkmcnt(3)
	v_mfma_f32_16x16x32_bf16 v[100:103], v[150:153], v[182:185], v[100:103]
	v_mfma_f32_16x16x32_bf16 v[96:99], v[158:161], v[182:185], v[96:99]
	s_waitcnt lgkmcnt(1)
	v_mfma_f32_16x16x32_bf16 v[84:87], v[150:153], v[190:193], v[84:87]
	v_mfma_f32_16x16x32_bf16 v[80:83], v[158:161], v[190:193], v[80:83]
	v_mfma_f32_16x16x32_bf16 v[124:127], v[154:157], v[170:173], v[124:127]
	s_add_i32 s24, 0, 0x1c000
	v_mfma_f32_16x16x32_bf16 v[120:123], v[162:165], v[170:173], v[120:123]
	s_add_i32 s3, s3, s29
	v_mfma_f32_16x16x32_bf16 v[116:119], v[154:157], v[178:181], v[116:119]
	v_add_u32_e32 v196, s24, v146
	v_mfma_f32_16x16x32_bf16 v[112:115], v[162:165], v[178:181], v[112:115]
	v_lshl_add_u64 v[194:195], v[194:195], 0, s[8:9]
	v_mfma_f32_16x16x32_bf16 v[100:103], v[154:157], v[186:189], v[100:103]
	v_mfma_f32_16x16x32_bf16 v[96:99], v[162:165], v[186:189], v[96:99]
	s_waitcnt lgkmcnt(0)
	v_mfma_f32_16x16x32_bf16 v[84:87], v[154:157], v[198:201], v[84:87]
	s_mov_b32 m0, s3
	v_mfma_f32_16x16x32_bf16 v[80:83], v[162:165], v[198:201], v[80:83]
	s_barrier
	s_setprio 0
	ds_read_b128 v[202:205], v196
	ds_read_b128 v[206:209], v196 offset:1024
	ds_read_b128 v[210:213], v196 offset:2048
	global_load_lds_dwordx4 v[194:195], off
	v_lshl_add_u64 v[194:195], v[218:219], 0, s[8:9]
	s_add_i32 m0, s3, 0x2000
	ds_read_b128 v[214:217], v196 offset:3072
	global_load_lds_dwordx4 v[194:195], off
	s_setprio 1
	s_barrier
	s_waitcnt lgkmcnt(3)
	v_mfma_f32_16x16x32_bf16 v[108:111], v[202:205], v[166:169], v[108:111]
	s_waitcnt lgkmcnt(1)
	v_mfma_f32_16x16x32_bf16 v[104:107], v[210:213], v[166:169], v[104:107]
	v_mfma_f32_16x16x32_bf16 v[92:95], v[202:205], v[174:177], v[92:95]
	v_mfma_f32_16x16x32_bf16 v[88:91], v[210:213], v[174:177], v[88:91]
	v_mfma_f32_16x16x32_bf16 v[76:79], v[202:205], v[182:185], v[76:79]
	v_mfma_f32_16x16x32_bf16 v[72:75], v[210:213], v[182:185], v[72:75]
	v_mfma_f32_16x16x32_bf16 v[68:71], v[202:205], v[190:193], v[68:71]
	v_mfma_f32_16x16x32_bf16 v[64:67], v[210:213], v[190:193], v[64:67]
	v_mfma_f32_16x16x32_bf16 v[108:111], v[206:209], v[170:173], v[108:111]
	s_mov_b32 m0, s39
	s_waitcnt lgkmcnt(0)
	v_mfma_f32_16x16x32_bf16 v[104:107], v[214:217], v[170:173], v[104:107]
	v_lshl_add_u64 v[194:195], v[220:221], 0, s[8:9]
	v_mfma_f32_16x16x32_bf16 v[92:95], v[206:209], v[178:181], v[92:95]
	v_mfma_f32_16x16x32_bf16 v[88:91], v[214:217], v[178:181], v[88:91]
	v_mfma_f32_16x16x32_bf16 v[76:79], v[206:209], v[186:189], v[76:79]
	v_mfma_f32_16x16x32_bf16 v[72:75], v[214:217], v[186:189], v[72:75]
	v_mfma_f32_16x16x32_bf16 v[68:71], v[206:209], v[198:201], v[68:71]
	v_mfma_f32_16x16x32_bf16 v[64:67], v[214:217], v[198:201], v[64:67]
	s_barrier
	s_setprio 0
	ds_read_b128 v[166:169], v148 offset:49152
	ds_read_b128 v[170:173], v148 offset:50176
	ds_read_b128 v[174:177], v148 offset:51200
	ds_read_b128 v[178:181], v148 offset:52224
	ds_read_b128 v[182:185], v148 offset:53248
	ds_read_b128 v[186:189], v148 offset:54272
	ds_read_b128 v[190:193], v148 offset:55296
	global_load_lds_dwordx4 v[194:195], off
	v_lshl_add_u64 v[194:195], v[222:223], 0, s[8:9]
	s_mov_b32 m0, s42
	ds_read_b128 v[198:201], v148 offset:56320
	global_load_lds_dwordx4 v[194:195], off
	s_waitcnt vmcnt(10)
	s_setprio 1
	s_barrier
; #define PG8_STAGE(bufoff, gbase, voff) do { _Pragma("unroll") for (int _i = 0; _i < 2; ++_i) \
;         __builtin_amdgcn_global_load_lds((const unsigned*)((const char*)(gbase) + (voff)[_i]), (LAS unsigned*)(lds + (bufoff) + ldsw + _i * 8192), 16, 0, 0); } while (0)
; #define PG8_MMA(ai, bj, At, Bt) do { __builtin_amdgcn_s_setprio(1); _Pragma("unroll") for (int m = 0; m < 4; ++m) _Pragma("unroll") for (int n = 0; n < 2; ++n) _Pragma("unroll") for (int k = 0; k < 2; ++k) \
;         acc[ai][bj][m][n] = __builtin_amdgcn_mfma_f32_16x16x32_bf16(Bt[n][k], At[m][k], acc[ai][bj][m][n], 0, 0, 0); __builtin_amdgcn_s_setprio(0); } while (0)
; #define PG8_WAIT_V(n) asm volatile("s_waitcnt vmcnt(" #n ")" ::: "memory")
; #define PG8_WAIT_L(n) asm volatile("s_waitcnt lgkmcnt(" #n ")" ::: "memory")
; #define PG8_BAR __builtin_amdgcn_s_barrier()
; #define PG8_SCHED __builtin_amdgcn_sched_barrier(0)
; template <class Map, class Epi>
; DI void gemm_phase(LAS unsigned char* lds, const Map& MP, const Epi& E, const int nM, const int nN, const int K, const int lda, const int ldb) {
;     ...
;             PG8_BAR; PG8_WAIT_L(0); PG8_MMA(1, 0, At, B0); PG8_BAR; PG8_SCHED;
;             PG8_STAGE(PG8_SB(1, 1), b3 + hstepB, voffB);
;             PG8_WAIT_V(6); PG8_BAR; PG8_MMA(1, 1, At, B1); PG8_BAR;
;         }
	s_waitcnt lgkmcnt(7)
	v_mfma_f32_16x16x32_bf16 v[60:63], v[150:153], v[166:169], v[60:63]
	v_mfma_f32_16x16x32_bf16 v[56:59], v[158:161], v[166:169], v[56:59]
	s_waitcnt lgkmcnt(5)
	v_mfma_f32_16x16x32_bf16 v[52:55], v[150:153], v[174:177], v[52:55]
	v_mfma_f32_16x16x32_bf16 v[48:51], v[158:161], v[174:177], v[48:51]
	s_waitcnt lgkmcnt(3)
	v_mfma_f32_16x16x32_bf16 v[36:39], v[150:153], v[182:185], v[36:39]
	v_mfma_f32_16x16x32_bf16 v[32:35], v[158:161], v[182:185], v[32:35]
	s_waitcnt lgkmcnt(1)
	v_mfma_f32_16x16x32_bf16 v[20:23], v[150:153], v[190:193], v[20:23]
	v_mfma_f32_16x16x32_bf16 v[16:19], v[158:161], v[190:193], v[16:19]
	v_mfma_f32_16x16x32_bf16 v[60:63], v[154:157], v[170:173], v[60:63]
	s_add_u32 s22, s22, 0x80080
	s_addc_u32 s23, s23, 0
	v_mfma_f32_16x16x32_bf16 v[56:59], v[162:165], v[170:173], v[56:59]
	s_add_i32 s3, s24, s29
	v_mfma_f32_16x16x32_bf16 v[52:55], v[154:157], v[178:181], v[52:55]
	v_mfma_f32_16x16x32_bf16 v[48:51], v[162:165], v[178:181], v[48:51]
	v_mfma_f32_16x16x32_bf16 v[36:39], v[154:157], v[186:189], v[36:39]
	v_mfma_f32_16x16x32_bf16 v[32:35], v[162:165], v[186:189], v[32:35]
	s_waitcnt lgkmcnt(0)
	v_mfma_f32_16x16x32_bf16 v[20:23], v[154:157], v[198:201], v[20:23]
	s_mov_b32 m0, s3
	v_mfma_f32_16x16x32_bf16 v[16:19], v[162:165], v[198:201], v[16:19]
	s_barrier
	s_setprio 0
	global_load_lds_dwordx4 v132, s[22:23]
	s_add_i32 m0, s3, 0x2000
	s_nop 0
	global_load_lds_dwordx4 v128, s[22:23]
	s_waitcnt vmcnt(6)
	s_setprio 1
	s_barrier
	v_mfma_f32_16x16x32_bf16 v[44:47], v[202:205], v[166:169], v[44:47]
	v_mfma_f32_16x16x32_bf16 v[40:43], v[210:213], v[166:169], v[40:43]
	ds_read_b128 v[150:153], v147
	v_mfma_f32_16x16x32_bf16 v[28:31], v[202:205], v[174:177], v[28:31]
	v_mfma_f32_16x16x32_bf16 v[24:27], v[210:213], v[174:177], v[24:27]
	ds_read_b128 v[154:157], v147 offset:1024
	v_mfma_f32_16x16x32_bf16 v[12:15], v[202:205], v[182:185], v[12:15]
	v_mfma_f32_16x16x32_bf16 v[8:11], v[210:213], v[182:185], v[8:11]
	ds_read_b128 v[158:161], v147 offset:2048
	v_mfma_f32_16x16x32_bf16 v[4:7], v[202:205], v[190:193], v[4:7]
	v_mfma_f32_16x16x32_bf16 v[0:3], v[210:213], v[190:193], v[0:3]
	ds_read_b128 v[162:165], v147 offset:3072
	v_mfma_f32_16x16x32_bf16 v[44:47], v[206:209], v[170:173], v[44:47]
	s_add_i32 s54, s54, 2
	v_mfma_f32_16x16x32_bf16 v[40:43], v[214:217], v[170:173], v[40:43]
	s_add_u32 s52, s52, 0x100
	s_addc_u32 s53, s53, 0
	v_mfma_f32_16x16x32_bf16 v[28:31], v[206:209], v[178:181], v[28:31]
	s_add_u32 s20, s20, 0x100
	s_addc_u32 s21, s21, 0
	v_mfma_f32_16x16x32_bf16 v[24:27], v[214:217], v[178:181], v[24:27]
	s_cmp_gt_u32 s54, 29
	v_mfma_f32_16x16x32_bf16 v[12:15], v[206:209], v[186:189], v[12:15]
	v_mfma_f32_16x16x32_bf16 v[8:11], v[214:217], v[186:189], v[8:11]
	v_mfma_f32_16x16x32_bf16 v[4:7], v[206:209], v[198:201], v[4:7]
	v_mfma_f32_16x16x32_bf16 v[0:3], v[214:217], v[198:201], v[0:3]
	s_barrier
	s_setprio 0
	s_cbranch_scc0 .LBB1_693
; DI unsigned pack2(float a, float b) { f32x2 v = {a, b}; hwbf16x2 r = __builtin_convertvector(v, hwbf16x2); return __builtin_bit_cast(unsigned, r); }
;     DI void operator()(const f32x4 (&acc)[2][2][4][2], const Unit& u, int wr, int wc, int fr, int fq) const {
;         bf16_t* O = O1; int ldc = ldc1, pn = u.pn; if (pn >= split) { O = O2; ldc = ldc2; pn -= split; }
;         const int row0 = u.pm * BM + wr * 64 + fr, col0 = pn * BM + wc * 32 + 8 * fq;
; #pragma unroll
;         for (int ai = 0; ai < 2; ++ai)
; #pragma unroll
;             for (int m = 0; m < 4; ++m) { bf16_t* rowp = O + (size_t)(row0 + ai * HALF + m * 16) * ldc + col0;
; #pragma unroll
;                 for (int bj = 0; bj < 2; ++bj) { const f32x4 v0 = acc[ai][bj][m][0], v1 = acc[ai][bj][m][1];
;                     u32x4 o; o[0] = pack2(v0[0], v0[1]); o[1] = pack2(v0[2], v0[3]); o[2] = pack2(v1[0], v1[1]); o[3] = pack2(v1[2], v1[3]);
;                     *(u32x4*)(rowp + bj * HALF) = o; } }
;     }
	s_waitcnt lgkmcnt(0)
	s_lshl_b32 s3, s10, 8
	v_mov_b32_e32 v150, v144
	v_mov_b32_e32 v151, v145
	s_add_i32 s3, s3, s37
	v_cvt_pk_bf16_f32 v68, v68, v69
	v_add_u32_e32 v154, s3, v150
	s_lshl_b32 s3, s47, 8
	s_or_b32 s3, s3, s38
	v_lshl_add_u32 v150, v151, 3, s3
	v_ashrrev_i32_e32 v151, 31, v150
	v_lshl_add_u64 v[150:151], v[150:151], 1, s[6:7]
	v_cvt_pk_bf16_f32 v69, v70, v71
	v_cvt_pk_bf16_f32 v70, v64, v65
	v_add_u32_e32 v64, 0x80, v154
	v_mad_i64_i32 v[152:153], s[20:21], v154, s46, v[150:151]
	v_cvt_pk_bf16_f32 v108, v108, v109
	v_cvt_pk_bf16_f32 v109, v110, v111
	v_cvt_pk_bf16_f32 v110, v104, v105
	v_cvt_pk_bf16_f32 v111, v106, v107
	v_add_u32_e32 v104, 16, v154
	v_mad_i64_i32 v[64:65], s[20:21], v64, s46, v[150:151]
	v_cvt_pk_bf16_f32 v44, v44, v45
	v_cvt_pk_bf16_f32 v45, v46, v47
	v_cvt_pk_bf16_f32 v46, v40, v41
	v_cvt_pk_bf16_f32 v47, v42, v43
	v_add_u32_e32 v40, 0x90, v154
	global_store_dwordx4 v[152:153], v[108:111], off offset:256
	v_cvt_pk_bf16_f32 v92, v92, v93
	v_cvt_pk_bf16_f32 v93, v94, v95
	v_mad_i64_i32 v[108:109], s[20:21], v104, s46, v[150:151]
	v_cvt_pk_bf16_f32 v94, v88, v89
	v_cvt_pk_bf16_f32 v95, v90, v91
	v_add_u32_e32 v88, 32, v154
	global_store_dwordx4 v[64:65], v[44:47], off offset:256
	v_cvt_pk_bf16_f32 v28, v28, v29
	v_cvt_pk_bf16_f32 v29, v30, v31
	v_mad_i64_i32 v[44:45], s[20:21], v40, s46, v[150:151]
	v_cvt_pk_bf16_f32 v30, v24, v25
	v_cvt_pk_bf16_f32 v31, v26, v27
	v_add_u32_e32 v24, 0xa0, v154
	global_store_dwordx4 v[108:109], v[92:95], off offset:256
	v_cvt_pk_bf16_f32 v76, v76, v77
	v_cvt_pk_bf16_f32 v77, v78, v79
	v_mad_i64_i32 v[92:93], s[20:21], v88, s46, v[150:151]
	v_cvt_pk_bf16_f32 v78, v72, v73
	v_cvt_pk_bf16_f32 v79, v74, v75
	v_add_u32_e32 v72, 48, v154
	global_store_dwordx4 v[44:45], v[28:31], off offset:256
	v_cvt_pk_bf16_f32 v12, v12, v13
	v_cvt_pk_bf16_f32 v13, v14, v15
	v_mad_i64_i32 v[28:29], s[20:21], v24, s46, v[150:151]
	v_cvt_pk_bf16_f32 v14, v8, v9
	v_cvt_pk_bf16_f32 v15, v10, v11
	v_add_u32_e32 v8, 0xb0, v154
	global_store_dwordx4 v[92:93], v[76:79], off offset:256
	global_store_dwordx4 v[28:29], v[12:15], off offset:256
	v_cvt_pk_bf16_f32 v124, v124, v125
	v_mad_i64_i32 v[76:77], s[20:21], v72, s46, v[150:151]
	v_mad_i64_i32 v[12:13], s[20:21], v8, s46, v[150:151]
	v_cvt_pk_bf16_f32 v125, v126, v127
	v_cvt_pk_bf16_f32 v126, v120, v121
	v_cvt_pk_bf16_f32 v127, v122, v123
	v_cvt_pk_bf16_f32 v104, v116, v117
	v_cvt_pk_bf16_f32 v105, v118, v119
	v_cvt_pk_bf16_f32 v106, v112, v113
	v_cvt_pk_bf16_f32 v107, v114, v115
	v_cvt_pk_bf16_f32 v88, v100, v101
	v_cvt_pk_bf16_f32 v89, v102, v103
	v_cvt_pk_bf16_f32 v90, v96, v97
	v_cvt_pk_bf16_f32 v91, v98, v99
	v_cvt_pk_bf16_f32 v72, v84, v85
	v_cvt_pk_bf16_f32 v73, v86, v87
	v_cvt_pk_bf16_f32 v74, v80, v81
	v_cvt_pk_bf16_f32 v75, v82, v83
	v_cvt_pk_bf16_f32 v71, v66, v67
	v_cvt_pk_bf16_f32 v60, v60, v61
	v_cvt_pk_bf16_f32 v61, v62, v63
	v_cvt_pk_bf16_f32 v62, v56, v57
	v_cvt_pk_bf16_f32 v63, v58, v59
	v_cvt_pk_bf16_f32 v40, v52, v53
	v_cvt_pk_bf16_f32 v41, v54, v55
	v_cvt_pk_bf16_f32 v42, v48, v49
	v_cvt_pk_bf16_f32 v43, v50, v51
	v_cvt_pk_bf16_f32 v24, v36, v37
	v_cvt_pk_bf16_f32 v25, v38, v39
	v_cvt_pk_bf16_f32 v26, v32, v33
	v_cvt_pk_bf16_f32 v27, v34, v35
	v_cvt_pk_bf16_f32 v8, v20, v21
	v_cvt_pk_bf16_f32 v9, v22, v23
	v_cvt_pk_bf16_f32 v10, v16, v17
	v_cvt_pk_bf16_f32 v11, v18, v19
	v_cvt_pk_bf16_f32 v4, v4, v5
	v_cvt_pk_bf16_f32 v5, v6, v7
	v_cvt_pk_bf16_f32 v6, v0, v1
	v_cvt_pk_bf16_f32 v7, v2, v3
	s_and_b64 vcc, exec, s[40:41]
	s_mov_b32 s47, s12
	s_mov_b32 s10, s14
	s_mov_b64 s[20:21], s[18:19]
	s_mov_b64 s[22:23], s[16:17]
	global_store_dwordx4 v[152:153], v[124:127], off
	global_store_dwordx4 v[108:109], v[104:107], off
	global_store_dwordx4 v[92:93], v[88:91], off
	global_store_dwordx4 v[76:77], v[72:75], off
	global_store_dwordx4 v[76:77], v[68:71], off offset:256
	global_store_dwordx4 v[64:65], v[60:63], off
	global_store_dwordx4 v[44:45], v[40:43], off
	global_store_dwordx4 v[28:29], v[24:27], off
	global_store_dwordx4 v[12:13], v[8:11], off
	global_store_dwordx4 v[12:13], v[4:7], off offset:256
	s_cbranch_vccz .LBB1_690
	s_waitcnt vmcnt(0)
	s_cmpk_gt_u32 s4, 0xff
	s_cbranch_scc1 .LBB1_697
	s_barrier

;     DI const char* a(const Unit& u) const { return (const char*)(A + (size_t)u.pm * BM * lda); }
;     DI const char* a(const Unit& u) const { return (const char*)(A + (size_t)u.pm * BM * 2048 + (u.pn >> 1) * 512); }
;     DI const char* a(const Unit& u) const { return (const char*)((u.pn < 12 ? A1 : A2) + (size_t)u.pm * BM * 512); }
; #define PG8_STAGE(bufoff, gbase, voff) do { _Pragma("unroll") for (int _i = 0; _i < 2; ++_i) \
;         __builtin_amdgcn_global_load_lds((const unsigned*)((const char*)(gbase) + (voff)[_i]), (LAS unsigned*)(lds + (bufoff) + ldsw + _i * 8192), 16, 0, 0); } while (0)
; #define PG8_LDA(dst, b, h) do { _Pragma("unroll") for (int m = 0; m < 4; ++m) _Pragma("unroll") for (int k = 0; k < 2; ++k) dst[m][k] = *(const LAS bf16x8*)(lds + PG8_SA(b, h) + aoff + m * 2048 + k * 1024); } while (0)
; #define PG8_LDB(dst, b, h) do { _Pragma("unroll") for (int n = 0; n < 2; ++n) _Pragma("unroll") for (int k = 0; k < 2; ++k) dst[n][k] = *(const LAS bf16x8*)(lds + PG8_SB(b, h) + boff + n * 2048 + k * 1024); } while (0)
; template <class Map, class Epi>
; DI void gemm_phase(LAS unsigned char* lds, const Map& MP, const Epi& E, const int nM, const int nN, const int K, const int lda, const int ldb) {
;     ...
;     for (;;) {
;         const bool has_next = sched_next(ui + 1, nM, nN, G, cblk, nxt);
;         const char* nA = has_next ? MP.a(nxt) : cA; const char* nB = has_next ? MP.b(nxt) : cB;
;         for (int t = 0; t < nt; t += 2) {
;             const bool last = (t == nt - 2);
;             const char* a1 = cA + (size_t)(t + 1) * kstep;
;             const char* a2 = last ? nA : cA + (size_t)(t + 2) * kstep; const char* b2 = last ? nB : cB + (size_t)(t + 2) * kstep;
;             const char* a3 = a2 + kstep; const char* b3 = b2 + kstep;
;             PG8_LDB(B0, 0, 0); PG8_SCHED; PG8_LDA(At, 0, 0); PG8_STAGE(PG8_SA(1, 1), a1 + hstepA, voffA);
;             PG8_WAIT_L(8); PG8_BAR; PG8_WAIT_L(0); PG8_MMA(0, 0, At, B0); PG8_BAR; PG8_SCHED;
;             PG8_LDB(B1, 0, 1); PG8_STAGE(PG8_SB(0, 0), b2, voffB);
;             PG8_BAR; PG8_WAIT_L(0); PG8_MMA(0, 1, At, B1); PG8_BAR;
;             PG8_LDA(At, 0, 1); PG8_STAGE(PG8_SA(0, 0), a2, voffA);
;             PG8_BAR; PG8_WAIT_L(0); PG8_MMA(1, 0, At, B0); PG8_BAR; PG8_SCHED;
;             PG8_STAGE(PG8_SB(0, 1), b2 + hstepB, voffB);
;             PG8_WAIT_V(6); PG8_BAR; PG8_MMA(1, 1, At, B1); PG8_BAR;
.LBB1_925:
	s_add_u32 s3, s10, 0xfff80080
	s_addc_u32 s12, s11, -1
	s_cmp_eq_u32 s48, 28
	s_cselect_b32 s15, s4, s12
	s_cselect_b32 s14, s5, s3
	s_cselect_b32 s13, s37, s47
	s_cselect_b32 s12, s38, s39
	s_add_i32 m0, s24, 0xc000
	ds_read_b128 v[168:171], v150
	ds_read_b128 v[172:175], v150 offset:1024
	ds_read_b128 v[176:179], v150 offset:2048
	ds_read_b128 v[180:183], v150 offset:3072
	ds_read_b128 v[184:187], v150 offset:4096
	ds_read_b128 v[188:191], v150 offset:5120
	ds_read_b128 v[192:195], v150 offset:6144
	ds_read_b128 v[198:201], v150 offset:7168
	global_load_lds_dwordx4 v138, s[10:11]
	s_add_i32 m0, s24, 0xe000
	s_nop 0
	global_load_lds_dwordx4 v136, s[10:11]
	s_waitcnt lgkmcnt(8)
	s_setprio 1
	s_barrier
	s_waitcnt lgkmcnt(7)
	v_mfma_f32_16x16x32_bf16 v[124:127], v[152:155], v[168:171], v[124:127]
	v_mfma_f32_16x16x32_bf16 v[120:123], v[160:163], v[168:171], v[120:123]
	s_waitcnt lgkmcnt(5)
	v_mfma_f32_16x16x32_bf16 v[108:111], v[152:155], v[176:179], v[108:111]
	v_mfma_f32_16x16x32_bf16 v[104:107], v[160:163], v[176:179], v[104:107]
	s_waitcnt lgkmcnt(3)
	v_mfma_f32_16x16x32_bf16 v[92:95], v[152:155], v[184:187], v[92:95]
	v_mfma_f32_16x16x32_bf16 v[88:91], v[160:163], v[184:187], v[88:91]
	s_waitcnt lgkmcnt(1)
	v_mfma_f32_16x16x32_bf16 v[76:79], v[152:155], v[192:195], v[76:79]
	v_mfma_f32_16x16x32_bf16 v[72:75], v[160:163], v[192:195], v[72:75]
	v_mfma_f32_16x16x32_bf16 v[124:127], v[156:159], v[172:175], v[124:127]
	s_add_i32 s3, s35, s22
	v_mfma_f32_16x16x32_bf16 v[120:123], v[164:167], v[172:175], v[120:123]
	v_lshl_add_u64 v[144:145], s[12:13], 0, v[132:133]
	v_mfma_f32_16x16x32_bf16 v[108:111], v[156:159], v[180:183], v[108:111]
	v_lshl_add_u64 v[218:219], s[12:13], 0, v[128:129]
	v_mfma_f32_16x16x32_bf16 v[104:107], v[164:167], v[180:183], v[104:107]
	v_mfma_f32_16x16x32_bf16 v[92:95], v[156:159], v[188:191], v[92:95]
	v_mfma_f32_16x16x32_bf16 v[88:91], v[164:167], v[188:191], v[88:91]
	s_waitcnt lgkmcnt(0)
	v_mfma_f32_16x16x32_bf16 v[76:79], v[156:159], v[198:201], v[76:79]
	s_mov_b32 m0, s3
	v_mfma_f32_16x16x32_bf16 v[72:75], v[164:167], v[198:201], v[72:75]
	s_barrier
	s_setprio 0
	ds_read_b128 v[202:205], v151
	ds_read_b128 v[206:209], v151 offset:1024
	ds_read_b128 v[210:213], v151 offset:2048
	global_load_lds_dwordx4 v[144:145], off
	s_add_i32 m0, s3, 0x2000
	ds_read_b128 v[214:217], v151 offset:3072
	global_load_lds_dwordx4 v[218:219], off
	s_setprio 1
	s_barrier
	s_waitcnt lgkmcnt(3)
	v_mfma_f32_16x16x32_bf16 v[116:119], v[202:205], v[168:171], v[116:119]
	s_waitcnt lgkmcnt(1)
	v_mfma_f32_16x16x32_bf16 v[112:115], v[210:213], v[168:171], v[112:115]
	v_mfma_f32_16x16x32_bf16 v[100:103], v[202:205], v[176:179], v[100:103]
	v_mfma_f32_16x16x32_bf16 v[96:99], v[210:213], v[176:179], v[96:99]
	v_mfma_f32_16x16x32_bf16 v[84:87], v[202:205], v[184:187], v[84:87]
	v_mfma_f32_16x16x32_bf16 v[80:83], v[210:213], v[184:187], v[80:83]
	v_mfma_f32_16x16x32_bf16 v[68:71], v[202:205], v[192:195], v[68:71]
	v_mfma_f32_16x16x32_bf16 v[64:67], v[210:213], v[192:195], v[64:67]
	v_mfma_f32_16x16x32_bf16 v[116:119], v[206:209], v[172:175], v[116:119]
	v_lshl_add_u64 v[222:223], s[14:15], 0, v[130:131]
	s_mov_b32 m0, s24
	s_waitcnt lgkmcnt(0)
	v_mfma_f32_16x16x32_bf16 v[112:115], v[214:217], v[172:175], v[112:115]
	v_lshl_add_u64 v[220:221], s[14:15], 0, v[134:135]
	v_mfma_f32_16x16x32_bf16 v[100:103], v[206:209], v[180:183], v[100:103]
	v_mfma_f32_16x16x32_bf16 v[96:99], v[214:217], v[180:183], v[96:99]
	v_mfma_f32_16x16x32_bf16 v[84:87], v[206:209], v[188:191], v[84:87]
	v_mfma_f32_16x16x32_bf16 v[80:83], v[214:217], v[188:191], v[80:83]
	v_mfma_f32_16x16x32_bf16 v[68:71], v[206:209], v[198:201], v[68:71]
	v_mfma_f32_16x16x32_bf16 v[64:67], v[214:217], v[198:201], v[64:67]
	s_barrier
	s_setprio 0
	ds_read_b128 v[168:171], v150 offset:16384
	ds_read_b128 v[172:175], v150 offset:17408
	ds_read_b128 v[176:179], v150 offset:18432
	ds_read_b128 v[180:183], v150 offset:19456
	ds_read_b128 v[184:187], v150 offset:20480
	ds_read_b128 v[188:191], v150 offset:21504
	ds_read_b128 v[192:195], v150 offset:22528
	global_load_lds_dwordx4 v[220:221], off
	s_mov_b32 m0, s9
	ds_read_b128 v[198:201], v150 offset:23552
	global_load_lds_dwordx4 v[222:223], off
	s_waitcnt vmcnt(10)
	s_setprio 1
	s_barrier
	s_waitcnt lgkmcnt(7)
	v_mfma_f32_16x16x32_bf16 v[60:63], v[152:155], v[168:171], v[60:63]
	v_mfma_f32_16x16x32_bf16 v[56:59], v[160:163], v[168:171], v[56:59]
	s_waitcnt lgkmcnt(5)
	v_mfma_f32_16x16x32_bf16 v[44:47], v[152:155], v[176:179], v[44:47]
	v_mfma_f32_16x16x32_bf16 v[40:43], v[160:163], v[176:179], v[40:43]
	s_waitcnt lgkmcnt(3)
	v_mfma_f32_16x16x32_bf16 v[28:31], v[152:155], v[184:187], v[28:31]
	v_mfma_f32_16x16x32_bf16 v[24:27], v[160:163], v[184:187], v[24:27]
	s_waitcnt lgkmcnt(1)
	v_mfma_f32_16x16x32_bf16 v[12:15], v[152:155], v[192:195], v[12:15]
	v_mfma_f32_16x16x32_bf16 v[8:11], v[160:163], v[192:195], v[8:11]
	v_mfma_f32_16x16x32_bf16 v[60:63], v[156:159], v[172:175], v[60:63]
	s_add_u32 s56, s12, 0x80000
	s_addc_u32 s57, s13, 0
	v_mfma_f32_16x16x32_bf16 v[56:59], v[164:167], v[172:175], v[56:59]
	s_add_i32 s3, s36, s22
	v_mfma_f32_16x16x32_bf16 v[44:47], v[156:159], v[180:183], v[44:47]
	v_mfma_f32_16x16x32_bf16 v[40:43], v[164:167], v[180:183], v[40:43]
	v_mfma_f32_16x16x32_bf16 v[28:31], v[156:159], v[188:191], v[28:31]
	v_mfma_f32_16x16x32_bf16 v[24:27], v[164:167], v[188:191], v[24:27]
	s_waitcnt lgkmcnt(0)
	v_mfma_f32_16x16x32_bf16 v[12:15], v[156:159], v[198:201], v[12:15]
	s_mov_b32 m0, s3
	v_mfma_f32_16x16x32_bf16 v[8:11], v[164:167], v[198:201], v[8:11]
	s_barrier
; #define PG8_STAGE(bufoff, gbase, voff) do { _Pragma("unroll") for (int _i = 0; _i < 2; ++_i) \
;         __builtin_amdgcn_global_load_lds((const unsigned*)((const char*)(gbase) + (voff)[_i]), (LAS unsigned*)(lds + (bufoff) + ldsw + _i * 8192), 16, 0, 0); } while (0)
; #define PG8_LDA(dst, b, h) do { _Pragma("unroll") for (int m = 0; m < 4; ++m) _Pragma("unroll") for (int k = 0; k < 2; ++k) dst[m][k] = *(const LAS bf16x8*)(lds + PG8_SA(b, h) + aoff + m * 2048 + k * 1024); } while (0)
; #define PG8_LDB(dst, b, h) do { _Pragma("unroll") for (int n = 0; n < 2; ++n) _Pragma("unroll") for (int k = 0; k < 2; ++k) dst[n][k] = *(const LAS bf16x8*)(lds + PG8_SB(b, h) + boff + n * 2048 + k * 1024); } while (0)
; #define PG8_MMA(ai, bj, At, Bt) do { __builtin_amdgcn_s_setprio(1); _Pragma("unroll") for (int m = 0; m < 4; ++m) _Pragma("unroll") for (int n = 0; n < 2; ++n) _Pragma("unroll") for (int k = 0; k < 2; ++k) \
;         acc[ai][bj][m][n] = __builtin_amdgcn_mfma_f32_16x16x32_bf16(Bt[n][k], At[m][k], acc[ai][bj][m][n], 0, 0, 0); __builtin_amdgcn_s_setprio(0); } while (0)
; #define PG8_WAIT_V(n) asm volatile("s_waitcnt vmcnt(" #n ")" ::: "memory")
; #define PG8_WAIT_L(n) asm volatile("s_waitcnt lgkmcnt(" #n ")" ::: "memory")
; #define PG8_BAR __builtin_amdgcn_s_barrier()
; #define PG8_SCHED __builtin_amdgcn_sched_barrier(0)
; template <class Map, class Epi>
; DI void gemm_phase(LAS unsigned char* lds, const Map& MP, const Epi& E, const int nM, const int nN, const int K, const int lda, const int ldb) {
;     ...
;             PG8_BAR; PG8_WAIT_L(0); PG8_MMA(1, 0, At, B0); PG8_BAR; PG8_SCHED;
;             PG8_STAGE(PG8_SB(0, 1), b2 + hstepB, voffB);
;             PG8_WAIT_V(6); PG8_BAR; PG8_MMA(1, 1, At, B1); PG8_BAR;
;             PG8_LDB(B0, 1, 0); PG8_SCHED; PG8_LDA(At, 1, 0); PG8_STAGE(PG8_SA(0, 1), a2 + hstepA, voffA);
;             PG8_WAIT_L(8); PG8_BAR; PG8_WAIT_L(0); PG8_MMA(0, 0, At, B0); PG8_BAR; PG8_SCHED;
;             PG8_LDB(B1, 1, 1); PG8_STAGE(PG8_SB(1, 0), b3, voffB);
;             PG8_BAR; PG8_WAIT_L(0); PG8_MMA(0, 1, At, B1); PG8_BAR;
;             PG8_LDA(At, 1, 1); PG8_STAGE(PG8_SA(1, 0), a3, voffA);
;             PG8_BAR; PG8_WAIT_L(0); PG8_MMA(1, 0, At, B0); PG8_BAR; PG8_SCHED;
;             PG8_STAGE(PG8_SB(1, 1), b3 + hstepB, voffB);
;             PG8_WAIT_V(6); PG8_BAR; PG8_MMA(1, 1, At, B1); PG8_BAR;
	s_setprio 0
	global_load_lds_dwordx4 v132, s[56:57]
	s_add_i32 m0, s3, 0x2000
	s_nop 0
	global_load_lds_dwordx4 v128, s[56:57]
	s_waitcnt vmcnt(6)
	s_setprio 1
	s_barrier
	v_mfma_f32_16x16x32_bf16 v[52:55], v[202:205], v[168:171], v[52:55]
	v_mfma_f32_16x16x32_bf16 v[48:51], v[210:213], v[168:171], v[48:51]
	s_add_i32 s3, 0, 0x18000
	v_add_u32_e32 v164, s3, v148
	ds_read_b128 v[152:155], v164
	v_mfma_f32_16x16x32_bf16 v[36:39], v[202:205], v[176:179], v[36:39]
	v_mfma_f32_16x16x32_bf16 v[32:35], v[210:213], v[176:179], v[32:35]
	ds_read_b128 v[156:159], v164 offset:1024
	v_mfma_f32_16x16x32_bf16 v[20:23], v[202:205], v[184:187], v[20:23]
	v_mfma_f32_16x16x32_bf16 v[16:19], v[210:213], v[184:187], v[16:19]
	ds_read_b128 v[160:163], v164 offset:2048
	v_mfma_f32_16x16x32_bf16 v[4:7], v[202:205], v[192:195], v[4:7]
	v_mfma_f32_16x16x32_bf16 v[0:3], v[210:213], v[192:195], v[0:3]
	ds_read_b128 v[164:167], v164 offset:3072
	v_mfma_f32_16x16x32_bf16 v[52:55], v[206:209], v[172:175], v[52:55]
	s_add_u32 s14, s14, 0x80000
	s_addc_u32 s15, s15, 0
	v_mfma_f32_16x16x32_bf16 v[48:51], v[214:217], v[172:175], v[48:51]
	v_mfma_f32_16x16x32_bf16 v[36:39], v[206:209], v[180:183], v[36:39]
	v_mfma_f32_16x16x32_bf16 v[32:35], v[214:217], v[180:183], v[32:35]
	v_mfma_f32_16x16x32_bf16 v[20:23], v[206:209], v[188:191], v[20:23]
	v_mfma_f32_16x16x32_bf16 v[16:19], v[214:217], v[188:191], v[16:19]
	v_mfma_f32_16x16x32_bf16 v[4:7], v[206:209], v[198:201], v[4:7]
	s_mov_b32 m0, s25
	v_mfma_f32_16x16x32_bf16 v[0:3], v[214:217], v[198:201], v[0:3]
	s_barrier
	s_setprio 0
	ds_read_b128 v[168:171], v150 offset:32768
	ds_read_b128 v[172:175], v150 offset:33792
	ds_read_b128 v[176:179], v150 offset:34816
	ds_read_b128 v[180:183], v150 offset:35840
	ds_read_b128 v[184:187], v150 offset:36864
	ds_read_b128 v[188:191], v150 offset:37888
	ds_read_b128 v[192:195], v150 offset:38912
	global_load_lds_dwordx4 v134, s[14:15]
	s_mov_b32 m0, s26
	ds_read_b128 v[198:201], v150 offset:39936
	global_load_lds_dwordx4 v130, s[14:15]
	s_waitcnt lgkmcnt(8)
	s_setprio 1
	s_barrier
	s_waitcnt lgkmcnt(7)
	v_mfma_f32_16x16x32_bf16 v[124:127], v[152:155], v[168:171], v[124:127]
	v_mfma_f32_16x16x32_bf16 v[120:123], v[160:163], v[168:171], v[120:123]
	s_waitcnt lgkmcnt(5)
	v_mfma_f32_16x16x32_bf16 v[108:111], v[152:155], v[176:179], v[108:111]
	v_mfma_f32_16x16x32_bf16 v[104:107], v[160:163], v[176:179], v[104:107]
	s_waitcnt lgkmcnt(3)
	v_mfma_f32_16x16x32_bf16 v[92:95], v[152:155], v[184:187], v[92:95]
	v_mfma_f32_16x16x32_bf16 v[88:91], v[160:163], v[184:187], v[88:91]
	s_waitcnt lgkmcnt(1)
	v_mfma_f32_16x16x32_bf16 v[76:79], v[152:155], v[192:195], v[76:79]
	v_mfma_f32_16x16x32_bf16 v[72:75], v[160:163], v[192:195], v[72:75]
	v_mfma_f32_16x16x32_bf16 v[124:127], v[156:159], v[172:175], v[124:127]
	s_add_i32 s14, 0, 0x1c000
	v_mfma_f32_16x16x32_bf16 v[120:123], v[164:167], v[172:175], v[120:123]
	s_add_i32 s3, s3, s22
	v_mfma_f32_16x16x32_bf16 v[108:111], v[156:159], v[180:183], v[108:111]
	v_add_u32_e32 v196, s14, v148
	v_mfma_f32_16x16x32_bf16 v[104:107], v[164:167], v[180:183], v[104:107]
	v_lshl_add_u64 v[144:145], v[144:145], 0, s[44:45]
	v_mfma_f32_16x16x32_bf16 v[92:95], v[156:159], v[188:191], v[92:95]
	v_mfma_f32_16x16x32_bf16 v[88:91], v[164:167], v[188:191], v[88:91]
	s_waitcnt lgkmcnt(0)
	v_mfma_f32_16x16x32_bf16 v[76:79], v[156:159], v[198:201], v[76:79]
	s_mov_b32 m0, s3
	v_mfma_f32_16x16x32_bf16 v[72:75], v[164:167], v[198:201], v[72:75]
	s_barrier
	s_setprio 0
	ds_read_b128 v[202:205], v196
	ds_read_b128 v[206:209], v196 offset:1024
	ds_read_b128 v[210:213], v196 offset:2048
	global_load_lds_dwordx4 v[144:145], off
	v_lshl_add_u64 v[144:145], v[218:219], 0, s[44:45]
	s_add_i32 m0, s3, 0x2000
	ds_read_b128 v[214:217], v196 offset:3072
	global_load_lds_dwordx4 v[144:145], off
	s_setprio 1
	s_barrier
	s_waitcnt lgkmcnt(3)
	v_mfma_f32_16x16x32_bf16 v[116:119], v[202:205], v[168:171], v[116:119]
	s_waitcnt lgkmcnt(1)
	v_mfma_f32_16x16x32_bf16 v[112:115], v[210:213], v[168:171], v[112:115]
	v_mfma_f32_16x16x32_bf16 v[100:103], v[202:205], v[176:179], v[100:103]
	v_mfma_f32_16x16x32_bf16 v[96:99], v[210:213], v[176:179], v[96:99]
	v_mfma_f32_16x16x32_bf16 v[84:87], v[202:205], v[184:187], v[84:87]
	v_mfma_f32_16x16x32_bf16 v[80:83], v[210:213], v[184:187], v[80:83]
	v_mfma_f32_16x16x32_bf16 v[68:71], v[202:205], v[192:195], v[68:71]
	v_mfma_f32_16x16x32_bf16 v[64:67], v[210:213], v[192:195], v[64:67]
	v_mfma_f32_16x16x32_bf16 v[116:119], v[206:209], v[172:175], v[116:119]
	s_mov_b32 m0, s30
	s_waitcnt lgkmcnt(0)
	v_mfma_f32_16x16x32_bf16 v[112:115], v[214:217], v[172:175], v[112:115]
	v_lshl_add_u64 v[144:145], v[220:221], 0, s[44:45]
	v_mfma_f32_16x16x32_bf16 v[100:103], v[206:209], v[180:183], v[100:103]
	v_mfma_f32_16x16x32_bf16 v[96:99], v[214:217], v[180:183], v[96:99]
	v_mfma_f32_16x16x32_bf16 v[84:87], v[206:209], v[188:191], v[84:87]
	v_mfma_f32_16x16x32_bf16 v[80:83], v[214:217], v[188:191], v[80:83]
	v_mfma_f32_16x16x32_bf16 v[68:71], v[206:209], v[198:201], v[68:71]
	v_mfma_f32_16x16x32_bf16 v[64:67], v[214:217], v[198:201], v[64:67]
	s_barrier
	s_setprio 0
	ds_read_b128 v[168:171], v150 offset:49152
	ds_read_b128 v[172:175], v150 offset:50176
	ds_read_b128 v[176:179], v150 offset:51200
	ds_read_b128 v[180:183], v150 offset:52224
	ds_read_b128 v[184:187], v150 offset:53248
	ds_read_b128 v[188:191], v150 offset:54272
	ds_read_b128 v[192:195], v150 offset:55296
	global_load_lds_dwordx4 v[144:145], off
	v_lshl_add_u64 v[144:145], v[222:223], 0, s[44:45]
	s_mov_b32 m0, s31
	ds_read_b128 v[198:201], v150 offset:56320
	global_load_lds_dwordx4 v[144:145], off
	s_waitcnt vmcnt(10)
	s_setprio 1
	s_barrier
; DI unsigned pack2(float a, float b) { f32x2 v = {a, b}; hwbf16x2 r = __builtin_convertvector(v, hwbf16x2); return __builtin_bit_cast(unsigned, r); }
; DI float bflo(unsigned w) { return __uint_as_float(w << 16); }
; DI float bfhi(unsigned w) { return __uint_as_float(w & 0xffff0000u); }
; #define PG8_WAIT_V(n) asm volatile("s_waitcnt vmcnt(" #n ")" ::: "memory")
;     DI void operator()(const f32x4 (&acc)[2][2][4][2], const Unit& u, int wr, int wc, int fr, int fq) const {
;         const int row0 = u.pm * BM + wr * 64 + fr, col0 = u.pn * BM + wc * 32 + 8 * fq;
;         f32x4 sc[2][2];
; #pragma unroll
;         for (int bj = 0; bj < 2; ++bj)
; #pragma unroll
;             for (int n = 0; n < 2; ++n) sc[bj][n] = scale ? *(const f32x4*)(scale + col0 + bj * HALF + 4 * n) : (f32x4){1.f, 1.f, 1.f, 1.f};
; #pragma unroll
;         for (int ai = 0; ai < 2; ++ai)
; #pragma unroll
;             for (int m = 0; m < 4; ++m) { const size_t ro = (size_t)(row0 + ai * HALF + m * 16) * D + col0;
; #pragma unroll
;                 for (int bj = 0; bj < 2; ++bj) {
;                     f32x4 x0, x1;
;                     if constexpr (IB) { const u32x4 w = *(const u32x4*)((const bf16_t*)Xin + ro + bj * HALF);
;                         x0 = (f32x4){bflo(w[0]), bfhi(w[0]), bflo(w[1]), bfhi(w[1])}; x1 = (f32x4){bflo(w[2]), bfhi(w[2]), bflo(w[3]), bfhi(w[3])}; }
;                     else { x0 = *(const f32x4*)((const float*)Xin + ro + bj * HALF); x1 = *(const f32x4*)((const float*)Xin + ro + bj * HALF + 4); }
;                     x0 += acc[ai][bj][m][0] * sc[bj][0]; x1 += acc[ai][bj][m][1] * sc[bj][1];
;                     if constexpr (OB) { u32x4 o; o[0] = pack2(x0[0], x0[1]); o[1] = pack2(x0[2], x0[3]); o[2] = pack2(x1[0], x1[1]); o[3] = pack2(x1[2], x1[3]);
;                         *(u32x4*)((bf16_t*)Xout + ro + bj * HALF) = o; }
;                     else { *(f32x4*)((float*)Xout + ro + bj * HALF) = x0; *(f32x4*)((float*)Xout + ro + bj * HALF + 4) = x1; } } }
; template <class Map, class Epi>
; DI void gemm_phase(LAS unsigned char* lds, const Map& MP, const Epi& E, const int nM, const int nN, const int K, const int lda, const int ldb) {
;     ...
;             PG8_BAR; PG8_WAIT_L(0); PG8_MMA(1, 0, At, B0); PG8_BAR; PG8_SCHED;
;             PG8_STAGE(PG8_SB(1, 1), b3 + hstepB, voffB);
;             PG8_WAIT_V(6); PG8_BAR; PG8_MMA(1, 1, At, B1); PG8_BAR;
;         }
	s_waitcnt lgkmcnt(7)
	v_mfma_f32_16x16x32_bf16 v[60:63], v[152:155], v[168:171], v[60:63]
	v_mfma_f32_16x16x32_bf16 v[56:59], v[160:163], v[168:171], v[56:59]
	s_waitcnt lgkmcnt(5)
	v_mfma_f32_16x16x32_bf16 v[44:47], v[152:155], v[176:179], v[44:47]
	v_mfma_f32_16x16x32_bf16 v[40:43], v[160:163], v[176:179], v[40:43]
	s_waitcnt lgkmcnt(3)
	v_mfma_f32_16x16x32_bf16 v[28:31], v[152:155], v[184:187], v[28:31]
	v_mfma_f32_16x16x32_bf16 v[24:27], v[160:163], v[184:187], v[24:27]
	s_waitcnt lgkmcnt(1)
	v_mfma_f32_16x16x32_bf16 v[12:15], v[152:155], v[192:195], v[12:15]
	v_mfma_f32_16x16x32_bf16 v[8:11], v[160:163], v[192:195], v[8:11]
	v_mfma_f32_16x16x32_bf16 v[60:63], v[156:159], v[172:175], v[60:63]
	s_add_u32 s12, s12, 0x80080
	s_addc_u32 s13, s13, 0
	v_mfma_f32_16x16x32_bf16 v[56:59], v[164:167], v[172:175], v[56:59]
	s_add_i32 s3, s14, s22
	v_mfma_f32_16x16x32_bf16 v[44:47], v[156:159], v[180:183], v[44:47]
	v_mfma_f32_16x16x32_bf16 v[40:43], v[164:167], v[180:183], v[40:43]
	v_mfma_f32_16x16x32_bf16 v[28:31], v[156:159], v[188:191], v[28:31]
	v_mfma_f32_16x16x32_bf16 v[24:27], v[164:167], v[188:191], v[24:27]
	s_waitcnt lgkmcnt(0)
	v_mfma_f32_16x16x32_bf16 v[12:15], v[156:159], v[198:201], v[12:15]
	s_mov_b32 m0, s3
	v_mfma_f32_16x16x32_bf16 v[8:11], v[164:167], v[198:201], v[8:11]
	s_barrier
	s_setprio 0
	global_load_lds_dwordx4 v132, s[12:13]
	s_add_i32 m0, s3, 0x2000
	s_nop 0
	global_load_lds_dwordx4 v128, s[12:13]
	s_waitcnt vmcnt(6)
	s_setprio 1
	s_barrier
	v_mfma_f32_16x16x32_bf16 v[52:55], v[202:205], v[168:171], v[52:55]
	v_mfma_f32_16x16x32_bf16 v[48:51], v[210:213], v[168:171], v[48:51]
	ds_read_b128 v[152:155], v149
	v_mfma_f32_16x16x32_bf16 v[36:39], v[202:205], v[176:179], v[36:39]
	v_mfma_f32_16x16x32_bf16 v[32:35], v[210:213], v[176:179], v[32:35]
	ds_read_b128 v[156:159], v149 offset:1024
	v_mfma_f32_16x16x32_bf16 v[20:23], v[202:205], v[184:187], v[20:23]
	v_mfma_f32_16x16x32_bf16 v[16:19], v[210:213], v[184:187], v[16:19]
	ds_read_b128 v[160:163], v149 offset:2048
	v_mfma_f32_16x16x32_bf16 v[4:7], v[202:205], v[192:195], v[4:7]
	v_mfma_f32_16x16x32_bf16 v[0:3], v[210:213], v[192:195], v[0:3]
	ds_read_b128 v[164:167], v149 offset:3072
	v_mfma_f32_16x16x32_bf16 v[52:55], v[206:209], v[172:175], v[52:55]
	s_add_i32 s48, s48, 2
	v_mfma_f32_16x16x32_bf16 v[48:51], v[214:217], v[172:175], v[48:51]
	s_add_u32 s39, s39, 0x100
	s_addc_u32 s47, s47, 0
	v_mfma_f32_16x16x32_bf16 v[36:39], v[206:209], v[180:183], v[36:39]
	s_add_u32 s10, s10, 0x100
	s_addc_u32 s11, s11, 0
	v_mfma_f32_16x16x32_bf16 v[32:35], v[214:217], v[180:183], v[32:35]
	s_cmp_gt_u32 s48, 29
	v_mfma_f32_16x16x32_bf16 v[20:23], v[206:209], v[188:191], v[20:23]
	v_mfma_f32_16x16x32_bf16 v[16:19], v[214:217], v[188:191], v[16:19]
	v_mfma_f32_16x16x32_bf16 v[4:7], v[206:209], v[198:201], v[4:7]
	v_mfma_f32_16x16x32_bf16 v[0:3], v[214:217], v[198:201], v[0:3]
	s_barrier
	s_setprio 0
	s_cbranch_scc0 .LBB1_925
	s_waitcnt lgkmcnt(0)
	v_mov_b32_e32 v152, v147
	v_mov_b32_e32 v144, v146
	s_lshl_b32 s2, s2, 8
	s_or_b32 s2, s2, s29
	v_lshl_add_u32 v144, v144, 3, s2
	s_lshl_b32 s2, s8, 8
	s_add_i32 s2, s2, s28
	v_add_u32_e32 v152, s2, v152
	v_ashrrev_i32_e32 v153, 31, v152
	v_lshlrev_b64 v[152:153], 12, v[152:153]
	v_ashrrev_i32_e32 v145, 31, v144
	v_lshl_add_u64 v[152:153], s[42:43], 0, v[152:153]
	v_lshl_add_u64 v[144:145], v[144:145], 1, v[152:153]
	global_load_dwordx4 v[160:163], v[144:145], off
	global_load_dwordx4 v[164:167], v[144:145], off offset:256
	s_mov_b64 s[98:99], 0x10000
	v_lshl_add_u64 v[154:155], v[144:145], 0, s[98:99]
	global_load_dwordx4 v[168:171], v[154:155], off
	global_load_dwordx4 v[172:175], v[154:155], off offset:256
	s_mov_b64 s[98:99], 0x20000
	v_lshl_add_u64 v[154:155], v[144:145], 0, s[98:99]
	global_load_dwordx4 v[176:179], v[154:155], off
	global_load_dwordx4 v[180:183], v[154:155], off offset:256
	s_mov_b64 s[98:99], 0x30000
	v_lshl_add_u64 v[154:155], v[144:145], 0, s[98:99]
	global_load_dwordx4 v[184:187], v[154:155], off
	global_load_dwordx4 v[188:191], v[154:155], off offset:256
	s_mov_b64 s[98:99], 0x80000
	v_lshl_add_u64 v[154:155], v[144:145], 0, s[98:99]
	global_load_dwordx4 v[192:195], v[154:155], off
	global_load_dwordx4 v[198:201], v[154:155], off offset:256
	s_mov_b64 s[98:99], 0x90000
	v_lshl_add_u64 v[154:155], v[144:145], 0, s[98:99]
	global_load_dwordx4 v[202:205], v[154:155], off
	global_load_dwordx4 v[206:209], v[154:155], off offset:256
	s_mov_b64 s[98:99], 0xa0000
	v_lshl_add_u64 v[154:155], v[144:145], 0, s[98:99]
	global_load_dwordx4 v[210:213], v[154:155], off
	global_load_dwordx4 v[214:217], v[154:155], off offset:256
	s_mov_b64 s[98:99], 0xb0000
	v_lshl_add_u64 v[154:155], v[144:145], 0, s[98:99]
	global_load_dwordx4 v[248:251], v[154:155], off
	global_load_dwordx4 v[252:255], v[154:155], off offset:256
	s_waitcnt vmcnt(15)
	s_nop 1
	v_mov_b32_e32 v152, v160
	v_mov_b32_e32 v153, v161
	v_mov_b32_e32 v154, v162
	v_mov_b32_e32 v155, v163
	s_mov_b64 s[2:3], 0x10000
	s_mov_b32 s8, s52
	s_mov_b64 s[10:11], s[6:7]
	s_mov_b64 s[12:13], s[54:55]
	s_waitcnt lgkmcnt(0)
	v_lshlrev_b32_e32 v156, 16, v152
	v_and_b32_e32 v157, 0xffff0000, v152
	v_lshlrev_b32_e32 v152, 16, v153
	v_and_b32_e32 v153, 0xffff0000, v153
	v_lshlrev_b32_e32 v158, 16, v154
	v_and_b32_e32 v159, 0xffff0000, v154
	v_lshlrev_b32_e32 v154, 16, v155
	v_and_b32_e32 v155, 0xffff0000, v155
	v_pk_add_f32 v[126:127], v[126:127], v[152:153]
	v_pk_add_f32 v[124:125], v[124:125], v[156:157]
	v_pk_add_f32 v[152:153], v[122:123], v[154:155]
	v_pk_add_f32 v[122:123], v[120:121], v[158:159]
	v_cvt_pk_bf16_f32 v120, v124, v125
	v_cvt_pk_bf16_f32 v121, v126, v127
	v_cvt_pk_bf16_f32 v122, v122, v123
	v_cvt_pk_bf16_f32 v123, v152, v153
	global_store_dwordx4 v[144:145], v[120:123], off
	s_waitcnt vmcnt(15)
; DI unsigned pack2(float a, float b) { f32x2 v = {a, b}; hwbf16x2 r = __builtin_convertvector(v, hwbf16x2); return __builtin_bit_cast(unsigned, r); }
; DI float bflo(unsigned w) { return __uint_as_float(w << 16); }
; DI float bfhi(unsigned w) { return __uint_as_float(w & 0xffff0000u); }
;     DI void operator()(const f32x4 (&acc)[2][2][4][2], const Unit& u, int wr, int wc, int fr, int fq) const {
;     ...
;         for (int ai = 0; ai < 2; ++ai)
; #pragma unroll
;             for (int m = 0; m < 4; ++m) { const size_t ro = (size_t)(row0 + ai * HALF + m * 16) * D + col0;
; #pragma unroll
;                 for (int bj = 0; bj < 2; ++bj) {
;                     f32x4 x0, x1;
;                     if constexpr (IB) { const u32x4 w = *(const u32x4*)((const bf16_t*)Xin + ro + bj * HALF);
;                         x0 = (f32x4){bflo(w[0]), bfhi(w[0]), bflo(w[1]), bfhi(w[1])}; x1 = (f32x4){bflo(w[2]), bfhi(w[2]), bflo(w[3]), bfhi(w[3])}; }
;                     else { x0 = *(const f32x4*)((const float*)Xin + ro + bj * HALF); x1 = *(const f32x4*)((const float*)Xin + ro + bj * HALF + 4); }
;                     x0 += acc[ai][bj][m][0] * sc[bj][0]; x1 += acc[ai][bj][m][1] * sc[bj][1];
;                     if constexpr (OB) { u32x4 o; o[0] = pack2(x0[0], x0[1]); o[1] = pack2(x0[2], x0[3]); o[2] = pack2(x1[0], x1[1]); o[3] = pack2(x1[2], x1[3]);
;                         *(u32x4*)((bf16_t*)Xout + ro + bj * HALF) = o; }
;                     else { *(f32x4*)((float*)Xout + ro + bj * HALF) = x0; *(f32x4*)((float*)Xout + ro + bj * HALF + 4) = x1; } } }
	s_nop 1
	v_mov_b32_e32 v120, v164
	v_mov_b32_e32 v121, v165
	v_mov_b32_e32 v122, v166
	v_mov_b32_e32 v123, v167
	s_waitcnt lgkmcnt(0)
	v_lshlrev_b32_e32 v124, 16, v120
	v_and_b32_e32 v125, 0xffff0000, v120
	v_lshlrev_b32_e32 v120, 16, v121
	v_and_b32_e32 v121, 0xffff0000, v121
	v_lshlrev_b32_e32 v126, 16, v122
	v_and_b32_e32 v127, 0xffff0000, v122
	v_lshlrev_b32_e32 v122, 16, v123
	v_and_b32_e32 v123, 0xffff0000, v123
	v_pk_add_f32 v[116:117], v[116:117], v[124:125]
	v_pk_add_f32 v[118:119], v[118:119], v[120:121]
	v_pk_add_f32 v[120:121], v[114:115], v[122:123]
	v_pk_add_f32 v[114:115], v[112:113], v[126:127]
	v_cvt_pk_bf16_f32 v112, v116, v117
	v_lshl_add_u64 v[116:117], v[144:145], 0, s[2:3]
	s_mov_b32 s2, 0x10000
	v_cvt_pk_bf16_f32 v113, v118, v119
	v_add_co_u32_e32 v118, vcc, s2, v144
	v_cvt_pk_bf16_f32 v114, v114, v115
	v_cvt_pk_bf16_f32 v115, v120, v121
	v_addc_co_u32_e32 v119, vcc, 0, v145, vcc
	global_store_dwordx4 v[144:145], v[112:115], off offset:256
	s_waitcnt vmcnt(15)
	s_nop 1
	v_mov_b32_e32 v112, v168
	v_mov_b32_e32 v113, v169
	v_mov_b32_e32 v114, v170
	v_mov_b32_e32 v115, v171
	s_mov_b64 s[2:3], 0x20000
	s_waitcnt lgkmcnt(0)
	v_lshlrev_b32_e32 v120, 16, v112
	v_and_b32_e32 v121, 0xffff0000, v112
	v_lshlrev_b32_e32 v112, 16, v113
	v_and_b32_e32 v113, 0xffff0000, v113
	v_lshlrev_b32_e32 v122, 16, v114
	v_and_b32_e32 v123, 0xffff0000, v114
	v_lshlrev_b32_e32 v114, 16, v115
	v_and_b32_e32 v115, 0xffff0000, v115
	v_pk_add_f32 v[110:111], v[110:111], v[112:113]
	v_pk_add_f32 v[108:109], v[108:109], v[120:121]
	v_pk_add_f32 v[112:113], v[106:107], v[114:115]
	v_pk_add_f32 v[106:107], v[104:105], v[122:123]
	v_cvt_pk_bf16_f32 v104, v108, v109
	v_cvt_pk_bf16_f32 v105, v110, v111
	v_cvt_pk_bf16_f32 v106, v106, v107
	v_cvt_pk_bf16_f32 v107, v112, v113
	global_store_dwordx4 v[118:119], v[104:107], off
	s_waitcnt vmcnt(15)
	s_nop 1
	v_mov_b32_e32 v104, v172
	v_mov_b32_e32 v105, v173
	v_mov_b32_e32 v106, v174
	v_mov_b32_e32 v107, v175
	s_waitcnt lgkmcnt(0)
	v_lshlrev_b32_e32 v108, 16, v104
	v_and_b32_e32 v109, 0xffff0000, v104
	v_lshlrev_b32_e32 v104, 16, v105
	v_and_b32_e32 v105, 0xffff0000, v105
	v_lshlrev_b32_e32 v110, 16, v106
	v_and_b32_e32 v111, 0xffff0000, v106
	v_lshlrev_b32_e32 v106, 16, v107
	v_and_b32_e32 v107, 0xffff0000, v107
	v_pk_add_f32 v[100:101], v[100:101], v[108:109]
	v_pk_add_f32 v[102:103], v[102:103], v[104:105]
	v_pk_add_f32 v[104:105], v[98:99], v[106:107]
	v_pk_add_f32 v[98:99], v[96:97], v[110:111]
	v_cvt_pk_bf16_f32 v96, v100, v101
	v_lshl_add_u64 v[100:101], v[144:145], 0, s[2:3]
	s_mov_b32 s2, 0x20000
	v_cvt_pk_bf16_f32 v97, v102, v103
	v_add_co_u32_e32 v102, vcc, s2, v144
	v_cvt_pk_bf16_f32 v98, v98, v99
	v_cvt_pk_bf16_f32 v99, v104, v105
	v_addc_co_u32_e32 v103, vcc, 0, v145, vcc
	global_store_dwordx4 v[116:117], v[96:99], off offset:256
	s_waitcnt vmcnt(15)
	s_nop 1
	v_mov_b32_e32 v96, v176
	v_mov_b32_e32 v97, v177
	v_mov_b32_e32 v98, v178
	v_mov_b32_e32 v99, v179
	s_mov_b64 s[2:3], 0x30000
	s_waitcnt lgkmcnt(0)
	v_lshlrev_b32_e32 v104, 16, v96
	v_and_b32_e32 v105, 0xffff0000, v96
	v_lshlrev_b32_e32 v96, 16, v97
	v_and_b32_e32 v97, 0xffff0000, v97
	v_lshlrev_b32_e32 v106, 16, v98
	v_and_b32_e32 v107, 0xffff0000, v98
	v_lshlrev_b32_e32 v98, 16, v99
	v_and_b32_e32 v99, 0xffff0000, v99
	v_pk_add_f32 v[94:95], v[94:95], v[96:97]
	v_pk_add_f32 v[92:93], v[92:93], v[104:105]
	v_pk_add_f32 v[96:97], v[90:91], v[98:99]
	v_pk_add_f32 v[90:91], v[88:89], v[106:107]
	v_cvt_pk_bf16_f32 v88, v92, v93
	v_cvt_pk_bf16_f32 v89, v94, v95
	v_cvt_pk_bf16_f32 v90, v90, v91
	v_cvt_pk_bf16_f32 v91, v96, v97
	global_store_dwordx4 v[102:103], v[88:91], off
	s_waitcnt vmcnt(15)
	s_nop 1
	v_mov_b32_e32 v88, v180
	v_mov_b32_e32 v89, v181
	v_mov_b32_e32 v90, v182
	v_mov_b32_e32 v91, v183
	s_waitcnt lgkmcnt(0)
	v_lshlrev_b32_e32 v92, 16, v88
	v_and_b32_e32 v93, 0xffff0000, v88
	v_lshlrev_b32_e32 v88, 16, v89
	v_and_b32_e32 v89, 0xffff0000, v89
	v_lshlrev_b32_e32 v94, 16, v90
	v_and_b32_e32 v95, 0xffff0000, v90
	v_lshlrev_b32_e32 v90, 16, v91
	v_and_b32_e32 v91, 0xffff0000, v91
	v_pk_add_f32 v[86:87], v[86:87], v[88:89]
	v_pk_add_f32 v[84:85], v[84:85], v[92:93]
	v_pk_add_f32 v[88:89], v[82:83], v[90:91]
	v_pk_add_f32 v[82:83], v[80:81], v[94:95]
	v_cvt_pk_bf16_f32 v80, v84, v85
	v_cvt_pk_bf16_f32 v81, v86, v87
	v_cvt_pk_bf16_f32 v82, v82, v83
	v_cvt_pk_bf16_f32 v83, v88, v89
	global_store_dwordx4 v[100:101], v[80:83], off offset:256
	s_nop 1
	v_lshl_add_u64 v[80:81], v[144:145], 0, s[2:3]
	s_mov_b32 s2, 0x30000
	v_add_co_u32_e32 v86, vcc, s2, v144
	s_mov_b64 s[2:3], 0x80000
	s_nop 0
	v_addc_co_u32_e32 v87, vcc, 0, v145, vcc
	s_waitcnt vmcnt(15)
	s_nop 1
	v_mov_b32_e32 v82, v184
	v_mov_b32_e32 v83, v185
	v_mov_b32_e32 v84, v186
	v_mov_b32_e32 v85, v187
	s_waitcnt lgkmcnt(0)
	v_lshlrev_b32_e32 v88, 16, v82
	v_and_b32_e32 v89, 0xffff0000, v82
	v_lshlrev_b32_e32 v82, 16, v83
	v_and_b32_e32 v83, 0xffff0000, v83
	v_lshlrev_b32_e32 v90, 16, v84
	v_and_b32_e32 v91, 0xffff0000, v84
	v_lshlrev_b32_e32 v84, 16, v85
	v_and_b32_e32 v85, 0xffff0000, v85
	v_pk_add_f32 v[78:79], v[78:79], v[82:83]
	v_pk_add_f32 v[76:77], v[76:77], v[88:89]
	v_pk_add_f32 v[82:83], v[74:75], v[84:85]
	v_pk_add_f32 v[74:75], v[72:73], v[90:91]
	v_cvt_pk_bf16_f32 v72, v76, v77
	v_cvt_pk_bf16_f32 v73, v78, v79
	v_cvt_pk_bf16_f32 v74, v74, v75
	v_cvt_pk_bf16_f32 v75, v82, v83
	global_store_dwordx4 v[86:87], v[72:75], off
	s_waitcnt vmcnt(15)
	s_nop 1
	v_mov_b32_e32 v72, v188
	v_mov_b32_e32 v73, v189
	v_mov_b32_e32 v74, v190
	v_mov_b32_e32 v75, v191
	s_waitcnt lgkmcnt(0)
; DI unsigned pack2(float a, float b) { f32x2 v = {a, b}; hwbf16x2 r = __builtin_convertvector(v, hwbf16x2); return __builtin_bit_cast(unsigned, r); }
; DI float bflo(unsigned w) { return __uint_as_float(w << 16); }
; DI float bfhi(unsigned w) { return __uint_as_float(w & 0xffff0000u); }
;     DI void operator()(const f32x4 (&acc)[2][2][4][2], const Unit& u, int wr, int wc, int fr, int fq) const {
;     ...
;         for (int ai = 0; ai < 2; ++ai)
; #pragma unroll
;             for (int m = 0; m < 4; ++m) { const size_t ro = (size_t)(row0 + ai * HALF + m * 16) * D + col0;
; #pragma unroll
;                 for (int bj = 0; bj < 2; ++bj) {
;                     f32x4 x0, x1;
;                     if constexpr (IB) { const u32x4 w = *(const u32x4*)((const bf16_t*)Xin + ro + bj * HALF);
;                         x0 = (f32x4){bflo(w[0]), bfhi(w[0]), bflo(w[1]), bfhi(w[1])}; x1 = (f32x4){bflo(w[2]), bfhi(w[2]), bflo(w[3]), bfhi(w[3])}; }
;                     else { x0 = *(const f32x4*)((const float*)Xin + ro + bj * HALF); x1 = *(const f32x4*)((const float*)Xin + ro + bj * HALF + 4); }
;                     x0 += acc[ai][bj][m][0] * sc[bj][0]; x1 += acc[ai][bj][m][1] * sc[bj][1];
;                     if constexpr (OB) { u32x4 o; o[0] = pack2(x0[0], x0[1]); o[1] = pack2(x0[2], x0[3]); o[2] = pack2(x1[0], x1[1]); o[3] = pack2(x1[2], x1[3]);
;                         *(u32x4*)((bf16_t*)Xout + ro + bj * HALF) = o; }
;                     else { *(f32x4*)((float*)Xout + ro + bj * HALF) = x0; *(f32x4*)((float*)Xout + ro + bj * HALF + 4) = x1; } } }
	v_lshlrev_b32_e32 v76, 16, v72
	v_and_b32_e32 v77, 0xffff0000, v72
	v_lshlrev_b32_e32 v72, 16, v73
	v_and_b32_e32 v73, 0xffff0000, v73
	v_lshlrev_b32_e32 v78, 16, v74
	v_and_b32_e32 v79, 0xffff0000, v74
	v_lshlrev_b32_e32 v74, 16, v75
	v_and_b32_e32 v75, 0xffff0000, v75
	v_pk_add_f32 v[70:71], v[70:71], v[72:73]
	v_pk_add_f32 v[68:69], v[68:69], v[76:77]
	v_pk_add_f32 v[72:73], v[66:67], v[74:75]
	v_pk_add_f32 v[66:67], v[64:65], v[78:79]
	v_cvt_pk_bf16_f32 v64, v68, v69
	v_cvt_pk_bf16_f32 v65, v70, v71
	v_cvt_pk_bf16_f32 v66, v66, v67
	v_cvt_pk_bf16_f32 v67, v72, v73
	global_store_dwordx4 v[80:81], v[64:67], off offset:256
	s_nop 1
	v_lshl_add_u64 v[64:65], v[144:145], 0, s[2:3]
	s_mov_b32 s2, 0x80000
	v_add_co_u32_e32 v70, vcc, s2, v144
	s_mov_b64 s[2:3], 0x90000
	s_nop 0
	v_addc_co_u32_e32 v71, vcc, 0, v145, vcc
	s_waitcnt vmcnt(15)
	s_nop 1
	v_mov_b32_e32 v66, v192
	v_mov_b32_e32 v67, v193
	v_mov_b32_e32 v68, v194
	v_mov_b32_e32 v69, v195
	s_waitcnt lgkmcnt(0)
	v_lshlrev_b32_e32 v72, 16, v66
	v_and_b32_e32 v73, 0xffff0000, v66
	v_lshlrev_b32_e32 v66, 16, v67
	v_and_b32_e32 v67, 0xffff0000, v67
	v_lshlrev_b32_e32 v74, 16, v68
	v_and_b32_e32 v75, 0xffff0000, v68
	v_lshlrev_b32_e32 v68, 16, v69
	v_and_b32_e32 v69, 0xffff0000, v69
	v_pk_add_f32 v[62:63], v[62:63], v[66:67]
	v_pk_add_f32 v[60:61], v[60:61], v[72:73]
	v_pk_add_f32 v[66:67], v[58:59], v[68:69]
	v_pk_add_f32 v[58:59], v[56:57], v[74:75]
	v_cvt_pk_bf16_f32 v56, v60, v61
	v_cvt_pk_bf16_f32 v57, v62, v63
	v_cvt_pk_bf16_f32 v58, v58, v59
	v_cvt_pk_bf16_f32 v59, v66, v67
	global_store_dwordx4 v[70:71], v[56:59], off
	s_waitcnt vmcnt(15)
	s_nop 1
	v_mov_b32_e32 v56, v198
	v_mov_b32_e32 v57, v199
	v_mov_b32_e32 v58, v200
	v_mov_b32_e32 v59, v201
	s_waitcnt lgkmcnt(0)
	v_lshlrev_b32_e32 v60, 16, v56
	v_and_b32_e32 v61, 0xffff0000, v56
	v_lshlrev_b32_e32 v56, 16, v57
	v_and_b32_e32 v57, 0xffff0000, v57
	v_lshlrev_b32_e32 v62, 16, v58
	v_and_b32_e32 v63, 0xffff0000, v58
	v_lshlrev_b32_e32 v58, 16, v59
	v_and_b32_e32 v59, 0xffff0000, v59
	v_pk_add_f32 v[54:55], v[54:55], v[56:57]
	v_pk_add_f32 v[52:53], v[52:53], v[60:61]
	v_pk_add_f32 v[56:57], v[50:51], v[58:59]
	v_pk_add_f32 v[50:51], v[48:49], v[62:63]
	v_cvt_pk_bf16_f32 v48, v52, v53
	v_cvt_pk_bf16_f32 v49, v54, v55
	v_cvt_pk_bf16_f32 v50, v50, v51
	v_cvt_pk_bf16_f32 v51, v56, v57
	global_store_dwordx4 v[64:65], v[48:51], off offset:256
	s_nop 1
	v_lshl_add_u64 v[48:49], v[144:145], 0, s[2:3]
	s_mov_b32 s2, 0x90000
	v_add_co_u32_e32 v54, vcc, s2, v144
	s_mov_b64 s[2:3], 0xa0000
	s_nop 0
	v_addc_co_u32_e32 v55, vcc, 0, v145, vcc
	s_waitcnt vmcnt(15)
	s_nop 1
	v_mov_b32_e32 v50, v202
	v_mov_b32_e32 v51, v203
	v_mov_b32_e32 v52, v204
	v_mov_b32_e32 v53, v205
	s_waitcnt lgkmcnt(0)
	v_lshlrev_b32_e32 v56, 16, v50
	v_and_b32_e32 v57, 0xffff0000, v50
	v_lshlrev_b32_e32 v50, 16, v51
	v_and_b32_e32 v51, 0xffff0000, v51
	v_lshlrev_b32_e32 v58, 16, v52
	v_and_b32_e32 v59, 0xffff0000, v52
	v_lshlrev_b32_e32 v52, 16, v53
	v_and_b32_e32 v53, 0xffff0000, v53
	v_pk_add_f32 v[46:47], v[46:47], v[50:51]
	v_pk_add_f32 v[44:45], v[44:45], v[56:57]
	v_pk_add_f32 v[50:51], v[42:43], v[52:53]
	v_pk_add_f32 v[42:43], v[40:41], v[58:59]
	v_cvt_pk_bf16_f32 v40, v44, v45
	v_cvt_pk_bf16_f32 v41, v46, v47
	v_cvt_pk_bf16_f32 v42, v42, v43
	v_cvt_pk_bf16_f32 v43, v50, v51
	global_store_dwordx4 v[54:55], v[40:43], off
	s_waitcnt vmcnt(15)
	s_nop 1
	v_mov_b32_e32 v40, v206
	v_mov_b32_e32 v41, v207
	v_mov_b32_e32 v42, v208
	v_mov_b32_e32 v43, v209
	s_waitcnt lgkmcnt(0)
; DI unsigned pack2(float a, float b) { f32x2 v = {a, b}; hwbf16x2 r = __builtin_convertvector(v, hwbf16x2); return __builtin_bit_cast(unsigned, r); }
; DI float bflo(unsigned w) { return __uint_as_float(w << 16); }
; DI float bfhi(unsigned w) { return __uint_as_float(w & 0xffff0000u); }
;     DI const char* a(const Unit& u) const { return (const char*)(A + (size_t)u.pm * BM * lda); }
;     DI const char* a(const Unit& u) const { return (const char*)(A + (size_t)u.pm * BM * 2048 + (u.pn >> 1) * 512); }
;     DI void operator()(const f32x4 (&acc)[2][2][4][2], const Unit& u, int wr, int wc, int fr, int fq) const {
;     ...
;         for (int ai = 0; ai < 2; ++ai)
; #pragma unroll
;             for (int m = 0; m < 4; ++m) { const size_t ro = (size_t)(row0 + ai * HALF + m * 16) * D + col0;
; #pragma unroll
;                 for (int bj = 0; bj < 2; ++bj) {
;                     f32x4 x0, x1;
;                     if constexpr (IB) { const u32x4 w = *(const u32x4*)((const bf16_t*)Xin + ro + bj * HALF);
;                         x0 = (f32x4){bflo(w[0]), bfhi(w[0]), bflo(w[1]), bfhi(w[1])}; x1 = (f32x4){bflo(w[2]), bfhi(w[2]), bflo(w[3]), bfhi(w[3])}; }
;                     else { x0 = *(const f32x4*)((const float*)Xin + ro + bj * HALF); x1 = *(const f32x4*)((const float*)Xin + ro + bj * HALF + 4); }
;                     x0 += acc[ai][bj][m][0] * sc[bj][0]; x1 += acc[ai][bj][m][1] * sc[bj][1];
;                     if constexpr (OB) { u32x4 o; o[0] = pack2(x0[0], x0[1]); o[1] = pack2(x0[2], x0[3]); o[2] = pack2(x1[0], x1[1]); o[3] = pack2(x1[2], x1[3]);
;                         *(u32x4*)((bf16_t*)Xout + ro + bj * HALF) = o; }
;                     else { *(f32x4*)((float*)Xout + ro + bj * HALF) = x0; *(f32x4*)((float*)Xout + ro + bj * HALF + 4) = x1; } } }
; template <class Map, class Epi>
; DI void gemm_phase(LAS unsigned char* lds, const Map& MP, const Epi& E, const int nM, const int nN, const int K, const int lda, const int ldb) {
;     ...
;         if (!has_next) break;
; #pragma unroll
;         for (int a = 0; a < 2; ++a)
; #pragma unroll
;             for (int b = 0; b < 2; ++b)
; #pragma unroll
;                 for (int m = 0; m < 4; ++m)
; #pragma unroll
;                     for (int n = 0; n < 2; ++n) acc[a][b][m][n] = (f32x4){0.f, 0.f, 0.f, 0.f};
;         cur = nxt; cA = nA; cB = nB; ++ui;
	v_lshlrev_b32_e32 v44, 16, v40
	v_and_b32_e32 v45, 0xffff0000, v40
	v_lshlrev_b32_e32 v40, 16, v41
	v_and_b32_e32 v41, 0xffff0000, v41
	v_lshlrev_b32_e32 v46, 16, v42
	v_and_b32_e32 v47, 0xffff0000, v42
	v_lshlrev_b32_e32 v42, 16, v43
	v_and_b32_e32 v43, 0xffff0000, v43
	v_pk_add_f32 v[38:39], v[38:39], v[40:41]
	v_pk_add_f32 v[36:37], v[36:37], v[44:45]
	v_pk_add_f32 v[40:41], v[34:35], v[42:43]
	v_pk_add_f32 v[34:35], v[32:33], v[46:47]
	v_cvt_pk_bf16_f32 v32, v36, v37
	v_cvt_pk_bf16_f32 v33, v38, v39
	v_cvt_pk_bf16_f32 v34, v34, v35
	v_cvt_pk_bf16_f32 v35, v40, v41
	global_store_dwordx4 v[48:49], v[32:35], off offset:256
	s_nop 1
	v_lshl_add_u64 v[32:33], v[144:145], 0, s[2:3]
	s_mov_b32 s2, 0xa0000
	v_add_co_u32_e32 v38, vcc, s2, v144
	s_mov_b64 s[2:3], 0xb0000
	s_nop 0
	v_addc_co_u32_e32 v39, vcc, 0, v145, vcc
	s_waitcnt vmcnt(15)
	s_nop 1
	v_mov_b32_e32 v34, v210
	v_mov_b32_e32 v35, v211
	v_mov_b32_e32 v36, v212
	v_mov_b32_e32 v37, v213
	s_waitcnt lgkmcnt(0)
	v_lshlrev_b32_e32 v40, 16, v34
	v_and_b32_e32 v41, 0xffff0000, v34
	v_lshlrev_b32_e32 v34, 16, v35
	v_and_b32_e32 v35, 0xffff0000, v35
	v_lshlrev_b32_e32 v42, 16, v36
	v_and_b32_e32 v43, 0xffff0000, v36
	v_lshlrev_b32_e32 v36, 16, v37
	v_and_b32_e32 v37, 0xffff0000, v37
	v_pk_add_f32 v[30:31], v[30:31], v[34:35]
	v_pk_add_f32 v[28:29], v[28:29], v[40:41]
	v_pk_add_f32 v[34:35], v[26:27], v[36:37]
	v_pk_add_f32 v[26:27], v[24:25], v[42:43]
	v_cvt_pk_bf16_f32 v24, v28, v29
	v_cvt_pk_bf16_f32 v25, v30, v31
	v_cvt_pk_bf16_f32 v26, v26, v27
	v_cvt_pk_bf16_f32 v27, v34, v35
	global_store_dwordx4 v[38:39], v[24:27], off
	s_waitcnt vmcnt(15)
	s_nop 1
	v_mov_b32_e32 v24, v214
	v_mov_b32_e32 v25, v215
	v_mov_b32_e32 v26, v216
	v_mov_b32_e32 v27, v217
	s_waitcnt lgkmcnt(0)
	v_lshlrev_b32_e32 v28, 16, v24
	v_and_b32_e32 v29, 0xffff0000, v24
	v_lshlrev_b32_e32 v24, 16, v25
	v_and_b32_e32 v25, 0xffff0000, v25
	v_lshlrev_b32_e32 v30, 16, v26
	v_and_b32_e32 v31, 0xffff0000, v26
	v_lshlrev_b32_e32 v26, 16, v27
	v_and_b32_e32 v27, 0xffff0000, v27
	v_pk_add_f32 v[22:23], v[22:23], v[24:25]
	v_pk_add_f32 v[20:21], v[20:21], v[28:29]
	v_pk_add_f32 v[24:25], v[18:19], v[26:27]
	v_pk_add_f32 v[18:19], v[16:17], v[30:31]
	v_cvt_pk_bf16_f32 v16, v20, v21
	v_cvt_pk_bf16_f32 v17, v22, v23
	v_cvt_pk_bf16_f32 v18, v18, v19
	v_cvt_pk_bf16_f32 v19, v24, v25
	global_store_dwordx4 v[32:33], v[16:19], off offset:256
	s_nop 1
	v_lshl_add_u64 v[16:17], v[144:145], 0, s[2:3]
	s_mov_b32 s2, 0xb0000
	v_add_co_u32_e32 v22, vcc, s2, v144
	s_mov_b32 s2, s46
	s_nop 0
	v_addc_co_u32_e32 v23, vcc, 0, v145, vcc
	s_waitcnt vmcnt(15)
	s_nop 1
	v_mov_b32_e32 v18, v248
	v_mov_b32_e32 v19, v249
	v_mov_b32_e32 v20, v250
	v_mov_b32_e32 v21, v251
	s_and_b64 vcc, exec, s[40:41]
	s_waitcnt lgkmcnt(0)
	v_lshlrev_b32_e32 v24, 16, v18
	v_and_b32_e32 v25, 0xffff0000, v18
	v_lshlrev_b32_e32 v18, 16, v19
	v_and_b32_e32 v19, 0xffff0000, v19
	v_lshlrev_b32_e32 v26, 16, v20
	v_and_b32_e32 v27, 0xffff0000, v20
	v_lshlrev_b32_e32 v20, 16, v21
	v_and_b32_e32 v21, 0xffff0000, v21
	v_pk_add_f32 v[14:15], v[14:15], v[18:19]
	v_pk_add_f32 v[12:13], v[12:13], v[24:25]
	v_pk_add_f32 v[18:19], v[10:11], v[20:21]
	v_pk_add_f32 v[10:11], v[8:9], v[26:27]
	v_cvt_pk_bf16_f32 v8, v12, v13
	v_cvt_pk_bf16_f32 v9, v14, v15
	v_cvt_pk_bf16_f32 v10, v10, v11
	v_cvt_pk_bf16_f32 v11, v18, v19
	global_store_dwordx4 v[22:23], v[8:11], off
	s_waitcnt vmcnt(15)
	s_nop 1
	v_mov_b32_e32 v8, v252
	v_mov_b32_e32 v9, v253
	v_mov_b32_e32 v10, v254
	v_mov_b32_e32 v11, v255
	s_waitcnt lgkmcnt(0)
	v_lshlrev_b32_e32 v12, 16, v8
	v_and_b32_e32 v13, 0xffff0000, v8
	v_lshlrev_b32_e32 v8, 16, v9
	v_and_b32_e32 v9, 0xffff0000, v9
	v_lshlrev_b32_e32 v14, 16, v10
	v_and_b32_e32 v15, 0xffff0000, v10
	v_lshlrev_b32_e32 v10, 16, v11
	v_and_b32_e32 v11, 0xffff0000, v11
	v_pk_add_f32 v[6:7], v[6:7], v[8:9]
	v_pk_add_f32 v[4:5], v[4:5], v[12:13]
	v_pk_add_f32 v[8:9], v[2:3], v[10:11]
	v_pk_add_f32 v[2:3], v[0:1], v[14:15]
	v_cvt_pk_bf16_f32 v0, v4, v5
	v_cvt_pk_bf16_f32 v1, v6, v7
	v_cvt_pk_bf16_f32 v2, v2, v3
	v_cvt_pk_bf16_f32 v3, v8, v9
	global_store_dwordx4 v[16:17], v[0:3], off offset:256
	s_cbranch_vccz .LBB1_922
	s_waitcnt vmcnt(0)
	s_cmpk_gt_u32 s17, 0xff
	s_cbranch_scc1 .LBB1_929
	s_barrier

;     DI const char* a(const Unit& u) const { return (const char*)(A + (size_t)u.pm * BM * lda); }
;     DI const char* a(const Unit& u) const { return (const char*)(A + (size_t)u.pm * BM * 2048 + (u.pn >> 1) * 512); }
;     DI const char* a(const Unit& u) const { return (const char*)((u.pn < 12 ? A1 : A2) + (size_t)u.pm * BM * 512); }
; #define PG8_STAGE(bufoff, gbase, voff) do { _Pragma("unroll") for (int _i = 0; _i < 2; ++_i) \
;         __builtin_amdgcn_global_load_lds((const unsigned*)((const char*)(gbase) + (voff)[_i]), (LAS unsigned*)(lds + (bufoff) + ldsw + _i * 8192), 16, 0, 0); } while (0)
; #define PG8_LDA(dst, b, h) do { _Pragma("unroll") for (int m = 0; m < 4; ++m) _Pragma("unroll") for (int k = 0; k < 2; ++k) dst[m][k] = *(const LAS bf16x8*)(lds + PG8_SA(b, h) + aoff + m * 2048 + k * 1024); } while (0)
; #define PG8_LDB(dst, b, h) do { _Pragma("unroll") for (int n = 0; n < 2; ++n) _Pragma("unroll") for (int k = 0; k < 2; ++k) dst[n][k] = *(const LAS bf16x8*)(lds + PG8_SB(b, h) + boff + n * 2048 + k * 1024); } while (0)
; template <class Map, class Epi>
; DI void gemm_phase(LAS unsigned char* lds, const Map& MP, const Epi& E, const int nM, const int nN, const int K, const int lda, const int ldb) {
;     ...
;     for (;;) {
;         const bool has_next = sched_next(ui + 1, nM, nN, G, cblk, nxt);
;         const char* nA = has_next ? MP.a(nxt) : cA; const char* nB = has_next ? MP.b(nxt) : cB;
;         for (int t = 0; t < nt; t += 2) {
;             const bool last = (t == nt - 2);
;             const char* a1 = cA + (size_t)(t + 1) * kstep;
;             const char* a2 = last ? nA : cA + (size_t)(t + 2) * kstep; const char* b2 = last ? nB : cB + (size_t)(t + 2) * kstep;
;             const char* a3 = a2 + kstep; const char* b3 = b2 + kstep;
;             PG8_LDB(B0, 0, 0); PG8_SCHED; PG8_LDA(At, 0, 0); PG8_STAGE(PG8_SA(1, 1), a1 + hstepA, voffA);
;             PG8_WAIT_L(8); PG8_BAR; PG8_WAIT_L(0); PG8_MMA(0, 0, At, B0); PG8_BAR; PG8_SCHED;
;             PG8_LDB(B1, 0, 1); PG8_STAGE(PG8_SB(0, 0), b2, voffB);
;             PG8_BAR; PG8_WAIT_L(0); PG8_MMA(0, 1, At, B1); PG8_BAR;
;             PG8_LDA(At, 0, 1); PG8_STAGE(PG8_SA(0, 0), a2, voffA);
;             PG8_BAR; PG8_WAIT_L(0); PG8_MMA(1, 0, At, B0); PG8_BAR; PG8_SCHED;
;             PG8_STAGE(PG8_SB(0, 1), b2 + hstepB, voffB);
;             PG8_WAIT_V(6); PG8_BAR; PG8_MMA(1, 1, At, B1); PG8_BAR;
.LBB1_1069:
	s_add_u32 s24, s42, 0xfff80080
	s_addc_u32 s25, s43, -1
	s_cmp_eq_u32 s3, 28
	s_cselect_b32 s47, s23, s25
	s_cselect_b32 s46, s58, s24
	s_cselect_b32 s25, s21, vcc_hi
	s_cselect_b32 s24, s59, vcc_lo
	s_add_i32 m0, s38, 0xc000
	ds_read_b128 v[96:99], v190
	ds_read_b128 v[100:103], v190 offset:1024
	ds_read_b128 v[108:111], v190 offset:2048
	ds_read_b128 v[112:115], v190 offset:3072
	ds_read_b128 v[160:163], v190 offset:4096
	ds_read_b128 v[164:167], v190 offset:5120
	ds_read_b128 v[198:201], v190 offset:6144
	ds_read_b128 v[202:205], v190 offset:7168
	global_load_lds_dwordx4 v178, s[42:43]
	s_add_i32 m0, s38, 0xe000
	s_nop 0
	global_load_lds_dwordx4 v176, s[42:43]
	s_waitcnt lgkmcnt(8)
	s_setprio 1
	s_barrier
	s_waitcnt lgkmcnt(7)
	v_mfma_f32_16x16x32_bf16 v[148:151], v[80:83], v[96:99], v[148:151]
	v_mfma_f32_16x16x32_bf16 v[144:147], v[88:91], v[96:99], v[144:147]
	s_waitcnt lgkmcnt(5)
	v_mfma_f32_16x16x32_bf16 v[136:139], v[80:83], v[108:111], v[136:139]
	v_mfma_f32_16x16x32_bf16 v[128:131], v[88:91], v[108:111], v[128:131]
	s_waitcnt lgkmcnt(3)
	v_mfma_f32_16x16x32_bf16 v[120:123], v[80:83], v[160:163], v[120:123]
	v_mfma_f32_16x16x32_bf16 v[104:107], v[88:91], v[160:163], v[104:107]
	s_waitcnt lgkmcnt(1)
	v_mfma_f32_16x16x32_bf16 v[76:79], v[80:83], v[198:201], v[76:79]
	v_mfma_f32_16x16x32_bf16 v[72:75], v[88:91], v[198:201], v[72:75]
	v_mfma_f32_16x16x32_bf16 v[148:151], v[84:87], v[100:103], v[148:151]
	s_add_i32 s68, s31, s66
	v_mfma_f32_16x16x32_bf16 v[144:147], v[92:95], v[100:103], v[144:147]
	v_lshl_add_u64 v[184:185], s[24:25], 0, v[172:173]
	v_mfma_f32_16x16x32_bf16 v[136:139], v[84:87], v[112:115], v[136:139]
	v_lshl_add_u64 v[194:195], s[24:25], 0, v[168:169]
	v_mfma_f32_16x16x32_bf16 v[128:131], v[92:95], v[112:115], v[128:131]
	v_mfma_f32_16x16x32_bf16 v[120:123], v[84:87], v[164:167], v[120:123]
	v_mfma_f32_16x16x32_bf16 v[104:107], v[92:95], v[164:167], v[104:107]
	s_waitcnt lgkmcnt(0)
	v_mfma_f32_16x16x32_bf16 v[76:79], v[84:87], v[202:205], v[76:79]
	s_mov_b32 m0, s68
	v_mfma_f32_16x16x32_bf16 v[72:75], v[92:95], v[202:205], v[72:75]
	s_barrier
	s_setprio 0
	ds_read_b128 v[206:209], v191
	ds_read_b128 v[210:213], v191 offset:1024
	ds_read_b128 v[214:217], v191 offset:2048
	global_load_lds_dwordx4 v[184:185], off
	s_add_i32 m0, s68, 0x2000
	ds_read_b128 v[218:221], v191 offset:3072
	global_load_lds_dwordx4 v[194:195], off
	s_setprio 1
	s_barrier
	s_waitcnt lgkmcnt(3)
	v_mfma_f32_16x16x32_bf16 v[156:159], v[206:209], v[96:99], v[156:159]
	s_waitcnt lgkmcnt(1)
	v_mfma_f32_16x16x32_bf16 v[96:99], v[214:217], v[96:99], v[152:155]
	v_mfma_f32_16x16x32_bf16 v[156:159], v[210:213], v[100:103], v[156:159]
	s_waitcnt lgkmcnt(0)
	v_mfma_f32_16x16x32_bf16 v[96:99], v[218:221], v[100:103], v[96:99]
	v_mfma_f32_16x16x32_bf16 v[100:103], v[206:209], v[108:111], v[140:143]
	v_mfma_f32_16x16x32_bf16 v[108:111], v[214:217], v[108:111], v[132:135]
	v_mfma_f32_16x16x32_bf16 v[116:119], v[214:217], v[160:163], v[116:119]
	v_mfma_f32_16x16x32_bf16 v[68:71], v[206:209], v[198:201], v[68:71]
	v_mfma_f32_16x16x32_bf16 v[64:67], v[214:217], v[198:201], v[64:67]
	v_lshl_add_u64 v[234:235], s[46:47], 0, v[170:171]
	s_mov_b32 m0, s38
	v_mfma_f32_16x16x32_bf16 v[100:103], v[210:213], v[112:115], v[100:103]
	v_lshl_add_u64 v[226:227], s[46:47], 0, v[174:175]
	v_mfma_f32_16x16x32_bf16 v[108:111], v[218:221], v[112:115], v[108:111]
	v_mfma_f32_16x16x32_bf16 v[112:115], v[206:209], v[160:163], v[124:127]
	v_mfma_f32_16x16x32_bf16 v[116:119], v[218:221], v[164:167], v[116:119]
	v_mfma_f32_16x16x32_bf16 v[68:71], v[210:213], v[202:205], v[68:71]
	v_mfma_f32_16x16x32_bf16 v[64:67], v[218:221], v[202:205], v[64:67]
	v_mfma_f32_16x16x32_bf16 v[112:115], v[210:213], v[164:167], v[112:115]
	s_barrier
	s_setprio 0
	ds_read_b128 v[124:127], v190 offset:16384
	ds_read_b128 v[132:135], v190 offset:17408
	ds_read_b128 v[140:143], v190 offset:18432
	ds_read_b128 v[152:155], v190 offset:19456
	ds_read_b128 v[160:163], v190 offset:20480
	ds_read_b128 v[164:167], v190 offset:21504
	ds_read_b128 v[198:201], v190 offset:22528
	global_load_lds_dwordx4 v[226:227], off
	s_mov_b32 m0, s39
	ds_read_b128 v[202:205], v190 offset:23552
	global_load_lds_dwordx4 v[234:235], off
	s_waitcnt vmcnt(10)
	s_setprio 1
	s_barrier
	s_waitcnt lgkmcnt(7)
	v_mfma_f32_16x16x32_bf16 v[60:63], v[80:83], v[124:127], v[60:63]
	v_mfma_f32_16x16x32_bf16 v[48:51], v[88:91], v[124:127], v[48:51]
	s_waitcnt lgkmcnt(5)
	v_mfma_f32_16x16x32_bf16 v[40:43], v[80:83], v[140:143], v[40:43]
	v_mfma_f32_16x16x32_bf16 v[32:35], v[88:91], v[140:143], v[32:35]
	s_waitcnt lgkmcnt(3)
	v_mfma_f32_16x16x32_bf16 v[24:27], v[80:83], v[160:163], v[24:27]
	v_mfma_f32_16x16x32_bf16 v[16:19], v[88:91], v[160:163], v[16:19]
	s_waitcnt lgkmcnt(1)
	v_mfma_f32_16x16x32_bf16 v[12:15], v[80:83], v[198:201], v[12:15]
	v_mfma_f32_16x16x32_bf16 v[8:11], v[88:91], v[198:201], v[8:11]
	v_mfma_f32_16x16x32_bf16 v[60:63], v[84:87], v[132:135], v[60:63]
	s_add_u32 s68, s24, 0x80000
	s_addc_u32 s69, s25, 0
	v_mfma_f32_16x16x32_bf16 v[48:51], v[92:95], v[132:135], v[48:51]
	s_add_i32 s70, s2, s66
	v_mfma_f32_16x16x32_bf16 v[40:43], v[84:87], v[152:155], v[40:43]
	v_mfma_f32_16x16x32_bf16 v[32:35], v[92:95], v[152:155], v[32:35]
	v_mfma_f32_16x16x32_bf16 v[24:27], v[84:87], v[164:167], v[24:27]
	v_mfma_f32_16x16x32_bf16 v[16:19], v[92:95], v[164:167], v[16:19]
	s_waitcnt lgkmcnt(0)
	v_mfma_f32_16x16x32_bf16 v[12:15], v[84:87], v[202:205], v[12:15]
	s_mov_b32 m0, s70
	v_mfma_f32_16x16x32_bf16 v[8:11], v[92:95], v[202:205], v[8:11]
	s_barrier
; #define PG8_STAGE(bufoff, gbase, voff) do { _Pragma("unroll") for (int _i = 0; _i < 2; ++_i) \
;         __builtin_amdgcn_global_load_lds((const unsigned*)((const char*)(gbase) + (voff)[_i]), (LAS unsigned*)(lds + (bufoff) + ldsw + _i * 8192), 16, 0, 0); } while (0)
; #define PG8_LDA(dst, b, h) do { _Pragma("unroll") for (int m = 0; m < 4; ++m) _Pragma("unroll") for (int k = 0; k < 2; ++k) dst[m][k] = *(const LAS bf16x8*)(lds + PG8_SA(b, h) + aoff + m * 2048 + k * 1024); } while (0)
; #define PG8_LDB(dst, b, h) do { _Pragma("unroll") for (int n = 0; n < 2; ++n) _Pragma("unroll") for (int k = 0; k < 2; ++k) dst[n][k] = *(const LAS bf16x8*)(lds + PG8_SB(b, h) + boff + n * 2048 + k * 1024); } while (0)
; #define PG8_MMA(ai, bj, At, Bt) do { __builtin_amdgcn_s_setprio(1); _Pragma("unroll") for (int m = 0; m < 4; ++m) _Pragma("unroll") for (int n = 0; n < 2; ++n) _Pragma("unroll") for (int k = 0; k < 2; ++k) \
;         acc[ai][bj][m][n] = __builtin_amdgcn_mfma_f32_16x16x32_bf16(Bt[n][k], At[m][k], acc[ai][bj][m][n], 0, 0, 0); __builtin_amdgcn_s_setprio(0); } while (0)
; #define PG8_WAIT_V(n) asm volatile("s_waitcnt vmcnt(" #n ")" ::: "memory")
; #define PG8_WAIT_L(n) asm volatile("s_waitcnt lgkmcnt(" #n ")" ::: "memory")
; #define PG8_BAR __builtin_amdgcn_s_barrier()
; #define PG8_SCHED __builtin_amdgcn_sched_barrier(0)
; template <class Map, class Epi>
; DI void gemm_phase(LAS unsigned char* lds, const Map& MP, const Epi& E, const int nM, const int nN, const int K, const int lda, const int ldb) {
;     ...
;             PG8_BAR; PG8_WAIT_L(0); PG8_MMA(1, 0, At, B0); PG8_BAR; PG8_SCHED;
;             PG8_STAGE(PG8_SB(0, 1), b2 + hstepB, voffB);
;             PG8_WAIT_V(6); PG8_BAR; PG8_MMA(1, 1, At, B1); PG8_BAR;
;             PG8_LDB(B0, 1, 0); PG8_SCHED; PG8_LDA(At, 1, 0); PG8_STAGE(PG8_SA(0, 1), a2 + hstepA, voffA);
;             PG8_WAIT_L(8); PG8_BAR; PG8_WAIT_L(0); PG8_MMA(0, 0, At, B0); PG8_BAR; PG8_SCHED;
;             PG8_LDB(B1, 1, 1); PG8_STAGE(PG8_SB(1, 0), b3, voffB);
;             PG8_BAR; PG8_WAIT_L(0); PG8_MMA(0, 1, At, B1); PG8_BAR;
;             PG8_LDA(At, 1, 1); PG8_STAGE(PG8_SA(1, 0), a3, voffA);
;             PG8_BAR; PG8_WAIT_L(0); PG8_MMA(1, 0, At, B0); PG8_BAR; PG8_SCHED;
;             PG8_STAGE(PG8_SB(1, 1), b3 + hstepB, voffB);
;             PG8_WAIT_V(6); PG8_BAR; PG8_MMA(1, 1, At, B1); PG8_BAR;
	s_setprio 0
	global_load_lds_dwordx4 v172, s[68:69]
	s_add_i32 m0, s70, 0x2000
	s_nop 0
	global_load_lds_dwordx4 v168, s[68:69]
	s_waitcnt vmcnt(6)
	s_setprio 1
	s_barrier
	v_mfma_f32_16x16x32_bf16 v[56:59], v[206:209], v[124:127], v[56:59]
	v_mfma_f32_16x16x32_bf16 v[52:55], v[214:217], v[124:127], v[52:55]
	s_add_i32 s68, 0, 0x18000
	v_add_u32_e32 v92, s68, v188
	ds_read_b128 v[80:83], v92
	v_mfma_f32_16x16x32_bf16 v[44:47], v[206:209], v[140:143], v[44:47]
	v_mfma_f32_16x16x32_bf16 v[36:39], v[214:217], v[140:143], v[36:39]
	ds_read_b128 v[84:87], v92 offset:1024
	v_mfma_f32_16x16x32_bf16 v[28:31], v[206:209], v[160:163], v[28:31]
	v_mfma_f32_16x16x32_bf16 v[20:23], v[214:217], v[160:163], v[20:23]
	ds_read_b128 v[88:91], v92 offset:2048
	v_mfma_f32_16x16x32_bf16 v[4:7], v[206:209], v[198:201], v[4:7]
	v_mfma_f32_16x16x32_bf16 v[0:3], v[214:217], v[198:201], v[0:3]
	ds_read_b128 v[92:95], v92 offset:3072
	v_mfma_f32_16x16x32_bf16 v[56:59], v[210:213], v[132:135], v[56:59]
	s_add_u32 s46, s46, 0x80000
	s_addc_u32 s47, s47, 0
	v_mfma_f32_16x16x32_bf16 v[52:55], v[218:221], v[132:135], v[52:55]
	v_mfma_f32_16x16x32_bf16 v[44:47], v[210:213], v[152:155], v[44:47]
	v_mfma_f32_16x16x32_bf16 v[36:39], v[218:221], v[152:155], v[36:39]
	v_mfma_f32_16x16x32_bf16 v[28:31], v[210:213], v[164:167], v[28:31]
	v_mfma_f32_16x16x32_bf16 v[20:23], v[218:221], v[164:167], v[20:23]
	v_mfma_f32_16x16x32_bf16 v[4:7], v[210:213], v[202:205], v[4:7]
	s_mov_b32 m0, s56
	v_mfma_f32_16x16x32_bf16 v[0:3], v[218:221], v[202:205], v[0:3]
	s_barrier
	s_setprio 0
	ds_read_b128 v[124:127], v190 offset:32768
	ds_read_b128 v[132:135], v190 offset:33792
	ds_read_b128 v[160:163], v190 offset:34816
	ds_read_b128 v[164:167], v190 offset:35840
	ds_read_b128 v[198:201], v190 offset:36864
	ds_read_b128 v[202:205], v190 offset:37888
	ds_read_b128 v[206:209], v190 offset:38912
	global_load_lds_dwordx4 v174, s[46:47]
	s_mov_b32 m0, s57
	ds_read_b128 v[210:213], v190 offset:39936
	global_load_lds_dwordx4 v170, s[46:47]
	s_waitcnt lgkmcnt(8)
	s_setprio 1
	s_barrier
	s_waitcnt lgkmcnt(7)
	v_mfma_f32_16x16x32_bf16 v[140:143], v[80:83], v[124:127], v[148:151]
	s_waitcnt lgkmcnt(6)
	v_mfma_f32_16x16x32_bf16 v[148:151], v[84:87], v[132:135], v[140:143]
	v_mfma_f32_16x16x32_bf16 v[140:143], v[88:91], v[124:127], v[144:147]
	s_waitcnt lgkmcnt(5)
	v_mfma_f32_16x16x32_bf16 v[136:139], v[80:83], v[160:163], v[136:139]
	v_mfma_f32_16x16x32_bf16 v[128:131], v[88:91], v[160:163], v[128:131]
	s_waitcnt lgkmcnt(3)
	v_mfma_f32_16x16x32_bf16 v[120:123], v[80:83], v[198:201], v[120:123]
	v_mfma_f32_16x16x32_bf16 v[104:107], v[88:91], v[198:201], v[104:107]
	s_waitcnt lgkmcnt(1)
	v_mfma_f32_16x16x32_bf16 v[76:79], v[80:83], v[206:209], v[76:79]
	v_mfma_f32_16x16x32_bf16 v[72:75], v[88:91], v[206:209], v[72:75]
	s_add_i32 s46, 0, 0x1c000
	v_mfma_f32_16x16x32_bf16 v[144:147], v[92:95], v[132:135], v[140:143]
	v_add_u32_e32 v140, s46, v188
	v_mfma_f32_16x16x32_bf16 v[136:139], v[84:87], v[164:167], v[136:139]
	s_add_i32 s47, s68, s66
	v_mfma_f32_16x16x32_bf16 v[128:131], v[92:95], v[164:167], v[128:131]
	v_mfma_f32_16x16x32_bf16 v[120:123], v[84:87], v[202:205], v[120:123]
	v_mfma_f32_16x16x32_bf16 v[104:107], v[92:95], v[202:205], v[104:107]
	s_waitcnt lgkmcnt(0)
	v_mfma_f32_16x16x32_bf16 v[76:79], v[84:87], v[210:213], v[76:79]
	s_mov_b32 m0, s47
	v_mfma_f32_16x16x32_bf16 v[72:75], v[92:95], v[210:213], v[72:75]
	s_barrier
	s_setprio 0
	ds_read_b128 v[214:217], v140
	ds_read_b128 v[218:221], v140 offset:1024
	ds_read_b128 v[222:225], v140 offset:2048
	ds_read_b128 v[230:233], v140 offset:3072
	v_lshl_add_u64 v[140:141], v[184:185], 0, s[14:15]
	global_load_lds_dwordx4 v[140:141], off
	v_lshl_add_u64 v[140:141], v[194:195], 0, s[14:15]
	s_add_i32 m0, s47, 0x2000
	s_nop 0
	global_load_lds_dwordx4 v[140:141], off
	s_setprio 1
	s_barrier
	s_waitcnt lgkmcnt(1)
	v_mfma_f32_16x16x32_bf16 v[96:99], v[222:225], v[124:127], v[96:99]
	v_mfma_f32_16x16x32_bf16 v[140:143], v[214:217], v[124:127], v[156:159]
	s_waitcnt lgkmcnt(0)
	v_mfma_f32_16x16x32_bf16 v[152:155], v[230:233], v[132:135], v[96:99]
	v_mfma_f32_16x16x32_bf16 v[96:99], v[214:217], v[160:163], v[100:103]
	v_mfma_f32_16x16x32_bf16 v[156:159], v[218:221], v[132:135], v[140:143]
	v_mfma_f32_16x16x32_bf16 v[140:143], v[218:221], v[164:167], v[96:99]
	v_mfma_f32_16x16x32_bf16 v[96:99], v[222:225], v[160:163], v[108:111]
	v_mfma_f32_16x16x32_bf16 v[132:135], v[230:233], v[164:167], v[96:99]
	v_mfma_f32_16x16x32_bf16 v[96:99], v[214:217], v[198:201], v[112:115]
	s_mov_b32 m0, s63
	v_mfma_f32_16x16x32_bf16 v[124:127], v[218:221], v[202:205], v[96:99]
	v_lshl_add_u64 v[184:185], v[226:227], 0, s[14:15]
	v_mfma_f32_16x16x32_bf16 v[96:99], v[222:225], v[198:201], v[116:119]
	v_mfma_f32_16x16x32_bf16 v[68:71], v[214:217], v[206:209], v[68:71]
	v_mfma_f32_16x16x32_bf16 v[64:67], v[222:225], v[206:209], v[64:67]
	v_mfma_f32_16x16x32_bf16 v[116:119], v[230:233], v[202:205], v[96:99]
	v_mfma_f32_16x16x32_bf16 v[68:71], v[218:221], v[210:213], v[68:71]
	v_mfma_f32_16x16x32_bf16 v[64:67], v[230:233], v[210:213], v[64:67]
	s_barrier
	s_setprio 0
	ds_read_b128 v[96:99], v190 offset:49152
	ds_read_b128 v[100:103], v190 offset:50176
	ds_read_b128 v[108:111], v190 offset:51200
	ds_read_b128 v[112:115], v190 offset:52224
	ds_read_b128 v[160:163], v190 offset:53248
	ds_read_b128 v[164:167], v190 offset:54272
	ds_read_b128 v[198:201], v190 offset:55296
	global_load_lds_dwordx4 v[184:185], off
	v_lshl_add_u64 v[184:185], v[234:235], 0, s[14:15]
	s_mov_b32 m0, s4
	ds_read_b128 v[202:205], v190 offset:56320
	global_load_lds_dwordx4 v[184:185], off
	s_waitcnt vmcnt(10)
	s_setprio 1
	s_barrier
; #define PG8_STAGE(bufoff, gbase, voff) do { _Pragma("unroll") for (int _i = 0; _i < 2; ++_i) \
;         __builtin_amdgcn_global_load_lds((const unsigned*)((const char*)(gbase) + (voff)[_i]), (LAS unsigned*)(lds + (bufoff) + ldsw + _i * 8192), 16, 0, 0); } while (0)
; #define PG8_MMA(ai, bj, At, Bt) do { __builtin_amdgcn_s_setprio(1); _Pragma("unroll") for (int m = 0; m < 4; ++m) _Pragma("unroll") for (int n = 0; n < 2; ++n) _Pragma("unroll") for (int k = 0; k < 2; ++k) \
;         acc[ai][bj][m][n] = __builtin_amdgcn_mfma_f32_16x16x32_bf16(Bt[n][k], At[m][k], acc[ai][bj][m][n], 0, 0, 0); __builtin_amdgcn_s_setprio(0); } while (0)
; #define PG8_WAIT_V(n) asm volatile("s_waitcnt vmcnt(" #n ")" ::: "memory")
; #define PG8_WAIT_L(n) asm volatile("s_waitcnt lgkmcnt(" #n ")" ::: "memory")
; #define PG8_BAR __builtin_amdgcn_s_barrier()
; #define PG8_SCHED __builtin_amdgcn_sched_barrier(0)
; template <class Map, class Epi>
; DI void gemm_phase(LAS unsigned char* lds, const Map& MP, const Epi& E, const int nM, const int nN, const int K, const int lda, const int ldb) {
;     ...
;             PG8_BAR; PG8_WAIT_L(0); PG8_MMA(1, 0, At, B0); PG8_BAR; PG8_SCHED;
;             PG8_STAGE(PG8_SB(1, 1), b3 + hstepB, voffB);
;             PG8_WAIT_V(6); PG8_BAR; PG8_MMA(1, 1, At, B1); PG8_BAR;
;         }
	s_waitcnt lgkmcnt(7)
	v_mfma_f32_16x16x32_bf16 v[60:63], v[80:83], v[96:99], v[60:63]
	v_mfma_f32_16x16x32_bf16 v[48:51], v[88:91], v[96:99], v[48:51]
	s_waitcnt lgkmcnt(5)
	v_mfma_f32_16x16x32_bf16 v[40:43], v[80:83], v[108:111], v[40:43]
	v_mfma_f32_16x16x32_bf16 v[32:35], v[88:91], v[108:111], v[32:35]
	s_waitcnt lgkmcnt(3)
	v_mfma_f32_16x16x32_bf16 v[24:27], v[80:83], v[160:163], v[24:27]
	v_mfma_f32_16x16x32_bf16 v[16:19], v[88:91], v[160:163], v[16:19]
	s_waitcnt lgkmcnt(1)
	v_mfma_f32_16x16x32_bf16 v[12:15], v[80:83], v[198:201], v[12:15]
	v_mfma_f32_16x16x32_bf16 v[8:11], v[88:91], v[198:201], v[8:11]
	v_mfma_f32_16x16x32_bf16 v[60:63], v[84:87], v[100:103], v[60:63]
	s_add_u32 s24, s24, 0x80080
	s_addc_u32 s25, s25, 0
	v_mfma_f32_16x16x32_bf16 v[48:51], v[92:95], v[100:103], v[48:51]
	s_add_i32 s46, s46, s66
	v_mfma_f32_16x16x32_bf16 v[40:43], v[84:87], v[112:115], v[40:43]
	v_mfma_f32_16x16x32_bf16 v[32:35], v[92:95], v[112:115], v[32:35]
	v_mfma_f32_16x16x32_bf16 v[24:27], v[84:87], v[164:167], v[24:27]
	v_mfma_f32_16x16x32_bf16 v[16:19], v[92:95], v[164:167], v[16:19]
	s_waitcnt lgkmcnt(0)
	v_mfma_f32_16x16x32_bf16 v[12:15], v[84:87], v[202:205], v[12:15]
	s_mov_b32 m0, s46
	v_mfma_f32_16x16x32_bf16 v[8:11], v[92:95], v[202:205], v[8:11]
	s_barrier
	s_setprio 0
	global_load_lds_dwordx4 v172, s[24:25]
	s_add_i32 m0, s46, 0x2000
	s_nop 0
	global_load_lds_dwordx4 v168, s[24:25]
	s_waitcnt vmcnt(6)
	s_setprio 1
	s_barrier
	v_mfma_f32_16x16x32_bf16 v[56:59], v[214:217], v[96:99], v[56:59]
	v_mfma_f32_16x16x32_bf16 v[52:55], v[222:225], v[96:99], v[52:55]
	ds_read_b128 v[80:83], v189
	v_mfma_f32_16x16x32_bf16 v[44:47], v[214:217], v[108:111], v[44:47]
	v_mfma_f32_16x16x32_bf16 v[36:39], v[222:225], v[108:111], v[36:39]
	ds_read_b128 v[84:87], v189 offset:1024
	v_mfma_f32_16x16x32_bf16 v[28:31], v[214:217], v[160:163], v[28:31]
	v_mfma_f32_16x16x32_bf16 v[20:23], v[222:225], v[160:163], v[20:23]
	ds_read_b128 v[88:91], v189 offset:2048
	v_mfma_f32_16x16x32_bf16 v[4:7], v[214:217], v[198:201], v[4:7]
	v_mfma_f32_16x16x32_bf16 v[0:3], v[222:225], v[198:201], v[0:3]
	ds_read_b128 v[92:95], v189 offset:3072
	v_mfma_f32_16x16x32_bf16 v[56:59], v[218:221], v[100:103], v[56:59]
	s_add_i32 s3, s3, 2
	v_mfma_f32_16x16x32_bf16 v[52:55], v[230:233], v[100:103], v[52:55]
	s_add_u32 vcc_lo, vcc_lo, 0x100
	s_addc_u32 vcc_hi, vcc_hi, 0
	v_mfma_f32_16x16x32_bf16 v[44:47], v[218:221], v[112:115], v[44:47]
	s_add_u32 s42, s42, 0x100
	s_addc_u32 s43, s43, 0
	v_mfma_f32_16x16x32_bf16 v[36:39], v[230:233], v[112:115], v[36:39]
	s_cmp_gt_u32 s3, 29
	v_mfma_f32_16x16x32_bf16 v[28:31], v[218:221], v[164:167], v[28:31]
	v_mfma_f32_16x16x32_bf16 v[20:23], v[230:233], v[164:167], v[20:23]
	v_mfma_f32_16x16x32_bf16 v[4:7], v[218:221], v[202:205], v[4:7]
	v_mfma_f32_16x16x32_bf16 v[0:3], v[230:233], v[202:205], v[0:3]
	s_barrier
	s_setprio 0
	s_cbranch_scc0 .LBB1_1069
; DI float silu_mul(float g, float v) { return g * v * __builtin_amdgcn_rcpf(1.0f + __builtin_amdgcn_exp2f(-LOG2E * g)); }
;     DI void operator()(const f32x4 (&acc)[2][2][4][2], const Unit& u, int wr, int wc, int fr, int fq) const {
;         const int row0 = u.pm * BM + wr * 64 + fr, ch0 = u.pn * 128 + wc * 32 + 8 * fq;
;         f32x4 w0[2], w1[2], w2[2], bb[2];
; #pragma unroll
;         for (int n = 0; n < 2; ++n) { w0[n] = *(const f32x4*)(cw + ch0 + 4 * n); w1[n] = *(const f32x4*)(cw + DFF + ch0 + 4 * n); w2[n] = *(const f32x4*)(cw + 2 * DFF + ch0 + 4 * n); bb[n] = *(const f32x4*)(cb + ch0 + 4 * n); }
; #pragma unroll
;         for (int ai = 0; ai < 2; ++ai)
; #pragma unroll
;             for (int m = 0; m < 4; ++m) {
;                 const bool efirst = (m == 0) && (fr == 0), elast = (m == 3) && (fr == 15);
;                 const int row = row0 + ai * HALF + m * 16;
;                 f32x4 gc[2];
; #pragma unroll
;                 for (int n = 0; n < 2; ++n) {
;                     const f32x4 g = acc[ai][0][m][n];
;                     const f32x4 gprev = acc[ai][0][m > 0 ? m - 1 : 0][n], gnext = acc[ai][0][m < 3 ? m + 1 : 3][n];
;                     f32x4 up, dn;
; #pragma unroll
;                     for (int e = 0; e < 4; ++e) {
;                         const float pu = (m > 0 && fr == 15) ? gprev[e] : g[e];
;                         const float pd = (m < 3 && fr == 0) ? gnext[e] : g[e];
;                         up[e] = dpp_ror1(pu); dn[e] = dpp_ror15(pd);
;                     }
;                     if (efirst) up = (f32x4){0.f, 0.f, 0.f, 0.f};
;                     if (elast) dn = (f32x4){0.f, 0.f, 0.f, 0.f};
;                     gc[n] = w0[n] * up + w1[n] * g + w2[n] * dn + bb[n];
;                 }
;                 if (efirst || elast) {
;                     const size_t eo = (size_t)((row >> 6) * 2 + (elast ? 1 : 0)) * DFF + ch0;
; #pragma unroll
;                     for (int n = 0; n < 2; ++n) { *(f32x4*)(EP + eo + 4 * n) = gc[n]; *(f32x4*)(ER + eo + 4 * n) = acc[ai][0][m][n]; *(f32x4*)(EV + eo + 4 * n) = acc[ai][1][m][n]; }
;                 } else {
;                     const f32x4 v0 = acc[ai][1][m][0], v1 = acc[ai][1][m][1];
;                     u32x4 o;
;                     o[0] = pack2(silu_mul(gc[0][0], v0[0]), silu_mul(gc[0][1], v0[1])); o[1] = pack2(silu_mul(gc[0][2], v0[2]), silu_mul(gc[0][3], v0[3]));
	s_waitcnt lgkmcnt(0)
	s_lshl_b32 s21, s45, 7
	v_mov_b32_e32 v194, v186
	v_mov_b32_e32 v80, v187
	s_or_b32 s21, s21, s62
	v_lshl_add_u32 v184, v80, 3, s21
	v_ashrrev_i32_e32 v185, 31, v184
	v_lshlrev_b64 v[80:81], 2, v[184:185]
	v_lshl_add_u64 v[84:85], s[6:7], 0, v[80:81]
	v_lshl_add_u64 v[88:89], s[16:17], 0, v[80:81]
	v_lshl_add_u64 v[92:93], s[18:19], 0, v[80:81]
	v_lshl_add_u64 v[112:113], s[52:53], 0, v[80:81]
	global_load_dwordx4 v[80:83], v[84:85], off offset:16
	global_load_dwordx4 v[96:99], v[84:85], off
	s_nop 0
	global_load_dwordx4 v[84:87], v[88:89], off offset:16
	global_load_dwordx4 v[100:103], v[88:89], off
	s_nop 0
	global_load_dwordx4 v[88:91], v[92:93], off offset:16
	global_load_dwordx4 v[108:111], v[92:93], off
	s_nop 0
	global_load_dwordx4 v[92:95], v[112:113], off offset:16
	s_nop 0
	global_load_dwordx4 v[112:115], v[112:113], off
	v_cmp_eq_u32_e32 vcc, 0, v194
	s_nop 0
	s_nop 0
	v_cndmask_b32_e32 v161, v148, v136, vcc
	v_cndmask_b32_e32 v162, v149, v137, vcc
	v_cndmask_b32_e32 v163, v150, v138, vcc
	v_mov_b32_dpp v160, v161 row_ror:15 row_mask:0xf bank_mask:0xf
	s_nop 0
	s_nop 0
	v_mov_b32_dpp v161, v162 row_ror:15 row_mask:0xf bank_mask:0xf
	v_mov_b32_dpp v164, v150 row_ror:1 row_mask:0xf bank_mask:0xf
	v_cndmask_b32_e32 v165, v151, v139, vcc
	v_mov_b32_dpp v162, v163 row_ror:15 row_mask:0xf bank_mask:0xf
	v_mov_b32_dpp v195, v151 row_ror:1 row_mask:0xf bank_mask:0xf
	v_mov_b32_dpp v166, v148 row_ror:1 row_mask:0xf bank_mask:0xf
	v_mov_b32_dpp v167, v149 row_ror:1 row_mask:0xf bank_mask:0xf
	v_mov_b32_dpp v163, v165 row_ror:15 row_mask:0xf bank_mask:0xf
	v_cndmask_b32_e64 v165, v195, 0, vcc
	v_cndmask_b32_e64 v164, v164, 0, vcc
	v_cndmask_b32_e64 v167, v167, 0, vcc
	v_cndmask_b32_e64 v166, v166, 0, vcc
	s_nop 0
	s_nop 0
	v_mov_b32_dpp v195, v144 row_ror:1 row_mask:0xf bank_mask:0xf
	v_mov_b32_dpp v196, v145 row_ror:1 row_mask:0xf bank_mask:0xf
	v_mov_b32_dpp v198, v146 row_ror:1 row_mask:0xf bank_mask:0xf
	v_cndmask_b32_e32 v199, v147, v131, vcc
	v_mov_b32_dpp v200, v147 row_ror:1 row_mask:0xf bank_mask:0xf
	v_cndmask_b32_e64 v198, v198, 0, vcc
	v_cndmask_b32_e64 v201, v196, 0, vcc
	s_lshl_b32 s3, s44, 8
	s_add_i32 s3, s3, s49
	v_add_u32_e32 v193, s3, v194
	v_cmp_ne_u32_e64 s[46:47], 0, v194
	s_waitcnt vmcnt(0)
	v_pk_mul_f32 v[164:165], v[98:99], v[164:165]
	v_pk_mul_f32 v[166:167], v[96:97], v[166:167]
	v_pk_fma_f32 v[164:165], v[150:151], v[102:103], v[164:165]
	v_pk_fma_f32 v[166:167], v[148:149], v[100:101], v[166:167]
	v_pk_fma_f32 v[162:163], v[110:111], v[162:163], v[164:165]
	v_cndmask_b32_e32 v165, v144, v128, vcc
	v_pk_fma_f32 v[160:161], v[108:109], v[160:161], v[166:167]
	v_cndmask_b32_e32 v166, v145, v129, vcc
	v_mov_b32_dpp v164, v165 row_ror:15 row_mask:0xf bank_mask:0xf
	v_cndmask_b32_e32 v167, v146, v130, vcc
	v_pk_add_f32 v[162:163], v[114:115], v[162:163]
	v_mov_b32_dpp v165, v166 row_ror:15 row_mask:0xf bank_mask:0xf
	v_pk_add_f32 v[160:161], v[112:113], v[160:161]
	s_nop 0
	v_mov_b32_dpp v166, v167 row_ror:15 row_mask:0xf bank_mask:0xf
	s_nop 1
	v_mov_b32_dpp v167, v199 row_ror:15 row_mask:0xf bank_mask:0xf
	v_cndmask_b32_e64 v199, v200, 0, vcc
	v_cndmask_b32_e64 v200, v195, 0, vcc
	v_pk_mul_f32 v[200:201], v[80:81], v[200:201]
	v_pk_mul_f32 v[198:199], v[82:83], v[198:199]
	v_pk_fma_f32 v[200:201], v[144:145], v[84:85], v[200:201]
	v_pk_fma_f32 v[198:199], v[146:147], v[86:87], v[198:199]
	v_pk_fma_f32 v[164:165], v[88:89], v[164:165], v[200:201]
	v_pk_fma_f32 v[166:167], v[90:91], v[166:167], v[198:199]
	v_pk_add_f32 v[164:165], v[92:93], v[164:165]
	v_pk_add_f32 v[166:167], v[94:95], v[166:167]
	s_and_saveexec_b64 s[24:25], s[46:47]
	s_xor_b64 s[24:25], exec, s[24:25]
	s_cbranch_execz .LBB1_1072
	v_mul_f32_e32 v195, 0xbfb8aa3b, v160
	v_exp_f32_e32 v195, v195
	v_mul_f32_e32 v196, 0xbfb8aa3b, v161
	v_exp_f32_e32 v196, v196
	v_pk_mul_f32 v[160:161], v[156:157], v[160:161]
	v_add_f32_e32 v195, 1.0, v195
	v_rcp_f32_e32 v198, v195
	v_add_f32_e32 v196, 1.0, v196
	v_mul_f32_e32 v195, 0xbfb8aa3b, v162
	v_rcp_f32_e32 v199, v196
	v_exp_f32_e32 v195, v195
	v_mul_f32_e32 v196, 0xbfb8aa3b, v163
	v_exp_f32_e32 v196, v196
	v_pk_mul_f32 v[160:161], v[160:161], v[198:199]
	v_add_f32_e32 v195, 1.0, v195
	v_rcp_f32_e32 v200, v195
	v_add_f32_e32 v195, 1.0, v196
	v_rcp_f32_e32 v201, v195
	v_cvt_pk_bf16_f32 v160, v160, v161
	v_mul_f32_e32 v161, 0xbfb8aa3b, v164
	v_exp_f32_e32 v195, v161
	v_mul_f32_e32 v161, 0xbfb8aa3b, v165
	v_exp_f32_e32 v196, v161
	v_pk_mul_f32 v[162:163], v[158:159], v[162:163]
	v_pk_mul_f32 v[164:165], v[152:153], v[164:165]
	v_pk_mul_f32 v[162:163], v[162:163], v[200:201]
	s_nop 0
	v_cvt_pk_bf16_f32 v161, v162, v163
	v_add_f32_e32 v162, 1.0, v195
	v_mul_f32_e32 v195, 0xbfb8aa3b, v166
	v_add_f32_e32 v163, 1.0, v196
	v_exp_f32_e32 v195, v195
	v_mul_f32_e32 v196, 0xbfb8aa3b, v167
	v_exp_f32_e32 v196, v196
	v_rcp_f32_e32 v162, v162
	v_add_f32_e32 v195, 1.0, v195
	v_rcp_f32_e32 v198, v195
	v_add_f32_e32 v195, 1.0, v196
	v_rcp_f32_e32 v163, v163
	v_rcp_f32_e32 v199, v195
	v_pk_mul_f32 v[166:167], v[154:155], v[166:167]
	v_pk_mul_f32 v[162:163], v[164:165], v[162:163]
	v_pk_mul_f32 v[164:165], v[166:167], v[198:199]
	v_cvt_pk_bf16_f32 v162, v162, v163
	v_cvt_pk_bf16_f32 v163, v164, v165
	v_mov_b64_e32 v[164:165], s[54:55]
	v_mad_i64_i32 v[164:165], s[42:43], v193, s60, v[164:165]
	v_lshl_add_u64 v[164:165], v[184:185], 1, v[164:165]
	global_store_dwordx4 v[164:165], v[160:163], off

;     DI const char* a(const Unit& u) const { return (const char*)(A + (size_t)u.pm * BM * lda); }
;     DI const char* a(const Unit& u) const { return (const char*)(A + (size_t)u.pm * BM * 2048 + (u.pn >> 1) * 512); }
;     DI const char* a(const Unit& u) const { return (const char*)((u.pn < 12 ? A1 : A2) + (size_t)u.pm * BM * 512); }
; #define PG8_STAGE(bufoff, gbase, voff) do { _Pragma("unroll") for (int _i = 0; _i < 2; ++_i) \
;         __builtin_amdgcn_global_load_lds((const unsigned*)((const char*)(gbase) + (voff)[_i]), (LAS unsigned*)(lds + (bufoff) + ldsw + _i * 8192), 16, 0, 0); } while (0)
; #define PG8_LDA(dst, b, h) do { _Pragma("unroll") for (int m = 0; m < 4; ++m) _Pragma("unroll") for (int k = 0; k < 2; ++k) dst[m][k] = *(const LAS bf16x8*)(lds + PG8_SA(b, h) + aoff + m * 2048 + k * 1024); } while (0)
; #define PG8_LDB(dst, b, h) do { _Pragma("unroll") for (int n = 0; n < 2; ++n) _Pragma("unroll") for (int k = 0; k < 2; ++k) dst[n][k] = *(const LAS bf16x8*)(lds + PG8_SB(b, h) + boff + n * 2048 + k * 1024); } while (0)
; template <class Map, class Epi>
; DI void gemm_phase(LAS unsigned char* lds, const Map& MP, const Epi& E, const int nM, const int nN, const int K, const int lda, const int ldb) {
;     ...
;     for (;;) {
;         const bool has_next = sched_next(ui + 1, nM, nN, G, cblk, nxt);
;         const char* nA = has_next ? MP.a(nxt) : cA; const char* nB = has_next ? MP.b(nxt) : cB;
;         for (int t = 0; t < nt; t += 2) {
;             const bool last = (t == nt - 2);
;             const char* a1 = cA + (size_t)(t + 1) * kstep;
;             const char* a2 = last ? nA : cA + (size_t)(t + 2) * kstep; const char* b2 = last ? nB : cB + (size_t)(t + 2) * kstep;
;             const char* a3 = a2 + kstep; const char* b3 = b2 + kstep;
;             PG8_LDB(B0, 0, 0); PG8_SCHED; PG8_LDA(At, 0, 0); PG8_STAGE(PG8_SA(1, 1), a1 + hstepA, voffA);
;             PG8_WAIT_L(8); PG8_BAR; PG8_WAIT_L(0); PG8_MMA(0, 0, At, B0); PG8_BAR; PG8_SCHED;
;             PG8_LDB(B1, 0, 1); PG8_STAGE(PG8_SB(0, 0), b2, voffB);
;             PG8_BAR; PG8_WAIT_L(0); PG8_MMA(0, 1, At, B1); PG8_BAR;
;             PG8_LDA(At, 0, 1); PG8_STAGE(PG8_SA(0, 0), a2, voffA);
;             PG8_BAR; PG8_WAIT_L(0); PG8_MMA(1, 0, At, B0); PG8_BAR; PG8_SCHED;
;             PG8_STAGE(PG8_SB(0, 1), b2 + hstepB, voffB);
;             PG8_WAIT_V(6); PG8_BAR; PG8_MMA(1, 1, At, B1); PG8_BAR;
.LBB1_1239:
	s_add_u32 s10, s8, 0x100
	s_addc_u32 s11, s9, 0
	s_cmpk_eq_i32 s3, 0x54
	s_cselect_b32 s15, s43, s11
	s_cselect_b32 s14, s42, s10
	s_cselect_b32 s13, s7, s38
	s_cselect_b32 s12, s6, s5
	s_add_i32 m0, s24, 0xc000
	ds_read_b128 v[168:171], v150
	ds_read_b128 v[172:175], v150 offset:1024
	ds_read_b128 v[176:179], v150 offset:2048
	ds_read_b128 v[180:183], v150 offset:3072
	ds_read_b128 v[184:187], v150 offset:4096
	ds_read_b128 v[188:191], v150 offset:5120
	ds_read_b128 v[192:195], v150 offset:6144
	ds_read_b128 v[198:201], v150 offset:7168
	global_load_lds_dwordx4 v138, s[8:9]
	s_add_i32 m0, s24, 0xe000
	s_nop 0
	global_load_lds_dwordx4 v136, s[8:9]
	s_waitcnt lgkmcnt(8)
	s_setprio 1
	s_barrier
	s_waitcnt lgkmcnt(7)
	v_mfma_f32_16x16x32_bf16 v[124:127], v[152:155], v[168:171], v[124:127]
	v_mfma_f32_16x16x32_bf16 v[120:123], v[160:163], v[168:171], v[120:123]
	s_waitcnt lgkmcnt(5)
	v_mfma_f32_16x16x32_bf16 v[108:111], v[152:155], v[176:179], v[108:111]
	v_mfma_f32_16x16x32_bf16 v[104:107], v[160:163], v[176:179], v[104:107]
	s_waitcnt lgkmcnt(3)
	v_mfma_f32_16x16x32_bf16 v[92:95], v[152:155], v[184:187], v[92:95]
	v_mfma_f32_16x16x32_bf16 v[88:91], v[160:163], v[184:187], v[88:91]
	s_waitcnt lgkmcnt(1)
	v_mfma_f32_16x16x32_bf16 v[76:79], v[152:155], v[192:195], v[76:79]
	v_mfma_f32_16x16x32_bf16 v[72:75], v[160:163], v[192:195], v[72:75]
	v_mfma_f32_16x16x32_bf16 v[124:127], v[156:159], v[172:175], v[124:127]
	s_add_i32 s8, s35, s22
	v_mfma_f32_16x16x32_bf16 v[120:123], v[164:167], v[172:175], v[120:123]
	v_lshl_add_u64 v[144:145], s[12:13], 0, v[132:133]
	v_mfma_f32_16x16x32_bf16 v[108:111], v[156:159], v[180:183], v[108:111]
	v_lshl_add_u64 v[218:219], s[12:13], 0, v[128:129]
	v_mfma_f32_16x16x32_bf16 v[104:107], v[164:167], v[180:183], v[104:107]
	v_mfma_f32_16x16x32_bf16 v[92:95], v[156:159], v[188:191], v[92:95]
	v_mfma_f32_16x16x32_bf16 v[88:91], v[164:167], v[188:191], v[88:91]
	s_waitcnt lgkmcnt(0)
	v_mfma_f32_16x16x32_bf16 v[76:79], v[156:159], v[198:201], v[76:79]
	s_mov_b32 m0, s8
	v_mfma_f32_16x16x32_bf16 v[72:75], v[164:167], v[198:201], v[72:75]
	s_barrier
	s_setprio 0
	ds_read_b128 v[202:205], v151
	ds_read_b128 v[206:209], v151 offset:1024
	ds_read_b128 v[210:213], v151 offset:2048
	global_load_lds_dwordx4 v[144:145], off
	s_add_i32 m0, s8, 0x2000
	ds_read_b128 v[214:217], v151 offset:3072
	global_load_lds_dwordx4 v[218:219], off
	s_setprio 1
	s_barrier
	s_waitcnt lgkmcnt(3)
	v_mfma_f32_16x16x32_bf16 v[116:119], v[202:205], v[168:171], v[116:119]
	s_waitcnt lgkmcnt(1)
	v_mfma_f32_16x16x32_bf16 v[112:115], v[210:213], v[168:171], v[112:115]
	v_mfma_f32_16x16x32_bf16 v[100:103], v[202:205], v[176:179], v[100:103]
	v_mfma_f32_16x16x32_bf16 v[96:99], v[210:213], v[176:179], v[96:99]
	v_mfma_f32_16x16x32_bf16 v[84:87], v[202:205], v[184:187], v[84:87]
	v_mfma_f32_16x16x32_bf16 v[80:83], v[210:213], v[184:187], v[80:83]
	v_mfma_f32_16x16x32_bf16 v[68:71], v[202:205], v[192:195], v[68:71]
	v_mfma_f32_16x16x32_bf16 v[64:67], v[210:213], v[192:195], v[64:67]
	v_mfma_f32_16x16x32_bf16 v[116:119], v[206:209], v[172:175], v[116:119]
	v_lshl_add_u64 v[222:223], s[14:15], 0, v[130:131]
	s_mov_b32 m0, s24
	s_waitcnt lgkmcnt(0)
	v_mfma_f32_16x16x32_bf16 v[112:115], v[214:217], v[172:175], v[112:115]
	v_lshl_add_u64 v[220:221], s[14:15], 0, v[134:135]
	v_mfma_f32_16x16x32_bf16 v[100:103], v[206:209], v[180:183], v[100:103]
	v_mfma_f32_16x16x32_bf16 v[96:99], v[214:217], v[180:183], v[96:99]
	v_mfma_f32_16x16x32_bf16 v[84:87], v[206:209], v[188:191], v[84:87]
	v_mfma_f32_16x16x32_bf16 v[80:83], v[214:217], v[188:191], v[80:83]
	v_mfma_f32_16x16x32_bf16 v[68:71], v[206:209], v[198:201], v[68:71]
	v_mfma_f32_16x16x32_bf16 v[64:67], v[214:217], v[198:201], v[64:67]
	s_barrier
	s_setprio 0
	ds_read_b128 v[168:171], v150 offset:16384
	ds_read_b128 v[172:175], v150 offset:17408
	ds_read_b128 v[176:179], v150 offset:18432
	ds_read_b128 v[180:183], v150 offset:19456
	ds_read_b128 v[184:187], v150 offset:20480
	ds_read_b128 v[188:191], v150 offset:21504
	ds_read_b128 v[192:195], v150 offset:22528
	global_load_lds_dwordx4 v[220:221], off
	s_mov_b32 m0, s25
	ds_read_b128 v[198:201], v150 offset:23552
	global_load_lds_dwordx4 v[222:223], off
	s_waitcnt vmcnt(10)
	s_setprio 1
	s_barrier
	s_waitcnt lgkmcnt(7)
	v_mfma_f32_16x16x32_bf16 v[60:63], v[152:155], v[168:171], v[60:63]
	v_mfma_f32_16x16x32_bf16 v[56:59], v[160:163], v[168:171], v[56:59]
	s_waitcnt lgkmcnt(5)
	v_mfma_f32_16x16x32_bf16 v[44:47], v[152:155], v[176:179], v[44:47]
	v_mfma_f32_16x16x32_bf16 v[40:43], v[160:163], v[176:179], v[40:43]
	s_waitcnt lgkmcnt(3)
	v_mfma_f32_16x16x32_bf16 v[28:31], v[152:155], v[184:187], v[28:31]
	v_mfma_f32_16x16x32_bf16 v[24:27], v[160:163], v[184:187], v[24:27]
	s_waitcnt lgkmcnt(1)
	v_mfma_f32_16x16x32_bf16 v[12:15], v[152:155], v[192:195], v[12:15]
	v_mfma_f32_16x16x32_bf16 v[8:11], v[160:163], v[192:195], v[8:11]
	v_mfma_f32_16x16x32_bf16 v[60:63], v[156:159], v[172:175], v[60:63]
	s_add_u32 s8, s12, 0x160000
	s_addc_u32 s9, s13, 0
	v_mfma_f32_16x16x32_bf16 v[56:59], v[164:167], v[172:175], v[56:59]
	s_add_i32 s39, s36, s22
	v_mfma_f32_16x16x32_bf16 v[44:47], v[156:159], v[180:183], v[44:47]
	v_mfma_f32_16x16x32_bf16 v[40:43], v[164:167], v[180:183], v[40:43]
	v_mfma_f32_16x16x32_bf16 v[28:31], v[156:159], v[188:191], v[28:31]
	v_mfma_f32_16x16x32_bf16 v[24:27], v[164:167], v[188:191], v[24:27]
	s_waitcnt lgkmcnt(0)
	v_mfma_f32_16x16x32_bf16 v[12:15], v[156:159], v[198:201], v[12:15]
	s_mov_b32 m0, s39
	v_mfma_f32_16x16x32_bf16 v[8:11], v[164:167], v[198:201], v[8:11]
	s_barrier
; #define PG8_STAGE(bufoff, gbase, voff) do { _Pragma("unroll") for (int _i = 0; _i < 2; ++_i) \
;         __builtin_amdgcn_global_load_lds((const unsigned*)((const char*)(gbase) + (voff)[_i]), (LAS unsigned*)(lds + (bufoff) + ldsw + _i * 8192), 16, 0, 0); } while (0)
; #define PG8_LDA(dst, b, h) do { _Pragma("unroll") for (int m = 0; m < 4; ++m) _Pragma("unroll") for (int k = 0; k < 2; ++k) dst[m][k] = *(const LAS bf16x8*)(lds + PG8_SA(b, h) + aoff + m * 2048 + k * 1024); } while (0)
; #define PG8_LDB(dst, b, h) do { _Pragma("unroll") for (int n = 0; n < 2; ++n) _Pragma("unroll") for (int k = 0; k < 2; ++k) dst[n][k] = *(const LAS bf16x8*)(lds + PG8_SB(b, h) + boff + n * 2048 + k * 1024); } while (0)
; #define PG8_MMA(ai, bj, At, Bt) do { __builtin_amdgcn_s_setprio(1); _Pragma("unroll") for (int m = 0; m < 4; ++m) _Pragma("unroll") for (int n = 0; n < 2; ++n) _Pragma("unroll") for (int k = 0; k < 2; ++k) \
;         acc[ai][bj][m][n] = __builtin_amdgcn_mfma_f32_16x16x32_bf16(Bt[n][k], At[m][k], acc[ai][bj][m][n], 0, 0, 0); __builtin_amdgcn_s_setprio(0); } while (0)
; #define PG8_WAIT_V(n) asm volatile("s_waitcnt vmcnt(" #n ")" ::: "memory")
; #define PG8_WAIT_L(n) asm volatile("s_waitcnt lgkmcnt(" #n ")" ::: "memory")
; #define PG8_BAR __builtin_amdgcn_s_barrier()
; #define PG8_SCHED __builtin_amdgcn_sched_barrier(0)
; template <class Map, class Epi>
; DI void gemm_phase(LAS unsigned char* lds, const Map& MP, const Epi& E, const int nM, const int nN, const int K, const int lda, const int ldb) {
;     ...
;             PG8_BAR; PG8_WAIT_L(0); PG8_MMA(1, 0, At, B0); PG8_BAR; PG8_SCHED;
;             PG8_STAGE(PG8_SB(0, 1), b2 + hstepB, voffB);
;             PG8_WAIT_V(6); PG8_BAR; PG8_MMA(1, 1, At, B1); PG8_BAR;
;             PG8_LDB(B0, 1, 0); PG8_SCHED; PG8_LDA(At, 1, 0); PG8_STAGE(PG8_SA(0, 1), a2 + hstepA, voffA);
;             PG8_WAIT_L(8); PG8_BAR; PG8_WAIT_L(0); PG8_MMA(0, 0, At, B0); PG8_BAR; PG8_SCHED;
;             PG8_LDB(B1, 1, 1); PG8_STAGE(PG8_SB(1, 0), b3, voffB);
;             PG8_BAR; PG8_WAIT_L(0); PG8_MMA(0, 1, At, B1); PG8_BAR;
;             PG8_LDA(At, 1, 1); PG8_STAGE(PG8_SA(1, 0), a3, voffA);
;             PG8_BAR; PG8_WAIT_L(0); PG8_MMA(1, 0, At, B0); PG8_BAR; PG8_SCHED;
;             PG8_STAGE(PG8_SB(1, 1), b3 + hstepB, voffB);
;             PG8_WAIT_V(6); PG8_BAR; PG8_MMA(1, 1, At, B1); PG8_BAR;
	s_setprio 0
	global_load_lds_dwordx4 v132, s[8:9]
	s_add_i32 m0, s39, 0x2000
	s_nop 0
	global_load_lds_dwordx4 v128, s[8:9]
	s_waitcnt vmcnt(6)
	s_setprio 1
	s_barrier
	v_mfma_f32_16x16x32_bf16 v[52:55], v[202:205], v[168:171], v[52:55]
	v_mfma_f32_16x16x32_bf16 v[48:51], v[210:213], v[168:171], v[48:51]
	s_add_i32 s39, 0, 0x18000
	v_add_u32_e32 v164, s39, v148
	ds_read_b128 v[152:155], v164
	v_mfma_f32_16x16x32_bf16 v[36:39], v[202:205], v[176:179], v[36:39]
	v_mfma_f32_16x16x32_bf16 v[32:35], v[210:213], v[176:179], v[32:35]
	ds_read_b128 v[156:159], v164 offset:1024
	v_mfma_f32_16x16x32_bf16 v[20:23], v[202:205], v[184:187], v[20:23]
	v_mfma_f32_16x16x32_bf16 v[16:19], v[210:213], v[184:187], v[16:19]
	ds_read_b128 v[160:163], v164 offset:2048
	v_mfma_f32_16x16x32_bf16 v[4:7], v[202:205], v[192:195], v[4:7]
	v_mfma_f32_16x16x32_bf16 v[0:3], v[210:213], v[192:195], v[0:3]
	ds_read_b128 v[164:167], v164 offset:3072
	v_mfma_f32_16x16x32_bf16 v[52:55], v[206:209], v[172:175], v[52:55]
	s_add_u32 s8, s14, 0x160000
	s_addc_u32 s9, s15, 0
	v_mfma_f32_16x16x32_bf16 v[48:51], v[214:217], v[172:175], v[48:51]
	v_mfma_f32_16x16x32_bf16 v[36:39], v[206:209], v[180:183], v[36:39]
	v_mfma_f32_16x16x32_bf16 v[32:35], v[214:217], v[180:183], v[32:35]
	v_mfma_f32_16x16x32_bf16 v[20:23], v[206:209], v[188:191], v[20:23]
	v_mfma_f32_16x16x32_bf16 v[16:19], v[214:217], v[188:191], v[16:19]
	v_mfma_f32_16x16x32_bf16 v[4:7], v[206:209], v[198:201], v[4:7]
	s_mov_b32 m0, s26
	v_mfma_f32_16x16x32_bf16 v[0:3], v[214:217], v[198:201], v[0:3]
	s_barrier
	s_setprio 0
	ds_read_b128 v[168:171], v150 offset:32768
	ds_read_b128 v[172:175], v150 offset:33792
	ds_read_b128 v[176:179], v150 offset:34816
	ds_read_b128 v[180:183], v150 offset:35840
	ds_read_b128 v[184:187], v150 offset:36864
	ds_read_b128 v[188:191], v150 offset:37888
	ds_read_b128 v[192:195], v150 offset:38912
	global_load_lds_dwordx4 v134, s[8:9]
	s_mov_b32 m0, s27
	ds_read_b128 v[198:201], v150 offset:39936
	global_load_lds_dwordx4 v130, s[8:9]
	s_waitcnt lgkmcnt(8)
	s_setprio 1
	s_barrier
	s_waitcnt lgkmcnt(7)
	v_mfma_f32_16x16x32_bf16 v[124:127], v[152:155], v[168:171], v[124:127]
	v_mfma_f32_16x16x32_bf16 v[120:123], v[160:163], v[168:171], v[120:123]
	s_waitcnt lgkmcnt(5)
	v_mfma_f32_16x16x32_bf16 v[108:111], v[152:155], v[176:179], v[108:111]
	v_mfma_f32_16x16x32_bf16 v[104:107], v[160:163], v[176:179], v[104:107]
	s_waitcnt lgkmcnt(3)
	v_mfma_f32_16x16x32_bf16 v[92:95], v[152:155], v[184:187], v[92:95]
	v_mfma_f32_16x16x32_bf16 v[88:91], v[160:163], v[184:187], v[88:91]
	s_waitcnt lgkmcnt(1)
	v_mfma_f32_16x16x32_bf16 v[76:79], v[152:155], v[192:195], v[76:79]
	v_mfma_f32_16x16x32_bf16 v[72:75], v[160:163], v[192:195], v[72:75]
	v_mfma_f32_16x16x32_bf16 v[124:127], v[156:159], v[172:175], v[124:127]
	s_add_i32 s14, 0, 0x1c000
	v_mfma_f32_16x16x32_bf16 v[120:123], v[164:167], v[172:175], v[120:123]
	s_add_i32 s8, s39, s22
	v_mfma_f32_16x16x32_bf16 v[108:111], v[156:159], v[180:183], v[108:111]
	v_add_u32_e32 v196, s14, v148
	v_mfma_f32_16x16x32_bf16 v[104:107], v[164:167], v[180:183], v[104:107]
	v_lshl_add_u64 v[144:145], v[144:145], 0, s[52:53]
	v_mfma_f32_16x16x32_bf16 v[92:95], v[156:159], v[188:191], v[92:95]
	v_mfma_f32_16x16x32_bf16 v[88:91], v[164:167], v[188:191], v[88:91]
	s_waitcnt lgkmcnt(0)
	v_mfma_f32_16x16x32_bf16 v[76:79], v[156:159], v[198:201], v[76:79]
	s_mov_b32 m0, s8
	v_mfma_f32_16x16x32_bf16 v[72:75], v[164:167], v[198:201], v[72:75]
	s_barrier
	s_setprio 0
	ds_read_b128 v[202:205], v196
	ds_read_b128 v[206:209], v196 offset:1024
	ds_read_b128 v[210:213], v196 offset:2048
	global_load_lds_dwordx4 v[144:145], off
	v_lshl_add_u64 v[144:145], v[218:219], 0, s[52:53]
	s_add_i32 m0, s8, 0x2000
	ds_read_b128 v[214:217], v196 offset:3072
	global_load_lds_dwordx4 v[144:145], off
	s_setprio 1
	s_barrier
	s_waitcnt lgkmcnt(3)
	v_mfma_f32_16x16x32_bf16 v[116:119], v[202:205], v[168:171], v[116:119]
	s_waitcnt lgkmcnt(1)
	v_mfma_f32_16x16x32_bf16 v[112:115], v[210:213], v[168:171], v[112:115]
	v_mfma_f32_16x16x32_bf16 v[100:103], v[202:205], v[176:179], v[100:103]
	v_mfma_f32_16x16x32_bf16 v[96:99], v[210:213], v[176:179], v[96:99]
	v_mfma_f32_16x16x32_bf16 v[84:87], v[202:205], v[184:187], v[84:87]
	v_mfma_f32_16x16x32_bf16 v[80:83], v[210:213], v[184:187], v[80:83]
	v_mfma_f32_16x16x32_bf16 v[68:71], v[202:205], v[192:195], v[68:71]
	v_mfma_f32_16x16x32_bf16 v[64:67], v[210:213], v[192:195], v[64:67]
	v_mfma_f32_16x16x32_bf16 v[116:119], v[206:209], v[172:175], v[116:119]
	s_mov_b32 m0, s30
	s_waitcnt lgkmcnt(0)
	v_mfma_f32_16x16x32_bf16 v[112:115], v[214:217], v[172:175], v[112:115]
	v_lshl_add_u64 v[144:145], v[220:221], 0, s[52:53]
	v_mfma_f32_16x16x32_bf16 v[100:103], v[206:209], v[180:183], v[100:103]
	v_mfma_f32_16x16x32_bf16 v[96:99], v[214:217], v[180:183], v[96:99]
	v_mfma_f32_16x16x32_bf16 v[84:87], v[206:209], v[188:191], v[84:87]
	v_mfma_f32_16x16x32_bf16 v[80:83], v[214:217], v[188:191], v[80:83]
	v_mfma_f32_16x16x32_bf16 v[68:71], v[206:209], v[198:201], v[68:71]
	v_mfma_f32_16x16x32_bf16 v[64:67], v[214:217], v[198:201], v[64:67]
	s_barrier
	s_setprio 0
	ds_read_b128 v[168:171], v150 offset:49152
	ds_read_b128 v[172:175], v150 offset:50176
	ds_read_b128 v[176:179], v150 offset:51200
	ds_read_b128 v[180:183], v150 offset:52224
	ds_read_b128 v[184:187], v150 offset:53248
	ds_read_b128 v[188:191], v150 offset:54272
	ds_read_b128 v[192:195], v150 offset:55296
	global_load_lds_dwordx4 v[144:145], off
	v_lshl_add_u64 v[144:145], v[222:223], 0, s[52:53]
	s_mov_b32 m0, s31
	ds_read_b128 v[198:201], v150 offset:56320
	global_load_lds_dwordx4 v[144:145], off
	s_waitcnt vmcnt(10)
	s_setprio 1
	s_barrier
; DI unsigned pack2(float a, float b) { f32x2 v = {a, b}; hwbf16x2 r = __builtin_convertvector(v, hwbf16x2); return __builtin_bit_cast(unsigned, r); }
; DI float bflo(unsigned w) { return __uint_as_float(w << 16); }
; DI float bfhi(unsigned w) { return __uint_as_float(w & 0xffff0000u); }
; #define PG8_WAIT_V(n) asm volatile("s_waitcnt vmcnt(" #n ")" ::: "memory")
;     DI void operator()(const f32x4 (&acc)[2][2][4][2], const Unit& u, int wr, int wc, int fr, int fq) const {
;         const int row0 = u.pm * BM + wr * 64 + fr, col0 = u.pn * BM + wc * 32 + 8 * fq;
;         f32x4 sc[2][2];
; #pragma unroll
;         for (int bj = 0; bj < 2; ++bj)
; #pragma unroll
;             for (int n = 0; n < 2; ++n) sc[bj][n] = scale ? *(const f32x4*)(scale + col0 + bj * HALF + 4 * n) : (f32x4){1.f, 1.f, 1.f, 1.f};
; #pragma unroll
;         for (int ai = 0; ai < 2; ++ai)
; #pragma unroll
;             for (int m = 0; m < 4; ++m) { const size_t ro = (size_t)(row0 + ai * HALF + m * 16) * D + col0;
; #pragma unroll
;                 for (int bj = 0; bj < 2; ++bj) {
;                     f32x4 x0, x1;
;                     if constexpr (IB) { const u32x4 w = *(const u32x4*)((const bf16_t*)Xin + ro + bj * HALF);
;                         x0 = (f32x4){bflo(w[0]), bfhi(w[0]), bflo(w[1]), bfhi(w[1])}; x1 = (f32x4){bflo(w[2]), bfhi(w[2]), bflo(w[3]), bfhi(w[3])}; }
;                     else { x0 = *(const f32x4*)((const float*)Xin + ro + bj * HALF); x1 = *(const f32x4*)((const float*)Xin + ro + bj * HALF + 4); }
;                     x0 += acc[ai][bj][m][0] * sc[bj][0]; x1 += acc[ai][bj][m][1] * sc[bj][1];
;                     if constexpr (OB) { u32x4 o; o[0] = pack2(x0[0], x0[1]); o[1] = pack2(x0[2], x0[3]); o[2] = pack2(x1[0], x1[1]); o[3] = pack2(x1[2], x1[3]);
;                         *(u32x4*)((bf16_t*)Xout + ro + bj * HALF) = o; }
;                     else { *(f32x4*)((float*)Xout + ro + bj * HALF) = x0; *(f32x4*)((float*)Xout + ro + bj * HALF + 4) = x1; } } }
; template <class Map, class Epi>
; DI void gemm_phase(LAS unsigned char* lds, const Map& MP, const Epi& E, const int nM, const int nN, const int K, const int lda, const int ldb) {
;     ...
;             PG8_BAR; PG8_WAIT_L(0); PG8_MMA(1, 0, At, B0); PG8_BAR; PG8_SCHED;
;             PG8_STAGE(PG8_SB(1, 1), b3 + hstepB, voffB);
;             PG8_WAIT_V(6); PG8_BAR; PG8_MMA(1, 1, At, B1); PG8_BAR;
;         }
	s_waitcnt lgkmcnt(7)
	v_mfma_f32_16x16x32_bf16 v[60:63], v[152:155], v[168:171], v[60:63]
	v_mfma_f32_16x16x32_bf16 v[56:59], v[160:163], v[168:171], v[56:59]
	s_waitcnt lgkmcnt(5)
	v_mfma_f32_16x16x32_bf16 v[44:47], v[152:155], v[176:179], v[44:47]
	v_mfma_f32_16x16x32_bf16 v[40:43], v[160:163], v[176:179], v[40:43]
	s_waitcnt lgkmcnt(3)
	v_mfma_f32_16x16x32_bf16 v[28:31], v[152:155], v[184:187], v[28:31]
	v_mfma_f32_16x16x32_bf16 v[24:27], v[160:163], v[184:187], v[24:27]
	s_waitcnt lgkmcnt(1)
	v_mfma_f32_16x16x32_bf16 v[12:15], v[152:155], v[192:195], v[12:15]
	v_mfma_f32_16x16x32_bf16 v[8:11], v[160:163], v[192:195], v[8:11]
	v_mfma_f32_16x16x32_bf16 v[60:63], v[156:159], v[172:175], v[60:63]
	s_add_u32 s8, s12, 0x160080
	s_addc_u32 s9, s13, 0
	v_mfma_f32_16x16x32_bf16 v[56:59], v[164:167], v[172:175], v[56:59]
	s_add_i32 s12, s14, s22
	v_mfma_f32_16x16x32_bf16 v[44:47], v[156:159], v[180:183], v[44:47]
	v_mfma_f32_16x16x32_bf16 v[40:43], v[164:167], v[180:183], v[40:43]
	v_mfma_f32_16x16x32_bf16 v[28:31], v[156:159], v[188:191], v[28:31]
	v_mfma_f32_16x16x32_bf16 v[24:27], v[164:167], v[188:191], v[24:27]
	s_waitcnt lgkmcnt(0)
	v_mfma_f32_16x16x32_bf16 v[12:15], v[156:159], v[198:201], v[12:15]
	s_mov_b32 m0, s12
	v_mfma_f32_16x16x32_bf16 v[8:11], v[164:167], v[198:201], v[8:11]
	s_barrier
	s_setprio 0
	global_load_lds_dwordx4 v132, s[8:9]
	s_add_i32 m0, s12, 0x2000
	s_nop 0
	global_load_lds_dwordx4 v128, s[8:9]
	s_waitcnt vmcnt(6)
	s_setprio 1
	s_barrier
	v_mfma_f32_16x16x32_bf16 v[52:55], v[202:205], v[168:171], v[52:55]
	v_mfma_f32_16x16x32_bf16 v[48:51], v[210:213], v[168:171], v[48:51]
	ds_read_b128 v[152:155], v149
	v_mfma_f32_16x16x32_bf16 v[36:39], v[202:205], v[176:179], v[36:39]
	v_mfma_f32_16x16x32_bf16 v[32:35], v[210:213], v[176:179], v[32:35]
	ds_read_b128 v[156:159], v149 offset:1024
	v_mfma_f32_16x16x32_bf16 v[20:23], v[202:205], v[184:187], v[20:23]
	v_mfma_f32_16x16x32_bf16 v[16:19], v[210:213], v[184:187], v[16:19]
	ds_read_b128 v[160:163], v149 offset:2048
	v_mfma_f32_16x16x32_bf16 v[4:7], v[202:205], v[192:195], v[4:7]
	v_mfma_f32_16x16x32_bf16 v[0:3], v[210:213], v[192:195], v[0:3]
	ds_read_b128 v[164:167], v149 offset:3072
	v_mfma_f32_16x16x32_bf16 v[52:55], v[206:209], v[172:175], v[52:55]
	s_add_i32 s3, s3, 2
	v_mfma_f32_16x16x32_bf16 v[48:51], v[214:217], v[172:175], v[48:51]
	s_add_u32 s5, s5, 0x100
	s_addc_u32 s38, s38, 0
	v_mfma_f32_16x16x32_bf16 v[36:39], v[206:209], v[180:183], v[36:39]
	s_cmpk_gt_u32 s3, 0x55
	v_mfma_f32_16x16x32_bf16 v[32:35], v[214:217], v[180:183], v[32:35]
	s_mov_b64 s[8:9], s[10:11]
	v_mfma_f32_16x16x32_bf16 v[20:23], v[206:209], v[188:191], v[20:23]
	v_mfma_f32_16x16x32_bf16 v[16:19], v[214:217], v[188:191], v[16:19]
	v_mfma_f32_16x16x32_bf16 v[4:7], v[206:209], v[198:201], v[4:7]
	v_mfma_f32_16x16x32_bf16 v[0:3], v[214:217], v[198:201], v[0:3]
	s_barrier
	s_setprio 0
	s_cbranch_scc0 .LBB1_1239
	s_waitcnt lgkmcnt(0)
	v_mov_b32_e32 v152, v147
	v_mov_b32_e32 v144, v146
	s_lshl_b32 s2, s2, 8
	s_add_i32 s2, s2, s29
	s_lshl_b32 s3, s4, 8
	v_add_u32_e32 v152, s2, v152
	s_or_b32 s3, s3, s54
	v_ashrrev_i32_e32 v153, 31, v152
	v_lshl_add_u32 v144, v144, 3, s3
	v_lshlrev_b64 v[152:153], 12, v[152:153]
	v_ashrrev_i32_e32 v145, 31, v144
	v_lshl_add_u64 v[152:153], s[46:47], 0, v[152:153]
	v_lshl_add_u64 v[144:145], v[144:145], 1, v[152:153]
	global_load_dwordx4 v[160:163], v[144:145], off
	global_load_dwordx4 v[164:167], v[144:145], off offset:256
	s_mov_b64 s[98:99], 0x10000
	v_lshl_add_u64 v[154:155], v[144:145], 0, s[98:99]
	global_load_dwordx4 v[168:171], v[154:155], off
	global_load_dwordx4 v[172:175], v[154:155], off offset:256
	s_mov_b64 s[98:99], 0x20000
	v_lshl_add_u64 v[154:155], v[144:145], 0, s[98:99]
	global_load_dwordx4 v[176:179], v[154:155], off
	global_load_dwordx4 v[180:183], v[154:155], off offset:256
	s_mov_b64 s[98:99], 0x30000
	v_lshl_add_u64 v[154:155], v[144:145], 0, s[98:99]
	global_load_dwordx4 v[184:187], v[154:155], off
	global_load_dwordx4 v[188:191], v[154:155], off offset:256
	s_mov_b64 s[98:99], 0x80000
	v_lshl_add_u64 v[154:155], v[144:145], 0, s[98:99]
	global_load_dwordx4 v[192:195], v[154:155], off
	global_load_dwordx4 v[198:201], v[154:155], off offset:256
	s_mov_b64 s[98:99], 0x90000
	v_lshl_add_u64 v[154:155], v[144:145], 0, s[98:99]
	global_load_dwordx4 v[202:205], v[154:155], off
	global_load_dwordx4 v[206:209], v[154:155], off offset:256
	s_mov_b64 s[98:99], 0xa0000
	v_lshl_add_u64 v[154:155], v[144:145], 0, s[98:99]
	global_load_dwordx4 v[210:213], v[154:155], off
	global_load_dwordx4 v[214:217], v[154:155], off offset:256
	s_mov_b64 s[98:99], 0xb0000
	v_lshl_add_u64 v[154:155], v[144:145], 0, s[98:99]
	global_load_dwordx4 v[248:251], v[154:155], off
	global_load_dwordx4 v[252:255], v[154:155], off offset:256
	s_waitcnt vmcnt(15)
	s_nop 1
	v_mov_b32_e32 v152, v160
	v_mov_b32_e32 v153, v161
	v_mov_b32_e32 v154, v162
	v_mov_b32_e32 v155, v163
	s_mov_b64 s[2:3], 0x10000
	s_mov_b32 s4, s37
	s_mov_b64 s[10:11], s[6:7]
	s_mov_b64 s[8:9], s[42:43]
	s_waitcnt lgkmcnt(0)
	v_lshlrev_b32_e32 v156, 16, v152
	v_and_b32_e32 v157, 0xffff0000, v152
	v_lshlrev_b32_e32 v152, 16, v153
	v_and_b32_e32 v153, 0xffff0000, v153
	v_lshlrev_b32_e32 v158, 16, v154
	v_and_b32_e32 v159, 0xffff0000, v154
	v_lshlrev_b32_e32 v154, 16, v155
	v_and_b32_e32 v155, 0xffff0000, v155
	v_pk_add_f32 v[126:127], v[126:127], v[152:153]
	v_pk_add_f32 v[124:125], v[124:125], v[156:157]
	v_pk_add_f32 v[152:153], v[122:123], v[154:155]
	v_pk_add_f32 v[122:123], v[120:121], v[158:159]
	v_cvt_pk_bf16_f32 v120, v124, v125
	v_cvt_pk_bf16_f32 v121, v126, v127
	v_cvt_pk_bf16_f32 v122, v122, v123
	v_cvt_pk_bf16_f32 v123, v152, v153
	global_store_dwordx4 v[144:145], v[120:123], off
	s_waitcnt vmcnt(15)
; DI unsigned pack2(float a, float b) { f32x2 v = {a, b}; hwbf16x2 r = __builtin_convertvector(v, hwbf16x2); return __builtin_bit_cast(unsigned, r); }
; DI float bflo(unsigned w) { return __uint_as_float(w << 16); }
; DI float bfhi(unsigned w) { return __uint_as_float(w & 0xffff0000u); }
;     DI void operator()(const f32x4 (&acc)[2][2][4][2], const Unit& u, int wr, int wc, int fr, int fq) const {
;     ...
;         for (int ai = 0; ai < 2; ++ai)
; #pragma unroll
;             for (int m = 0; m < 4; ++m) { const size_t ro = (size_t)(row0 + ai * HALF + m * 16) * D + col0;
; #pragma unroll
;                 for (int bj = 0; bj < 2; ++bj) {
;                     f32x4 x0, x1;
;                     if constexpr (IB) { const u32x4 w = *(const u32x4*)((const bf16_t*)Xin + ro + bj * HALF);
;                         x0 = (f32x4){bflo(w[0]), bfhi(w[0]), bflo(w[1]), bfhi(w[1])}; x1 = (f32x4){bflo(w[2]), bfhi(w[2]), bflo(w[3]), bfhi(w[3])}; }
;                     else { x0 = *(const f32x4*)((const float*)Xin + ro + bj * HALF); x1 = *(const f32x4*)((const float*)Xin + ro + bj * HALF + 4); }
;                     x0 += acc[ai][bj][m][0] * sc[bj][0]; x1 += acc[ai][bj][m][1] * sc[bj][1];
;                     if constexpr (OB) { u32x4 o; o[0] = pack2(x0[0], x0[1]); o[1] = pack2(x0[2], x0[3]); o[2] = pack2(x1[0], x1[1]); o[3] = pack2(x1[2], x1[3]);
;                         *(u32x4*)((bf16_t*)Xout + ro + bj * HALF) = o; }
;                     else { *(f32x4*)((float*)Xout + ro + bj * HALF) = x0; *(f32x4*)((float*)Xout + ro + bj * HALF + 4) = x1; } } }
	s_nop 1
	v_mov_b32_e32 v120, v164
	v_mov_b32_e32 v121, v165
	v_mov_b32_e32 v122, v166
	v_mov_b32_e32 v123, v167
	s_waitcnt lgkmcnt(0)
	v_lshlrev_b32_e32 v124, 16, v120
	v_and_b32_e32 v125, 0xffff0000, v120
	v_lshlrev_b32_e32 v120, 16, v121
	v_and_b32_e32 v121, 0xffff0000, v121
	v_lshlrev_b32_e32 v126, 16, v122
	v_and_b32_e32 v127, 0xffff0000, v122
	v_lshlrev_b32_e32 v122, 16, v123
	v_and_b32_e32 v123, 0xffff0000, v123
	v_pk_add_f32 v[116:117], v[116:117], v[124:125]
	v_pk_add_f32 v[118:119], v[118:119], v[120:121]
	v_pk_add_f32 v[120:121], v[114:115], v[122:123]
	v_pk_add_f32 v[114:115], v[112:113], v[126:127]
	v_cvt_pk_bf16_f32 v112, v116, v117
	v_lshl_add_u64 v[116:117], v[144:145], 0, s[2:3]
	s_mov_b32 s2, 0x10000
	v_cvt_pk_bf16_f32 v113, v118, v119
	v_add_co_u32_e32 v118, vcc, s2, v144
	v_cvt_pk_bf16_f32 v114, v114, v115
	v_cvt_pk_bf16_f32 v115, v120, v121
	v_addc_co_u32_e32 v119, vcc, 0, v145, vcc
	global_store_dwordx4 v[144:145], v[112:115], off offset:256
	s_waitcnt vmcnt(15)
	s_nop 1
	v_mov_b32_e32 v112, v168
	v_mov_b32_e32 v113, v169
	v_mov_b32_e32 v114, v170
	v_mov_b32_e32 v115, v171
	s_mov_b64 s[2:3], 0x20000
	s_waitcnt lgkmcnt(0)
	v_lshlrev_b32_e32 v120, 16, v112
	v_and_b32_e32 v121, 0xffff0000, v112
	v_lshlrev_b32_e32 v112, 16, v113
	v_and_b32_e32 v113, 0xffff0000, v113
	v_lshlrev_b32_e32 v122, 16, v114
	v_and_b32_e32 v123, 0xffff0000, v114
	v_lshlrev_b32_e32 v114, 16, v115
	v_and_b32_e32 v115, 0xffff0000, v115
	v_pk_add_f32 v[110:111], v[110:111], v[112:113]
	v_pk_add_f32 v[108:109], v[108:109], v[120:121]
	v_pk_add_f32 v[112:113], v[106:107], v[114:115]
	v_pk_add_f32 v[106:107], v[104:105], v[122:123]
	v_cvt_pk_bf16_f32 v104, v108, v109
	v_cvt_pk_bf16_f32 v105, v110, v111
	v_cvt_pk_bf16_f32 v106, v106, v107
	v_cvt_pk_bf16_f32 v107, v112, v113
	global_store_dwordx4 v[118:119], v[104:107], off
	s_waitcnt vmcnt(15)
	s_nop 1
	v_mov_b32_e32 v104, v172
	v_mov_b32_e32 v105, v173
	v_mov_b32_e32 v106, v174
	v_mov_b32_e32 v107, v175
	s_waitcnt lgkmcnt(0)
	v_lshlrev_b32_e32 v108, 16, v104
	v_and_b32_e32 v109, 0xffff0000, v104
	v_lshlrev_b32_e32 v104, 16, v105
	v_and_b32_e32 v105, 0xffff0000, v105
	v_lshlrev_b32_e32 v110, 16, v106
	v_and_b32_e32 v111, 0xffff0000, v106
	v_lshlrev_b32_e32 v106, 16, v107
	v_and_b32_e32 v107, 0xffff0000, v107
	v_pk_add_f32 v[100:101], v[100:101], v[108:109]
	v_pk_add_f32 v[102:103], v[102:103], v[104:105]
	v_pk_add_f32 v[104:105], v[98:99], v[106:107]
	v_pk_add_f32 v[98:99], v[96:97], v[110:111]
	v_cvt_pk_bf16_f32 v96, v100, v101
	v_lshl_add_u64 v[100:101], v[144:145], 0, s[2:3]
	s_mov_b32 s2, 0x20000
	v_cvt_pk_bf16_f32 v97, v102, v103
	v_add_co_u32_e32 v102, vcc, s2, v144
	v_cvt_pk_bf16_f32 v98, v98, v99
	v_cvt_pk_bf16_f32 v99, v104, v105
	v_addc_co_u32_e32 v103, vcc, 0, v145, vcc
	global_store_dwordx4 v[116:117], v[96:99], off offset:256
	s_waitcnt vmcnt(15)
	s_nop 1
	v_mov_b32_e32 v96, v176
	v_mov_b32_e32 v97, v177
	v_mov_b32_e32 v98, v178
	v_mov_b32_e32 v99, v179
	s_mov_b64 s[2:3], 0x30000
	s_waitcnt lgkmcnt(0)
	v_lshlrev_b32_e32 v104, 16, v96
	v_and_b32_e32 v105, 0xffff0000, v96
	v_lshlrev_b32_e32 v96, 16, v97
	v_and_b32_e32 v97, 0xffff0000, v97
	v_lshlrev_b32_e32 v106, 16, v98
	v_and_b32_e32 v107, 0xffff0000, v98
	v_lshlrev_b32_e32 v98, 16, v99
	v_and_b32_e32 v99, 0xffff0000, v99
	v_pk_add_f32 v[94:95], v[94:95], v[96:97]
	v_pk_add_f32 v[92:93], v[92:93], v[104:105]
	v_pk_add_f32 v[96:97], v[90:91], v[98:99]
	v_pk_add_f32 v[90:91], v[88:89], v[106:107]
	v_cvt_pk_bf16_f32 v88, v92, v93
	v_cvt_pk_bf16_f32 v89, v94, v95
	v_cvt_pk_bf16_f32 v90, v90, v91
	v_cvt_pk_bf16_f32 v91, v96, v97
	global_store_dwordx4 v[102:103], v[88:91], off
	s_waitcnt vmcnt(15)
	s_nop 1
	v_mov_b32_e32 v88, v180
	v_mov_b32_e32 v89, v181
	v_mov_b32_e32 v90, v182
	v_mov_b32_e32 v91, v183
	s_waitcnt lgkmcnt(0)
	v_lshlrev_b32_e32 v92, 16, v88
	v_and_b32_e32 v93, 0xffff0000, v88
	v_lshlrev_b32_e32 v88, 16, v89
	v_and_b32_e32 v89, 0xffff0000, v89
	v_lshlrev_b32_e32 v94, 16, v90
	v_and_b32_e32 v95, 0xffff0000, v90
	v_lshlrev_b32_e32 v90, 16, v91
	v_and_b32_e32 v91, 0xffff0000, v91
	v_pk_add_f32 v[86:87], v[86:87], v[88:89]
	v_pk_add_f32 v[84:85], v[84:85], v[92:93]
	v_pk_add_f32 v[88:89], v[82:83], v[90:91]
	v_pk_add_f32 v[82:83], v[80:81], v[94:95]
	v_cvt_pk_bf16_f32 v80, v84, v85
	v_cvt_pk_bf16_f32 v81, v86, v87
	v_cvt_pk_bf16_f32 v82, v82, v83
	v_cvt_pk_bf16_f32 v83, v88, v89
	global_store_dwordx4 v[100:101], v[80:83], off offset:256
	s_nop 1
	v_lshl_add_u64 v[80:81], v[144:145], 0, s[2:3]
	s_mov_b32 s2, 0x30000
	v_add_co_u32_e32 v86, vcc, s2, v144
	s_mov_b64 s[2:3], 0x80000
	s_nop 0
	v_addc_co_u32_e32 v87, vcc, 0, v145, vcc
	s_waitcnt vmcnt(15)
	s_nop 1
	v_mov_b32_e32 v82, v184
	v_mov_b32_e32 v83, v185
	v_mov_b32_e32 v84, v186
	v_mov_b32_e32 v85, v187
	s_waitcnt lgkmcnt(0)
	v_lshlrev_b32_e32 v88, 16, v82
	v_and_b32_e32 v89, 0xffff0000, v82
	v_lshlrev_b32_e32 v82, 16, v83
	v_and_b32_e32 v83, 0xffff0000, v83
	v_lshlrev_b32_e32 v90, 16, v84
	v_and_b32_e32 v91, 0xffff0000, v84
	v_lshlrev_b32_e32 v84, 16, v85
	v_and_b32_e32 v85, 0xffff0000, v85
	v_pk_add_f32 v[78:79], v[78:79], v[82:83]
	v_pk_add_f32 v[76:77], v[76:77], v[88:89]
	v_pk_add_f32 v[82:83], v[74:75], v[84:85]
	v_pk_add_f32 v[74:75], v[72:73], v[90:91]
	v_cvt_pk_bf16_f32 v72, v76, v77
	v_cvt_pk_bf16_f32 v73, v78, v79
	v_cvt_pk_bf16_f32 v74, v74, v75
	v_cvt_pk_bf16_f32 v75, v82, v83
	global_store_dwordx4 v[86:87], v[72:75], off
	s_waitcnt vmcnt(15)
	s_nop 1
	v_mov_b32_e32 v72, v188
	v_mov_b32_e32 v73, v189
	v_mov_b32_e32 v74, v190
	v_mov_b32_e32 v75, v191
	s_waitcnt lgkmcnt(0)
; DI unsigned pack2(float a, float b) { f32x2 v = {a, b}; hwbf16x2 r = __builtin_convertvector(v, hwbf16x2); return __builtin_bit_cast(unsigned, r); }
; DI float bflo(unsigned w) { return __uint_as_float(w << 16); }
; DI float bfhi(unsigned w) { return __uint_as_float(w & 0xffff0000u); }
;     DI void operator()(const f32x4 (&acc)[2][2][4][2], const Unit& u, int wr, int wc, int fr, int fq) const {
;     ...
;             for (int m = 0; m < 4; ++m) { const size_t ro = (size_t)(row0 + ai * HALF + m * 16) * D + col0;
; #pragma unroll
;                 for (int bj = 0; bj < 2; ++bj) {
;                     f32x4 x0, x1;
;                     if constexpr (IB) { const u32x4 w = *(const u32x4*)((const bf16_t*)Xin + ro + bj * HALF);
;                         x0 = (f32x4){bflo(w[0]), bfhi(w[0]), bflo(w[1]), bfhi(w[1])}; x1 = (f32x4){bflo(w[2]), bfhi(w[2]), bflo(w[3]), bfhi(w[3])}; }
;                     else { x0 = *(const f32x4*)((const float*)Xin + ro + bj * HALF); x1 = *(const f32x4*)((const float*)Xin + ro + bj * HALF + 4); }
;                     x0 += acc[ai][bj][m][0] * sc[bj][0]; x1 += acc[ai][bj][m][1] * sc[bj][1];
;                     if constexpr (OB) { u32x4 o; o[0] = pack2(x0[0], x0[1]); o[1] = pack2(x0[2], x0[3]); o[2] = pack2(x1[0], x1[1]); o[3] = pack2(x1[2], x1[3]);
;                         *(u32x4*)((bf16_t*)Xout + ro + bj * HALF) = o; }
;                     else { *(f32x4*)((float*)Xout + ro + bj * HALF) = x0; *(f32x4*)((float*)Xout + ro + bj * HALF + 4) = x1; } } }
	v_lshlrev_b32_e32 v76, 16, v72
	v_and_b32_e32 v77, 0xffff0000, v72
	v_lshlrev_b32_e32 v72, 16, v73
	v_and_b32_e32 v73, 0xffff0000, v73
	v_lshlrev_b32_e32 v78, 16, v74
	v_and_b32_e32 v79, 0xffff0000, v74
	v_lshlrev_b32_e32 v74, 16, v75
	v_and_b32_e32 v75, 0xffff0000, v75
	v_pk_add_f32 v[70:71], v[70:71], v[72:73]
	v_pk_add_f32 v[68:69], v[68:69], v[76:77]
	v_pk_add_f32 v[72:73], v[66:67], v[74:75]
	v_pk_add_f32 v[66:67], v[64:65], v[78:79]
	v_cvt_pk_bf16_f32 v64, v68, v69
	v_cvt_pk_bf16_f32 v65, v70, v71
	v_cvt_pk_bf16_f32 v66, v66, v67
	v_cvt_pk_bf16_f32 v67, v72, v73
	global_store_dwordx4 v[80:81], v[64:67], off offset:256
	s_nop 1
	v_lshl_add_u64 v[64:65], v[144:145], 0, s[2:3]
	s_mov_b32 s2, 0x80000
	v_add_co_u32_e32 v70, vcc, s2, v144
	s_mov_b64 s[2:3], 0x90000
	s_nop 0
	v_addc_co_u32_e32 v71, vcc, 0, v145, vcc
	s_waitcnt vmcnt(15)
	s_nop 1
	v_mov_b32_e32 v66, v192
	v_mov_b32_e32 v67, v193
	v_mov_b32_e32 v68, v194
	v_mov_b32_e32 v69, v195
	s_waitcnt lgkmcnt(0)
	v_lshlrev_b32_e32 v72, 16, v66
	v_and_b32_e32 v73, 0xffff0000, v66
	v_lshlrev_b32_e32 v66, 16, v67
	v_and_b32_e32 v67, 0xffff0000, v67
	v_lshlrev_b32_e32 v74, 16, v68
	v_and_b32_e32 v75, 0xffff0000, v68
	v_lshlrev_b32_e32 v68, 16, v69
	v_and_b32_e32 v69, 0xffff0000, v69
	v_pk_add_f32 v[62:63], v[62:63], v[66:67]
	v_pk_add_f32 v[60:61], v[60:61], v[72:73]
	v_pk_add_f32 v[66:67], v[58:59], v[68:69]
	v_pk_add_f32 v[58:59], v[56:57], v[74:75]
	v_cvt_pk_bf16_f32 v56, v60, v61
	v_cvt_pk_bf16_f32 v57, v62, v63
	v_cvt_pk_bf16_f32 v58, v58, v59
	v_cvt_pk_bf16_f32 v59, v66, v67
	global_store_dwordx4 v[70:71], v[56:59], off
	s_waitcnt vmcnt(15)
	s_nop 1
	v_mov_b32_e32 v56, v198
	v_mov_b32_e32 v57, v199
	v_mov_b32_e32 v58, v200
	v_mov_b32_e32 v59, v201
	s_waitcnt lgkmcnt(0)
	v_lshlrev_b32_e32 v60, 16, v56
	v_and_b32_e32 v61, 0xffff0000, v56
	v_lshlrev_b32_e32 v56, 16, v57
	v_and_b32_e32 v57, 0xffff0000, v57
	v_lshlrev_b32_e32 v62, 16, v58
	v_and_b32_e32 v63, 0xffff0000, v58
	v_lshlrev_b32_e32 v58, 16, v59
	v_and_b32_e32 v59, 0xffff0000, v59
	v_pk_add_f32 v[54:55], v[54:55], v[56:57]
	v_pk_add_f32 v[52:53], v[52:53], v[60:61]
	v_pk_add_f32 v[56:57], v[50:51], v[58:59]
	v_pk_add_f32 v[50:51], v[48:49], v[62:63]
	v_cvt_pk_bf16_f32 v48, v52, v53
	v_cvt_pk_bf16_f32 v49, v54, v55
	v_cvt_pk_bf16_f32 v50, v50, v51
	v_cvt_pk_bf16_f32 v51, v56, v57
	global_store_dwordx4 v[64:65], v[48:51], off offset:256
	s_nop 1
	v_lshl_add_u64 v[48:49], v[144:145], 0, s[2:3]
	s_mov_b32 s2, 0x90000
	v_add_co_u32_e32 v54, vcc, s2, v144
	s_mov_b64 s[2:3], 0xa0000
	s_nop 0
	v_addc_co_u32_e32 v55, vcc, 0, v145, vcc
	s_waitcnt vmcnt(15)
	s_nop 1
	v_mov_b32_e32 v50, v202
	v_mov_b32_e32 v51, v203
	v_mov_b32_e32 v52, v204
	v_mov_b32_e32 v53, v205
	s_waitcnt lgkmcnt(0)
	v_lshlrev_b32_e32 v56, 16, v50
	v_and_b32_e32 v57, 0xffff0000, v50
	v_lshlrev_b32_e32 v50, 16, v51
	v_and_b32_e32 v51, 0xffff0000, v51
	v_lshlrev_b32_e32 v58, 16, v52
	v_and_b32_e32 v59, 0xffff0000, v52
	v_lshlrev_b32_e32 v52, 16, v53
	v_and_b32_e32 v53, 0xffff0000, v53
	v_pk_add_f32 v[46:47], v[46:47], v[50:51]
	v_pk_add_f32 v[44:45], v[44:45], v[56:57]
	v_pk_add_f32 v[50:51], v[42:43], v[52:53]
	v_pk_add_f32 v[42:43], v[40:41], v[58:59]
	v_cvt_pk_bf16_f32 v40, v44, v45
	v_cvt_pk_bf16_f32 v41, v46, v47
	v_cvt_pk_bf16_f32 v42, v42, v43
	v_cvt_pk_bf16_f32 v43, v50, v51
	global_store_dwordx4 v[54:55], v[40:43], off
	s_waitcnt vmcnt(15)
	s_nop 1
	v_mov_b32_e32 v40, v206
	v_mov_b32_e32 v41, v207
	v_mov_b32_e32 v42, v208
	v_mov_b32_e32 v43, v209
	s_waitcnt lgkmcnt(0)
; DI unsigned pack2(float a, float b) { f32x2 v = {a, b}; hwbf16x2 r = __builtin_convertvector(v, hwbf16x2); return __builtin_bit_cast(unsigned, r); }
; DI float bflo(unsigned w) { return __uint_as_float(w << 16); }
; DI float bfhi(unsigned w) { return __uint_as_float(w & 0xffff0000u); }
;     DI const char* a(const Unit& u) const { return (const char*)(A + (size_t)u.pm * BM * lda); }
; #define PG8_BAR __builtin_amdgcn_s_barrier()
;     DI void operator()(const f32x4 (&acc)[2][2][4][2], const Unit& u, int wr, int wc, int fr, int fq) const {
;     ...
;             for (int m = 0; m < 4; ++m) { const size_t ro = (size_t)(row0 + ai * HALF + m * 16) * D + col0;
; #pragma unroll
;                 for (int bj = 0; bj < 2; ++bj) {
;                     f32x4 x0, x1;
;                     if constexpr (IB) { const u32x4 w = *(const u32x4*)((const bf16_t*)Xin + ro + bj * HALF);
;                         x0 = (f32x4){bflo(w[0]), bfhi(w[0]), bflo(w[1]), bfhi(w[1])}; x1 = (f32x4){bflo(w[2]), bfhi(w[2]), bflo(w[3]), bfhi(w[3])}; }
;                     else { x0 = *(const f32x4*)((const float*)Xin + ro + bj * HALF); x1 = *(const f32x4*)((const float*)Xin + ro + bj * HALF + 4); }
;                     x0 += acc[ai][bj][m][0] * sc[bj][0]; x1 += acc[ai][bj][m][1] * sc[bj][1];
;                     if constexpr (OB) { u32x4 o; o[0] = pack2(x0[0], x0[1]); o[1] = pack2(x0[2], x0[3]); o[2] = pack2(x1[0], x1[1]); o[3] = pack2(x1[2], x1[3]);
;                         *(u32x4*)((bf16_t*)Xout + ro + bj * HALF) = o; }
;                     else { *(f32x4*)((float*)Xout + ro + bj * HALF) = x0; *(f32x4*)((float*)Xout + ro + bj * HALF + 4) = x1; } } }
; template <class Map, class Epi>
; DI void gemm_phase(LAS unsigned char* lds, const Map& MP, const Epi& E, const int nM, const int nN, const int K, const int lda, const int ldb) {
;     ...
;         { int frr = fr, fqq = fq; asm volatile("" : "+v"(frr), "+v"(fqq)); E(acc, cur, wr, wc, frr, fqq); }
;         if (!has_next) break;
; #pragma unroll
;         for (int a = 0; a < 2; ++a)
; #pragma unroll
;             for (int b = 0; b < 2; ++b)
; #pragma unroll
;                 for (int m = 0; m < 4; ++m)
; #pragma unroll
;                     for (int n = 0; n < 2; ++n) acc[a][b][m][n] = (f32x4){0.f, 0.f, 0.f, 0.f};
;         cur = nxt; cA = nA; cB = nB; ++ui;
;     }
;     PG8_WAIT_V(0);
;     if (wr == 0) PG8_BAR;
;     PG8_BAR;
	v_lshlrev_b32_e32 v44, 16, v40
	v_and_b32_e32 v45, 0xffff0000, v40
	v_lshlrev_b32_e32 v40, 16, v41
	v_and_b32_e32 v41, 0xffff0000, v41
	v_lshlrev_b32_e32 v46, 16, v42
	v_and_b32_e32 v47, 0xffff0000, v42
	v_lshlrev_b32_e32 v42, 16, v43
	v_and_b32_e32 v43, 0xffff0000, v43
	v_pk_add_f32 v[38:39], v[38:39], v[40:41]
	v_pk_add_f32 v[36:37], v[36:37], v[44:45]
	v_pk_add_f32 v[40:41], v[34:35], v[42:43]
	v_pk_add_f32 v[34:35], v[32:33], v[46:47]
	v_cvt_pk_bf16_f32 v32, v36, v37
	v_cvt_pk_bf16_f32 v33, v38, v39
	v_cvt_pk_bf16_f32 v34, v34, v35
	v_cvt_pk_bf16_f32 v35, v40, v41
	global_store_dwordx4 v[48:49], v[32:35], off offset:256
	s_nop 1
	v_lshl_add_u64 v[32:33], v[144:145], 0, s[2:3]
	s_mov_b32 s2, 0xa0000
	v_add_co_u32_e32 v38, vcc, s2, v144
	s_mov_b64 s[2:3], 0xb0000
	s_nop 0
	v_addc_co_u32_e32 v39, vcc, 0, v145, vcc
	s_waitcnt vmcnt(15)
	s_nop 1
	v_mov_b32_e32 v34, v210
	v_mov_b32_e32 v35, v211
	v_mov_b32_e32 v36, v212
	v_mov_b32_e32 v37, v213
	s_waitcnt lgkmcnt(0)
	v_lshlrev_b32_e32 v40, 16, v34
	v_and_b32_e32 v41, 0xffff0000, v34
	v_lshlrev_b32_e32 v34, 16, v35
	v_and_b32_e32 v35, 0xffff0000, v35
	v_lshlrev_b32_e32 v42, 16, v36
	v_and_b32_e32 v43, 0xffff0000, v36
	v_lshlrev_b32_e32 v36, 16, v37
	v_and_b32_e32 v37, 0xffff0000, v37
	v_pk_add_f32 v[30:31], v[30:31], v[34:35]
	v_pk_add_f32 v[28:29], v[28:29], v[40:41]
	v_pk_add_f32 v[34:35], v[26:27], v[36:37]
	v_pk_add_f32 v[26:27], v[24:25], v[42:43]
	v_cvt_pk_bf16_f32 v24, v28, v29
	v_cvt_pk_bf16_f32 v25, v30, v31
	v_cvt_pk_bf16_f32 v26, v26, v27
	v_cvt_pk_bf16_f32 v27, v34, v35
	global_store_dwordx4 v[38:39], v[24:27], off
	s_waitcnt vmcnt(15)
	s_nop 1
	v_mov_b32_e32 v24, v214
	v_mov_b32_e32 v25, v215
	v_mov_b32_e32 v26, v216
	v_mov_b32_e32 v27, v217
	s_waitcnt lgkmcnt(0)
	v_lshlrev_b32_e32 v28, 16, v24
	v_and_b32_e32 v29, 0xffff0000, v24
	v_lshlrev_b32_e32 v24, 16, v25
	v_and_b32_e32 v25, 0xffff0000, v25
	v_lshlrev_b32_e32 v30, 16, v26
	v_and_b32_e32 v31, 0xffff0000, v26
	v_lshlrev_b32_e32 v26, 16, v27
	v_and_b32_e32 v27, 0xffff0000, v27
	v_pk_add_f32 v[22:23], v[22:23], v[24:25]
	v_pk_add_f32 v[20:21], v[20:21], v[28:29]
	v_pk_add_f32 v[24:25], v[18:19], v[26:27]
	v_pk_add_f32 v[18:19], v[16:17], v[30:31]
	v_cvt_pk_bf16_f32 v16, v20, v21
	v_cvt_pk_bf16_f32 v17, v22, v23
	v_cvt_pk_bf16_f32 v18, v18, v19
	v_cvt_pk_bf16_f32 v19, v24, v25
	global_store_dwordx4 v[32:33], v[16:19], off offset:256
	s_nop 1
	v_lshl_add_u64 v[16:17], v[144:145], 0, s[2:3]
	s_mov_b32 s2, 0xb0000
	v_add_co_u32_e32 v22, vcc, s2, v144
	s_mov_b32 s2, s55
	s_nop 0
	v_addc_co_u32_e32 v23, vcc, 0, v145, vcc
	s_waitcnt vmcnt(15)
	s_nop 1
	v_mov_b32_e32 v18, v248
	v_mov_b32_e32 v19, v249
	v_mov_b32_e32 v20, v250
	v_mov_b32_e32 v21, v251
	s_and_b64 vcc, exec, s[40:41]
	s_waitcnt lgkmcnt(0)
	v_lshlrev_b32_e32 v24, 16, v18
	v_and_b32_e32 v25, 0xffff0000, v18
	v_lshlrev_b32_e32 v18, 16, v19
	v_and_b32_e32 v19, 0xffff0000, v19
	v_lshlrev_b32_e32 v26, 16, v20
	v_and_b32_e32 v27, 0xffff0000, v20
	v_lshlrev_b32_e32 v20, 16, v21
	v_and_b32_e32 v21, 0xffff0000, v21
	v_pk_add_f32 v[14:15], v[14:15], v[18:19]
	v_pk_add_f32 v[12:13], v[12:13], v[24:25]
	v_pk_add_f32 v[18:19], v[10:11], v[20:21]
	v_pk_add_f32 v[10:11], v[8:9], v[26:27]
	v_cvt_pk_bf16_f32 v8, v12, v13
	v_cvt_pk_bf16_f32 v9, v14, v15
	v_cvt_pk_bf16_f32 v10, v10, v11
	v_cvt_pk_bf16_f32 v11, v18, v19
	global_store_dwordx4 v[22:23], v[8:11], off
	s_waitcnt vmcnt(15)
	s_nop 1
	v_mov_b32_e32 v8, v252
	v_mov_b32_e32 v9, v253
	v_mov_b32_e32 v10, v254
	v_mov_b32_e32 v11, v255
	s_waitcnt lgkmcnt(0)
	v_lshlrev_b32_e32 v12, 16, v8
	v_and_b32_e32 v13, 0xffff0000, v8
	v_lshlrev_b32_e32 v8, 16, v9
	v_and_b32_e32 v9, 0xffff0000, v9
	v_lshlrev_b32_e32 v14, 16, v10
	v_and_b32_e32 v15, 0xffff0000, v10
	v_lshlrev_b32_e32 v10, 16, v11
	v_and_b32_e32 v11, 0xffff0000, v11
	v_pk_add_f32 v[6:7], v[6:7], v[8:9]
	v_pk_add_f32 v[4:5], v[4:5], v[12:13]
	v_pk_add_f32 v[8:9], v[2:3], v[10:11]
	v_pk_add_f32 v[2:3], v[0:1], v[14:15]
	v_cvt_pk_bf16_f32 v0, v4, v5
	v_cvt_pk_bf16_f32 v1, v6, v7
	v_cvt_pk_bf16_f32 v2, v2, v3
	v_cvt_pk_bf16_f32 v3, v8, v9
	global_store_dwordx4 v[16:17], v[0:3], off offset:256
	s_cbranch_vccz .LBB1_1232
	s_waitcnt vmcnt(0)
	s_cmpk_gt_u32 s17, 0xff
	s_cbranch_scc1 .LBB1_1243
	s_barrier

; #define PG8_STAGE(bufoff, gbase, voff) do { _Pragma("unroll") for (int _i = 0; _i < 2; ++_i) \
;         __builtin_amdgcn_global_load_lds((const unsigned*)((const char*)(gbase) + (voff)[_i]), (LAS unsigned*)(lds + (bufoff) + ldsw + _i * 8192), 16, 0, 0); } while (0)
; #define PG8_LDA(dst, b, h) do { _Pragma("unroll") for (int m = 0; m < 4; ++m) _Pragma("unroll") for (int k = 0; k < 2; ++k) dst[m][k] = *(const LAS bf16x8*)(lds + PG8_SA(b, h) + aoff + m * 2048 + k * 1024); } while (0)
; #define PG8_LDB(dst, b, h) do { _Pragma("unroll") for (int n = 0; n < 2; ++n) _Pragma("unroll") for (int k = 0; k < 2; ++k) dst[n][k] = *(const LAS bf16x8*)(lds + PG8_SB(b, h) + boff + n * 2048 + k * 1024); } while (0)
; #define PG8_MMA(ai, bj, At, Bt) do { __builtin_amdgcn_s_setprio(1); _Pragma("unroll") for (int m = 0; m < 4; ++m) _Pragma("unroll") for (int n = 0; n < 2; ++n) _Pragma("unroll") for (int k = 0; k < 2; ++k) \
;         acc[ai][bj][m][n] = __builtin_amdgcn_mfma_f32_16x16x32_bf16(Bt[n][k], At[m][k], acc[ai][bj][m][n], 0, 0, 0); __builtin_amdgcn_s_setprio(0); } while (0)
; #define PG8_WAIT_V(n) asm volatile("s_waitcnt vmcnt(" #n ")" ::: "memory")
; #define PG8_WAIT_L(n) asm volatile("s_waitcnt lgkmcnt(" #n ")" ::: "memory")
; #define PG8_BAR __builtin_amdgcn_s_barrier()
; #define PG8_SCHED __builtin_amdgcn_sched_barrier(0)
; template <class Map, class Epi>
; DI void gemm_phase(LAS unsigned char* lds, const Map& MP, const Epi& E, const int nM, const int nN, const int K, const int lda, const int ldb) {
;     ...
;             PG8_LDB(B0, 0, 0); PG8_SCHED; PG8_LDA(At, 0, 0); PG8_STAGE(PG8_SA(1, 1), a1 + hstepA, voffA);
;             PG8_WAIT_L(8); PG8_BAR; PG8_WAIT_L(0); PG8_MMA(0, 0, At, B0); PG8_BAR; PG8_SCHED;
;             PG8_LDB(B1, 0, 1); PG8_STAGE(PG8_SB(0, 0), b2, voffB);
;             PG8_BAR; PG8_WAIT_L(0); PG8_MMA(0, 1, At, B1); PG8_BAR;
;             PG8_LDA(At, 0, 1); PG8_STAGE(PG8_SA(0, 0), a2, voffA);
;             PG8_BAR; PG8_WAIT_L(0); PG8_MMA(1, 0, At, B0); PG8_BAR; PG8_SCHED;
;             PG8_STAGE(PG8_SB(0, 1), b2 + hstepB, voffB);
;             PG8_WAIT_V(6); PG8_BAR; PG8_MMA(1, 1, At, B1); PG8_BAR;
.LBB1_1382:
	s_add_u32 s22, s20, 0xfff80080
	s_addc_u32 s23, s21, -1
	s_cmp_eq_u32 s3, 28
	s_cselect_b32 s25, s15, s23
	s_cselect_b32 s24, s48, s22
	s_cselect_b32 s23, s13, s53
	s_cselect_b32 s22, s49, s52
	s_add_i32 m0, s31, 0xc000
	ds_read_b128 v[166:169], v148
	ds_read_b128 v[170:173], v148 offset:1024
	ds_read_b128 v[174:177], v148 offset:2048
	ds_read_b128 v[178:181], v148 offset:3072
	ds_read_b128 v[182:185], v148 offset:4096
	ds_read_b128 v[186:189], v148 offset:5120
	ds_read_b128 v[190:193], v148 offset:6144
	ds_read_b128 v[198:201], v148 offset:7168
	global_load_lds_dwordx4 v138, s[20:21]
	s_add_i32 m0, s31, 0xe000
	s_nop 0
	global_load_lds_dwordx4 v136, s[20:21]
	s_waitcnt lgkmcnt(8)
	s_setprio 1
	s_barrier
	s_waitcnt lgkmcnt(7)
	v_mfma_f32_16x16x32_bf16 v[124:127], v[150:153], v[166:169], v[124:127]
	v_mfma_f32_16x16x32_bf16 v[120:123], v[158:161], v[166:169], v[120:123]
	s_waitcnt lgkmcnt(5)
	v_mfma_f32_16x16x32_bf16 v[116:119], v[150:153], v[174:177], v[116:119]
	v_mfma_f32_16x16x32_bf16 v[112:115], v[158:161], v[174:177], v[112:115]
	s_waitcnt lgkmcnt(3)
	v_mfma_f32_16x16x32_bf16 v[100:103], v[150:153], v[182:185], v[100:103]
	v_mfma_f32_16x16x32_bf16 v[96:99], v[158:161], v[182:185], v[96:99]
	s_waitcnt lgkmcnt(1)
	v_mfma_f32_16x16x32_bf16 v[84:87], v[150:153], v[190:193], v[84:87]
	v_mfma_f32_16x16x32_bf16 v[80:83], v[158:161], v[190:193], v[80:83]
	v_mfma_f32_16x16x32_bf16 v[124:127], v[154:157], v[170:173], v[124:127]
	s_add_i32 s54, s44, s29
	v_mfma_f32_16x16x32_bf16 v[120:123], v[162:165], v[170:173], v[120:123]
	v_lshl_add_u64 v[194:195], s[22:23], 0, v[132:133]
	v_mfma_f32_16x16x32_bf16 v[116:119], v[154:157], v[178:181], v[116:119]
	v_lshl_add_u64 v[218:219], s[22:23], 0, v[128:129]
	v_mfma_f32_16x16x32_bf16 v[112:115], v[162:165], v[178:181], v[112:115]
	v_mfma_f32_16x16x32_bf16 v[100:103], v[154:157], v[186:189], v[100:103]
	v_mfma_f32_16x16x32_bf16 v[96:99], v[162:165], v[186:189], v[96:99]
	s_waitcnt lgkmcnt(0)
	v_mfma_f32_16x16x32_bf16 v[84:87], v[154:157], v[198:201], v[84:87]
	s_mov_b32 m0, s54
	v_mfma_f32_16x16x32_bf16 v[80:83], v[162:165], v[198:201], v[80:83]
	s_barrier
	s_setprio 0
	ds_read_b128 v[202:205], v149
	ds_read_b128 v[206:209], v149 offset:1024
	ds_read_b128 v[210:213], v149 offset:2048
	global_load_lds_dwordx4 v[194:195], off
	s_add_i32 m0, s54, 0x2000
	ds_read_b128 v[214:217], v149 offset:3072
	global_load_lds_dwordx4 v[218:219], off
	s_setprio 1
	s_barrier
	s_waitcnt lgkmcnt(3)
	v_mfma_f32_16x16x32_bf16 v[108:111], v[202:205], v[166:169], v[108:111]
	s_waitcnt lgkmcnt(1)
	v_mfma_f32_16x16x32_bf16 v[104:107], v[210:213], v[166:169], v[104:107]
	v_mfma_f32_16x16x32_bf16 v[92:95], v[202:205], v[174:177], v[92:95]
	v_mfma_f32_16x16x32_bf16 v[88:91], v[210:213], v[174:177], v[88:91]
	v_mfma_f32_16x16x32_bf16 v[76:79], v[202:205], v[182:185], v[76:79]
	v_mfma_f32_16x16x32_bf16 v[72:75], v[210:213], v[182:185], v[72:75]
	v_mfma_f32_16x16x32_bf16 v[68:71], v[202:205], v[190:193], v[68:71]
	v_mfma_f32_16x16x32_bf16 v[64:67], v[210:213], v[190:193], v[64:67]
	v_mfma_f32_16x16x32_bf16 v[108:111], v[206:209], v[170:173], v[108:111]
	v_lshl_add_u64 v[222:223], s[24:25], 0, v[130:131]
	s_mov_b32 m0, s31
	s_waitcnt lgkmcnt(0)
	v_mfma_f32_16x16x32_bf16 v[104:107], v[214:217], v[170:173], v[104:107]
	v_lshl_add_u64 v[220:221], s[24:25], 0, v[134:135]
	v_mfma_f32_16x16x32_bf16 v[92:95], v[206:209], v[178:181], v[92:95]
	v_mfma_f32_16x16x32_bf16 v[88:91], v[214:217], v[178:181], v[88:91]
	v_mfma_f32_16x16x32_bf16 v[76:79], v[206:209], v[186:189], v[76:79]
	v_mfma_f32_16x16x32_bf16 v[72:75], v[214:217], v[186:189], v[72:75]
	v_mfma_f32_16x16x32_bf16 v[68:71], v[206:209], v[198:201], v[68:71]
	v_mfma_f32_16x16x32_bf16 v[64:67], v[214:217], v[198:201], v[64:67]
	s_barrier
	s_setprio 0
	ds_read_b128 v[166:169], v148 offset:16384
	ds_read_b128 v[170:173], v148 offset:17408
	ds_read_b128 v[174:177], v148 offset:18432
	ds_read_b128 v[178:181], v148 offset:19456
	ds_read_b128 v[182:185], v148 offset:20480
	ds_read_b128 v[186:189], v148 offset:21504
	ds_read_b128 v[190:193], v148 offset:22528
	global_load_lds_dwordx4 v[220:221], off
	s_mov_b32 m0, s11
	ds_read_b128 v[198:201], v148 offset:23552
	global_load_lds_dwordx4 v[222:223], off
	s_waitcnt vmcnt(10)
	s_setprio 1
	s_barrier
	s_waitcnt lgkmcnt(7)
	v_mfma_f32_16x16x32_bf16 v[60:63], v[150:153], v[166:169], v[60:63]
	v_mfma_f32_16x16x32_bf16 v[56:59], v[158:161], v[166:169], v[56:59]
	s_waitcnt lgkmcnt(5)
	v_mfma_f32_16x16x32_bf16 v[52:55], v[150:153], v[174:177], v[52:55]
	v_mfma_f32_16x16x32_bf16 v[48:51], v[158:161], v[174:177], v[48:51]
	s_waitcnt lgkmcnt(3)
	v_mfma_f32_16x16x32_bf16 v[36:39], v[150:153], v[182:185], v[36:39]
	v_mfma_f32_16x16x32_bf16 v[32:35], v[158:161], v[182:185], v[32:35]
	s_waitcnt lgkmcnt(1)
	v_mfma_f32_16x16x32_bf16 v[20:23], v[150:153], v[190:193], v[20:23]
	v_mfma_f32_16x16x32_bf16 v[16:19], v[158:161], v[190:193], v[16:19]
	v_mfma_f32_16x16x32_bf16 v[60:63], v[154:157], v[170:173], v[60:63]
	s_add_u32 s54, s22, 0x80000
	s_addc_u32 s55, s23, 0
	v_mfma_f32_16x16x32_bf16 v[56:59], v[162:165], v[170:173], v[56:59]
	s_add_i32 s56, s45, s29
	v_mfma_f32_16x16x32_bf16 v[52:55], v[154:157], v[178:181], v[52:55]
	v_mfma_f32_16x16x32_bf16 v[48:51], v[162:165], v[178:181], v[48:51]
	v_mfma_f32_16x16x32_bf16 v[36:39], v[154:157], v[186:189], v[36:39]
	v_mfma_f32_16x16x32_bf16 v[32:35], v[162:165], v[186:189], v[32:35]
	s_waitcnt lgkmcnt(0)
	v_mfma_f32_16x16x32_bf16 v[20:23], v[154:157], v[198:201], v[20:23]
	s_mov_b32 m0, s56
	v_mfma_f32_16x16x32_bf16 v[16:19], v[162:165], v[198:201], v[16:19]
	s_barrier
; #define PG8_STAGE(bufoff, gbase, voff) do { _Pragma("unroll") for (int _i = 0; _i < 2; ++_i) \
;         __builtin_amdgcn_global_load_lds((const unsigned*)((const char*)(gbase) + (voff)[_i]), (LAS unsigned*)(lds + (bufoff) + ldsw + _i * 8192), 16, 0, 0); } while (0)
; #define PG8_LDA(dst, b, h) do { _Pragma("unroll") for (int m = 0; m < 4; ++m) _Pragma("unroll") for (int k = 0; k < 2; ++k) dst[m][k] = *(const LAS bf16x8*)(lds + PG8_SA(b, h) + aoff + m * 2048 + k * 1024); } while (0)
; #define PG8_LDB(dst, b, h) do { _Pragma("unroll") for (int n = 0; n < 2; ++n) _Pragma("unroll") for (int k = 0; k < 2; ++k) dst[n][k] = *(const LAS bf16x8*)(lds + PG8_SB(b, h) + boff + n * 2048 + k * 1024); } while (0)
; #define PG8_MMA(ai, bj, At, Bt) do { __builtin_amdgcn_s_setprio(1); _Pragma("unroll") for (int m = 0; m < 4; ++m) _Pragma("unroll") for (int n = 0; n < 2; ++n) _Pragma("unroll") for (int k = 0; k < 2; ++k) \
;         acc[ai][bj][m][n] = __builtin_amdgcn_mfma_f32_16x16x32_bf16(Bt[n][k], At[m][k], acc[ai][bj][m][n], 0, 0, 0); __builtin_amdgcn_s_setprio(0); } while (0)
; #define PG8_WAIT_V(n) asm volatile("s_waitcnt vmcnt(" #n ")" ::: "memory")
; #define PG8_WAIT_L(n) asm volatile("s_waitcnt lgkmcnt(" #n ")" ::: "memory")
; #define PG8_BAR __builtin_amdgcn_s_barrier()
; #define PG8_SCHED __builtin_amdgcn_sched_barrier(0)
; template <class Map, class Epi>
; DI void gemm_phase(LAS unsigned char* lds, const Map& MP, const Epi& E, const int nM, const int nN, const int K, const int lda, const int ldb) {
;     ...
;             PG8_LDA(At, 0, 1); PG8_STAGE(PG8_SA(0, 0), a2, voffA);
;             PG8_BAR; PG8_WAIT_L(0); PG8_MMA(1, 0, At, B0); PG8_BAR; PG8_SCHED;
;             PG8_STAGE(PG8_SB(0, 1), b2 + hstepB, voffB);
;             PG8_WAIT_V(6); PG8_BAR; PG8_MMA(1, 1, At, B1); PG8_BAR;
;             PG8_LDB(B0, 1, 0); PG8_SCHED; PG8_LDA(At, 1, 0); PG8_STAGE(PG8_SA(0, 1), a2 + hstepA, voffA);
;             PG8_WAIT_L(8); PG8_BAR; PG8_WAIT_L(0); PG8_MMA(0, 0, At, B0); PG8_BAR; PG8_SCHED;
;             PG8_LDB(B1, 1, 1); PG8_STAGE(PG8_SB(1, 0), b3, voffB);
;             PG8_BAR; PG8_WAIT_L(0); PG8_MMA(0, 1, At, B1); PG8_BAR;
;             PG8_LDA(At, 1, 1); PG8_STAGE(PG8_SA(1, 0), a3, voffA);
	s_setprio 0
	global_load_lds_dwordx4 v132, s[54:55]
	s_add_i32 m0, s56, 0x2000
	s_nop 0
	global_load_lds_dwordx4 v128, s[54:55]
	s_waitcnt vmcnt(6)
	s_setprio 1
	s_barrier
	v_mfma_f32_16x16x32_bf16 v[44:47], v[202:205], v[166:169], v[44:47]
	v_mfma_f32_16x16x32_bf16 v[40:43], v[210:213], v[166:169], v[40:43]
	s_add_i32 s54, 0, 0x18000
	v_add_u32_e32 v162, s54, v146
	ds_read_b128 v[150:153], v162
	v_mfma_f32_16x16x32_bf16 v[28:31], v[202:205], v[174:177], v[28:31]
	v_mfma_f32_16x16x32_bf16 v[24:27], v[210:213], v[174:177], v[24:27]
	ds_read_b128 v[154:157], v162 offset:1024
	v_mfma_f32_16x16x32_bf16 v[12:15], v[202:205], v[182:185], v[12:15]
	v_mfma_f32_16x16x32_bf16 v[8:11], v[210:213], v[182:185], v[8:11]
	ds_read_b128 v[158:161], v162 offset:2048
	v_mfma_f32_16x16x32_bf16 v[4:7], v[202:205], v[190:193], v[4:7]
	v_mfma_f32_16x16x32_bf16 v[0:3], v[210:213], v[190:193], v[0:3]
	ds_read_b128 v[162:165], v162 offset:3072
	v_mfma_f32_16x16x32_bf16 v[44:47], v[206:209], v[170:173], v[44:47]
	s_add_u32 s24, s24, 0x80000
	s_addc_u32 s25, s25, 0
	v_mfma_f32_16x16x32_bf16 v[40:43], v[214:217], v[170:173], v[40:43]
	v_mfma_f32_16x16x32_bf16 v[28:31], v[206:209], v[178:181], v[28:31]
	v_mfma_f32_16x16x32_bf16 v[24:27], v[214:217], v[178:181], v[24:27]
	v_mfma_f32_16x16x32_bf16 v[12:15], v[206:209], v[186:189], v[12:15]
	v_mfma_f32_16x16x32_bf16 v[8:11], v[214:217], v[186:189], v[8:11]
	v_mfma_f32_16x16x32_bf16 v[4:7], v[206:209], v[198:201], v[4:7]
	s_mov_b32 m0, s34
	v_mfma_f32_16x16x32_bf16 v[0:3], v[214:217], v[198:201], v[0:3]
	s_barrier
	s_setprio 0
	ds_read_b128 v[166:169], v148 offset:32768
	ds_read_b128 v[170:173], v148 offset:33792
	ds_read_b128 v[174:177], v148 offset:34816
	ds_read_b128 v[178:181], v148 offset:35840
	ds_read_b128 v[182:185], v148 offset:36864
	ds_read_b128 v[186:189], v148 offset:37888
	ds_read_b128 v[190:193], v148 offset:38912
	global_load_lds_dwordx4 v134, s[24:25]
	s_mov_b32 m0, s35
	ds_read_b128 v[198:201], v148 offset:39936
	global_load_lds_dwordx4 v130, s[24:25]
	s_waitcnt lgkmcnt(8)
	s_setprio 1
	s_barrier
	s_waitcnt lgkmcnt(7)
	v_mfma_f32_16x16x32_bf16 v[124:127], v[150:153], v[166:169], v[124:127]
	v_mfma_f32_16x16x32_bf16 v[120:123], v[158:161], v[166:169], v[120:123]
	s_waitcnt lgkmcnt(5)
	v_mfma_f32_16x16x32_bf16 v[116:119], v[150:153], v[174:177], v[116:119]
	v_mfma_f32_16x16x32_bf16 v[112:115], v[158:161], v[174:177], v[112:115]
	s_waitcnt lgkmcnt(3)
	v_mfma_f32_16x16x32_bf16 v[100:103], v[150:153], v[182:185], v[100:103]
	v_mfma_f32_16x16x32_bf16 v[96:99], v[158:161], v[182:185], v[96:99]
	s_waitcnt lgkmcnt(1)
	v_mfma_f32_16x16x32_bf16 v[84:87], v[150:153], v[190:193], v[84:87]
	v_mfma_f32_16x16x32_bf16 v[80:83], v[158:161], v[190:193], v[80:83]
	v_mfma_f32_16x16x32_bf16 v[124:127], v[154:157], v[170:173], v[124:127]
	s_add_i32 s24, 0, 0x1c000
	v_mfma_f32_16x16x32_bf16 v[120:123], v[162:165], v[170:173], v[120:123]
	s_add_i32 s25, s54, s29
	v_mfma_f32_16x16x32_bf16 v[116:119], v[154:157], v[178:181], v[116:119]
	v_add_u32_e32 v196, s24, v146
	v_mfma_f32_16x16x32_bf16 v[112:115], v[162:165], v[178:181], v[112:115]
	v_lshl_add_u64 v[194:195], v[194:195], 0, s[8:9]
	v_mfma_f32_16x16x32_bf16 v[100:103], v[154:157], v[186:189], v[100:103]
	v_mfma_f32_16x16x32_bf16 v[96:99], v[162:165], v[186:189], v[96:99]
	s_waitcnt lgkmcnt(0)
	v_mfma_f32_16x16x32_bf16 v[84:87], v[154:157], v[198:201], v[84:87]
	s_mov_b32 m0, s25
	v_mfma_f32_16x16x32_bf16 v[80:83], v[162:165], v[198:201], v[80:83]
	s_barrier
	s_setprio 0
	ds_read_b128 v[202:205], v196
	ds_read_b128 v[206:209], v196 offset:1024
	ds_read_b128 v[210:213], v196 offset:2048
	global_load_lds_dwordx4 v[194:195], off
	v_lshl_add_u64 v[194:195], v[218:219], 0, s[8:9]
	s_add_i32 m0, s25, 0x2000
	ds_read_b128 v[214:217], v196 offset:3072
	global_load_lds_dwordx4 v[194:195], off
	s_setprio 1
	s_barrier
	s_waitcnt lgkmcnt(3)
	v_mfma_f32_16x16x32_bf16 v[108:111], v[202:205], v[166:169], v[108:111]
	s_waitcnt lgkmcnt(1)
	v_mfma_f32_16x16x32_bf16 v[104:107], v[210:213], v[166:169], v[104:107]
	v_mfma_f32_16x16x32_bf16 v[92:95], v[202:205], v[174:177], v[92:95]
	v_mfma_f32_16x16x32_bf16 v[88:91], v[210:213], v[174:177], v[88:91]
	v_mfma_f32_16x16x32_bf16 v[76:79], v[202:205], v[182:185], v[76:79]
	v_mfma_f32_16x16x32_bf16 v[72:75], v[210:213], v[182:185], v[72:75]
	v_mfma_f32_16x16x32_bf16 v[68:71], v[202:205], v[190:193], v[68:71]
	v_mfma_f32_16x16x32_bf16 v[64:67], v[210:213], v[190:193], v[64:67]
	v_mfma_f32_16x16x32_bf16 v[108:111], v[206:209], v[170:173], v[108:111]
	s_mov_b32 m0, s39
	s_waitcnt lgkmcnt(0)
	v_mfma_f32_16x16x32_bf16 v[104:107], v[214:217], v[170:173], v[104:107]
	v_lshl_add_u64 v[194:195], v[220:221], 0, s[8:9]
	v_mfma_f32_16x16x32_bf16 v[92:95], v[206:209], v[178:181], v[92:95]
	v_mfma_f32_16x16x32_bf16 v[88:91], v[214:217], v[178:181], v[88:91]
	v_mfma_f32_16x16x32_bf16 v[76:79], v[206:209], v[186:189], v[76:79]
	v_mfma_f32_16x16x32_bf16 v[72:75], v[214:217], v[186:189], v[72:75]
	v_mfma_f32_16x16x32_bf16 v[68:71], v[206:209], v[198:201], v[68:71]
	v_mfma_f32_16x16x32_bf16 v[64:67], v[214:217], v[198:201], v[64:67]
	s_barrier
	s_setprio 0
	ds_read_b128 v[166:169], v148 offset:49152
	ds_read_b128 v[170:173], v148 offset:50176
	ds_read_b128 v[174:177], v148 offset:51200
	ds_read_b128 v[178:181], v148 offset:52224
	ds_read_b128 v[182:185], v148 offset:53248
	ds_read_b128 v[186:189], v148 offset:54272
	ds_read_b128 v[190:193], v148 offset:55296
	global_load_lds_dwordx4 v[194:195], off
	v_lshl_add_u64 v[194:195], v[222:223], 0, s[8:9]
	s_mov_b32 m0, s42
	ds_read_b128 v[198:201], v148 offset:56320
	global_load_lds_dwordx4 v[194:195], off
	s_waitcnt vmcnt(10)
	s_setprio 1
	s_barrier
; #define PG8_STAGE(bufoff, gbase, voff) do { _Pragma("unroll") for (int _i = 0; _i < 2; ++_i) \
;         __builtin_amdgcn_global_load_lds((const unsigned*)((const char*)(gbase) + (voff)[_i]), (LAS unsigned*)(lds + (bufoff) + ldsw + _i * 8192), 16, 0, 0); } while (0)
; #define PG8_LDA(dst, b, h) do { _Pragma("unroll") for (int m = 0; m < 4; ++m) _Pragma("unroll") for (int k = 0; k < 2; ++k) dst[m][k] = *(const LAS bf16x8*)(lds + PG8_SA(b, h) + aoff + m * 2048 + k * 1024); } while (0)
; #define PG8_LDB(dst, b, h) do { _Pragma("unroll") for (int n = 0; n < 2; ++n) _Pragma("unroll") for (int k = 0; k < 2; ++k) dst[n][k] = *(const LAS bf16x8*)(lds + PG8_SB(b, h) + boff + n * 2048 + k * 1024); } while (0)
; #define PG8_MMA(ai, bj, At, Bt) do { __builtin_amdgcn_s_setprio(1); _Pragma("unroll") for (int m = 0; m < 4; ++m) _Pragma("unroll") for (int n = 0; n < 2; ++n) _Pragma("unroll") for (int k = 0; k < 2; ++k) \
;         acc[ai][bj][m][n] = __builtin_amdgcn_mfma_f32_16x16x32_bf16(Bt[n][k], At[m][k], acc[ai][bj][m][n], 0, 0, 0); __builtin_amdgcn_s_setprio(0); } while (0)
; #define PG8_WAIT_V(n) asm volatile("s_waitcnt vmcnt(" #n ")" ::: "memory")
; #define PG8_WAIT_L(n) asm volatile("s_waitcnt lgkmcnt(" #n ")" ::: "memory")
; #define PG8_BAR __builtin_amdgcn_s_barrier()
; #define PG8_SCHED __builtin_amdgcn_sched_barrier(0)
; template <class Map, class Epi>
; DI void gemm_phase(LAS unsigned char* lds, const Map& MP, const Epi& E, const int nM, const int nN, const int K, const int lda, const int ldb) {
;     ...
;             PG8_LDB(B0, 0, 0); PG8_SCHED; PG8_LDA(At, 0, 0); PG8_STAGE(PG8_SA(1, 1), a1 + hstepA, voffA);
;     ...
;             PG8_LDA(At, 1, 1); PG8_STAGE(PG8_SA(1, 0), a3, voffA);
;             PG8_BAR; PG8_WAIT_L(0); PG8_MMA(1, 0, At, B0); PG8_BAR; PG8_SCHED;
;             PG8_STAGE(PG8_SB(1, 1), b3 + hstepB, voffB);
;             PG8_WAIT_V(6); PG8_BAR; PG8_MMA(1, 1, At, B1); PG8_BAR;
	s_waitcnt lgkmcnt(7)
	v_mfma_f32_16x16x32_bf16 v[60:63], v[150:153], v[166:169], v[60:63]
	v_mfma_f32_16x16x32_bf16 v[56:59], v[158:161], v[166:169], v[56:59]
	s_waitcnt lgkmcnt(5)
	v_mfma_f32_16x16x32_bf16 v[52:55], v[150:153], v[174:177], v[52:55]
	v_mfma_f32_16x16x32_bf16 v[48:51], v[158:161], v[174:177], v[48:51]
	s_waitcnt lgkmcnt(3)
	v_mfma_f32_16x16x32_bf16 v[36:39], v[150:153], v[182:185], v[36:39]
	v_mfma_f32_16x16x32_bf16 v[32:35], v[158:161], v[182:185], v[32:35]
	s_waitcnt lgkmcnt(1)
	v_mfma_f32_16x16x32_bf16 v[20:23], v[150:153], v[190:193], v[20:23]
	v_mfma_f32_16x16x32_bf16 v[16:19], v[158:161], v[190:193], v[16:19]
	v_mfma_f32_16x16x32_bf16 v[60:63], v[154:157], v[170:173], v[60:63]
	s_add_u32 s22, s22, 0x80080
	s_addc_u32 s23, s23, 0
	v_mfma_f32_16x16x32_bf16 v[56:59], v[162:165], v[170:173], v[56:59]
	s_add_i32 s24, s24, s29
	v_mfma_f32_16x16x32_bf16 v[52:55], v[154:157], v[178:181], v[52:55]
	v_mfma_f32_16x16x32_bf16 v[48:51], v[162:165], v[178:181], v[48:51]
	v_mfma_f32_16x16x32_bf16 v[36:39], v[154:157], v[186:189], v[36:39]
	v_mfma_f32_16x16x32_bf16 v[32:35], v[162:165], v[186:189], v[32:35]
	s_waitcnt lgkmcnt(0)
	v_mfma_f32_16x16x32_bf16 v[20:23], v[154:157], v[198:201], v[20:23]
	s_mov_b32 m0, s24
	v_mfma_f32_16x16x32_bf16 v[16:19], v[162:165], v[198:201], v[16:19]
	s_barrier
	s_setprio 0
	global_load_lds_dwordx4 v132, s[22:23]
	s_add_i32 m0, s24, 0x2000
	s_nop 0
	global_load_lds_dwordx4 v128, s[22:23]
	s_waitcnt vmcnt(6)
	s_setprio 1
	s_barrier
	v_mfma_f32_16x16x32_bf16 v[44:47], v[202:205], v[166:169], v[44:47]
	v_mfma_f32_16x16x32_bf16 v[40:43], v[210:213], v[166:169], v[40:43]
	ds_read_b128 v[150:153], v147
	v_mfma_f32_16x16x32_bf16 v[28:31], v[202:205], v[174:177], v[28:31]
	v_mfma_f32_16x16x32_bf16 v[24:27], v[210:213], v[174:177], v[24:27]
	ds_read_b128 v[154:157], v147 offset:1024
	v_mfma_f32_16x16x32_bf16 v[12:15], v[202:205], v[182:185], v[12:15]
	v_mfma_f32_16x16x32_bf16 v[8:11], v[210:213], v[182:185], v[8:11]
	ds_read_b128 v[158:161], v147 offset:2048
	v_mfma_f32_16x16x32_bf16 v[4:7], v[202:205], v[190:193], v[4:7]
	v_mfma_f32_16x16x32_bf16 v[0:3], v[210:213], v[190:193], v[0:3]
	ds_read_b128 v[162:165], v147 offset:3072
	v_mfma_f32_16x16x32_bf16 v[44:47], v[206:209], v[170:173], v[44:47]
	s_add_i32 s3, s3, 2
	v_mfma_f32_16x16x32_bf16 v[40:43], v[214:217], v[170:173], v[40:43]
	s_add_u32 s52, s52, 0x100
	s_addc_u32 s53, s53, 0
	v_mfma_f32_16x16x32_bf16 v[28:31], v[206:209], v[178:181], v[28:31]
	s_add_u32 s20, s20, 0x100
	s_addc_u32 s21, s21, 0
	v_mfma_f32_16x16x32_bf16 v[24:27], v[214:217], v[178:181], v[24:27]
	s_cmp_gt_u32 s3, 29
	v_mfma_f32_16x16x32_bf16 v[12:15], v[206:209], v[186:189], v[12:15]
	v_mfma_f32_16x16x32_bf16 v[8:11], v[214:217], v[186:189], v[8:11]
	v_mfma_f32_16x16x32_bf16 v[4:7], v[206:209], v[198:201], v[4:7]
	v_mfma_f32_16x16x32_bf16 v[0:3], v[214:217], v[198:201], v[0:3]
	s_barrier
	s_setprio 0
	s_cbranch_scc0 .LBB1_1382
; DI unsigned pack2(float a, float b) { f32x2 v = {a, b}; hwbf16x2 r = __builtin_convertvector(v, hwbf16x2); return __builtin_bit_cast(unsigned, r); }
;     DI const char* a(const Unit& u) const { return (const char*)(A + (size_t)u.pm * BM * lda); }
;     DI const char* a(const Unit& u) const { return (const char*)(A + (size_t)u.pm * BM * 2048 + (u.pn >> 1) * 512); }
;     DI const char* a(const Unit& u) const { return (const char*)((u.pn < 12 ? A1 : A2) + (size_t)u.pm * BM * 512); }
; #define PG8_WAIT_V(n) asm volatile("s_waitcnt vmcnt(" #n ")" ::: "memory")
; #define PG8_BAR __builtin_amdgcn_s_barrier()
;     DI void operator()(const f32x4 (&acc)[2][2][4][2], const Unit& u, int wr, int wc, int fr, int fq) const {
;         bf16_t* O = O1; int ldc = ldc1, pn = u.pn; if (pn >= split) { O = O2; ldc = ldc2; pn -= split; }
;         const int row0 = u.pm * BM + wr * 64 + fr, col0 = pn * BM + wc * 32 + 8 * fq;
; #pragma unroll
;         for (int ai = 0; ai < 2; ++ai)
; #pragma unroll
;             for (int m = 0; m < 4; ++m) { bf16_t* rowp = O + (size_t)(row0 + ai * HALF + m * 16) * ldc + col0;
; #pragma unroll
;                 for (int bj = 0; bj < 2; ++bj) { const f32x4 v0 = acc[ai][bj][m][0], v1 = acc[ai][bj][m][1];
;                     u32x4 o; o[0] = pack2(v0[0], v0[1]); o[1] = pack2(v0[2], v0[3]); o[2] = pack2(v1[0], v1[1]); o[3] = pack2(v1[2], v1[3]);
;                     *(u32x4*)(rowp + bj * HALF) = o; } }
;     }
; template <class Map, class Epi>
; DI void gemm_phase(LAS unsigned char* lds, const Map& MP, const Epi& E, const int nM, const int nN, const int K, const int lda, const int ldb) {
;     ...
;         { int frr = fr, fqq = fq; asm volatile("" : "+v"(frr), "+v"(fqq)); E(acc, cur, wr, wc, frr, fqq); }
;         if (!has_next) break;
; #pragma unroll
;         for (int a = 0; a < 2; ++a)
; #pragma unroll
;             for (int b = 0; b < 2; ++b)
; #pragma unroll
;                 for (int m = 0; m < 4; ++m)
; #pragma unroll
;                     for (int n = 0; n < 2; ++n) acc[a][b][m][n] = (f32x4){0.f, 0.f, 0.f, 0.f};
;         cur = nxt; cA = nA; cB = nB; ++ui;
;     }
;     PG8_WAIT_V(0);
;     if (wr == 0) PG8_BAR;
;     PG8_BAR;
	s_waitcnt lgkmcnt(0)
	s_lshl_b32 s3, s10, 8
	v_mov_b32_e32 v150, v144
	v_mov_b32_e32 v151, v145
	s_add_i32 s3, s3, s37
	v_cvt_pk_bf16_f32 v68, v68, v69
	v_add_u32_e32 v154, s3, v150
	s_lshl_b32 s3, s47, 8
	s_or_b32 s3, s3, s38
	v_lshl_add_u32 v150, v151, 3, s3
	v_ashrrev_i32_e32 v151, 31, v150
	v_lshl_add_u64 v[150:151], v[150:151], 1, s[6:7]
	v_cvt_pk_bf16_f32 v69, v70, v71
	v_cvt_pk_bf16_f32 v70, v64, v65
	v_add_u32_e32 v64, 0x80, v154
	v_mad_i64_i32 v[152:153], s[20:21], v154, s46, v[150:151]
	v_cvt_pk_bf16_f32 v108, v108, v109
	v_cvt_pk_bf16_f32 v109, v110, v111
	v_cvt_pk_bf16_f32 v110, v104, v105
	v_cvt_pk_bf16_f32 v111, v106, v107
	v_add_u32_e32 v104, 16, v154
	v_mad_i64_i32 v[64:65], s[20:21], v64, s46, v[150:151]
	v_cvt_pk_bf16_f32 v44, v44, v45
	v_cvt_pk_bf16_f32 v45, v46, v47
	v_cvt_pk_bf16_f32 v46, v40, v41
	v_cvt_pk_bf16_f32 v47, v42, v43
	v_add_u32_e32 v40, 0x90, v154
	global_store_dwordx4 v[152:153], v[108:111], off offset:256
	v_cvt_pk_bf16_f32 v92, v92, v93
	v_cvt_pk_bf16_f32 v93, v94, v95
	v_mad_i64_i32 v[108:109], s[20:21], v104, s46, v[150:151]
	v_cvt_pk_bf16_f32 v94, v88, v89
	v_cvt_pk_bf16_f32 v95, v90, v91
	v_add_u32_e32 v88, 32, v154
	global_store_dwordx4 v[64:65], v[44:47], off offset:256
	v_cvt_pk_bf16_f32 v28, v28, v29
	v_cvt_pk_bf16_f32 v29, v30, v31
	v_mad_i64_i32 v[44:45], s[20:21], v40, s46, v[150:151]
	v_cvt_pk_bf16_f32 v30, v24, v25
	v_cvt_pk_bf16_f32 v31, v26, v27
	v_add_u32_e32 v24, 0xa0, v154
	global_store_dwordx4 v[108:109], v[92:95], off offset:256
	v_cvt_pk_bf16_f32 v76, v76, v77
	v_cvt_pk_bf16_f32 v77, v78, v79
	v_mad_i64_i32 v[92:93], s[20:21], v88, s46, v[150:151]
	v_cvt_pk_bf16_f32 v78, v72, v73
	v_cvt_pk_bf16_f32 v79, v74, v75
	v_add_u32_e32 v72, 48, v154
	global_store_dwordx4 v[44:45], v[28:31], off offset:256
	v_cvt_pk_bf16_f32 v12, v12, v13
	v_cvt_pk_bf16_f32 v13, v14, v15
	v_mad_i64_i32 v[28:29], s[20:21], v24, s46, v[150:151]
	v_cvt_pk_bf16_f32 v14, v8, v9
	v_cvt_pk_bf16_f32 v15, v10, v11
	v_add_u32_e32 v8, 0xb0, v154
	global_store_dwordx4 v[92:93], v[76:79], off offset:256
	global_store_dwordx4 v[28:29], v[12:15], off offset:256
	v_cvt_pk_bf16_f32 v124, v124, v125
	v_mad_i64_i32 v[76:77], s[20:21], v72, s46, v[150:151]
	v_mad_i64_i32 v[12:13], s[20:21], v8, s46, v[150:151]
	v_cvt_pk_bf16_f32 v125, v126, v127
	v_cvt_pk_bf16_f32 v126, v120, v121
	v_cvt_pk_bf16_f32 v127, v122, v123
	v_cvt_pk_bf16_f32 v104, v116, v117
	v_cvt_pk_bf16_f32 v105, v118, v119
	v_cvt_pk_bf16_f32 v106, v112, v113
	v_cvt_pk_bf16_f32 v107, v114, v115
	v_cvt_pk_bf16_f32 v88, v100, v101
	v_cvt_pk_bf16_f32 v89, v102, v103
	v_cvt_pk_bf16_f32 v90, v96, v97
	v_cvt_pk_bf16_f32 v91, v98, v99
	v_cvt_pk_bf16_f32 v72, v84, v85
	v_cvt_pk_bf16_f32 v73, v86, v87
	v_cvt_pk_bf16_f32 v74, v80, v81
	v_cvt_pk_bf16_f32 v75, v82, v83
	v_cvt_pk_bf16_f32 v71, v66, v67
	v_cvt_pk_bf16_f32 v60, v60, v61
	v_cvt_pk_bf16_f32 v61, v62, v63
	v_cvt_pk_bf16_f32 v62, v56, v57
	v_cvt_pk_bf16_f32 v63, v58, v59
	v_cvt_pk_bf16_f32 v40, v52, v53
	v_cvt_pk_bf16_f32 v41, v54, v55
	v_cvt_pk_bf16_f32 v42, v48, v49
	v_cvt_pk_bf16_f32 v43, v50, v51
	v_cvt_pk_bf16_f32 v24, v36, v37
	v_cvt_pk_bf16_f32 v25, v38, v39
	v_cvt_pk_bf16_f32 v26, v32, v33
	v_cvt_pk_bf16_f32 v27, v34, v35
	v_cvt_pk_bf16_f32 v8, v20, v21
	v_cvt_pk_bf16_f32 v9, v22, v23
	v_cvt_pk_bf16_f32 v10, v16, v17
	v_cvt_pk_bf16_f32 v11, v18, v19
	v_cvt_pk_bf16_f32 v4, v4, v5
	v_cvt_pk_bf16_f32 v5, v6, v7
	v_cvt_pk_bf16_f32 v6, v0, v1
	v_cvt_pk_bf16_f32 v7, v2, v3
	s_and_b64 vcc, exec, s[40:41]
	s_mov_b32 s47, s12
	s_mov_b32 s10, s14
	s_mov_b64 s[20:21], s[18:19]
	s_mov_b64 s[22:23], s[16:17]
	global_store_dwordx4 v[152:153], v[124:127], off
	global_store_dwordx4 v[108:109], v[104:107], off
	global_store_dwordx4 v[92:93], v[88:91], off
	global_store_dwordx4 v[76:77], v[72:75], off
	global_store_dwordx4 v[76:77], v[68:71], off offset:256
	global_store_dwordx4 v[64:65], v[60:63], off
	global_store_dwordx4 v[44:45], v[40:43], off
	global_store_dwordx4 v[28:29], v[24:27], off
	global_store_dwordx4 v[12:13], v[8:11], off
	global_store_dwordx4 v[12:13], v[4:7], off offset:256
	s_cbranch_vccz .LBB1_1379
	s_waitcnt vmcnt(0)
	s_cmpk_gt_u32 s4, 0xff
	s_cbranch_scc1 .LBB1_1386
	s_barrier

; #define PG8_STAGE(bufoff, gbase, voff) do { _Pragma("unroll") for (int _i = 0; _i < 2; ++_i) \
;         __builtin_amdgcn_global_load_lds((const unsigned*)((const char*)(gbase) + (voff)[_i]), (LAS unsigned*)(lds + (bufoff) + ldsw + _i * 8192), 16, 0, 0); } while (0)
; #define PG8_LDA(dst, b, h) do { _Pragma("unroll") for (int m = 0; m < 4; ++m) _Pragma("unroll") for (int k = 0; k < 2; ++k) dst[m][k] = *(const LAS bf16x8*)(lds + PG8_SA(b, h) + aoff + m * 2048 + k * 1024); } while (0)
; #define PG8_LDB(dst, b, h) do { _Pragma("unroll") for (int n = 0; n < 2; ++n) _Pragma("unroll") for (int k = 0; k < 2; ++k) dst[n][k] = *(const LAS bf16x8*)(lds + PG8_SB(b, h) + boff + n * 2048 + k * 1024); } while (0)
; #define PG8_MMA(ai, bj, At, Bt) do { __builtin_amdgcn_s_setprio(1); _Pragma("unroll") for (int m = 0; m < 4; ++m) _Pragma("unroll") for (int n = 0; n < 2; ++n) _Pragma("unroll") for (int k = 0; k < 2; ++k) \
;         acc[ai][bj][m][n] = __builtin_amdgcn_mfma_f32_16x16x32_bf16(Bt[n][k], At[m][k], acc[ai][bj][m][n], 0, 0, 0); __builtin_amdgcn_s_setprio(0); } while (0)
; #define PG8_WAIT_V(n) asm volatile("s_waitcnt vmcnt(" #n ")" ::: "memory")
; #define PG8_WAIT_L(n) asm volatile("s_waitcnt lgkmcnt(" #n ")" ::: "memory")
; #define PG8_BAR __builtin_amdgcn_s_barrier()
; #define PG8_SCHED __builtin_amdgcn_sched_barrier(0)
; template <class Map, class Epi>
; DI void gemm_phase(LAS unsigned char* lds, const Map& MP, const Epi& E, const int nM, const int nN, const int K, const int lda, const int ldb) {
;     ...
;             PG8_LDB(B0, 0, 0); PG8_SCHED; PG8_LDA(At, 0, 0); PG8_STAGE(PG8_SA(1, 1), a1 + hstepA, voffA);
;             PG8_WAIT_L(8); PG8_BAR; PG8_WAIT_L(0); PG8_MMA(0, 0, At, B0); PG8_BAR; PG8_SCHED;
;             PG8_LDB(B1, 0, 1); PG8_STAGE(PG8_SB(0, 0), b2, voffB);
;             PG8_BAR; PG8_WAIT_L(0); PG8_MMA(0, 1, At, B1); PG8_BAR;
;             PG8_LDA(At, 0, 1); PG8_STAGE(PG8_SA(0, 0), a2, voffA);
;             PG8_BAR; PG8_WAIT_L(0); PG8_MMA(1, 0, At, B0); PG8_BAR; PG8_SCHED;
;             PG8_STAGE(PG8_SB(0, 1), b2 + hstepB, voffB);
;             PG8_WAIT_V(6); PG8_BAR; PG8_MMA(1, 1, At, B1); PG8_BAR;
.LBB1_1529:
	s_add_u32 s20, s18, 0xfffe0080
	s_addc_u32 s21, s19, -1
	s_cmp_eq_u32 s3, 4
	s_cselect_b32 s23, s13, s21
	s_cselect_b32 s22, s52, s20
	s_cselect_b32 s21, s53, s56
	s_cselect_b32 s20, s54, s55
	s_add_i32 m0, s11, 0xc000
	ds_read_b128 v[166:169], v148
	ds_read_b128 v[170:173], v148 offset:1024
	ds_read_b128 v[174:177], v148 offset:2048
	ds_read_b128 v[178:181], v148 offset:3072
	ds_read_b128 v[182:185], v148 offset:4096
	ds_read_b128 v[186:189], v148 offset:5120
	ds_read_b128 v[190:193], v148 offset:6144
	ds_read_b128 v[198:201], v148 offset:7168
	global_load_lds_dwordx4 v138, s[18:19]
	s_add_i32 m0, s11, 0xe000
	s_nop 0
	global_load_lds_dwordx4 v136, s[18:19]
	s_waitcnt lgkmcnt(8)
	s_setprio 1
	s_barrier
	s_waitcnt lgkmcnt(7)
	v_mfma_f32_16x16x32_bf16 v[124:127], v[150:153], v[166:169], v[124:127]
	v_mfma_f32_16x16x32_bf16 v[120:123], v[158:161], v[166:169], v[120:123]
	s_waitcnt lgkmcnt(5)
	v_mfma_f32_16x16x32_bf16 v[116:119], v[150:153], v[174:177], v[116:119]
	v_mfma_f32_16x16x32_bf16 v[112:115], v[158:161], v[174:177], v[112:115]
	s_waitcnt lgkmcnt(3)
	v_mfma_f32_16x16x32_bf16 v[100:103], v[150:153], v[182:185], v[100:103]
	v_mfma_f32_16x16x32_bf16 v[96:99], v[158:161], v[182:185], v[96:99]
	s_waitcnt lgkmcnt(1)
	v_mfma_f32_16x16x32_bf16 v[84:87], v[150:153], v[190:193], v[84:87]
	v_mfma_f32_16x16x32_bf16 v[80:83], v[158:161], v[190:193], v[80:83]
	v_mfma_f32_16x16x32_bf16 v[124:127], v[154:157], v[170:173], v[124:127]
	s_add_i32 s57, s47, s31
	v_mfma_f32_16x16x32_bf16 v[120:123], v[162:165], v[170:173], v[120:123]
	v_lshl_add_u64 v[194:195], s[20:21], 0, v[132:133]
	v_mfma_f32_16x16x32_bf16 v[116:119], v[154:157], v[178:181], v[116:119]
	v_lshl_add_u64 v[218:219], s[20:21], 0, v[128:129]
	v_mfma_f32_16x16x32_bf16 v[112:115], v[162:165], v[178:181], v[112:115]
	v_mfma_f32_16x16x32_bf16 v[100:103], v[154:157], v[186:189], v[100:103]
	v_mfma_f32_16x16x32_bf16 v[96:99], v[162:165], v[186:189], v[96:99]
	s_waitcnt lgkmcnt(0)
	v_mfma_f32_16x16x32_bf16 v[84:87], v[154:157], v[198:201], v[84:87]
	s_mov_b32 m0, s57
	v_mfma_f32_16x16x32_bf16 v[80:83], v[162:165], v[198:201], v[80:83]
	s_barrier
	s_setprio 0
	ds_read_b128 v[202:205], v149
	ds_read_b128 v[206:209], v149 offset:1024
	ds_read_b128 v[210:213], v149 offset:2048
	global_load_lds_dwordx4 v[194:195], off
	s_add_i32 m0, s57, 0x2000
	ds_read_b128 v[214:217], v149 offset:3072
	global_load_lds_dwordx4 v[218:219], off
	s_setprio 1
	s_barrier
	s_waitcnt lgkmcnt(3)
	v_mfma_f32_16x16x32_bf16 v[108:111], v[202:205], v[166:169], v[108:111]
	s_waitcnt lgkmcnt(1)
	v_mfma_f32_16x16x32_bf16 v[104:107], v[210:213], v[166:169], v[104:107]
	v_mfma_f32_16x16x32_bf16 v[92:95], v[202:205], v[174:177], v[92:95]
	v_mfma_f32_16x16x32_bf16 v[88:91], v[210:213], v[174:177], v[88:91]
	v_mfma_f32_16x16x32_bf16 v[76:79], v[202:205], v[182:185], v[76:79]
	v_mfma_f32_16x16x32_bf16 v[72:75], v[210:213], v[182:185], v[72:75]
	v_mfma_f32_16x16x32_bf16 v[68:71], v[202:205], v[190:193], v[68:71]
	v_mfma_f32_16x16x32_bf16 v[64:67], v[210:213], v[190:193], v[64:67]
	v_mfma_f32_16x16x32_bf16 v[108:111], v[206:209], v[170:173], v[108:111]
	v_lshl_add_u64 v[222:223], s[22:23], 0, v[130:131]
	s_mov_b32 m0, s11
	s_waitcnt lgkmcnt(0)
	v_mfma_f32_16x16x32_bf16 v[104:107], v[214:217], v[170:173], v[104:107]
	v_lshl_add_u64 v[220:221], s[22:23], 0, v[134:135]
	v_mfma_f32_16x16x32_bf16 v[92:95], v[206:209], v[178:181], v[92:95]
	v_mfma_f32_16x16x32_bf16 v[88:91], v[214:217], v[178:181], v[88:91]
	v_mfma_f32_16x16x32_bf16 v[76:79], v[206:209], v[186:189], v[76:79]
	v_mfma_f32_16x16x32_bf16 v[72:75], v[214:217], v[186:189], v[72:75]
	v_mfma_f32_16x16x32_bf16 v[68:71], v[206:209], v[198:201], v[68:71]
	v_mfma_f32_16x16x32_bf16 v[64:67], v[214:217], v[198:201], v[64:67]
	s_barrier
	s_setprio 0
	ds_read_b128 v[166:169], v148 offset:16384
	ds_read_b128 v[170:173], v148 offset:17408
	ds_read_b128 v[174:177], v148 offset:18432
	ds_read_b128 v[178:181], v148 offset:19456
	ds_read_b128 v[182:185], v148 offset:20480
	ds_read_b128 v[186:189], v148 offset:21504
	ds_read_b128 v[190:193], v148 offset:22528
	global_load_lds_dwordx4 v[220:221], off
	s_mov_b32 m0, s35
	ds_read_b128 v[198:201], v148 offset:23552
	global_load_lds_dwordx4 v[222:223], off
	s_waitcnt vmcnt(10)
	s_setprio 1
	s_barrier
	s_waitcnt lgkmcnt(7)
	v_mfma_f32_16x16x32_bf16 v[60:63], v[150:153], v[166:169], v[60:63]
	v_mfma_f32_16x16x32_bf16 v[56:59], v[158:161], v[166:169], v[56:59]
	s_waitcnt lgkmcnt(5)
	v_mfma_f32_16x16x32_bf16 v[52:55], v[150:153], v[174:177], v[52:55]
	v_mfma_f32_16x16x32_bf16 v[48:51], v[158:161], v[174:177], v[48:51]
	s_waitcnt lgkmcnt(3)
	v_mfma_f32_16x16x32_bf16 v[36:39], v[150:153], v[182:185], v[36:39]
	v_mfma_f32_16x16x32_bf16 v[32:35], v[158:161], v[182:185], v[32:35]
	s_waitcnt lgkmcnt(1)
	v_mfma_f32_16x16x32_bf16 v[20:23], v[150:153], v[190:193], v[20:23]
	v_mfma_f32_16x16x32_bf16 v[16:19], v[158:161], v[190:193], v[16:19]
	v_mfma_f32_16x16x32_bf16 v[60:63], v[154:157], v[170:173], v[60:63]
	s_add_u32 s58, s20, 0x20000
	s_addc_u32 s59, s21, 0
	v_mfma_f32_16x16x32_bf16 v[56:59], v[162:165], v[170:173], v[56:59]
	s_add_i32 s57, s48, s31
	v_mfma_f32_16x16x32_bf16 v[52:55], v[154:157], v[178:181], v[52:55]
	v_mfma_f32_16x16x32_bf16 v[48:51], v[162:165], v[178:181], v[48:51]
	v_mfma_f32_16x16x32_bf16 v[36:39], v[154:157], v[186:189], v[36:39]
	v_mfma_f32_16x16x32_bf16 v[32:35], v[162:165], v[186:189], v[32:35]
	s_waitcnt lgkmcnt(0)
	v_mfma_f32_16x16x32_bf16 v[20:23], v[154:157], v[198:201], v[20:23]
	s_mov_b32 m0, s57
	v_mfma_f32_16x16x32_bf16 v[16:19], v[162:165], v[198:201], v[16:19]
	s_barrier
; #define PG8_STAGE(bufoff, gbase, voff) do { _Pragma("unroll") for (int _i = 0; _i < 2; ++_i) \
;         __builtin_amdgcn_global_load_lds((const unsigned*)((const char*)(gbase) + (voff)[_i]), (LAS unsigned*)(lds + (bufoff) + ldsw + _i * 8192), 16, 0, 0); } while (0)
; #define PG8_LDA(dst, b, h) do { _Pragma("unroll") for (int m = 0; m < 4; ++m) _Pragma("unroll") for (int k = 0; k < 2; ++k) dst[m][k] = *(const LAS bf16x8*)(lds + PG8_SA(b, h) + aoff + m * 2048 + k * 1024); } while (0)
; #define PG8_LDB(dst, b, h) do { _Pragma("unroll") for (int n = 0; n < 2; ++n) _Pragma("unroll") for (int k = 0; k < 2; ++k) dst[n][k] = *(const LAS bf16x8*)(lds + PG8_SB(b, h) + boff + n * 2048 + k * 1024); } while (0)
; #define PG8_MMA(ai, bj, At, Bt) do { __builtin_amdgcn_s_setprio(1); _Pragma("unroll") for (int m = 0; m < 4; ++m) _Pragma("unroll") for (int n = 0; n < 2; ++n) _Pragma("unroll") for (int k = 0; k < 2; ++k) \
;         acc[ai][bj][m][n] = __builtin_amdgcn_mfma_f32_16x16x32_bf16(Bt[n][k], At[m][k], acc[ai][bj][m][n], 0, 0, 0); __builtin_amdgcn_s_setprio(0); } while (0)
; #define PG8_WAIT_V(n) asm volatile("s_waitcnt vmcnt(" #n ")" ::: "memory")
; #define PG8_WAIT_L(n) asm volatile("s_waitcnt lgkmcnt(" #n ")" ::: "memory")
; #define PG8_BAR __builtin_amdgcn_s_barrier()
; #define PG8_SCHED __builtin_amdgcn_sched_barrier(0)
; template <class Map, class Epi>
; DI void gemm_phase(LAS unsigned char* lds, const Map& MP, const Epi& E, const int nM, const int nN, const int K, const int lda, const int ldb) {
;     ...
;             PG8_LDA(At, 0, 1); PG8_STAGE(PG8_SA(0, 0), a2, voffA);
;             PG8_BAR; PG8_WAIT_L(0); PG8_MMA(1, 0, At, B0); PG8_BAR; PG8_SCHED;
;             PG8_STAGE(PG8_SB(0, 1), b2 + hstepB, voffB);
;             PG8_WAIT_V(6); PG8_BAR; PG8_MMA(1, 1, At, B1); PG8_BAR;
;             PG8_LDB(B0, 1, 0); PG8_SCHED; PG8_LDA(At, 1, 0); PG8_STAGE(PG8_SA(0, 1), a2 + hstepA, voffA);
;             PG8_WAIT_L(8); PG8_BAR; PG8_WAIT_L(0); PG8_MMA(0, 0, At, B0); PG8_BAR; PG8_SCHED;
;             PG8_LDB(B1, 1, 1); PG8_STAGE(PG8_SB(1, 0), b3, voffB);
;             PG8_BAR; PG8_WAIT_L(0); PG8_MMA(0, 1, At, B1); PG8_BAR;
;             PG8_LDA(At, 1, 1); PG8_STAGE(PG8_SA(1, 0), a3, voffA);
	s_setprio 0
	global_load_lds_dwordx4 v132, s[58:59]
	s_add_i32 m0, s57, 0x2000
	s_nop 0
	global_load_lds_dwordx4 v128, s[58:59]
	s_waitcnt vmcnt(6)
	s_setprio 1
	s_barrier
	v_mfma_f32_16x16x32_bf16 v[44:47], v[202:205], v[166:169], v[44:47]
	v_mfma_f32_16x16x32_bf16 v[40:43], v[210:213], v[166:169], v[40:43]
	s_add_i32 s57, 0, 0x18000
	v_add_u32_e32 v162, s57, v146
	ds_read_b128 v[150:153], v162
	v_mfma_f32_16x16x32_bf16 v[28:31], v[202:205], v[174:177], v[28:31]
	v_mfma_f32_16x16x32_bf16 v[24:27], v[210:213], v[174:177], v[24:27]
	ds_read_b128 v[154:157], v162 offset:1024
	v_mfma_f32_16x16x32_bf16 v[12:15], v[202:205], v[182:185], v[12:15]
	v_mfma_f32_16x16x32_bf16 v[8:11], v[210:213], v[182:185], v[8:11]
	ds_read_b128 v[158:161], v162 offset:2048
	v_mfma_f32_16x16x32_bf16 v[4:7], v[202:205], v[190:193], v[4:7]
	v_mfma_f32_16x16x32_bf16 v[0:3], v[210:213], v[190:193], v[0:3]
	ds_read_b128 v[162:165], v162 offset:3072
	v_mfma_f32_16x16x32_bf16 v[44:47], v[206:209], v[170:173], v[44:47]
	s_add_u32 s22, s22, 0x20000
	s_addc_u32 s23, s23, 0
	v_mfma_f32_16x16x32_bf16 v[40:43], v[214:217], v[170:173], v[40:43]
	v_mfma_f32_16x16x32_bf16 v[28:31], v[206:209], v[178:181], v[28:31]
	v_mfma_f32_16x16x32_bf16 v[24:27], v[214:217], v[178:181], v[24:27]
	v_mfma_f32_16x16x32_bf16 v[12:15], v[206:209], v[186:189], v[12:15]
	v_mfma_f32_16x16x32_bf16 v[8:11], v[214:217], v[186:189], v[8:11]
	v_mfma_f32_16x16x32_bf16 v[4:7], v[206:209], v[198:201], v[4:7]
	s_mov_b32 m0, s36
	v_mfma_f32_16x16x32_bf16 v[0:3], v[214:217], v[198:201], v[0:3]
	s_barrier
	s_setprio 0
	ds_read_b128 v[166:169], v148 offset:32768
	ds_read_b128 v[170:173], v148 offset:33792
	ds_read_b128 v[174:177], v148 offset:34816
	ds_read_b128 v[178:181], v148 offset:35840
	ds_read_b128 v[182:185], v148 offset:36864
	ds_read_b128 v[186:189], v148 offset:37888
	ds_read_b128 v[190:193], v148 offset:38912
	global_load_lds_dwordx4 v134, s[22:23]
	s_mov_b32 m0, s37
	ds_read_b128 v[198:201], v148 offset:39936
	global_load_lds_dwordx4 v130, s[22:23]
	s_waitcnt lgkmcnt(8)
	s_setprio 1
	s_barrier
	s_waitcnt lgkmcnt(7)
	v_mfma_f32_16x16x32_bf16 v[124:127], v[150:153], v[166:169], v[124:127]
	v_mfma_f32_16x16x32_bf16 v[120:123], v[158:161], v[166:169], v[120:123]
	s_waitcnt lgkmcnt(5)
	v_mfma_f32_16x16x32_bf16 v[116:119], v[150:153], v[174:177], v[116:119]
	v_mfma_f32_16x16x32_bf16 v[112:115], v[158:161], v[174:177], v[112:115]
	s_waitcnt lgkmcnt(3)
	v_mfma_f32_16x16x32_bf16 v[100:103], v[150:153], v[182:185], v[100:103]
	v_mfma_f32_16x16x32_bf16 v[96:99], v[158:161], v[182:185], v[96:99]
	s_waitcnt lgkmcnt(1)
	v_mfma_f32_16x16x32_bf16 v[84:87], v[150:153], v[190:193], v[84:87]
	v_mfma_f32_16x16x32_bf16 v[80:83], v[158:161], v[190:193], v[80:83]
	v_mfma_f32_16x16x32_bf16 v[124:127], v[154:157], v[170:173], v[124:127]
	s_add_i32 s22, 0, 0x1c000
	v_mfma_f32_16x16x32_bf16 v[120:123], v[162:165], v[170:173], v[120:123]
	s_add_i32 s23, s57, s31
	v_mfma_f32_16x16x32_bf16 v[116:119], v[154:157], v[178:181], v[116:119]
	v_add_u32_e32 v196, s22, v146
	v_mfma_f32_16x16x32_bf16 v[112:115], v[162:165], v[178:181], v[112:115]
	v_lshl_add_u64 v[194:195], v[194:195], 0, s[8:9]
	v_mfma_f32_16x16x32_bf16 v[100:103], v[154:157], v[186:189], v[100:103]
	v_mfma_f32_16x16x32_bf16 v[96:99], v[162:165], v[186:189], v[96:99]
	s_waitcnt lgkmcnt(0)
	v_mfma_f32_16x16x32_bf16 v[84:87], v[154:157], v[198:201], v[84:87]
	s_mov_b32 m0, s23
	v_mfma_f32_16x16x32_bf16 v[80:83], v[162:165], v[198:201], v[80:83]
	s_barrier
	s_setprio 0
	ds_read_b128 v[202:205], v196
	ds_read_b128 v[206:209], v196 offset:1024
	ds_read_b128 v[210:213], v196 offset:2048
	global_load_lds_dwordx4 v[194:195], off
	v_lshl_add_u64 v[194:195], v[218:219], 0, s[8:9]
	s_add_i32 m0, s23, 0x2000
	ds_read_b128 v[214:217], v196 offset:3072
	global_load_lds_dwordx4 v[194:195], off
	s_setprio 1
	s_barrier
	s_waitcnt lgkmcnt(3)
	v_mfma_f32_16x16x32_bf16 v[108:111], v[202:205], v[166:169], v[108:111]
	s_waitcnt lgkmcnt(1)
	v_mfma_f32_16x16x32_bf16 v[104:107], v[210:213], v[166:169], v[104:107]
	v_mfma_f32_16x16x32_bf16 v[92:95], v[202:205], v[174:177], v[92:95]
	v_mfma_f32_16x16x32_bf16 v[88:91], v[210:213], v[174:177], v[88:91]
	v_mfma_f32_16x16x32_bf16 v[76:79], v[202:205], v[182:185], v[76:79]
	v_mfma_f32_16x16x32_bf16 v[72:75], v[210:213], v[182:185], v[72:75]
	v_mfma_f32_16x16x32_bf16 v[68:71], v[202:205], v[190:193], v[68:71]
	v_mfma_f32_16x16x32_bf16 v[64:67], v[210:213], v[190:193], v[64:67]
	v_mfma_f32_16x16x32_bf16 v[108:111], v[206:209], v[170:173], v[108:111]
	s_mov_b32 m0, s43
	s_waitcnt lgkmcnt(0)
	v_mfma_f32_16x16x32_bf16 v[104:107], v[214:217], v[170:173], v[104:107]
	v_lshl_add_u64 v[194:195], v[220:221], 0, s[8:9]
	v_mfma_f32_16x16x32_bf16 v[92:95], v[206:209], v[178:181], v[92:95]
	v_mfma_f32_16x16x32_bf16 v[88:91], v[214:217], v[178:181], v[88:91]
	v_mfma_f32_16x16x32_bf16 v[76:79], v[206:209], v[186:189], v[76:79]
	v_mfma_f32_16x16x32_bf16 v[72:75], v[214:217], v[186:189], v[72:75]
	v_mfma_f32_16x16x32_bf16 v[68:71], v[206:209], v[198:201], v[68:71]
	v_mfma_f32_16x16x32_bf16 v[64:67], v[214:217], v[198:201], v[64:67]
	s_barrier
	s_setprio 0
	ds_read_b128 v[166:169], v148 offset:49152
	ds_read_b128 v[170:173], v148 offset:50176
	ds_read_b128 v[174:177], v148 offset:51200
	ds_read_b128 v[178:181], v148 offset:52224
	ds_read_b128 v[182:185], v148 offset:53248
	ds_read_b128 v[186:189], v148 offset:54272
	ds_read_b128 v[190:193], v148 offset:55296
	global_load_lds_dwordx4 v[194:195], off
	v_lshl_add_u64 v[194:195], v[222:223], 0, s[8:9]
	s_mov_b32 m0, s44
	ds_read_b128 v[198:201], v148 offset:56320
	global_load_lds_dwordx4 v[194:195], off
	s_waitcnt vmcnt(10)
	s_setprio 1
	s_barrier
; #define PG8_STAGE(bufoff, gbase, voff) do { _Pragma("unroll") for (int _i = 0; _i < 2; ++_i) \
;         __builtin_amdgcn_global_load_lds((const unsigned*)((const char*)(gbase) + (voff)[_i]), (LAS unsigned*)(lds + (bufoff) + ldsw + _i * 8192), 16, 0, 0); } while (0)
; #define PG8_LDA(dst, b, h) do { _Pragma("unroll") for (int m = 0; m < 4; ++m) _Pragma("unroll") for (int k = 0; k < 2; ++k) dst[m][k] = *(const LAS bf16x8*)(lds + PG8_SA(b, h) + aoff + m * 2048 + k * 1024); } while (0)
; #define PG8_LDB(dst, b, h) do { _Pragma("unroll") for (int n = 0; n < 2; ++n) _Pragma("unroll") for (int k = 0; k < 2; ++k) dst[n][k] = *(const LAS bf16x8*)(lds + PG8_SB(b, h) + boff + n * 2048 + k * 1024); } while (0)
; #define PG8_MMA(ai, bj, At, Bt) do { __builtin_amdgcn_s_setprio(1); _Pragma("unroll") for (int m = 0; m < 4; ++m) _Pragma("unroll") for (int n = 0; n < 2; ++n) _Pragma("unroll") for (int k = 0; k < 2; ++k) \
;         acc[ai][bj][m][n] = __builtin_amdgcn_mfma_f32_16x16x32_bf16(Bt[n][k], At[m][k], acc[ai][bj][m][n], 0, 0, 0); __builtin_amdgcn_s_setprio(0); } while (0)
; #define PG8_WAIT_V(n) asm volatile("s_waitcnt vmcnt(" #n ")" ::: "memory")
; #define PG8_WAIT_L(n) asm volatile("s_waitcnt lgkmcnt(" #n ")" ::: "memory")
; #define PG8_BAR __builtin_amdgcn_s_barrier()
; #define PG8_SCHED __builtin_amdgcn_sched_barrier(0)
; template <class Map, class Epi>
; DI void gemm_phase(LAS unsigned char* lds, const Map& MP, const Epi& E, const int nM, const int nN, const int K, const int lda, const int ldb) {
;     ...
;             PG8_LDB(B0, 0, 0); PG8_SCHED; PG8_LDA(At, 0, 0); PG8_STAGE(PG8_SA(1, 1), a1 + hstepA, voffA);
;     ...
;             PG8_LDA(At, 1, 1); PG8_STAGE(PG8_SA(1, 0), a3, voffA);
;             PG8_BAR; PG8_WAIT_L(0); PG8_MMA(1, 0, At, B0); PG8_BAR; PG8_SCHED;
;             PG8_STAGE(PG8_SB(1, 1), b3 + hstepB, voffB);
;             PG8_WAIT_V(6); PG8_BAR; PG8_MMA(1, 1, At, B1); PG8_BAR;
	s_waitcnt lgkmcnt(7)
	v_mfma_f32_16x16x32_bf16 v[60:63], v[150:153], v[166:169], v[60:63]
	v_mfma_f32_16x16x32_bf16 v[56:59], v[158:161], v[166:169], v[56:59]
	s_waitcnt lgkmcnt(5)
	v_mfma_f32_16x16x32_bf16 v[52:55], v[150:153], v[174:177], v[52:55]
	v_mfma_f32_16x16x32_bf16 v[48:51], v[158:161], v[174:177], v[48:51]
	s_waitcnt lgkmcnt(3)
	v_mfma_f32_16x16x32_bf16 v[36:39], v[150:153], v[182:185], v[36:39]
	v_mfma_f32_16x16x32_bf16 v[32:35], v[158:161], v[182:185], v[32:35]
	s_waitcnt lgkmcnt(1)
	v_mfma_f32_16x16x32_bf16 v[20:23], v[150:153], v[190:193], v[20:23]
	v_mfma_f32_16x16x32_bf16 v[16:19], v[158:161], v[190:193], v[16:19]
	v_mfma_f32_16x16x32_bf16 v[60:63], v[154:157], v[170:173], v[60:63]
	s_add_u32 s20, s20, 0x20080
	s_addc_u32 s21, s21, 0
	v_mfma_f32_16x16x32_bf16 v[56:59], v[162:165], v[170:173], v[56:59]
	s_add_i32 s22, s22, s31
	v_mfma_f32_16x16x32_bf16 v[52:55], v[154:157], v[178:181], v[52:55]
	v_mfma_f32_16x16x32_bf16 v[48:51], v[162:165], v[178:181], v[48:51]
	v_mfma_f32_16x16x32_bf16 v[36:39], v[154:157], v[186:189], v[36:39]
	v_mfma_f32_16x16x32_bf16 v[32:35], v[162:165], v[186:189], v[32:35]
	s_waitcnt lgkmcnt(0)
	v_mfma_f32_16x16x32_bf16 v[20:23], v[154:157], v[198:201], v[20:23]
	s_mov_b32 m0, s22
	v_mfma_f32_16x16x32_bf16 v[16:19], v[162:165], v[198:201], v[16:19]
	s_barrier
	s_setprio 0
	global_load_lds_dwordx4 v132, s[20:21]
	s_add_i32 m0, s22, 0x2000
	s_nop 0
	global_load_lds_dwordx4 v128, s[20:21]
	s_waitcnt vmcnt(6)
	s_setprio 1
	s_barrier
	v_mfma_f32_16x16x32_bf16 v[44:47], v[202:205], v[166:169], v[44:47]
	v_mfma_f32_16x16x32_bf16 v[40:43], v[210:213], v[166:169], v[40:43]
	ds_read_b128 v[150:153], v147
	v_mfma_f32_16x16x32_bf16 v[28:31], v[202:205], v[174:177], v[28:31]
	v_mfma_f32_16x16x32_bf16 v[24:27], v[210:213], v[174:177], v[24:27]
	ds_read_b128 v[154:157], v147 offset:1024
	v_mfma_f32_16x16x32_bf16 v[12:15], v[202:205], v[182:185], v[12:15]
	v_mfma_f32_16x16x32_bf16 v[8:11], v[210:213], v[182:185], v[8:11]
	ds_read_b128 v[158:161], v147 offset:2048
	v_mfma_f32_16x16x32_bf16 v[4:7], v[202:205], v[190:193], v[4:7]
	v_mfma_f32_16x16x32_bf16 v[0:3], v[210:213], v[190:193], v[0:3]
	ds_read_b128 v[162:165], v147 offset:3072
	v_mfma_f32_16x16x32_bf16 v[44:47], v[206:209], v[170:173], v[44:47]
	s_add_i32 s3, s3, 2
	v_mfma_f32_16x16x32_bf16 v[40:43], v[214:217], v[170:173], v[40:43]
	s_add_u32 s55, s55, 0x100
	s_addc_u32 s56, s56, 0
	v_mfma_f32_16x16x32_bf16 v[28:31], v[206:209], v[178:181], v[28:31]
	s_add_u32 s18, s18, 0x100
	s_addc_u32 s19, s19, 0
	v_mfma_f32_16x16x32_bf16 v[24:27], v[214:217], v[178:181], v[24:27]
	s_cmp_gt_u32 s3, 5
	v_mfma_f32_16x16x32_bf16 v[12:15], v[206:209], v[186:189], v[12:15]
	v_mfma_f32_16x16x32_bf16 v[8:11], v[214:217], v[186:189], v[8:11]
	v_mfma_f32_16x16x32_bf16 v[4:7], v[206:209], v[198:201], v[4:7]
	v_mfma_f32_16x16x32_bf16 v[0:3], v[214:217], v[198:201], v[0:3]
	s_barrier
	s_setprio 0
	s_cbranch_scc0 .LBB1_1529
; DI unsigned pack2(float a, float b) { f32x2 v = {a, b}; hwbf16x2 r = __builtin_convertvector(v, hwbf16x2); return __builtin_bit_cast(unsigned, r); }
;     DI void operator()(const f32x4 (&acc)[2][2][4][2], const Unit& u, int wr, int wc, int fr, int fq) const {
;         bf16_t* O = O1; int ldc = ldc1, pn = u.pn; if (pn >= split) { O = O2; ldc = ldc2; pn -= split; }
;         const int row0 = u.pm * BM + wr * 64 + fr, col0 = pn * BM + wc * 32 + 8 * fq;
; #pragma unroll
;         for (int ai = 0; ai < 2; ++ai)
; #pragma unroll
;             for (int m = 0; m < 4; ++m) { bf16_t* rowp = O + (size_t)(row0 + ai * HALF + m * 16) * ldc + col0;
; #pragma unroll
;                 for (int bj = 0; bj < 2; ++bj) { const f32x4 v0 = acc[ai][bj][m][0], v1 = acc[ai][bj][m][1];
;                     u32x4 o; o[0] = pack2(v0[0], v0[1]); o[1] = pack2(v0[2], v0[3]); o[2] = pack2(v1[0], v1[1]); o[3] = pack2(v1[2], v1[3]);
;                     *(u32x4*)(rowp + bj * HALF) = o; } }
;     }
	s_waitcnt lgkmcnt(0)
	s_cmp_lt_i32 s45, 12
	s_cselect_b32 s3, 0, -12
	s_mov_b32 s13, 0x1e510000
	s_movk_i32 s18, 0xc00
	s_cselect_b32 s13, s13, 0x2a510000
	s_cselect_b32 s20, s18, 0x1000
	s_add_i32 s3, s3, s45
	s_add_u32 s18, s6, s13
	v_mov_b32_e32 v150, v144
	v_mov_b32_e32 v151, v145
	s_addc_u32 s19, s7, 0
	s_lshl_b32 s10, s10, 8
	s_lshl_b32 s3, s3, 8
	s_add_i32 s10, s10, s39
	s_or_b32 s3, s3, s42
	v_add_u32_e32 v154, s10, v150
	v_lshl_add_u32 v150, v151, 3, s3
	v_ashrrev_i32_e32 v151, 31, v150
	v_lshl_add_u64 v[150:151], v[150:151], 1, s[18:19]
	v_mad_i64_i32 v[152:153], s[18:19], s20, v154, 0
	v_cvt_pk_bf16_f32 v108, v108, v109
	v_cvt_pk_bf16_f32 v109, v110, v111
	v_cvt_pk_bf16_f32 v110, v104, v105
	v_add_u32_e32 v104, 16, v154
	v_lshl_add_u64 v[152:153], v[152:153], 1, v[150:151]
	v_cvt_pk_bf16_f32 v111, v106, v107
	v_mad_i64_i32 v[104:105], s[18:19], s20, v104, 0
	v_cvt_pk_bf16_f32 v92, v92, v93
	v_cvt_pk_bf16_f32 v93, v94, v95
	v_cvt_pk_bf16_f32 v94, v88, v89
	v_add_u32_e32 v88, 32, v154
	v_cvt_pk_bf16_f32 v124, v124, v125
	v_cvt_pk_bf16_f32 v125, v126, v127
	v_cvt_pk_bf16_f32 v126, v120, v121
	v_cvt_pk_bf16_f32 v127, v122, v123
	global_store_dwordx4 v[152:153], v[108:111], off offset:256
	v_cvt_pk_bf16_f32 v95, v90, v91
	v_mad_i64_i32 v[88:89], s[18:19], s20, v88, 0
	v_lshl_add_u64 v[108:109], v[104:105], 1, v[150:151]
	v_cvt_pk_bf16_f32 v76, v76, v77
	v_cvt_pk_bf16_f32 v77, v78, v79
	v_cvt_pk_bf16_f32 v78, v72, v73
	v_add_u32_e32 v72, 48, v154
	v_cvt_pk_bf16_f32 v68, v68, v69
	v_cvt_pk_bf16_f32 v69, v70, v71
	v_cvt_pk_bf16_f32 v70, v64, v65
	v_add_u32_e32 v64, 0x80, v154
	global_store_dwordx4 v[152:153], v[124:127], off
	v_cvt_pk_bf16_f32 v104, v116, v117
	v_cvt_pk_bf16_f32 v105, v118, v119
	v_cvt_pk_bf16_f32 v106, v112, v113
	v_cvt_pk_bf16_f32 v107, v114, v115
	global_store_dwordx4 v[108:109], v[92:95], off offset:256
	v_cvt_pk_bf16_f32 v79, v74, v75
	v_mad_i64_i32 v[72:73], s[18:19], s20, v72, 0
	v_lshl_add_u64 v[92:93], v[88:89], 1, v[150:151]
	v_mad_i64_i32 v[64:65], s[18:19], s20, v64, 0
	v_cvt_pk_bf16_f32 v44, v44, v45
	v_cvt_pk_bf16_f32 v45, v46, v47
	v_cvt_pk_bf16_f32 v46, v40, v41
	v_add_u32_e32 v40, 0x90, v154
	global_store_dwordx4 v[108:109], v[104:107], off
	v_cvt_pk_bf16_f32 v88, v100, v101
	v_cvt_pk_bf16_f32 v89, v102, v103
	v_cvt_pk_bf16_f32 v90, v96, v97
	v_cvt_pk_bf16_f32 v91, v98, v99
	global_store_dwordx4 v[92:93], v[76:79], off offset:256
	v_cvt_pk_bf16_f32 v74, v80, v81
	v_cvt_pk_bf16_f32 v75, v82, v83
	v_lshl_add_u64 v[76:77], v[72:73], 1, v[150:151]
	v_cvt_pk_bf16_f32 v72, v84, v85
	v_cvt_pk_bf16_f32 v73, v86, v87
	v_cvt_pk_bf16_f32 v71, v66, v67
	v_lshl_add_u64 v[64:65], v[64:65], 1, v[150:151]
	v_cvt_pk_bf16_f32 v47, v42, v43
	v_mad_i64_i32 v[40:41], s[18:19], s20, v40, 0
	v_cvt_pk_bf16_f32 v28, v28, v29
	v_cvt_pk_bf16_f32 v29, v30, v31
	v_cvt_pk_bf16_f32 v30, v24, v25
	v_add_u32_e32 v24, 0xa0, v154
	global_store_dwordx4 v[92:93], v[88:91], off
	global_store_dwordx4 v[76:77], v[72:75], off
	global_store_dwordx4 v[76:77], v[68:71], off offset:256
	v_cvt_pk_bf16_f32 v60, v60, v61
	v_cvt_pk_bf16_f32 v61, v62, v63
	v_cvt_pk_bf16_f32 v62, v56, v57
	v_cvt_pk_bf16_f32 v63, v58, v59
	global_store_dwordx4 v[64:65], v[44:47], off offset:256
	v_cvt_pk_bf16_f32 v31, v26, v27
	v_mad_i64_i32 v[24:25], s[18:19], s20, v24, 0
	v_lshl_add_u64 v[44:45], v[40:41], 1, v[150:151]
	v_cvt_pk_bf16_f32 v12, v12, v13
	v_cvt_pk_bf16_f32 v13, v14, v15
	v_cvt_pk_bf16_f32 v14, v8, v9
	v_add_u32_e32 v8, 0xb0, v154
	global_store_dwordx4 v[64:65], v[60:63], off
	v_cvt_pk_bf16_f32 v40, v52, v53
	v_cvt_pk_bf16_f32 v41, v54, v55
	v_cvt_pk_bf16_f32 v42, v48, v49
	v_cvt_pk_bf16_f32 v43, v50, v51
	global_store_dwordx4 v[44:45], v[28:31], off offset:256
	v_cvt_pk_bf16_f32 v15, v10, v11
	v_mad_i64_i32 v[8:9], s[18:19], s20, v8, 0
	v_lshl_add_u64 v[28:29], v[24:25], 1, v[150:151]
	global_store_dwordx4 v[44:45], v[40:43], off
	v_cvt_pk_bf16_f32 v24, v36, v37
	v_cvt_pk_bf16_f32 v25, v38, v39
	v_cvt_pk_bf16_f32 v26, v32, v33
	v_cvt_pk_bf16_f32 v27, v34, v35
	global_store_dwordx4 v[28:29], v[12:15], off offset:256
	v_cvt_pk_bf16_f32 v10, v16, v17
	v_cvt_pk_bf16_f32 v11, v18, v19
	v_lshl_add_u64 v[12:13], v[8:9], 1, v[150:151]
	v_cvt_pk_bf16_f32 v8, v20, v21
	v_cvt_pk_bf16_f32 v9, v22, v23
	v_cvt_pk_bf16_f32 v4, v4, v5
	v_cvt_pk_bf16_f32 v5, v6, v7
	v_cvt_pk_bf16_f32 v6, v0, v1
	v_cvt_pk_bf16_f32 v7, v2, v3
	s_and_b64 vcc, exec, s[40:41]
	s_mov_b32 s45, s49
	s_mov_b32 s10, s12
	s_mov_b64 s[18:19], s[16:17]
	s_mov_b64 s[20:21], s[14:15]
	global_store_dwordx4 v[28:29], v[24:27], off
	global_store_dwordx4 v[12:13], v[8:11], off
	global_store_dwordx4 v[12:13], v[4:7], off offset:256
	s_cbranch_vccz .LBB1_1526
	s_waitcnt vmcnt(0)
	s_cmpk_gt_u32 s4, 0xff
	s_cbranch_scc1 .LBB1_1533
	s_barrier

; #define PG8_STAGE(bufoff, gbase, voff) do { _Pragma("unroll") for (int _i = 0; _i < 2; ++_i) \
;         __builtin_amdgcn_global_load_lds((const unsigned*)((const char*)(gbase) + (voff)[_i]), (LAS unsigned*)(lds + (bufoff) + ldsw + _i * 8192), 16, 0, 0); } while (0)
; #define PG8_LDA(dst, b, h) do { _Pragma("unroll") for (int m = 0; m < 4; ++m) _Pragma("unroll") for (int k = 0; k < 2; ++k) dst[m][k] = *(const LAS bf16x8*)(lds + PG8_SA(b, h) + aoff + m * 2048 + k * 1024); } while (0)
; #define PG8_LDB(dst, b, h) do { _Pragma("unroll") for (int n = 0; n < 2; ++n) _Pragma("unroll") for (int k = 0; k < 2; ++k) dst[n][k] = *(const LAS bf16x8*)(lds + PG8_SB(b, h) + boff + n * 2048 + k * 1024); } while (0)
; #define PG8_MMA(ai, bj, At, Bt) do { __builtin_amdgcn_s_setprio(1); _Pragma("unroll") for (int m = 0; m < 4; ++m) _Pragma("unroll") for (int n = 0; n < 2; ++n) _Pragma("unroll") for (int k = 0; k < 2; ++k) \
;         acc[ai][bj][m][n] = __builtin_amdgcn_mfma_f32_16x16x32_bf16(Bt[n][k], At[m][k], acc[ai][bj][m][n], 0, 0, 0); __builtin_amdgcn_s_setprio(0); } while (0)
; #define PG8_WAIT_V(n) asm volatile("s_waitcnt vmcnt(" #n ")" ::: "memory")
; #define PG8_WAIT_L(n) asm volatile("s_waitcnt lgkmcnt(" #n ")" ::: "memory")
; #define PG8_BAR __builtin_amdgcn_s_barrier()
; #define PG8_SCHED __builtin_amdgcn_sched_barrier(0)
; template <class Map, class Epi>
; DI void gemm_phase(LAS unsigned char* lds, const Map& MP, const Epi& E, const int nM, const int nN, const int K, const int lda, const int ldb) {
;     ...
;             PG8_LDB(B0, 0, 0); PG8_SCHED; PG8_LDA(At, 0, 0); PG8_STAGE(PG8_SA(1, 1), a1 + hstepA, voffA);
;             PG8_WAIT_L(8); PG8_BAR; PG8_WAIT_L(0); PG8_MMA(0, 0, At, B0); PG8_BAR; PG8_SCHED;
;             PG8_LDB(B1, 0, 1); PG8_STAGE(PG8_SB(0, 0), b2, voffB);
;             PG8_BAR; PG8_WAIT_L(0); PG8_MMA(0, 1, At, B1); PG8_BAR;
;             PG8_LDA(At, 0, 1); PG8_STAGE(PG8_SA(0, 0), a2, voffA);
;             PG8_BAR; PG8_WAIT_L(0); PG8_MMA(1, 0, At, B0); PG8_BAR; PG8_SCHED;
;             PG8_STAGE(PG8_SB(0, 1), b2 + hstepB, voffB);
;             PG8_WAIT_V(6); PG8_BAR; PG8_MMA(1, 1, At, B1); PG8_BAR;
.LBB1_1764:
	s_add_u32 s12, s10, 0xfff80080
	s_addc_u32 s13, s11, -1
	s_cmp_eq_u32 s3, 28
	s_cselect_b32 s15, s37, s13
	s_cselect_b32 s14, s38, s12
	s_cselect_b32 s13, s39, s48
	s_cselect_b32 s12, s45, s47
	s_add_i32 m0, s24, 0xc000
	ds_read_b128 v[168:171], v150
	ds_read_b128 v[172:175], v150 offset:1024
	ds_read_b128 v[176:179], v150 offset:2048
	ds_read_b128 v[180:183], v150 offset:3072
	ds_read_b128 v[184:187], v150 offset:4096
	ds_read_b128 v[188:191], v150 offset:5120
	ds_read_b128 v[192:195], v150 offset:6144
	ds_read_b128 v[198:201], v150 offset:7168
	global_load_lds_dwordx4 v138, s[10:11]
	s_add_i32 m0, s24, 0xe000
	s_nop 0
	global_load_lds_dwordx4 v136, s[10:11]
	s_waitcnt lgkmcnt(8)
	s_setprio 1
	s_barrier
	s_waitcnt lgkmcnt(7)
	v_mfma_f32_16x16x32_bf16 v[124:127], v[152:155], v[168:171], v[124:127]
	v_mfma_f32_16x16x32_bf16 v[120:123], v[160:163], v[168:171], v[120:123]
	s_waitcnt lgkmcnt(5)
	v_mfma_f32_16x16x32_bf16 v[108:111], v[152:155], v[176:179], v[108:111]
	v_mfma_f32_16x16x32_bf16 v[104:107], v[160:163], v[176:179], v[104:107]
	s_waitcnt lgkmcnt(3)
	v_mfma_f32_16x16x32_bf16 v[92:95], v[152:155], v[184:187], v[92:95]
	v_mfma_f32_16x16x32_bf16 v[88:91], v[160:163], v[184:187], v[88:91]
	s_waitcnt lgkmcnt(1)
	v_mfma_f32_16x16x32_bf16 v[76:79], v[152:155], v[192:195], v[76:79]
	v_mfma_f32_16x16x32_bf16 v[72:75], v[160:163], v[192:195], v[72:75]
	v_mfma_f32_16x16x32_bf16 v[124:127], v[156:159], v[172:175], v[124:127]
	s_add_i32 s49, s35, s22
	v_mfma_f32_16x16x32_bf16 v[120:123], v[164:167], v[172:175], v[120:123]
	v_lshl_add_u64 v[144:145], s[12:13], 0, v[132:133]
	v_mfma_f32_16x16x32_bf16 v[108:111], v[156:159], v[180:183], v[108:111]
	v_lshl_add_u64 v[218:219], s[12:13], 0, v[128:129]
	v_mfma_f32_16x16x32_bf16 v[104:107], v[164:167], v[180:183], v[104:107]
	v_mfma_f32_16x16x32_bf16 v[92:95], v[156:159], v[188:191], v[92:95]
	v_mfma_f32_16x16x32_bf16 v[88:91], v[164:167], v[188:191], v[88:91]
	s_waitcnt lgkmcnt(0)
	v_mfma_f32_16x16x32_bf16 v[76:79], v[156:159], v[198:201], v[76:79]
	s_mov_b32 m0, s49
	v_mfma_f32_16x16x32_bf16 v[72:75], v[164:167], v[198:201], v[72:75]
	s_barrier
	s_setprio 0
	ds_read_b128 v[202:205], v151
	ds_read_b128 v[206:209], v151 offset:1024
	ds_read_b128 v[210:213], v151 offset:2048
	global_load_lds_dwordx4 v[144:145], off
	s_add_i32 m0, s49, 0x2000
	ds_read_b128 v[214:217], v151 offset:3072
	global_load_lds_dwordx4 v[218:219], off
	s_setprio 1
	s_barrier
	s_waitcnt lgkmcnt(3)
	v_mfma_f32_16x16x32_bf16 v[116:119], v[202:205], v[168:171], v[116:119]
	s_waitcnt lgkmcnt(1)
	v_mfma_f32_16x16x32_bf16 v[112:115], v[210:213], v[168:171], v[112:115]
	v_mfma_f32_16x16x32_bf16 v[100:103], v[202:205], v[176:179], v[100:103]
	v_mfma_f32_16x16x32_bf16 v[96:99], v[210:213], v[176:179], v[96:99]
	v_mfma_f32_16x16x32_bf16 v[84:87], v[202:205], v[184:187], v[84:87]
	v_mfma_f32_16x16x32_bf16 v[80:83], v[210:213], v[184:187], v[80:83]
	v_mfma_f32_16x16x32_bf16 v[68:71], v[202:205], v[192:195], v[68:71]
	v_mfma_f32_16x16x32_bf16 v[64:67], v[210:213], v[192:195], v[64:67]
	v_mfma_f32_16x16x32_bf16 v[116:119], v[206:209], v[172:175], v[116:119]
	v_lshl_add_u64 v[222:223], s[14:15], 0, v[130:131]
	s_mov_b32 m0, s24
	s_waitcnt lgkmcnt(0)
	v_mfma_f32_16x16x32_bf16 v[112:115], v[214:217], v[172:175], v[112:115]
	v_lshl_add_u64 v[220:221], s[14:15], 0, v[134:135]
	v_mfma_f32_16x16x32_bf16 v[100:103], v[206:209], v[180:183], v[100:103]
	v_mfma_f32_16x16x32_bf16 v[96:99], v[214:217], v[180:183], v[96:99]
	v_mfma_f32_16x16x32_bf16 v[84:87], v[206:209], v[188:191], v[84:87]
	v_mfma_f32_16x16x32_bf16 v[80:83], v[214:217], v[188:191], v[80:83]
	v_mfma_f32_16x16x32_bf16 v[68:71], v[206:209], v[198:201], v[68:71]
	v_mfma_f32_16x16x32_bf16 v[64:67], v[214:217], v[198:201], v[64:67]
	s_barrier
	s_setprio 0
	ds_read_b128 v[168:171], v150 offset:16384
	ds_read_b128 v[172:175], v150 offset:17408
	ds_read_b128 v[176:179], v150 offset:18432
	ds_read_b128 v[180:183], v150 offset:19456
	ds_read_b128 v[184:187], v150 offset:20480
	ds_read_b128 v[188:191], v150 offset:21504
	ds_read_b128 v[192:195], v150 offset:22528
	global_load_lds_dwordx4 v[220:221], off
	s_mov_b32 m0, s9
	ds_read_b128 v[198:201], v150 offset:23552
	global_load_lds_dwordx4 v[222:223], off
	s_waitcnt vmcnt(10)
	s_setprio 1
	s_barrier
	s_waitcnt lgkmcnt(7)
	v_mfma_f32_16x16x32_bf16 v[60:63], v[152:155], v[168:171], v[60:63]
	v_mfma_f32_16x16x32_bf16 v[56:59], v[160:163], v[168:171], v[56:59]
	s_waitcnt lgkmcnt(5)
	v_mfma_f32_16x16x32_bf16 v[44:47], v[152:155], v[176:179], v[44:47]
	v_mfma_f32_16x16x32_bf16 v[40:43], v[160:163], v[176:179], v[40:43]
	s_waitcnt lgkmcnt(3)
	v_mfma_f32_16x16x32_bf16 v[28:31], v[152:155], v[184:187], v[28:31]
	v_mfma_f32_16x16x32_bf16 v[24:27], v[160:163], v[184:187], v[24:27]
	s_waitcnt lgkmcnt(1)
	v_mfma_f32_16x16x32_bf16 v[12:15], v[152:155], v[192:195], v[12:15]
	v_mfma_f32_16x16x32_bf16 v[8:11], v[160:163], v[192:195], v[8:11]
	v_mfma_f32_16x16x32_bf16 v[60:63], v[156:159], v[172:175], v[60:63]
	s_add_u32 s54, s12, 0x80000
	s_addc_u32 s55, s13, 0
	v_mfma_f32_16x16x32_bf16 v[56:59], v[164:167], v[172:175], v[56:59]
	s_add_i32 s49, s36, s22
	v_mfma_f32_16x16x32_bf16 v[44:47], v[156:159], v[180:183], v[44:47]
	v_mfma_f32_16x16x32_bf16 v[40:43], v[164:167], v[180:183], v[40:43]
	v_mfma_f32_16x16x32_bf16 v[28:31], v[156:159], v[188:191], v[28:31]
	v_mfma_f32_16x16x32_bf16 v[24:27], v[164:167], v[188:191], v[24:27]
	s_waitcnt lgkmcnt(0)
	v_mfma_f32_16x16x32_bf16 v[12:15], v[156:159], v[198:201], v[12:15]
	s_mov_b32 m0, s49
	v_mfma_f32_16x16x32_bf16 v[8:11], v[164:167], v[198:201], v[8:11]
	s_barrier
; #define PG8_STAGE(bufoff, gbase, voff) do { _Pragma("unroll") for (int _i = 0; _i < 2; ++_i) \
;         __builtin_amdgcn_global_load_lds((const unsigned*)((const char*)(gbase) + (voff)[_i]), (LAS unsigned*)(lds + (bufoff) + ldsw + _i * 8192), 16, 0, 0); } while (0)
; #define PG8_LDA(dst, b, h) do { _Pragma("unroll") for (int m = 0; m < 4; ++m) _Pragma("unroll") for (int k = 0; k < 2; ++k) dst[m][k] = *(const LAS bf16x8*)(lds + PG8_SA(b, h) + aoff + m * 2048 + k * 1024); } while (0)
; #define PG8_LDB(dst, b, h) do { _Pragma("unroll") for (int n = 0; n < 2; ++n) _Pragma("unroll") for (int k = 0; k < 2; ++k) dst[n][k] = *(const LAS bf16x8*)(lds + PG8_SB(b, h) + boff + n * 2048 + k * 1024); } while (0)
; #define PG8_MMA(ai, bj, At, Bt) do { __builtin_amdgcn_s_setprio(1); _Pragma("unroll") for (int m = 0; m < 4; ++m) _Pragma("unroll") for (int n = 0; n < 2; ++n) _Pragma("unroll") for (int k = 0; k < 2; ++k) \
;         acc[ai][bj][m][n] = __builtin_amdgcn_mfma_f32_16x16x32_bf16(Bt[n][k], At[m][k], acc[ai][bj][m][n], 0, 0, 0); __builtin_amdgcn_s_setprio(0); } while (0)
; #define PG8_WAIT_V(n) asm volatile("s_waitcnt vmcnt(" #n ")" ::: "memory")
; #define PG8_WAIT_L(n) asm volatile("s_waitcnt lgkmcnt(" #n ")" ::: "memory")
; #define PG8_BAR __builtin_amdgcn_s_barrier()
; #define PG8_SCHED __builtin_amdgcn_sched_barrier(0)
; template <class Map, class Epi>
; DI void gemm_phase(LAS unsigned char* lds, const Map& MP, const Epi& E, const int nM, const int nN, const int K, const int lda, const int ldb) {
;     ...
;             PG8_LDA(At, 0, 1); PG8_STAGE(PG8_SA(0, 0), a2, voffA);
;             PG8_BAR; PG8_WAIT_L(0); PG8_MMA(1, 0, At, B0); PG8_BAR; PG8_SCHED;
;             PG8_STAGE(PG8_SB(0, 1), b2 + hstepB, voffB);
;             PG8_WAIT_V(6); PG8_BAR; PG8_MMA(1, 1, At, B1); PG8_BAR;
;             PG8_LDB(B0, 1, 0); PG8_SCHED; PG8_LDA(At, 1, 0); PG8_STAGE(PG8_SA(0, 1), a2 + hstepA, voffA);
;             PG8_WAIT_L(8); PG8_BAR; PG8_WAIT_L(0); PG8_MMA(0, 0, At, B0); PG8_BAR; PG8_SCHED;
;             PG8_LDB(B1, 1, 1); PG8_STAGE(PG8_SB(1, 0), b3, voffB);
;             PG8_BAR; PG8_WAIT_L(0); PG8_MMA(0, 1, At, B1); PG8_BAR;
;             PG8_LDA(At, 1, 1); PG8_STAGE(PG8_SA(1, 0), a3, voffA);
	s_setprio 0
	global_load_lds_dwordx4 v132, s[54:55]
	s_add_i32 m0, s49, 0x2000
	s_nop 0
	global_load_lds_dwordx4 v128, s[54:55]
	s_waitcnt vmcnt(6)
	s_setprio 1
	s_barrier
	v_mfma_f32_16x16x32_bf16 v[52:55], v[202:205], v[168:171], v[52:55]
	v_mfma_f32_16x16x32_bf16 v[48:51], v[210:213], v[168:171], v[48:51]
	s_add_i32 s49, 0, 0x18000
	v_add_u32_e32 v164, s49, v148
	ds_read_b128 v[152:155], v164
	v_mfma_f32_16x16x32_bf16 v[36:39], v[202:205], v[176:179], v[36:39]
	v_mfma_f32_16x16x32_bf16 v[32:35], v[210:213], v[176:179], v[32:35]
	ds_read_b128 v[156:159], v164 offset:1024
	v_mfma_f32_16x16x32_bf16 v[20:23], v[202:205], v[184:187], v[20:23]
	v_mfma_f32_16x16x32_bf16 v[16:19], v[210:213], v[184:187], v[16:19]
	ds_read_b128 v[160:163], v164 offset:2048
	v_mfma_f32_16x16x32_bf16 v[4:7], v[202:205], v[192:195], v[4:7]
	v_mfma_f32_16x16x32_bf16 v[0:3], v[210:213], v[192:195], v[0:3]
	ds_read_b128 v[164:167], v164 offset:3072
	v_mfma_f32_16x16x32_bf16 v[52:55], v[206:209], v[172:175], v[52:55]
	s_add_u32 s14, s14, 0x80000
	s_addc_u32 s15, s15, 0
	v_mfma_f32_16x16x32_bf16 v[48:51], v[214:217], v[172:175], v[48:51]
	v_mfma_f32_16x16x32_bf16 v[36:39], v[206:209], v[180:183], v[36:39]
	v_mfma_f32_16x16x32_bf16 v[32:35], v[214:217], v[180:183], v[32:35]
	v_mfma_f32_16x16x32_bf16 v[20:23], v[206:209], v[188:191], v[20:23]
	v_mfma_f32_16x16x32_bf16 v[16:19], v[214:217], v[188:191], v[16:19]
	v_mfma_f32_16x16x32_bf16 v[4:7], v[206:209], v[198:201], v[4:7]
	s_mov_b32 m0, s25
	v_mfma_f32_16x16x32_bf16 v[0:3], v[214:217], v[198:201], v[0:3]
	s_barrier
	s_setprio 0
	ds_read_b128 v[168:171], v150 offset:32768
	ds_read_b128 v[172:175], v150 offset:33792
	ds_read_b128 v[176:179], v150 offset:34816
	ds_read_b128 v[180:183], v150 offset:35840
	ds_read_b128 v[184:187], v150 offset:36864
	ds_read_b128 v[188:191], v150 offset:37888
	ds_read_b128 v[192:195], v150 offset:38912
	global_load_lds_dwordx4 v134, s[14:15]
	s_mov_b32 m0, s26
	ds_read_b128 v[198:201], v150 offset:39936
	global_load_lds_dwordx4 v130, s[14:15]
	s_waitcnt lgkmcnt(8)
	s_setprio 1
	s_barrier
	s_waitcnt lgkmcnt(7)
	v_mfma_f32_16x16x32_bf16 v[124:127], v[152:155], v[168:171], v[124:127]
	v_mfma_f32_16x16x32_bf16 v[120:123], v[160:163], v[168:171], v[120:123]
	s_waitcnt lgkmcnt(5)
	v_mfma_f32_16x16x32_bf16 v[108:111], v[152:155], v[176:179], v[108:111]
	v_mfma_f32_16x16x32_bf16 v[104:107], v[160:163], v[176:179], v[104:107]
	s_waitcnt lgkmcnt(3)
	v_mfma_f32_16x16x32_bf16 v[92:95], v[152:155], v[184:187], v[92:95]
	v_mfma_f32_16x16x32_bf16 v[88:91], v[160:163], v[184:187], v[88:91]
	s_waitcnt lgkmcnt(1)
	v_mfma_f32_16x16x32_bf16 v[76:79], v[152:155], v[192:195], v[76:79]
	v_mfma_f32_16x16x32_bf16 v[72:75], v[160:163], v[192:195], v[72:75]
	v_mfma_f32_16x16x32_bf16 v[124:127], v[156:159], v[172:175], v[124:127]
	s_add_i32 s14, 0, 0x1c000
	v_mfma_f32_16x16x32_bf16 v[120:123], v[164:167], v[172:175], v[120:123]
	s_add_i32 s15, s49, s22
	v_mfma_f32_16x16x32_bf16 v[108:111], v[156:159], v[180:183], v[108:111]
	v_add_u32_e32 v196, s14, v148
	v_mfma_f32_16x16x32_bf16 v[104:107], v[164:167], v[180:183], v[104:107]
	v_lshl_add_u64 v[144:145], v[144:145], 0, s[42:43]
	v_mfma_f32_16x16x32_bf16 v[92:95], v[156:159], v[188:191], v[92:95]
	v_mfma_f32_16x16x32_bf16 v[88:91], v[164:167], v[188:191], v[88:91]
	s_waitcnt lgkmcnt(0)
	v_mfma_f32_16x16x32_bf16 v[76:79], v[156:159], v[198:201], v[76:79]
	s_mov_b32 m0, s15
	v_mfma_f32_16x16x32_bf16 v[72:75], v[164:167], v[198:201], v[72:75]
	s_barrier
	s_setprio 0
	ds_read_b128 v[202:205], v196
	ds_read_b128 v[206:209], v196 offset:1024
	ds_read_b128 v[210:213], v196 offset:2048
	global_load_lds_dwordx4 v[144:145], off
	v_lshl_add_u64 v[144:145], v[218:219], 0, s[42:43]
	s_add_i32 m0, s15, 0x2000
	ds_read_b128 v[214:217], v196 offset:3072
	global_load_lds_dwordx4 v[144:145], off
	s_setprio 1
	s_barrier
	s_waitcnt lgkmcnt(3)
	v_mfma_f32_16x16x32_bf16 v[116:119], v[202:205], v[168:171], v[116:119]
	s_waitcnt lgkmcnt(1)
	v_mfma_f32_16x16x32_bf16 v[112:115], v[210:213], v[168:171], v[112:115]
	v_mfma_f32_16x16x32_bf16 v[100:103], v[202:205], v[176:179], v[100:103]
	v_mfma_f32_16x16x32_bf16 v[96:99], v[210:213], v[176:179], v[96:99]
	v_mfma_f32_16x16x32_bf16 v[84:87], v[202:205], v[184:187], v[84:87]
	v_mfma_f32_16x16x32_bf16 v[80:83], v[210:213], v[184:187], v[80:83]
	v_mfma_f32_16x16x32_bf16 v[68:71], v[202:205], v[192:195], v[68:71]
	v_mfma_f32_16x16x32_bf16 v[64:67], v[210:213], v[192:195], v[64:67]
	v_mfma_f32_16x16x32_bf16 v[116:119], v[206:209], v[172:175], v[116:119]
	s_mov_b32 m0, s30
	s_waitcnt lgkmcnt(0)
	v_mfma_f32_16x16x32_bf16 v[112:115], v[214:217], v[172:175], v[112:115]
	v_lshl_add_u64 v[144:145], v[220:221], 0, s[42:43]
	v_mfma_f32_16x16x32_bf16 v[100:103], v[206:209], v[180:183], v[100:103]
	v_mfma_f32_16x16x32_bf16 v[96:99], v[214:217], v[180:183], v[96:99]
	v_mfma_f32_16x16x32_bf16 v[84:87], v[206:209], v[188:191], v[84:87]
	v_mfma_f32_16x16x32_bf16 v[80:83], v[214:217], v[188:191], v[80:83]
	v_mfma_f32_16x16x32_bf16 v[68:71], v[206:209], v[198:201], v[68:71]
	v_mfma_f32_16x16x32_bf16 v[64:67], v[214:217], v[198:201], v[64:67]
	s_barrier
	s_setprio 0
	ds_read_b128 v[168:171], v150 offset:49152
	ds_read_b128 v[172:175], v150 offset:50176
	ds_read_b128 v[176:179], v150 offset:51200
	ds_read_b128 v[180:183], v150 offset:52224
	ds_read_b128 v[184:187], v150 offset:53248
	ds_read_b128 v[188:191], v150 offset:54272
	ds_read_b128 v[192:195], v150 offset:55296
	global_load_lds_dwordx4 v[144:145], off
	v_lshl_add_u64 v[144:145], v[222:223], 0, s[42:43]
	s_mov_b32 m0, s31
	ds_read_b128 v[198:201], v150 offset:56320
	global_load_lds_dwordx4 v[144:145], off
	s_waitcnt vmcnt(10)
	s_setprio 1
	s_barrier
; DI float bflo(unsigned w) { return __uint_as_float(w << 16); }
;     DI void operator()(const f32x4 (&acc)[2][2][4][2], const Unit& u, int wr, int wc, int fr, int fq) const {
;         const int row0 = u.pm * BM + wr * 64 + fr, col0 = u.pn * BM + wc * 32 + 8 * fq;
;         f32x4 sc[2][2];
; #pragma unroll
;         for (int bj = 0; bj < 2; ++bj)
; #pragma unroll
;             for (int n = 0; n < 2; ++n) sc[bj][n] = scale ? *(const f32x4*)(scale + col0 + bj * HALF + 4 * n) : (f32x4){1.f, 1.f, 1.f, 1.f};
; #pragma unroll
;         for (int ai = 0; ai < 2; ++ai)
; #pragma unroll
;             for (int m = 0; m < 4; ++m) { const size_t ro = (size_t)(row0 + ai * HALF + m * 16) * D + col0;
; #pragma unroll
;                 for (int bj = 0; bj < 2; ++bj) {
;                     f32x4 x0, x1;
;                     if constexpr (IB) { const u32x4 w = *(const u32x4*)((const bf16_t*)Xin + ro + bj * HALF);
;                         x0 = (f32x4){bflo(w[0]), bfhi(w[0]), bflo(w[1]), bfhi(w[1])}; x1 = (f32x4){bflo(w[2]), bfhi(w[2]), bflo(w[3]), bfhi(w[3])}; }
;                     else { x0 = *(const f32x4*)((const float*)Xin + ro + bj * HALF); x1 = *(const f32x4*)((const float*)Xin + ro + bj * HALF + 4); }
;                     x0 += acc[ai][bj][m][0] * sc[bj][0]; x1 += acc[ai][bj][m][1] * sc[bj][1];
;                     if constexpr (OB) { u32x4 o; o[0] = pack2(x0[0], x0[1]); o[1] = pack2(x0[2], x0[3]); o[2] = pack2(x1[0], x1[1]); o[3] = pack2(x1[2], x1[3]);
;                         *(u32x4*)((bf16_t*)Xout + ro + bj * HALF) = o; }
;                     else { *(f32x4*)((float*)Xout + ro + bj * HALF) = x0; *(f32x4*)((float*)Xout + ro + bj * HALF + 4) = x1; } } }
;     }
; template <class Map, class Epi>
; DI void gemm_phase(LAS unsigned char* lds, const Map& MP, const Epi& E, const int nM, const int nN, const int K, const int lda, const int ldb) {
;     ...
;             PG8_WAIT_L(8); PG8_BAR; PG8_WAIT_L(0); PG8_MMA(0, 0, At, B0); PG8_BAR; PG8_SCHED;
;             PG8_LDB(B1, 1, 1); PG8_STAGE(PG8_SB(1, 0), b3, voffB);
;             PG8_BAR; PG8_WAIT_L(0); PG8_MMA(0, 1, At, B1); PG8_BAR;
;             PG8_LDA(At, 1, 1); PG8_STAGE(PG8_SA(1, 0), a3, voffA);
;             PG8_BAR; PG8_WAIT_L(0); PG8_MMA(1, 0, At, B0); PG8_BAR; PG8_SCHED;
;             PG8_STAGE(PG8_SB(1, 1), b3 + hstepB, voffB);
;             PG8_WAIT_V(6); PG8_BAR; PG8_MMA(1, 1, At, B1); PG8_BAR;
	s_waitcnt lgkmcnt(7)
	v_mfma_f32_16x16x32_bf16 v[60:63], v[152:155], v[168:171], v[60:63]
	v_mfma_f32_16x16x32_bf16 v[56:59], v[160:163], v[168:171], v[56:59]
	s_waitcnt lgkmcnt(5)
	v_mfma_f32_16x16x32_bf16 v[44:47], v[152:155], v[176:179], v[44:47]
	v_mfma_f32_16x16x32_bf16 v[40:43], v[160:163], v[176:179], v[40:43]
	s_waitcnt lgkmcnt(3)
	v_mfma_f32_16x16x32_bf16 v[28:31], v[152:155], v[184:187], v[28:31]
	v_mfma_f32_16x16x32_bf16 v[24:27], v[160:163], v[184:187], v[24:27]
	s_waitcnt lgkmcnt(1)
	v_mfma_f32_16x16x32_bf16 v[12:15], v[152:155], v[192:195], v[12:15]
	v_mfma_f32_16x16x32_bf16 v[8:11], v[160:163], v[192:195], v[8:11]
	v_mfma_f32_16x16x32_bf16 v[60:63], v[156:159], v[172:175], v[60:63]
	s_add_u32 s12, s12, 0x80080
	s_addc_u32 s13, s13, 0
	v_mfma_f32_16x16x32_bf16 v[56:59], v[164:167], v[172:175], v[56:59]
	s_add_i32 s14, s14, s22
	v_mfma_f32_16x16x32_bf16 v[44:47], v[156:159], v[180:183], v[44:47]
	v_mfma_f32_16x16x32_bf16 v[40:43], v[164:167], v[180:183], v[40:43]
	v_mfma_f32_16x16x32_bf16 v[28:31], v[156:159], v[188:191], v[28:31]
	v_mfma_f32_16x16x32_bf16 v[24:27], v[164:167], v[188:191], v[24:27]
	s_waitcnt lgkmcnt(0)
	v_mfma_f32_16x16x32_bf16 v[12:15], v[156:159], v[198:201], v[12:15]
	s_mov_b32 m0, s14
	v_mfma_f32_16x16x32_bf16 v[8:11], v[164:167], v[198:201], v[8:11]
	s_barrier
	s_setprio 0
	global_load_lds_dwordx4 v132, s[12:13]
	s_add_i32 m0, s14, 0x2000
	s_nop 0
	global_load_lds_dwordx4 v128, s[12:13]
	s_waitcnt vmcnt(6)
	s_setprio 1
	s_barrier
	v_mfma_f32_16x16x32_bf16 v[52:55], v[202:205], v[168:171], v[52:55]
	v_mfma_f32_16x16x32_bf16 v[48:51], v[210:213], v[168:171], v[48:51]
	ds_read_b128 v[152:155], v149
	v_mfma_f32_16x16x32_bf16 v[36:39], v[202:205], v[176:179], v[36:39]
	v_mfma_f32_16x16x32_bf16 v[32:35], v[210:213], v[176:179], v[32:35]
	ds_read_b128 v[156:159], v149 offset:1024
	v_mfma_f32_16x16x32_bf16 v[20:23], v[202:205], v[184:187], v[20:23]
	v_mfma_f32_16x16x32_bf16 v[16:19], v[210:213], v[184:187], v[16:19]
	ds_read_b128 v[160:163], v149 offset:2048
	v_mfma_f32_16x16x32_bf16 v[4:7], v[202:205], v[192:195], v[4:7]
	v_mfma_f32_16x16x32_bf16 v[0:3], v[210:213], v[192:195], v[0:3]
	ds_read_b128 v[164:167], v149 offset:3072
	v_mfma_f32_16x16x32_bf16 v[52:55], v[206:209], v[172:175], v[52:55]
	s_add_i32 s3, s3, 2
	v_mfma_f32_16x16x32_bf16 v[48:51], v[214:217], v[172:175], v[48:51]
	s_add_u32 s47, s47, 0x100
	s_addc_u32 s48, s48, 0
	v_mfma_f32_16x16x32_bf16 v[36:39], v[206:209], v[180:183], v[36:39]
	s_add_u32 s10, s10, 0x100
	s_addc_u32 s11, s11, 0
	v_mfma_f32_16x16x32_bf16 v[32:35], v[214:217], v[180:183], v[32:35]
	s_cmp_gt_u32 s3, 29
	v_mfma_f32_16x16x32_bf16 v[20:23], v[206:209], v[188:191], v[20:23]
	v_mfma_f32_16x16x32_bf16 v[16:19], v[214:217], v[188:191], v[16:19]
	v_mfma_f32_16x16x32_bf16 v[4:7], v[206:209], v[198:201], v[4:7]
	v_mfma_f32_16x16x32_bf16 v[0:3], v[214:217], v[198:201], v[0:3]
	s_barrier
	s_setprio 0
	s_cbranch_scc0 .LBB1_1764
	s_waitcnt lgkmcnt(0)
	v_mov_b32_e32 v152, v147
	v_mov_b32_e32 v144, v146
	s_lshl_b32 s2, s2, 8
	s_or_b32 s2, s2, s29
	v_lshl_add_u32 v144, v144, 3, s2
	s_lshl_b32 s2, s8, 8
	s_add_i32 s2, s2, s28
	v_add_u32_e32 v152, s2, v152
	v_ashrrev_i32_e32 v153, 31, v152
	v_lshlrev_b64 v[152:153], 12, v[152:153]
	v_ashrrev_i32_e32 v145, 31, v144
	v_lshl_add_u64 v[152:153], s[4:5], 0, v[152:153]
	v_lshl_add_u64 v[144:145], v[144:145], 1, v[152:153]
	global_load_dwordx4 v[160:163], v[144:145], off
	global_load_dwordx4 v[164:167], v[144:145], off offset:256
	s_mov_b64 s[98:99], 0x10000
	v_lshl_add_u64 v[154:155], v[144:145], 0, s[98:99]
	global_load_dwordx4 v[168:171], v[154:155], off
	global_load_dwordx4 v[172:175], v[154:155], off offset:256
	s_mov_b64 s[98:99], 0x20000
	v_lshl_add_u64 v[154:155], v[144:145], 0, s[98:99]
	global_load_dwordx4 v[176:179], v[154:155], off
	global_load_dwordx4 v[180:183], v[154:155], off offset:256
	s_mov_b64 s[98:99], 0x30000
	v_lshl_add_u64 v[154:155], v[144:145], 0, s[98:99]
	global_load_dwordx4 v[184:187], v[154:155], off
	global_load_dwordx4 v[188:191], v[154:155], off offset:256
	s_mov_b64 s[98:99], 0x80000
	v_lshl_add_u64 v[154:155], v[144:145], 0, s[98:99]
	global_load_dwordx4 v[192:195], v[154:155], off
	global_load_dwordx4 v[198:201], v[154:155], off offset:256
	s_mov_b64 s[98:99], 0x90000
	v_lshl_add_u64 v[154:155], v[144:145], 0, s[98:99]
	global_load_dwordx4 v[202:205], v[154:155], off
	global_load_dwordx4 v[206:209], v[154:155], off offset:256
	s_mov_b64 s[98:99], 0xa0000
	v_lshl_add_u64 v[154:155], v[144:145], 0, s[98:99]
	global_load_dwordx4 v[210:213], v[154:155], off
	global_load_dwordx4 v[214:217], v[154:155], off offset:256
	s_mov_b64 s[98:99], 0xb0000
	v_lshl_add_u64 v[154:155], v[144:145], 0, s[98:99]
	global_load_dwordx4 v[248:251], v[154:155], off
	global_load_dwordx4 v[252:255], v[154:155], off offset:256
	s_waitcnt vmcnt(15)
	s_nop 1
	v_mov_b32_e32 v152, v160
	v_mov_b32_e32 v153, v161
	v_mov_b32_e32 v154, v162
	v_mov_b32_e32 v155, v163
	s_mov_b64 s[2:3], 0x10000
	s_mov_b32 s8, s46
	s_mov_b64 s[10:11], s[6:7]
	s_mov_b64 s[12:13], s[52:53]
	s_waitcnt lgkmcnt(0)
	v_lshlrev_b32_e32 v156, 16, v152
	v_and_b32_e32 v157, 0xffff0000, v152
	v_lshlrev_b32_e32 v152, 16, v153
	v_and_b32_e32 v153, 0xffff0000, v153
	v_lshlrev_b32_e32 v158, 16, v154
	v_and_b32_e32 v159, 0xffff0000, v154
	v_lshlrev_b32_e32 v154, 16, v155
	v_and_b32_e32 v155, 0xffff0000, v155
	v_pk_add_f32 v[126:127], v[126:127], v[152:153]
	v_pk_add_f32 v[124:125], v[124:125], v[156:157]
	v_pk_add_f32 v[152:153], v[122:123], v[154:155]
	v_pk_add_f32 v[122:123], v[120:121], v[158:159]
	v_cvt_pk_bf16_f32 v120, v124, v125
	v_cvt_pk_bf16_f32 v121, v126, v127
	v_cvt_pk_bf16_f32 v122, v122, v123
	v_cvt_pk_bf16_f32 v123, v152, v153
	global_store_dwordx4 v[144:145], v[120:123], off
	s_waitcnt vmcnt(15)
; DI unsigned pack2(float a, float b) { f32x2 v = {a, b}; hwbf16x2 r = __builtin_convertvector(v, hwbf16x2); return __builtin_bit_cast(unsigned, r); }
; DI float bflo(unsigned w) { return __uint_as_float(w << 16); }
; DI float bfhi(unsigned w) { return __uint_as_float(w & 0xffff0000u); }
;     DI void operator()(const f32x4 (&acc)[2][2][4][2], const Unit& u, int wr, int wc, int fr, int fq) const {
;     ...
;             for (int m = 0; m < 4; ++m) { const size_t ro = (size_t)(row0 + ai * HALF + m * 16) * D + col0;
; #pragma unroll
;                 for (int bj = 0; bj < 2; ++bj) {
;                     f32x4 x0, x1;
;                     if constexpr (IB) { const u32x4 w = *(const u32x4*)((const bf16_t*)Xin + ro + bj * HALF);
;                         x0 = (f32x4){bflo(w[0]), bfhi(w[0]), bflo(w[1]), bfhi(w[1])}; x1 = (f32x4){bflo(w[2]), bfhi(w[2]), bflo(w[3]), bfhi(w[3])}; }
;                     else { x0 = *(const f32x4*)((const float*)Xin + ro + bj * HALF); x1 = *(const f32x4*)((const float*)Xin + ro + bj * HALF + 4); }
;                     x0 += acc[ai][bj][m][0] * sc[bj][0]; x1 += acc[ai][bj][m][1] * sc[bj][1];
;                     if constexpr (OB) { u32x4 o; o[0] = pack2(x0[0], x0[1]); o[1] = pack2(x0[2], x0[3]); o[2] = pack2(x1[0], x1[1]); o[3] = pack2(x1[2], x1[3]);
;                         *(u32x4*)((bf16_t*)Xout + ro + bj * HALF) = o; }
;                     else { *(f32x4*)((float*)Xout + ro + bj * HALF) = x0; *(f32x4*)((float*)Xout + ro + bj * HALF + 4) = x1; } } }
	s_nop 1
	v_mov_b32_e32 v120, v164
	v_mov_b32_e32 v121, v165
	v_mov_b32_e32 v122, v166
	v_mov_b32_e32 v123, v167
	s_waitcnt lgkmcnt(0)
	v_lshlrev_b32_e32 v124, 16, v120
	v_and_b32_e32 v125, 0xffff0000, v120
	v_lshlrev_b32_e32 v120, 16, v121
	v_and_b32_e32 v121, 0xffff0000, v121
	v_lshlrev_b32_e32 v126, 16, v122
	v_and_b32_e32 v127, 0xffff0000, v122
	v_lshlrev_b32_e32 v122, 16, v123
	v_and_b32_e32 v123, 0xffff0000, v123
	v_pk_add_f32 v[116:117], v[116:117], v[124:125]
	v_pk_add_f32 v[118:119], v[118:119], v[120:121]
	v_pk_add_f32 v[120:121], v[114:115], v[122:123]
	v_pk_add_f32 v[114:115], v[112:113], v[126:127]
	v_cvt_pk_bf16_f32 v112, v116, v117
	v_lshl_add_u64 v[116:117], v[144:145], 0, s[2:3]
	s_mov_b32 s2, 0x10000
	v_cvt_pk_bf16_f32 v113, v118, v119
	v_add_co_u32_e32 v118, vcc, s2, v144
	v_cvt_pk_bf16_f32 v114, v114, v115
	v_cvt_pk_bf16_f32 v115, v120, v121
	v_addc_co_u32_e32 v119, vcc, 0, v145, vcc
	global_store_dwordx4 v[144:145], v[112:115], off offset:256
	s_waitcnt vmcnt(15)
	s_nop 1
	v_mov_b32_e32 v112, v168
	v_mov_b32_e32 v113, v169
	v_mov_b32_e32 v114, v170
	v_mov_b32_e32 v115, v171
	s_mov_b64 s[2:3], 0x20000
	s_waitcnt lgkmcnt(0)
	v_lshlrev_b32_e32 v120, 16, v112
	v_and_b32_e32 v121, 0xffff0000, v112
	v_lshlrev_b32_e32 v112, 16, v113
	v_and_b32_e32 v113, 0xffff0000, v113
	v_lshlrev_b32_e32 v122, 16, v114
	v_and_b32_e32 v123, 0xffff0000, v114
	v_lshlrev_b32_e32 v114, 16, v115
	v_and_b32_e32 v115, 0xffff0000, v115
	v_pk_add_f32 v[110:111], v[110:111], v[112:113]
	v_pk_add_f32 v[108:109], v[108:109], v[120:121]
	v_pk_add_f32 v[112:113], v[106:107], v[114:115]
	v_pk_add_f32 v[106:107], v[104:105], v[122:123]
	v_cvt_pk_bf16_f32 v104, v108, v109
	v_cvt_pk_bf16_f32 v105, v110, v111
	v_cvt_pk_bf16_f32 v106, v106, v107
	v_cvt_pk_bf16_f32 v107, v112, v113
	global_store_dwordx4 v[118:119], v[104:107], off
	s_waitcnt vmcnt(15)
	s_nop 1
	v_mov_b32_e32 v104, v172
	v_mov_b32_e32 v105, v173
	v_mov_b32_e32 v106, v174
	v_mov_b32_e32 v107, v175
	s_waitcnt lgkmcnt(0)
	v_lshlrev_b32_e32 v108, 16, v104
	v_and_b32_e32 v109, 0xffff0000, v104
	v_lshlrev_b32_e32 v104, 16, v105
	v_and_b32_e32 v105, 0xffff0000, v105
	v_lshlrev_b32_e32 v110, 16, v106
	v_and_b32_e32 v111, 0xffff0000, v106
	v_lshlrev_b32_e32 v106, 16, v107
	v_and_b32_e32 v107, 0xffff0000, v107
	v_pk_add_f32 v[100:101], v[100:101], v[108:109]
	v_pk_add_f32 v[102:103], v[102:103], v[104:105]
	v_pk_add_f32 v[104:105], v[98:99], v[106:107]
	v_pk_add_f32 v[98:99], v[96:97], v[110:111]
	v_cvt_pk_bf16_f32 v96, v100, v101
	v_lshl_add_u64 v[100:101], v[144:145], 0, s[2:3]
	s_mov_b32 s2, 0x20000
	v_cvt_pk_bf16_f32 v97, v102, v103
	v_add_co_u32_e32 v102, vcc, s2, v144
	v_cvt_pk_bf16_f32 v98, v98, v99
	v_cvt_pk_bf16_f32 v99, v104, v105
	v_addc_co_u32_e32 v103, vcc, 0, v145, vcc
	global_store_dwordx4 v[116:117], v[96:99], off offset:256
	s_waitcnt vmcnt(15)
	s_nop 1
	v_mov_b32_e32 v96, v176
	v_mov_b32_e32 v97, v177
	v_mov_b32_e32 v98, v178
	v_mov_b32_e32 v99, v179
	s_mov_b64 s[2:3], 0x30000
	s_waitcnt lgkmcnt(0)
	v_lshlrev_b32_e32 v104, 16, v96
	v_and_b32_e32 v105, 0xffff0000, v96
	v_lshlrev_b32_e32 v96, 16, v97
	v_and_b32_e32 v97, 0xffff0000, v97
	v_lshlrev_b32_e32 v106, 16, v98
	v_and_b32_e32 v107, 0xffff0000, v98
	v_lshlrev_b32_e32 v98, 16, v99
	v_and_b32_e32 v99, 0xffff0000, v99
	v_pk_add_f32 v[94:95], v[94:95], v[96:97]
	v_pk_add_f32 v[92:93], v[92:93], v[104:105]
	v_pk_add_f32 v[96:97], v[90:91], v[98:99]
	v_pk_add_f32 v[90:91], v[88:89], v[106:107]
	v_cvt_pk_bf16_f32 v88, v92, v93
	v_cvt_pk_bf16_f32 v89, v94, v95
	v_cvt_pk_bf16_f32 v90, v90, v91
	v_cvt_pk_bf16_f32 v91, v96, v97
	global_store_dwordx4 v[102:103], v[88:91], off
	s_waitcnt vmcnt(15)
	s_nop 1
	v_mov_b32_e32 v88, v180
	v_mov_b32_e32 v89, v181
	v_mov_b32_e32 v90, v182
	v_mov_b32_e32 v91, v183
	s_waitcnt lgkmcnt(0)
	v_lshlrev_b32_e32 v92, 16, v88
	v_and_b32_e32 v93, 0xffff0000, v88
	v_lshlrev_b32_e32 v88, 16, v89
	v_and_b32_e32 v89, 0xffff0000, v89
	v_lshlrev_b32_e32 v94, 16, v90
	v_and_b32_e32 v95, 0xffff0000, v90
	v_lshlrev_b32_e32 v90, 16, v91
	v_and_b32_e32 v91, 0xffff0000, v91
	v_pk_add_f32 v[86:87], v[86:87], v[88:89]
	v_pk_add_f32 v[84:85], v[84:85], v[92:93]
	v_pk_add_f32 v[88:89], v[82:83], v[90:91]
	v_pk_add_f32 v[82:83], v[80:81], v[94:95]
	v_cvt_pk_bf16_f32 v80, v84, v85
	v_cvt_pk_bf16_f32 v81, v86, v87
	v_cvt_pk_bf16_f32 v82, v82, v83
	v_cvt_pk_bf16_f32 v83, v88, v89
	global_store_dwordx4 v[100:101], v[80:83], off offset:256
	s_nop 1
	v_lshl_add_u64 v[80:81], v[144:145], 0, s[2:3]
	s_mov_b32 s2, 0x30000
	v_add_co_u32_e32 v86, vcc, s2, v144
	s_mov_b64 s[2:3], 0x80000
	s_nop 0
	v_addc_co_u32_e32 v87, vcc, 0, v145, vcc
	s_waitcnt vmcnt(15)
	s_nop 1
	v_mov_b32_e32 v82, v184
	v_mov_b32_e32 v83, v185
	v_mov_b32_e32 v84, v186
	v_mov_b32_e32 v85, v187
	s_waitcnt lgkmcnt(0)
	v_lshlrev_b32_e32 v88, 16, v82
	v_and_b32_e32 v89, 0xffff0000, v82
	v_lshlrev_b32_e32 v82, 16, v83
	v_and_b32_e32 v83, 0xffff0000, v83
	v_lshlrev_b32_e32 v90, 16, v84
	v_and_b32_e32 v91, 0xffff0000, v84
	v_lshlrev_b32_e32 v84, 16, v85
	v_and_b32_e32 v85, 0xffff0000, v85
	v_pk_add_f32 v[78:79], v[78:79], v[82:83]
	v_pk_add_f32 v[76:77], v[76:77], v[88:89]
	v_pk_add_f32 v[82:83], v[74:75], v[84:85]
	v_pk_add_f32 v[74:75], v[72:73], v[90:91]
	v_cvt_pk_bf16_f32 v72, v76, v77
	v_cvt_pk_bf16_f32 v73, v78, v79
	v_cvt_pk_bf16_f32 v74, v74, v75
	v_cvt_pk_bf16_f32 v75, v82, v83
	global_store_dwordx4 v[86:87], v[72:75], off
	s_waitcnt vmcnt(15)
	s_nop 1
	v_mov_b32_e32 v72, v188
	v_mov_b32_e32 v73, v189
	v_mov_b32_e32 v74, v190
	v_mov_b32_e32 v75, v191
	s_waitcnt lgkmcnt(0)
; DI unsigned pack2(float a, float b) { f32x2 v = {a, b}; hwbf16x2 r = __builtin_convertvector(v, hwbf16x2); return __builtin_bit_cast(unsigned, r); }
; DI float bflo(unsigned w) { return __uint_as_float(w << 16); }
; DI float bfhi(unsigned w) { return __uint_as_float(w & 0xffff0000u); }
;     DI void operator()(const f32x4 (&acc)[2][2][4][2], const Unit& u, int wr, int wc, int fr, int fq) const {
;     ...
;             for (int m = 0; m < 4; ++m) { const size_t ro = (size_t)(row0 + ai * HALF + m * 16) * D + col0;
; #pragma unroll
;                 for (int bj = 0; bj < 2; ++bj) {
;                     f32x4 x0, x1;
;                     if constexpr (IB) { const u32x4 w = *(const u32x4*)((const bf16_t*)Xin + ro + bj * HALF);
;                         x0 = (f32x4){bflo(w[0]), bfhi(w[0]), bflo(w[1]), bfhi(w[1])}; x1 = (f32x4){bflo(w[2]), bfhi(w[2]), bflo(w[3]), bfhi(w[3])}; }
;                     else { x0 = *(const f32x4*)((const float*)Xin + ro + bj * HALF); x1 = *(const f32x4*)((const float*)Xin + ro + bj * HALF + 4); }
;                     x0 += acc[ai][bj][m][0] * sc[bj][0]; x1 += acc[ai][bj][m][1] * sc[bj][1];
;                     if constexpr (OB) { u32x4 o; o[0] = pack2(x0[0], x0[1]); o[1] = pack2(x0[2], x0[3]); o[2] = pack2(x1[0], x1[1]); o[3] = pack2(x1[2], x1[3]);
;                         *(u32x4*)((bf16_t*)Xout + ro + bj * HALF) = o; }
;                     else { *(f32x4*)((float*)Xout + ro + bj * HALF) = x0; *(f32x4*)((float*)Xout + ro + bj * HALF + 4) = x1; } } }
	v_lshlrev_b32_e32 v76, 16, v72
	v_and_b32_e32 v77, 0xffff0000, v72
	v_lshlrev_b32_e32 v72, 16, v73
	v_and_b32_e32 v73, 0xffff0000, v73
	v_lshlrev_b32_e32 v78, 16, v74
	v_and_b32_e32 v79, 0xffff0000, v74
	v_lshlrev_b32_e32 v74, 16, v75
	v_and_b32_e32 v75, 0xffff0000, v75
	v_pk_add_f32 v[70:71], v[70:71], v[72:73]
	v_pk_add_f32 v[68:69], v[68:69], v[76:77]
	v_pk_add_f32 v[72:73], v[66:67], v[74:75]
	v_pk_add_f32 v[66:67], v[64:65], v[78:79]
	v_cvt_pk_bf16_f32 v64, v68, v69
	v_cvt_pk_bf16_f32 v65, v70, v71
	v_cvt_pk_bf16_f32 v66, v66, v67
	v_cvt_pk_bf16_f32 v67, v72, v73
	global_store_dwordx4 v[80:81], v[64:67], off offset:256
	s_nop 1
	v_lshl_add_u64 v[64:65], v[144:145], 0, s[2:3]
	s_mov_b32 s2, 0x80000
	v_add_co_u32_e32 v70, vcc, s2, v144
	s_mov_b64 s[2:3], 0x90000
	s_nop 0
	v_addc_co_u32_e32 v71, vcc, 0, v145, vcc
	s_waitcnt vmcnt(15)
	s_nop 1
	v_mov_b32_e32 v66, v192
	v_mov_b32_e32 v67, v193
	v_mov_b32_e32 v68, v194
	v_mov_b32_e32 v69, v195
	s_waitcnt lgkmcnt(0)
	v_lshlrev_b32_e32 v72, 16, v66
	v_and_b32_e32 v73, 0xffff0000, v66
	v_lshlrev_b32_e32 v66, 16, v67
	v_and_b32_e32 v67, 0xffff0000, v67
	v_lshlrev_b32_e32 v74, 16, v68
	v_and_b32_e32 v75, 0xffff0000, v68
	v_lshlrev_b32_e32 v68, 16, v69
	v_and_b32_e32 v69, 0xffff0000, v69
	v_pk_add_f32 v[62:63], v[62:63], v[66:67]
	v_pk_add_f32 v[60:61], v[60:61], v[72:73]
	v_pk_add_f32 v[66:67], v[58:59], v[68:69]
	v_pk_add_f32 v[58:59], v[56:57], v[74:75]
	v_cvt_pk_bf16_f32 v56, v60, v61
	v_cvt_pk_bf16_f32 v57, v62, v63
	v_cvt_pk_bf16_f32 v58, v58, v59
	v_cvt_pk_bf16_f32 v59, v66, v67
	global_store_dwordx4 v[70:71], v[56:59], off
	s_waitcnt vmcnt(15)
	s_nop 1
	v_mov_b32_e32 v56, v198
	v_mov_b32_e32 v57, v199
	v_mov_b32_e32 v58, v200
	v_mov_b32_e32 v59, v201
	s_waitcnt lgkmcnt(0)
	v_lshlrev_b32_e32 v60, 16, v56
	v_and_b32_e32 v61, 0xffff0000, v56
	v_lshlrev_b32_e32 v56, 16, v57
	v_and_b32_e32 v57, 0xffff0000, v57
	v_lshlrev_b32_e32 v62, 16, v58
	v_and_b32_e32 v63, 0xffff0000, v58
	v_lshlrev_b32_e32 v58, 16, v59
	v_and_b32_e32 v59, 0xffff0000, v59
	v_pk_add_f32 v[54:55], v[54:55], v[56:57]
	v_pk_add_f32 v[52:53], v[52:53], v[60:61]
	v_pk_add_f32 v[56:57], v[50:51], v[58:59]
	v_pk_add_f32 v[50:51], v[48:49], v[62:63]
	v_cvt_pk_bf16_f32 v48, v52, v53
	v_cvt_pk_bf16_f32 v49, v54, v55
	v_cvt_pk_bf16_f32 v50, v50, v51
	v_cvt_pk_bf16_f32 v51, v56, v57
	global_store_dwordx4 v[64:65], v[48:51], off offset:256
	s_nop 1
	v_lshl_add_u64 v[48:49], v[144:145], 0, s[2:3]
	s_mov_b32 s2, 0x90000
	v_add_co_u32_e32 v54, vcc, s2, v144
	s_mov_b64 s[2:3], 0xa0000
	s_nop 0
	v_addc_co_u32_e32 v55, vcc, 0, v145, vcc
	s_waitcnt vmcnt(15)
	s_nop 1
	v_mov_b32_e32 v50, v202
	v_mov_b32_e32 v51, v203
	v_mov_b32_e32 v52, v204
	v_mov_b32_e32 v53, v205
	s_waitcnt lgkmcnt(0)
	v_lshlrev_b32_e32 v56, 16, v50
	v_and_b32_e32 v57, 0xffff0000, v50
	v_lshlrev_b32_e32 v50, 16, v51
	v_and_b32_e32 v51, 0xffff0000, v51
	v_lshlrev_b32_e32 v58, 16, v52
	v_and_b32_e32 v59, 0xffff0000, v52
	v_lshlrev_b32_e32 v52, 16, v53
	v_and_b32_e32 v53, 0xffff0000, v53
	v_pk_add_f32 v[46:47], v[46:47], v[50:51]
	v_pk_add_f32 v[44:45], v[44:45], v[56:57]
	v_pk_add_f32 v[50:51], v[42:43], v[52:53]
	v_pk_add_f32 v[42:43], v[40:41], v[58:59]
	v_cvt_pk_bf16_f32 v40, v44, v45
	v_cvt_pk_bf16_f32 v41, v46, v47
	v_cvt_pk_bf16_f32 v42, v42, v43
	v_cvt_pk_bf16_f32 v43, v50, v51
	global_store_dwordx4 v[54:55], v[40:43], off
	s_waitcnt vmcnt(15)
	s_nop 1
	v_mov_b32_e32 v40, v206
	v_mov_b32_e32 v41, v207
	v_mov_b32_e32 v42, v208
	v_mov_b32_e32 v43, v209
	s_waitcnt lgkmcnt(0)
; DI unsigned pack2(float a, float b) { f32x2 v = {a, b}; hwbf16x2 r = __builtin_convertvector(v, hwbf16x2); return __builtin_bit_cast(unsigned, r); }
; DI float bflo(unsigned w) { return __uint_as_float(w << 16); }
; DI float bfhi(unsigned w) { return __uint_as_float(w & 0xffff0000u); }
;     DI const char* a(const Unit& u) const { return (const char*)(A + (size_t)u.pm * BM * lda); }
; #define PG8_BAR __builtin_amdgcn_s_barrier()
;     DI void operator()(const f32x4 (&acc)[2][2][4][2], const Unit& u, int wr, int wc, int fr, int fq) const {
;     ...
;             for (int m = 0; m < 4; ++m) { const size_t ro = (size_t)(row0 + ai * HALF + m * 16) * D + col0;
; #pragma unroll
;                 for (int bj = 0; bj < 2; ++bj) {
;                     f32x4 x0, x1;
;                     if constexpr (IB) { const u32x4 w = *(const u32x4*)((const bf16_t*)Xin + ro + bj * HALF);
;                         x0 = (f32x4){bflo(w[0]), bfhi(w[0]), bflo(w[1]), bfhi(w[1])}; x1 = (f32x4){bflo(w[2]), bfhi(w[2]), bflo(w[3]), bfhi(w[3])}; }
;                     else { x0 = *(const f32x4*)((const float*)Xin + ro + bj * HALF); x1 = *(const f32x4*)((const float*)Xin + ro + bj * HALF + 4); }
;                     x0 += acc[ai][bj][m][0] * sc[bj][0]; x1 += acc[ai][bj][m][1] * sc[bj][1];
;                     if constexpr (OB) { u32x4 o; o[0] = pack2(x0[0], x0[1]); o[1] = pack2(x0[2], x0[3]); o[2] = pack2(x1[0], x1[1]); o[3] = pack2(x1[2], x1[3]);
;                         *(u32x4*)((bf16_t*)Xout + ro + bj * HALF) = o; }
;                     else { *(f32x4*)((float*)Xout + ro + bj * HALF) = x0; *(f32x4*)((float*)Xout + ro + bj * HALF + 4) = x1; } } }
; template <class Map, class Epi>
; DI void gemm_phase(LAS unsigned char* lds, const Map& MP, const Epi& E, const int nM, const int nN, const int K, const int lda, const int ldb) {
;     ...
;         { int frr = fr, fqq = fq; asm volatile("" : "+v"(frr), "+v"(fqq)); E(acc, cur, wr, wc, frr, fqq); }
;         if (!has_next) break;
; #pragma unroll
;         for (int a = 0; a < 2; ++a)
; #pragma unroll
;             for (int b = 0; b < 2; ++b)
; #pragma unroll
;                 for (int m = 0; m < 4; ++m)
; #pragma unroll
;                     for (int n = 0; n < 2; ++n) acc[a][b][m][n] = (f32x4){0.f, 0.f, 0.f, 0.f};
;         cur = nxt; cA = nA; cB = nB; ++ui;
;     }
;     PG8_WAIT_V(0);
;     if (wr == 0) PG8_BAR;
;     PG8_BAR;
	v_lshlrev_b32_e32 v44, 16, v40
	v_and_b32_e32 v45, 0xffff0000, v40
	v_lshlrev_b32_e32 v40, 16, v41
	v_and_b32_e32 v41, 0xffff0000, v41
	v_lshlrev_b32_e32 v46, 16, v42
	v_and_b32_e32 v47, 0xffff0000, v42
	v_lshlrev_b32_e32 v42, 16, v43
	v_and_b32_e32 v43, 0xffff0000, v43
	v_pk_add_f32 v[38:39], v[38:39], v[40:41]
	v_pk_add_f32 v[36:37], v[36:37], v[44:45]
	v_pk_add_f32 v[40:41], v[34:35], v[42:43]
	v_pk_add_f32 v[34:35], v[32:33], v[46:47]
	v_cvt_pk_bf16_f32 v32, v36, v37
	v_cvt_pk_bf16_f32 v33, v38, v39
	v_cvt_pk_bf16_f32 v34, v34, v35
	v_cvt_pk_bf16_f32 v35, v40, v41
	global_store_dwordx4 v[48:49], v[32:35], off offset:256
	s_nop 1
	v_lshl_add_u64 v[32:33], v[144:145], 0, s[2:3]
	s_mov_b32 s2, 0xa0000
	v_add_co_u32_e32 v38, vcc, s2, v144
	s_mov_b64 s[2:3], 0xb0000
	s_nop 0
	v_addc_co_u32_e32 v39, vcc, 0, v145, vcc
	s_waitcnt vmcnt(15)
	s_nop 1
	v_mov_b32_e32 v34, v210
	v_mov_b32_e32 v35, v211
	v_mov_b32_e32 v36, v212
	v_mov_b32_e32 v37, v213
	s_waitcnt lgkmcnt(0)
	v_lshlrev_b32_e32 v40, 16, v34
	v_and_b32_e32 v41, 0xffff0000, v34
	v_lshlrev_b32_e32 v34, 16, v35
	v_and_b32_e32 v35, 0xffff0000, v35
	v_lshlrev_b32_e32 v42, 16, v36
	v_and_b32_e32 v43, 0xffff0000, v36
	v_lshlrev_b32_e32 v36, 16, v37
	v_and_b32_e32 v37, 0xffff0000, v37
	v_pk_add_f32 v[30:31], v[30:31], v[34:35]
	v_pk_add_f32 v[28:29], v[28:29], v[40:41]
	v_pk_add_f32 v[34:35], v[26:27], v[36:37]
	v_pk_add_f32 v[26:27], v[24:25], v[42:43]
	v_cvt_pk_bf16_f32 v24, v28, v29
	v_cvt_pk_bf16_f32 v25, v30, v31
	v_cvt_pk_bf16_f32 v26, v26, v27
	v_cvt_pk_bf16_f32 v27, v34, v35
	global_store_dwordx4 v[38:39], v[24:27], off
	s_waitcnt vmcnt(15)
	s_nop 1
	v_mov_b32_e32 v24, v214
	v_mov_b32_e32 v25, v215
	v_mov_b32_e32 v26, v216
	v_mov_b32_e32 v27, v217
	s_waitcnt lgkmcnt(0)
	v_lshlrev_b32_e32 v28, 16, v24
	v_and_b32_e32 v29, 0xffff0000, v24
	v_lshlrev_b32_e32 v24, 16, v25
	v_and_b32_e32 v25, 0xffff0000, v25
	v_lshlrev_b32_e32 v30, 16, v26
	v_and_b32_e32 v31, 0xffff0000, v26
	v_lshlrev_b32_e32 v26, 16, v27
	v_and_b32_e32 v27, 0xffff0000, v27
	v_pk_add_f32 v[22:23], v[22:23], v[24:25]
	v_pk_add_f32 v[20:21], v[20:21], v[28:29]
	v_pk_add_f32 v[24:25], v[18:19], v[26:27]
	v_pk_add_f32 v[18:19], v[16:17], v[30:31]
	v_cvt_pk_bf16_f32 v16, v20, v21
	v_cvt_pk_bf16_f32 v17, v22, v23
	v_cvt_pk_bf16_f32 v18, v18, v19
	v_cvt_pk_bf16_f32 v19, v24, v25
	global_store_dwordx4 v[32:33], v[16:19], off offset:256
	s_nop 1
	v_lshl_add_u64 v[16:17], v[144:145], 0, s[2:3]
	s_mov_b32 s2, 0xb0000
	v_add_co_u32_e32 v22, vcc, s2, v144
	s_mov_b32 s2, s44
	s_nop 0
	v_addc_co_u32_e32 v23, vcc, 0, v145, vcc
	s_waitcnt vmcnt(15)
	s_nop 1
	v_mov_b32_e32 v18, v248
	v_mov_b32_e32 v19, v249
	v_mov_b32_e32 v20, v250
	v_mov_b32_e32 v21, v251
	s_and_b64 vcc, exec, s[40:41]
	s_waitcnt lgkmcnt(0)
	v_lshlrev_b32_e32 v24, 16, v18
	v_and_b32_e32 v25, 0xffff0000, v18
	v_lshlrev_b32_e32 v18, 16, v19
	v_and_b32_e32 v19, 0xffff0000, v19
	v_lshlrev_b32_e32 v26, 16, v20
	v_and_b32_e32 v27, 0xffff0000, v20
	v_lshlrev_b32_e32 v20, 16, v21
	v_and_b32_e32 v21, 0xffff0000, v21
	v_pk_add_f32 v[14:15], v[14:15], v[18:19]
	v_pk_add_f32 v[12:13], v[12:13], v[24:25]
	v_pk_add_f32 v[18:19], v[10:11], v[20:21]
	v_pk_add_f32 v[10:11], v[8:9], v[26:27]
	v_cvt_pk_bf16_f32 v8, v12, v13
	v_cvt_pk_bf16_f32 v9, v14, v15
	v_cvt_pk_bf16_f32 v10, v10, v11
	v_cvt_pk_bf16_f32 v11, v18, v19
	global_store_dwordx4 v[22:23], v[8:11], off
	s_waitcnt vmcnt(15)
	s_nop 1
	v_mov_b32_e32 v8, v252
	v_mov_b32_e32 v9, v253
	v_mov_b32_e32 v10, v254
	v_mov_b32_e32 v11, v255
	s_waitcnt lgkmcnt(0)
	v_lshlrev_b32_e32 v12, 16, v8
	v_and_b32_e32 v13, 0xffff0000, v8
	v_lshlrev_b32_e32 v8, 16, v9
	v_and_b32_e32 v9, 0xffff0000, v9
	v_lshlrev_b32_e32 v14, 16, v10
	v_and_b32_e32 v15, 0xffff0000, v10
	v_lshlrev_b32_e32 v10, 16, v11
	v_and_b32_e32 v11, 0xffff0000, v11
	v_pk_add_f32 v[6:7], v[6:7], v[8:9]
	v_pk_add_f32 v[4:5], v[4:5], v[12:13]
	v_pk_add_f32 v[8:9], v[2:3], v[10:11]
	v_pk_add_f32 v[2:3], v[0:1], v[14:15]
	v_cvt_pk_bf16_f32 v0, v4, v5
	v_cvt_pk_bf16_f32 v1, v6, v7
	v_cvt_pk_bf16_f32 v2, v2, v3
	v_cvt_pk_bf16_f32 v3, v8, v9
	global_store_dwordx4 v[16:17], v[0:3], off offset:256
	s_cbranch_vccz .LBB1_1761
	s_waitcnt vmcnt(0)
	s_cmpk_gt_u32 s17, 0xff
	s_cbranch_scc1 .LBB1_1768
	s_barrier

; #define PG8_STAGE(bufoff, gbase, voff) do { _Pragma("unroll") for (int _i = 0; _i < 2; ++_i) \
;         __builtin_amdgcn_global_load_lds((const unsigned*)((const char*)(gbase) + (voff)[_i]), (LAS unsigned*)(lds + (bufoff) + ldsw + _i * 8192), 16, 0, 0); } while (0)
; #define PG8_LDA(dst, b, h) do { _Pragma("unroll") for (int m = 0; m < 4; ++m) _Pragma("unroll") for (int k = 0; k < 2; ++k) dst[m][k] = *(const LAS bf16x8*)(lds + PG8_SA(b, h) + aoff + m * 2048 + k * 1024); } while (0)
; #define PG8_LDB(dst, b, h) do { _Pragma("unroll") for (int n = 0; n < 2; ++n) _Pragma("unroll") for (int k = 0; k < 2; ++k) dst[n][k] = *(const LAS bf16x8*)(lds + PG8_SB(b, h) + boff + n * 2048 + k * 1024); } while (0)
; #define PG8_MMA(ai, bj, At, Bt) do { __builtin_amdgcn_s_setprio(1); _Pragma("unroll") for (int m = 0; m < 4; ++m) _Pragma("unroll") for (int n = 0; n < 2; ++n) _Pragma("unroll") for (int k = 0; k < 2; ++k) \
;         acc[ai][bj][m][n] = __builtin_amdgcn_mfma_f32_16x16x32_bf16(Bt[n][k], At[m][k], acc[ai][bj][m][n], 0, 0, 0); __builtin_amdgcn_s_setprio(0); } while (0)
; #define PG8_WAIT_V(n) asm volatile("s_waitcnt vmcnt(" #n ")" ::: "memory")
; #define PG8_WAIT_L(n) asm volatile("s_waitcnt lgkmcnt(" #n ")" ::: "memory")
; #define PG8_BAR __builtin_amdgcn_s_barrier()
; #define PG8_SCHED __builtin_amdgcn_sched_barrier(0)
; template <class Map, class Epi>
; DI void gemm_phase(LAS unsigned char* lds, const Map& MP, const Epi& E, const int nM, const int nN, const int K, const int lda, const int ldb) {
;     ...
;             PG8_LDB(B0, 0, 0); PG8_SCHED; PG8_LDA(At, 0, 0); PG8_STAGE(PG8_SA(1, 1), a1 + hstepA, voffA);
;             PG8_WAIT_L(8); PG8_BAR; PG8_WAIT_L(0); PG8_MMA(0, 0, At, B0); PG8_BAR; PG8_SCHED;
;             PG8_LDB(B1, 0, 1); PG8_STAGE(PG8_SB(0, 0), b2, voffB);
;             PG8_BAR; PG8_WAIT_L(0); PG8_MMA(0, 1, At, B1); PG8_BAR;
;             PG8_LDA(At, 0, 1); PG8_STAGE(PG8_SA(0, 0), a2, voffA);
;             PG8_BAR; PG8_WAIT_L(0); PG8_MMA(1, 0, At, B0); PG8_BAR; PG8_SCHED;
;             PG8_STAGE(PG8_SB(0, 1), b2 + hstepB, voffB);
;             PG8_WAIT_V(6); PG8_BAR; PG8_MMA(1, 1, At, B1); PG8_BAR;
.LBB1_1908:
	s_add_u32 s28, s42, 0xfff80080
	s_addc_u32 s29, s43, -1
	s_cmp_eq_u32 s3, 28
	s_cselect_b32 s47, s23, s29
	s_cselect_b32 s46, s58, s28
	s_cselect_b32 s29, s21, vcc_hi
	s_cselect_b32 s28, s59, vcc_lo
	s_add_i32 m0, s38, 0xc000
	ds_read_b128 v[96:99], v190
	ds_read_b128 v[100:103], v190 offset:1024
	ds_read_b128 v[108:111], v190 offset:2048
	ds_read_b128 v[112:115], v190 offset:3072
	ds_read_b128 v[160:163], v190 offset:4096
	ds_read_b128 v[164:167], v190 offset:5120
	ds_read_b128 v[198:201], v190 offset:6144
	ds_read_b128 v[202:205], v190 offset:7168
	global_load_lds_dwordx4 v178, s[42:43]
	s_add_i32 m0, s38, 0xe000
	s_nop 0
	global_load_lds_dwordx4 v176, s[42:43]
	s_waitcnt lgkmcnt(8)
	s_setprio 1
	s_barrier
	s_waitcnt lgkmcnt(7)
	v_mfma_f32_16x16x32_bf16 v[148:151], v[80:83], v[96:99], v[148:151]
	v_mfma_f32_16x16x32_bf16 v[144:147], v[88:91], v[96:99], v[144:147]
	s_waitcnt lgkmcnt(5)
	v_mfma_f32_16x16x32_bf16 v[136:139], v[80:83], v[108:111], v[136:139]
	v_mfma_f32_16x16x32_bf16 v[128:131], v[88:91], v[108:111], v[128:131]
	s_waitcnt lgkmcnt(3)
	v_mfma_f32_16x16x32_bf16 v[120:123], v[80:83], v[160:163], v[120:123]
	v_mfma_f32_16x16x32_bf16 v[104:107], v[88:91], v[160:163], v[104:107]
	s_waitcnt lgkmcnt(1)
	v_mfma_f32_16x16x32_bf16 v[76:79], v[80:83], v[198:201], v[76:79]
	v_mfma_f32_16x16x32_bf16 v[72:75], v[88:91], v[198:201], v[72:75]
	v_mfma_f32_16x16x32_bf16 v[148:151], v[84:87], v[100:103], v[148:151]
	s_add_i32 s68, s2, s54
	v_mfma_f32_16x16x32_bf16 v[144:147], v[92:95], v[100:103], v[144:147]
	v_lshl_add_u64 v[184:185], s[28:29], 0, v[172:173]
	v_mfma_f32_16x16x32_bf16 v[136:139], v[84:87], v[112:115], v[136:139]
	v_lshl_add_u64 v[194:195], s[28:29], 0, v[168:169]
	v_mfma_f32_16x16x32_bf16 v[128:131], v[92:95], v[112:115], v[128:131]
	v_mfma_f32_16x16x32_bf16 v[120:123], v[84:87], v[164:167], v[120:123]
	v_mfma_f32_16x16x32_bf16 v[104:107], v[92:95], v[164:167], v[104:107]
	s_waitcnt lgkmcnt(0)
	v_mfma_f32_16x16x32_bf16 v[76:79], v[84:87], v[202:205], v[76:79]
	s_mov_b32 m0, s68
	v_mfma_f32_16x16x32_bf16 v[72:75], v[92:95], v[202:205], v[72:75]
	s_barrier
	s_setprio 0
	ds_read_b128 v[206:209], v191
	ds_read_b128 v[210:213], v191 offset:1024
	ds_read_b128 v[214:217], v191 offset:2048
	global_load_lds_dwordx4 v[184:185], off
	s_add_i32 m0, s68, 0x2000
	ds_read_b128 v[218:221], v191 offset:3072
	global_load_lds_dwordx4 v[194:195], off
	s_setprio 1
	s_barrier
	s_waitcnt lgkmcnt(3)
	v_mfma_f32_16x16x32_bf16 v[156:159], v[206:209], v[96:99], v[156:159]
	s_waitcnt lgkmcnt(1)
	v_mfma_f32_16x16x32_bf16 v[96:99], v[214:217], v[96:99], v[152:155]
	v_mfma_f32_16x16x32_bf16 v[156:159], v[210:213], v[100:103], v[156:159]
	s_waitcnt lgkmcnt(0)
	v_mfma_f32_16x16x32_bf16 v[96:99], v[218:221], v[100:103], v[96:99]
	v_mfma_f32_16x16x32_bf16 v[100:103], v[206:209], v[108:111], v[140:143]
	v_mfma_f32_16x16x32_bf16 v[108:111], v[214:217], v[108:111], v[132:135]
	v_mfma_f32_16x16x32_bf16 v[116:119], v[214:217], v[160:163], v[116:119]
	v_mfma_f32_16x16x32_bf16 v[68:71], v[206:209], v[198:201], v[68:71]
	v_mfma_f32_16x16x32_bf16 v[64:67], v[214:217], v[198:201], v[64:67]
	v_lshl_add_u64 v[234:235], s[46:47], 0, v[170:171]
	s_mov_b32 m0, s38
	v_mfma_f32_16x16x32_bf16 v[100:103], v[210:213], v[112:115], v[100:103]
	v_lshl_add_u64 v[226:227], s[46:47], 0, v[174:175]
	v_mfma_f32_16x16x32_bf16 v[108:111], v[218:221], v[112:115], v[108:111]
	v_mfma_f32_16x16x32_bf16 v[112:115], v[206:209], v[160:163], v[124:127]
	v_mfma_f32_16x16x32_bf16 v[116:119], v[218:221], v[164:167], v[116:119]
	v_mfma_f32_16x16x32_bf16 v[68:71], v[210:213], v[202:205], v[68:71]
	v_mfma_f32_16x16x32_bf16 v[64:67], v[218:221], v[202:205], v[64:67]
	v_mfma_f32_16x16x32_bf16 v[112:115], v[210:213], v[164:167], v[112:115]
	s_barrier
	s_setprio 0
	ds_read_b128 v[124:127], v190 offset:16384
	ds_read_b128 v[132:135], v190 offset:17408
	ds_read_b128 v[140:143], v190 offset:18432
	ds_read_b128 v[152:155], v190 offset:19456
	ds_read_b128 v[160:163], v190 offset:20480
	ds_read_b128 v[164:167], v190 offset:21504
	ds_read_b128 v[198:201], v190 offset:22528
	global_load_lds_dwordx4 v[226:227], off
	s_mov_b32 m0, s39
	ds_read_b128 v[202:205], v190 offset:23552
	global_load_lds_dwordx4 v[234:235], off
	s_waitcnt vmcnt(10)
	s_setprio 1
	s_barrier
	s_waitcnt lgkmcnt(7)
	v_mfma_f32_16x16x32_bf16 v[60:63], v[80:83], v[124:127], v[60:63]
	v_mfma_f32_16x16x32_bf16 v[48:51], v[88:91], v[124:127], v[48:51]
	s_waitcnt lgkmcnt(5)
	v_mfma_f32_16x16x32_bf16 v[40:43], v[80:83], v[140:143], v[40:43]
	v_mfma_f32_16x16x32_bf16 v[32:35], v[88:91], v[140:143], v[32:35]
	s_waitcnt lgkmcnt(3)
	v_mfma_f32_16x16x32_bf16 v[24:27], v[80:83], v[160:163], v[24:27]
	v_mfma_f32_16x16x32_bf16 v[16:19], v[88:91], v[160:163], v[16:19]
	s_waitcnt lgkmcnt(1)
	v_mfma_f32_16x16x32_bf16 v[12:15], v[80:83], v[198:201], v[12:15]
	v_mfma_f32_16x16x32_bf16 v[8:11], v[88:91], v[198:201], v[8:11]
	v_mfma_f32_16x16x32_bf16 v[60:63], v[84:87], v[132:135], v[60:63]
	s_add_u32 s68, s28, 0x80000
	s_addc_u32 s69, s29, 0
	v_mfma_f32_16x16x32_bf16 v[48:51], v[92:95], v[132:135], v[48:51]
	s_add_i32 s70, s31, s54
	v_mfma_f32_16x16x32_bf16 v[40:43], v[84:87], v[152:155], v[40:43]
	v_mfma_f32_16x16x32_bf16 v[32:35], v[92:95], v[152:155], v[32:35]
	v_mfma_f32_16x16x32_bf16 v[24:27], v[84:87], v[164:167], v[24:27]
	v_mfma_f32_16x16x32_bf16 v[16:19], v[92:95], v[164:167], v[16:19]
	s_waitcnt lgkmcnt(0)
	v_mfma_f32_16x16x32_bf16 v[12:15], v[84:87], v[202:205], v[12:15]
	s_mov_b32 m0, s70
	v_mfma_f32_16x16x32_bf16 v[8:11], v[92:95], v[202:205], v[8:11]
	s_barrier
; #define PG8_STAGE(bufoff, gbase, voff) do { _Pragma("unroll") for (int _i = 0; _i < 2; ++_i) \
;         __builtin_amdgcn_global_load_lds((const unsigned*)((const char*)(gbase) + (voff)[_i]), (LAS unsigned*)(lds + (bufoff) + ldsw + _i * 8192), 16, 0, 0); } while (0)
; #define PG8_LDA(dst, b, h) do { _Pragma("unroll") for (int m = 0; m < 4; ++m) _Pragma("unroll") for (int k = 0; k < 2; ++k) dst[m][k] = *(const LAS bf16x8*)(lds + PG8_SA(b, h) + aoff + m * 2048 + k * 1024); } while (0)
; #define PG8_LDB(dst, b, h) do { _Pragma("unroll") for (int n = 0; n < 2; ++n) _Pragma("unroll") for (int k = 0; k < 2; ++k) dst[n][k] = *(const LAS bf16x8*)(lds + PG8_SB(b, h) + boff + n * 2048 + k * 1024); } while (0)
; #define PG8_MMA(ai, bj, At, Bt) do { __builtin_amdgcn_s_setprio(1); _Pragma("unroll") for (int m = 0; m < 4; ++m) _Pragma("unroll") for (int n = 0; n < 2; ++n) _Pragma("unroll") for (int k = 0; k < 2; ++k) \
;         acc[ai][bj][m][n] = __builtin_amdgcn_mfma_f32_16x16x32_bf16(Bt[n][k], At[m][k], acc[ai][bj][m][n], 0, 0, 0); __builtin_amdgcn_s_setprio(0); } while (0)
; #define PG8_WAIT_V(n) asm volatile("s_waitcnt vmcnt(" #n ")" ::: "memory")
; #define PG8_WAIT_L(n) asm volatile("s_waitcnt lgkmcnt(" #n ")" ::: "memory")
; #define PG8_BAR __builtin_amdgcn_s_barrier()
; #define PG8_SCHED __builtin_amdgcn_sched_barrier(0)
; template <class Map, class Epi>
; DI void gemm_phase(LAS unsigned char* lds, const Map& MP, const Epi& E, const int nM, const int nN, const int K, const int lda, const int ldb) {
;     ...
;             PG8_LDA(At, 0, 1); PG8_STAGE(PG8_SA(0, 0), a2, voffA);
;             PG8_BAR; PG8_WAIT_L(0); PG8_MMA(1, 0, At, B0); PG8_BAR; PG8_SCHED;
;             PG8_STAGE(PG8_SB(0, 1), b2 + hstepB, voffB);
;             PG8_WAIT_V(6); PG8_BAR; PG8_MMA(1, 1, At, B1); PG8_BAR;
;             PG8_LDB(B0, 1, 0); PG8_SCHED; PG8_LDA(At, 1, 0); PG8_STAGE(PG8_SA(0, 1), a2 + hstepA, voffA);
;             PG8_WAIT_L(8); PG8_BAR; PG8_WAIT_L(0); PG8_MMA(0, 0, At, B0); PG8_BAR; PG8_SCHED;
;             PG8_LDB(B1, 1, 1); PG8_STAGE(PG8_SB(1, 0), b3, voffB);
;             PG8_BAR; PG8_WAIT_L(0); PG8_MMA(0, 1, At, B1); PG8_BAR;
;             PG8_LDA(At, 1, 1); PG8_STAGE(PG8_SA(1, 0), a3, voffA);
	s_setprio 0
	global_load_lds_dwordx4 v172, s[68:69]
	s_add_i32 m0, s70, 0x2000
	s_nop 0
	global_load_lds_dwordx4 v168, s[68:69]
	s_waitcnt vmcnt(6)
	s_setprio 1
	s_barrier
	v_mfma_f32_16x16x32_bf16 v[56:59], v[206:209], v[124:127], v[56:59]
	v_mfma_f32_16x16x32_bf16 v[52:55], v[214:217], v[124:127], v[52:55]
	s_add_i32 s68, 0, 0x18000
	v_add_u32_e32 v92, s68, v188
	ds_read_b128 v[80:83], v92
	v_mfma_f32_16x16x32_bf16 v[44:47], v[206:209], v[140:143], v[44:47]
	v_mfma_f32_16x16x32_bf16 v[36:39], v[214:217], v[140:143], v[36:39]
	ds_read_b128 v[84:87], v92 offset:1024
	v_mfma_f32_16x16x32_bf16 v[28:31], v[206:209], v[160:163], v[28:31]
	v_mfma_f32_16x16x32_bf16 v[20:23], v[214:217], v[160:163], v[20:23]
	ds_read_b128 v[88:91], v92 offset:2048
	v_mfma_f32_16x16x32_bf16 v[4:7], v[206:209], v[198:201], v[4:7]
	v_mfma_f32_16x16x32_bf16 v[0:3], v[214:217], v[198:201], v[0:3]
	ds_read_b128 v[92:95], v92 offset:3072
	v_mfma_f32_16x16x32_bf16 v[56:59], v[210:213], v[132:135], v[56:59]
	s_add_u32 s46, s46, 0x80000
	s_addc_u32 s47, s47, 0
	v_mfma_f32_16x16x32_bf16 v[52:55], v[218:221], v[132:135], v[52:55]
	v_mfma_f32_16x16x32_bf16 v[44:47], v[210:213], v[152:155], v[44:47]
	v_mfma_f32_16x16x32_bf16 v[36:39], v[218:221], v[152:155], v[36:39]
	v_mfma_f32_16x16x32_bf16 v[28:31], v[210:213], v[164:167], v[28:31]
	v_mfma_f32_16x16x32_bf16 v[20:23], v[218:221], v[164:167], v[20:23]
	v_mfma_f32_16x16x32_bf16 v[4:7], v[210:213], v[202:205], v[4:7]
	s_mov_b32 m0, s56
	v_mfma_f32_16x16x32_bf16 v[0:3], v[218:221], v[202:205], v[0:3]
	s_barrier
	s_setprio 0
	ds_read_b128 v[124:127], v190 offset:32768
	ds_read_b128 v[132:135], v190 offset:33792
	ds_read_b128 v[160:163], v190 offset:34816
	ds_read_b128 v[164:167], v190 offset:35840
	ds_read_b128 v[198:201], v190 offset:36864
	ds_read_b128 v[202:205], v190 offset:37888
	ds_read_b128 v[206:209], v190 offset:38912
	global_load_lds_dwordx4 v174, s[46:47]
	s_mov_b32 m0, s57
	ds_read_b128 v[210:213], v190 offset:39936
	global_load_lds_dwordx4 v170, s[46:47]
	s_waitcnt lgkmcnt(8)
	s_setprio 1
	s_barrier
	s_waitcnt lgkmcnt(7)
	v_mfma_f32_16x16x32_bf16 v[140:143], v[80:83], v[124:127], v[148:151]
	s_waitcnt lgkmcnt(6)
	v_mfma_f32_16x16x32_bf16 v[148:151], v[84:87], v[132:135], v[140:143]
	v_mfma_f32_16x16x32_bf16 v[140:143], v[88:91], v[124:127], v[144:147]
	s_waitcnt lgkmcnt(5)
	v_mfma_f32_16x16x32_bf16 v[136:139], v[80:83], v[160:163], v[136:139]
	v_mfma_f32_16x16x32_bf16 v[128:131], v[88:91], v[160:163], v[128:131]
	s_waitcnt lgkmcnt(3)
	v_mfma_f32_16x16x32_bf16 v[120:123], v[80:83], v[198:201], v[120:123]
	v_mfma_f32_16x16x32_bf16 v[104:107], v[88:91], v[198:201], v[104:107]
	s_waitcnt lgkmcnt(1)
	v_mfma_f32_16x16x32_bf16 v[76:79], v[80:83], v[206:209], v[76:79]
	v_mfma_f32_16x16x32_bf16 v[72:75], v[88:91], v[206:209], v[72:75]
	s_add_i32 s46, 0, 0x1c000
	v_mfma_f32_16x16x32_bf16 v[144:147], v[92:95], v[132:135], v[140:143]
	v_add_u32_e32 v140, s46, v188
	v_mfma_f32_16x16x32_bf16 v[136:139], v[84:87], v[164:167], v[136:139]
	s_add_i32 s47, s68, s54
	v_mfma_f32_16x16x32_bf16 v[128:131], v[92:95], v[164:167], v[128:131]
	v_mfma_f32_16x16x32_bf16 v[120:123], v[84:87], v[202:205], v[120:123]
	v_mfma_f32_16x16x32_bf16 v[104:107], v[92:95], v[202:205], v[104:107]
	s_waitcnt lgkmcnt(0)
	v_mfma_f32_16x16x32_bf16 v[76:79], v[84:87], v[210:213], v[76:79]
	s_mov_b32 m0, s47
	v_mfma_f32_16x16x32_bf16 v[72:75], v[92:95], v[210:213], v[72:75]
	s_barrier
	s_setprio 0
	ds_read_b128 v[214:217], v140
	ds_read_b128 v[218:221], v140 offset:1024
	ds_read_b128 v[222:225], v140 offset:2048
	ds_read_b128 v[230:233], v140 offset:3072
	v_lshl_add_u64 v[140:141], v[184:185], 0, s[14:15]
	global_load_lds_dwordx4 v[140:141], off
	v_lshl_add_u64 v[140:141], v[194:195], 0, s[14:15]
	s_add_i32 m0, s47, 0x2000
	s_nop 0
	global_load_lds_dwordx4 v[140:141], off
	s_setprio 1
	s_barrier
	s_waitcnt lgkmcnt(1)
	v_mfma_f32_16x16x32_bf16 v[96:99], v[222:225], v[124:127], v[96:99]
	v_mfma_f32_16x16x32_bf16 v[140:143], v[214:217], v[124:127], v[156:159]
	s_waitcnt lgkmcnt(0)
	v_mfma_f32_16x16x32_bf16 v[152:155], v[230:233], v[132:135], v[96:99]
	v_mfma_f32_16x16x32_bf16 v[96:99], v[214:217], v[160:163], v[100:103]
	v_mfma_f32_16x16x32_bf16 v[156:159], v[218:221], v[132:135], v[140:143]
	v_mfma_f32_16x16x32_bf16 v[140:143], v[218:221], v[164:167], v[96:99]
	v_mfma_f32_16x16x32_bf16 v[96:99], v[222:225], v[160:163], v[108:111]
	v_mfma_f32_16x16x32_bf16 v[132:135], v[230:233], v[164:167], v[96:99]
	v_mfma_f32_16x16x32_bf16 v[96:99], v[214:217], v[198:201], v[112:115]
	s_mov_b32 m0, s63
	v_mfma_f32_16x16x32_bf16 v[124:127], v[218:221], v[202:205], v[96:99]
	v_lshl_add_u64 v[184:185], v[226:227], 0, s[14:15]
	v_mfma_f32_16x16x32_bf16 v[96:99], v[222:225], v[198:201], v[116:119]
	v_mfma_f32_16x16x32_bf16 v[68:71], v[214:217], v[206:209], v[68:71]
	v_mfma_f32_16x16x32_bf16 v[64:67], v[222:225], v[206:209], v[64:67]
	v_mfma_f32_16x16x32_bf16 v[116:119], v[230:233], v[202:205], v[96:99]
	v_mfma_f32_16x16x32_bf16 v[68:71], v[218:221], v[210:213], v[68:71]
	v_mfma_f32_16x16x32_bf16 v[64:67], v[230:233], v[210:213], v[64:67]
	s_barrier
	s_setprio 0
	ds_read_b128 v[96:99], v190 offset:49152
	ds_read_b128 v[100:103], v190 offset:50176
	ds_read_b128 v[108:111], v190 offset:51200
	ds_read_b128 v[112:115], v190 offset:52224
	ds_read_b128 v[160:163], v190 offset:53248
	ds_read_b128 v[164:167], v190 offset:54272
	ds_read_b128 v[198:201], v190 offset:55296
	global_load_lds_dwordx4 v[184:185], off
	v_lshl_add_u64 v[184:185], v[234:235], 0, s[14:15]
	s_mov_b32 m0, s66
	ds_read_b128 v[202:205], v190 offset:56320
	global_load_lds_dwordx4 v[184:185], off
	s_waitcnt vmcnt(10)
	s_setprio 1
	s_barrier
; #define PG8_STAGE(bufoff, gbase, voff) do { _Pragma("unroll") for (int _i = 0; _i < 2; ++_i) \
;         __builtin_amdgcn_global_load_lds((const unsigned*)((const char*)(gbase) + (voff)[_i]), (LAS unsigned*)(lds + (bufoff) + ldsw + _i * 8192), 16, 0, 0); } while (0)
; #define PG8_LDA(dst, b, h) do { _Pragma("unroll") for (int m = 0; m < 4; ++m) _Pragma("unroll") for (int k = 0; k < 2; ++k) dst[m][k] = *(const LAS bf16x8*)(lds + PG8_SA(b, h) + aoff + m * 2048 + k * 1024); } while (0)
; #define PG8_LDB(dst, b, h) do { _Pragma("unroll") for (int n = 0; n < 2; ++n) _Pragma("unroll") for (int k = 0; k < 2; ++k) dst[n][k] = *(const LAS bf16x8*)(lds + PG8_SB(b, h) + boff + n * 2048 + k * 1024); } while (0)
; #define PG8_MMA(ai, bj, At, Bt) do { __builtin_amdgcn_s_setprio(1); _Pragma("unroll") for (int m = 0; m < 4; ++m) _Pragma("unroll") for (int n = 0; n < 2; ++n) _Pragma("unroll") for (int k = 0; k < 2; ++k) \
;         acc[ai][bj][m][n] = __builtin_amdgcn_mfma_f32_16x16x32_bf16(Bt[n][k], At[m][k], acc[ai][bj][m][n], 0, 0, 0); __builtin_amdgcn_s_setprio(0); } while (0)
; #define PG8_WAIT_V(n) asm volatile("s_waitcnt vmcnt(" #n ")" ::: "memory")
; #define PG8_WAIT_L(n) asm volatile("s_waitcnt lgkmcnt(" #n ")" ::: "memory")
; #define PG8_BAR __builtin_amdgcn_s_barrier()
; #define PG8_SCHED __builtin_amdgcn_sched_barrier(0)
; template <class Map, class Epi>
; DI void gemm_phase(LAS unsigned char* lds, const Map& MP, const Epi& E, const int nM, const int nN, const int K, const int lda, const int ldb) {
;     ...
;             PG8_LDB(B0, 0, 0); PG8_SCHED; PG8_LDA(At, 0, 0); PG8_STAGE(PG8_SA(1, 1), a1 + hstepA, voffA);
;     ...
;             PG8_LDA(At, 1, 1); PG8_STAGE(PG8_SA(1, 0), a3, voffA);
;             PG8_BAR; PG8_WAIT_L(0); PG8_MMA(1, 0, At, B0); PG8_BAR; PG8_SCHED;
;             PG8_STAGE(PG8_SB(1, 1), b3 + hstepB, voffB);
;             PG8_WAIT_V(6); PG8_BAR; PG8_MMA(1, 1, At, B1); PG8_BAR;
	s_waitcnt lgkmcnt(7)
	v_mfma_f32_16x16x32_bf16 v[60:63], v[80:83], v[96:99], v[60:63]
	v_mfma_f32_16x16x32_bf16 v[48:51], v[88:91], v[96:99], v[48:51]
	s_waitcnt lgkmcnt(5)
	v_mfma_f32_16x16x32_bf16 v[40:43], v[80:83], v[108:111], v[40:43]
	v_mfma_f32_16x16x32_bf16 v[32:35], v[88:91], v[108:111], v[32:35]
	s_waitcnt lgkmcnt(3)
	v_mfma_f32_16x16x32_bf16 v[24:27], v[80:83], v[160:163], v[24:27]
	v_mfma_f32_16x16x32_bf16 v[16:19], v[88:91], v[160:163], v[16:19]
	s_waitcnt lgkmcnt(1)
	v_mfma_f32_16x16x32_bf16 v[12:15], v[80:83], v[198:201], v[12:15]
	v_mfma_f32_16x16x32_bf16 v[8:11], v[88:91], v[198:201], v[8:11]
	v_mfma_f32_16x16x32_bf16 v[60:63], v[84:87], v[100:103], v[60:63]
	s_add_u32 s28, s28, 0x80080
	s_addc_u32 s29, s29, 0
	v_mfma_f32_16x16x32_bf16 v[48:51], v[92:95], v[100:103], v[48:51]
	s_add_i32 s46, s46, s54
	v_mfma_f32_16x16x32_bf16 v[40:43], v[84:87], v[112:115], v[40:43]
	v_mfma_f32_16x16x32_bf16 v[32:35], v[92:95], v[112:115], v[32:35]
	v_mfma_f32_16x16x32_bf16 v[24:27], v[84:87], v[164:167], v[24:27]
	v_mfma_f32_16x16x32_bf16 v[16:19], v[92:95], v[164:167], v[16:19]
	s_waitcnt lgkmcnt(0)
	v_mfma_f32_16x16x32_bf16 v[12:15], v[84:87], v[202:205], v[12:15]
	s_mov_b32 m0, s46
	v_mfma_f32_16x16x32_bf16 v[8:11], v[92:95], v[202:205], v[8:11]
	s_barrier
	s_setprio 0
	global_load_lds_dwordx4 v172, s[28:29]
	s_add_i32 m0, s46, 0x2000
	s_nop 0
	global_load_lds_dwordx4 v168, s[28:29]
	s_waitcnt vmcnt(6)
	s_setprio 1
	s_barrier
	v_mfma_f32_16x16x32_bf16 v[56:59], v[214:217], v[96:99], v[56:59]
	v_mfma_f32_16x16x32_bf16 v[52:55], v[222:225], v[96:99], v[52:55]
	ds_read_b128 v[80:83], v189
	v_mfma_f32_16x16x32_bf16 v[44:47], v[214:217], v[108:111], v[44:47]
	v_mfma_f32_16x16x32_bf16 v[36:39], v[222:225], v[108:111], v[36:39]
	ds_read_b128 v[84:87], v189 offset:1024
	v_mfma_f32_16x16x32_bf16 v[28:31], v[214:217], v[160:163], v[28:31]
	v_mfma_f32_16x16x32_bf16 v[20:23], v[222:225], v[160:163], v[20:23]
	ds_read_b128 v[88:91], v189 offset:2048
	v_mfma_f32_16x16x32_bf16 v[4:7], v[214:217], v[198:201], v[4:7]
	v_mfma_f32_16x16x32_bf16 v[0:3], v[222:225], v[198:201], v[0:3]
	ds_read_b128 v[92:95], v189 offset:3072
	v_mfma_f32_16x16x32_bf16 v[56:59], v[218:221], v[100:103], v[56:59]
	s_add_i32 s3, s3, 2
	v_mfma_f32_16x16x32_bf16 v[52:55], v[230:233], v[100:103], v[52:55]
	s_add_u32 vcc_lo, vcc_lo, 0x100
	s_addc_u32 vcc_hi, vcc_hi, 0
	v_mfma_f32_16x16x32_bf16 v[44:47], v[218:221], v[112:115], v[44:47]
	s_add_u32 s42, s42, 0x100
	s_addc_u32 s43, s43, 0
	v_mfma_f32_16x16x32_bf16 v[36:39], v[230:233], v[112:115], v[36:39]
	s_cmp_gt_u32 s3, 29
	v_mfma_f32_16x16x32_bf16 v[28:31], v[218:221], v[164:167], v[28:31]
	v_mfma_f32_16x16x32_bf16 v[20:23], v[230:233], v[164:167], v[20:23]
	v_mfma_f32_16x16x32_bf16 v[4:7], v[218:221], v[202:205], v[4:7]
	v_mfma_f32_16x16x32_bf16 v[0:3], v[230:233], v[202:205], v[0:3]
	s_barrier
	s_setprio 0
	s_cbranch_scc0 .LBB1_1908
; DI float silu_mul(float g, float v) { return g * v * __builtin_amdgcn_rcpf(1.0f + __builtin_amdgcn_exp2f(-LOG2E * g)); }
;     DI void operator()(const f32x4 (&acc)[2][2][4][2], const Unit& u, int wr, int wc, int fr, int fq) const {
;         const int row0 = u.pm * BM + wr * 64 + fr, ch0 = u.pn * 128 + wc * 32 + 8 * fq;
;         f32x4 w0[2], w1[2], w2[2], bb[2];
; #pragma unroll
;         for (int n = 0; n < 2; ++n) { w0[n] = *(const f32x4*)(cw + ch0 + 4 * n); w1[n] = *(const f32x4*)(cw + DFF + ch0 + 4 * n); w2[n] = *(const f32x4*)(cw + 2 * DFF + ch0 + 4 * n); bb[n] = *(const f32x4*)(cb + ch0 + 4 * n); }
; #pragma unroll
;         for (int ai = 0; ai < 2; ++ai)
; #pragma unroll
;             for (int m = 0; m < 4; ++m) {
;                 const bool efirst = (m == 0) && (fr == 0), elast = (m == 3) && (fr == 15);
;                 const int row = row0 + ai * HALF + m * 16;
;                 f32x4 gc[2];
; #pragma unroll
;                 for (int n = 0; n < 2; ++n) {
;                     const f32x4 g = acc[ai][0][m][n];
;                     const f32x4 gprev = acc[ai][0][m > 0 ? m - 1 : 0][n], gnext = acc[ai][0][m < 3 ? m + 1 : 3][n];
;                     f32x4 up, dn;
; #pragma unroll
;                     for (int e = 0; e < 4; ++e) {
;                         const float pu = (m > 0 && fr == 15) ? gprev[e] : g[e];
;                         const float pd = (m < 3 && fr == 0) ? gnext[e] : g[e];
;                         up[e] = dpp_ror1(pu); dn[e] = dpp_ror15(pd);
;                     }
;                     if (efirst) up = (f32x4){0.f, 0.f, 0.f, 0.f};
;                     if (elast) dn = (f32x4){0.f, 0.f, 0.f, 0.f};
;                     gc[n] = w0[n] * up + w1[n] * g + w2[n] * dn + bb[n];
;                 }
;                 if (efirst || elast) {
;                     const size_t eo = (size_t)((row >> 6) * 2 + (elast ? 1 : 0)) * DFF + ch0;
; #pragma unroll
;                     for (int n = 0; n < 2; ++n) { *(f32x4*)(EP + eo + 4 * n) = gc[n]; *(f32x4*)(ER + eo + 4 * n) = acc[ai][0][m][n]; *(f32x4*)(EV + eo + 4 * n) = acc[ai][1][m][n]; }
;                 } else {
;                     const f32x4 v0 = acc[ai][1][m][0], v1 = acc[ai][1][m][1];
;                     u32x4 o;
;                     o[0] = pack2(silu_mul(gc[0][0], v0[0]), silu_mul(gc[0][1], v0[1])); o[1] = pack2(silu_mul(gc[0][2], v0[2]), silu_mul(gc[0][3], v0[3]));
	s_waitcnt lgkmcnt(0)
	s_lshl_b32 s21, s45, 7
	v_mov_b32_e32 v194, v186
	v_mov_b32_e32 v80, v187
	s_or_b32 s21, s21, s62
	v_lshl_add_u32 v184, v80, 3, s21
	v_ashrrev_i32_e32 v185, 31, v184
	v_lshlrev_b64 v[80:81], 2, v[184:185]
	v_lshl_add_u64 v[84:85], s[4:5], 0, v[80:81]
	v_lshl_add_u64 v[88:89], s[16:17], 0, v[80:81]
	v_lshl_add_u64 v[92:93], s[18:19], 0, v[80:81]
	v_lshl_add_u64 v[112:113], s[6:7], 0, v[80:81]
	global_load_dwordx4 v[80:83], v[84:85], off offset:16
	global_load_dwordx4 v[96:99], v[84:85], off
	s_nop 0
	global_load_dwordx4 v[84:87], v[88:89], off offset:16
	global_load_dwordx4 v[100:103], v[88:89], off
	s_nop 0
	global_load_dwordx4 v[88:91], v[92:93], off offset:16
	global_load_dwordx4 v[108:111], v[92:93], off
	s_nop 0
	global_load_dwordx4 v[92:95], v[112:113], off offset:16
	s_nop 0
	global_load_dwordx4 v[112:115], v[112:113], off
	v_cmp_eq_u32_e32 vcc, 0, v194
	s_nop 0
	s_nop 0
	v_cndmask_b32_e32 v161, v148, v136, vcc
	v_cndmask_b32_e32 v162, v149, v137, vcc
	v_cndmask_b32_e32 v163, v150, v138, vcc
	v_mov_b32_dpp v160, v161 row_ror:15 row_mask:0xf bank_mask:0xf
	s_nop 0
	s_nop 0
	v_mov_b32_dpp v161, v162 row_ror:15 row_mask:0xf bank_mask:0xf
	v_mov_b32_dpp v164, v150 row_ror:1 row_mask:0xf bank_mask:0xf
	v_cndmask_b32_e32 v165, v151, v139, vcc
	v_mov_b32_dpp v162, v163 row_ror:15 row_mask:0xf bank_mask:0xf
	v_mov_b32_dpp v195, v151 row_ror:1 row_mask:0xf bank_mask:0xf
	v_mov_b32_dpp v166, v148 row_ror:1 row_mask:0xf bank_mask:0xf
	v_mov_b32_dpp v167, v149 row_ror:1 row_mask:0xf bank_mask:0xf
	v_mov_b32_dpp v163, v165 row_ror:15 row_mask:0xf bank_mask:0xf
	v_cndmask_b32_e64 v165, v195, 0, vcc
	v_cndmask_b32_e64 v164, v164, 0, vcc
	v_cndmask_b32_e64 v167, v167, 0, vcc
	v_cndmask_b32_e64 v166, v166, 0, vcc
	s_nop 0
	s_nop 0
	v_mov_b32_dpp v195, v144 row_ror:1 row_mask:0xf bank_mask:0xf
	v_mov_b32_dpp v196, v145 row_ror:1 row_mask:0xf bank_mask:0xf
	v_mov_b32_dpp v198, v146 row_ror:1 row_mask:0xf bank_mask:0xf
	v_cndmask_b32_e32 v199, v147, v131, vcc
	v_mov_b32_dpp v200, v147 row_ror:1 row_mask:0xf bank_mask:0xf
	v_cndmask_b32_e64 v198, v198, 0, vcc
	v_cndmask_b32_e64 v201, v196, 0, vcc
	s_lshl_b32 s3, s44, 8
	s_add_i32 s3, s3, s49
	v_add_u32_e32 v193, s3, v194
	v_cmp_ne_u32_e64 s[46:47], 0, v194
	s_waitcnt vmcnt(0)
	v_pk_mul_f32 v[164:165], v[98:99], v[164:165]
	v_pk_mul_f32 v[166:167], v[96:97], v[166:167]
	v_pk_fma_f32 v[164:165], v[150:151], v[102:103], v[164:165]
	v_pk_fma_f32 v[166:167], v[148:149], v[100:101], v[166:167]
	v_pk_fma_f32 v[162:163], v[110:111], v[162:163], v[164:165]
	v_cndmask_b32_e32 v165, v144, v128, vcc
	v_pk_fma_f32 v[160:161], v[108:109], v[160:161], v[166:167]
	v_cndmask_b32_e32 v166, v145, v129, vcc
	v_mov_b32_dpp v164, v165 row_ror:15 row_mask:0xf bank_mask:0xf
	v_cndmask_b32_e32 v167, v146, v130, vcc
	v_pk_add_f32 v[162:163], v[114:115], v[162:163]
	v_mov_b32_dpp v165, v166 row_ror:15 row_mask:0xf bank_mask:0xf
	v_pk_add_f32 v[160:161], v[112:113], v[160:161]
	s_nop 0
	v_mov_b32_dpp v166, v167 row_ror:15 row_mask:0xf bank_mask:0xf
	s_nop 1
	v_mov_b32_dpp v167, v199 row_ror:15 row_mask:0xf bank_mask:0xf
	v_cndmask_b32_e64 v199, v200, 0, vcc
	v_cndmask_b32_e64 v200, v195, 0, vcc
	v_pk_mul_f32 v[200:201], v[80:81], v[200:201]
	v_pk_mul_f32 v[198:199], v[82:83], v[198:199]
	v_pk_fma_f32 v[200:201], v[144:145], v[84:85], v[200:201]
	v_pk_fma_f32 v[198:199], v[146:147], v[86:87], v[198:199]
	v_pk_fma_f32 v[164:165], v[88:89], v[164:165], v[200:201]
	v_pk_fma_f32 v[166:167], v[90:91], v[166:167], v[198:199]
	v_pk_add_f32 v[164:165], v[92:93], v[164:165]
	v_pk_add_f32 v[166:167], v[94:95], v[166:167]
	s_and_saveexec_b64 s[28:29], s[46:47]
	s_xor_b64 s[28:29], exec, s[28:29]
	s_cbranch_execz .LBB1_1911
	v_mul_f32_e32 v195, 0xbfb8aa3b, v160
	v_exp_f32_e32 v195, v195
	v_mul_f32_e32 v196, 0xbfb8aa3b, v161
	v_exp_f32_e32 v196, v196
	v_pk_mul_f32 v[160:161], v[156:157], v[160:161]
	v_add_f32_e32 v195, 1.0, v195
	v_rcp_f32_e32 v198, v195
	v_add_f32_e32 v196, 1.0, v196
	v_mul_f32_e32 v195, 0xbfb8aa3b, v162
	v_rcp_f32_e32 v199, v196
	v_exp_f32_e32 v195, v195
	v_mul_f32_e32 v196, 0xbfb8aa3b, v163
	v_exp_f32_e32 v196, v196
	v_pk_mul_f32 v[160:161], v[160:161], v[198:199]
	v_add_f32_e32 v195, 1.0, v195
	v_rcp_f32_e32 v200, v195
	v_add_f32_e32 v195, 1.0, v196
	v_rcp_f32_e32 v201, v195
	v_cvt_pk_bf16_f32 v160, v160, v161
	v_mul_f32_e32 v161, 0xbfb8aa3b, v164
	v_exp_f32_e32 v195, v161
	v_mul_f32_e32 v161, 0xbfb8aa3b, v165
	v_exp_f32_e32 v196, v161
	v_pk_mul_f32 v[162:163], v[158:159], v[162:163]
	v_pk_mul_f32 v[164:165], v[152:153], v[164:165]
	v_pk_mul_f32 v[162:163], v[162:163], v[200:201]
	s_nop 0
	v_cvt_pk_bf16_f32 v161, v162, v163
	v_add_f32_e32 v162, 1.0, v195
	v_mul_f32_e32 v195, 0xbfb8aa3b, v166
	v_add_f32_e32 v163, 1.0, v196
	v_exp_f32_e32 v195, v195
	v_mul_f32_e32 v196, 0xbfb8aa3b, v167
	v_exp_f32_e32 v196, v196
	v_rcp_f32_e32 v162, v162
	v_add_f32_e32 v195, 1.0, v195
	v_rcp_f32_e32 v198, v195
	v_add_f32_e32 v195, 1.0, v196
	v_rcp_f32_e32 v163, v163
	v_rcp_f32_e32 v199, v195
	v_pk_mul_f32 v[166:167], v[154:155], v[166:167]
	v_pk_mul_f32 v[162:163], v[164:165], v[162:163]
	v_pk_mul_f32 v[164:165], v[166:167], v[198:199]
	v_cvt_pk_bf16_f32 v162, v162, v163
	v_cvt_pk_bf16_f32 v163, v164, v165
	v_mov_b64_e32 v[164:165], s[52:53]
	v_mad_i64_i32 v[164:165], s[42:43], v193, s60, v[164:165]
	v_lshl_add_u64 v[164:165], v[184:185], 1, v[164:165]
	global_store_dwordx4 v[164:165], v[160:163], off

; #define PG8_STAGE(bufoff, gbase, voff) do { _Pragma("unroll") for (int _i = 0; _i < 2; ++_i) \
;         __builtin_amdgcn_global_load_lds((const unsigned*)((const char*)(gbase) + (voff)[_i]), (LAS unsigned*)(lds + (bufoff) + ldsw + _i * 8192), 16, 0, 0); } while (0)
; #define PG8_LDA(dst, b, h) do { _Pragma("unroll") for (int m = 0; m < 4; ++m) _Pragma("unroll") for (int k = 0; k < 2; ++k) dst[m][k] = *(const LAS bf16x8*)(lds + PG8_SA(b, h) + aoff + m * 2048 + k * 1024); } while (0)
; #define PG8_LDB(dst, b, h) do { _Pragma("unroll") for (int n = 0; n < 2; ++n) _Pragma("unroll") for (int k = 0; k < 2; ++k) dst[n][k] = *(const LAS bf16x8*)(lds + PG8_SB(b, h) + boff + n * 2048 + k * 1024); } while (0)
; #define PG8_MMA(ai, bj, At, Bt) do { __builtin_amdgcn_s_setprio(1); _Pragma("unroll") for (int m = 0; m < 4; ++m) _Pragma("unroll") for (int n = 0; n < 2; ++n) _Pragma("unroll") for (int k = 0; k < 2; ++k) \
;         acc[ai][bj][m][n] = __builtin_amdgcn_mfma_f32_16x16x32_bf16(Bt[n][k], At[m][k], acc[ai][bj][m][n], 0, 0, 0); __builtin_amdgcn_s_setprio(0); } while (0)
; #define PG8_WAIT_V(n) asm volatile("s_waitcnt vmcnt(" #n ")" ::: "memory")
; #define PG8_WAIT_L(n) asm volatile("s_waitcnt lgkmcnt(" #n ")" ::: "memory")
; #define PG8_BAR __builtin_amdgcn_s_barrier()
; #define PG8_SCHED __builtin_amdgcn_sched_barrier(0)
; template <class Map, class Epi>
; DI void gemm_phase(LAS unsigned char* lds, const Map& MP, const Epi& E, const int nM, const int nN, const int K, const int lda, const int ldb) {
;     ...
;             PG8_LDB(B0, 0, 0); PG8_SCHED; PG8_LDA(At, 0, 0); PG8_STAGE(PG8_SA(1, 1), a1 + hstepA, voffA);
;             PG8_WAIT_L(8); PG8_BAR; PG8_WAIT_L(0); PG8_MMA(0, 0, At, B0); PG8_BAR; PG8_SCHED;
;             PG8_LDB(B1, 0, 1); PG8_STAGE(PG8_SB(0, 0), b2, voffB);
;             PG8_BAR; PG8_WAIT_L(0); PG8_MMA(0, 1, At, B1); PG8_BAR;
;             PG8_LDA(At, 0, 1); PG8_STAGE(PG8_SA(0, 0), a2, voffA);
;             PG8_BAR; PG8_WAIT_L(0); PG8_MMA(1, 0, At, B0); PG8_BAR; PG8_SCHED;
;             PG8_STAGE(PG8_SB(0, 1), b2 + hstepB, voffB);
;             PG8_WAIT_V(6); PG8_BAR; PG8_MMA(1, 1, At, B1); PG8_BAR;
.LBB1_2078:
	s_add_u32 s10, s8, 0x100
	s_addc_u32 s11, s9, 0
	s_cmpk_eq_i32 s3, 0x54
	s_cselect_b32 s15, s43, s11
	s_cselect_b32 s14, s42, s10
	s_cselect_b32 s13, s7, s44
	s_cselect_b32 s12, s6, s39
	s_add_i32 m0, s24, 0xc000
	ds_read_b128 v[168:171], v150
	ds_read_b128 v[172:175], v150 offset:1024
	ds_read_b128 v[176:179], v150 offset:2048
	ds_read_b128 v[180:183], v150 offset:3072
	ds_read_b128 v[184:187], v150 offset:4096
	ds_read_b128 v[188:191], v150 offset:5120
	ds_read_b128 v[192:195], v150 offset:6144
	ds_read_b128 v[198:201], v150 offset:7168
	global_load_lds_dwordx4 v138, s[8:9]
	s_add_i32 m0, s24, 0xe000
	s_nop 0
	global_load_lds_dwordx4 v136, s[8:9]
	s_waitcnt lgkmcnt(8)
	s_setprio 1
	s_barrier
	s_waitcnt lgkmcnt(7)
	v_mfma_f32_16x16x32_bf16 v[124:127], v[152:155], v[168:171], v[124:127]
	v_mfma_f32_16x16x32_bf16 v[120:123], v[160:163], v[168:171], v[120:123]
	s_waitcnt lgkmcnt(5)
	v_mfma_f32_16x16x32_bf16 v[108:111], v[152:155], v[176:179], v[108:111]
	v_mfma_f32_16x16x32_bf16 v[104:107], v[160:163], v[176:179], v[104:107]
	s_waitcnt lgkmcnt(3)
	v_mfma_f32_16x16x32_bf16 v[92:95], v[152:155], v[184:187], v[92:95]
	v_mfma_f32_16x16x32_bf16 v[88:91], v[160:163], v[184:187], v[88:91]
	s_waitcnt lgkmcnt(1)
	v_mfma_f32_16x16x32_bf16 v[76:79], v[152:155], v[192:195], v[76:79]
	v_mfma_f32_16x16x32_bf16 v[72:75], v[160:163], v[192:195], v[72:75]
	v_mfma_f32_16x16x32_bf16 v[124:127], v[156:159], v[172:175], v[124:127]
	s_add_i32 s8, s35, s22
	v_mfma_f32_16x16x32_bf16 v[120:123], v[164:167], v[172:175], v[120:123]
	v_lshl_add_u64 v[144:145], s[12:13], 0, v[132:133]
	v_mfma_f32_16x16x32_bf16 v[108:111], v[156:159], v[180:183], v[108:111]
	v_lshl_add_u64 v[218:219], s[12:13], 0, v[128:129]
	v_mfma_f32_16x16x32_bf16 v[104:107], v[164:167], v[180:183], v[104:107]
	v_mfma_f32_16x16x32_bf16 v[92:95], v[156:159], v[188:191], v[92:95]
	v_mfma_f32_16x16x32_bf16 v[88:91], v[164:167], v[188:191], v[88:91]
	s_waitcnt lgkmcnt(0)
	v_mfma_f32_16x16x32_bf16 v[76:79], v[156:159], v[198:201], v[76:79]
	s_mov_b32 m0, s8
	v_mfma_f32_16x16x32_bf16 v[72:75], v[164:167], v[198:201], v[72:75]
	s_barrier
	s_setprio 0
	ds_read_b128 v[202:205], v151
	ds_read_b128 v[206:209], v151 offset:1024
	ds_read_b128 v[210:213], v151 offset:2048
	global_load_lds_dwordx4 v[144:145], off
	s_add_i32 m0, s8, 0x2000
	ds_read_b128 v[214:217], v151 offset:3072
	global_load_lds_dwordx4 v[218:219], off
	s_setprio 1
	s_barrier
	s_waitcnt lgkmcnt(3)
	v_mfma_f32_16x16x32_bf16 v[116:119], v[202:205], v[168:171], v[116:119]
	s_waitcnt lgkmcnt(1)
	v_mfma_f32_16x16x32_bf16 v[112:115], v[210:213], v[168:171], v[112:115]
	v_mfma_f32_16x16x32_bf16 v[100:103], v[202:205], v[176:179], v[100:103]
	v_mfma_f32_16x16x32_bf16 v[96:99], v[210:213], v[176:179], v[96:99]
	v_mfma_f32_16x16x32_bf16 v[84:87], v[202:205], v[184:187], v[84:87]
	v_mfma_f32_16x16x32_bf16 v[80:83], v[210:213], v[184:187], v[80:83]
	v_mfma_f32_16x16x32_bf16 v[68:71], v[202:205], v[192:195], v[68:71]
	v_mfma_f32_16x16x32_bf16 v[64:67], v[210:213], v[192:195], v[64:67]
	v_mfma_f32_16x16x32_bf16 v[116:119], v[206:209], v[172:175], v[116:119]
	v_lshl_add_u64 v[222:223], s[14:15], 0, v[130:131]
	s_mov_b32 m0, s24
	s_waitcnt lgkmcnt(0)
	v_mfma_f32_16x16x32_bf16 v[112:115], v[214:217], v[172:175], v[112:115]
	v_lshl_add_u64 v[220:221], s[14:15], 0, v[134:135]
	v_mfma_f32_16x16x32_bf16 v[100:103], v[206:209], v[180:183], v[100:103]
	v_mfma_f32_16x16x32_bf16 v[96:99], v[214:217], v[180:183], v[96:99]
	v_mfma_f32_16x16x32_bf16 v[84:87], v[206:209], v[188:191], v[84:87]
	v_mfma_f32_16x16x32_bf16 v[80:83], v[214:217], v[188:191], v[80:83]
	v_mfma_f32_16x16x32_bf16 v[68:71], v[206:209], v[198:201], v[68:71]
	v_mfma_f32_16x16x32_bf16 v[64:67], v[214:217], v[198:201], v[64:67]
	s_barrier
	s_setprio 0
	ds_read_b128 v[168:171], v150 offset:16384
	ds_read_b128 v[172:175], v150 offset:17408
	ds_read_b128 v[176:179], v150 offset:18432
	ds_read_b128 v[180:183], v150 offset:19456
	ds_read_b128 v[184:187], v150 offset:20480
	ds_read_b128 v[188:191], v150 offset:21504
	ds_read_b128 v[192:195], v150 offset:22528
	global_load_lds_dwordx4 v[220:221], off
	s_mov_b32 m0, s25
	ds_read_b128 v[198:201], v150 offset:23552
	global_load_lds_dwordx4 v[222:223], off
	s_waitcnt vmcnt(10)
	s_setprio 1
	s_barrier
	s_waitcnt lgkmcnt(7)
	v_mfma_f32_16x16x32_bf16 v[60:63], v[152:155], v[168:171], v[60:63]
	v_mfma_f32_16x16x32_bf16 v[56:59], v[160:163], v[168:171], v[56:59]
	s_waitcnt lgkmcnt(5)
	v_mfma_f32_16x16x32_bf16 v[44:47], v[152:155], v[176:179], v[44:47]
	v_mfma_f32_16x16x32_bf16 v[40:43], v[160:163], v[176:179], v[40:43]
	s_waitcnt lgkmcnt(3)
	v_mfma_f32_16x16x32_bf16 v[28:31], v[152:155], v[184:187], v[28:31]
	v_mfma_f32_16x16x32_bf16 v[24:27], v[160:163], v[184:187], v[24:27]
	s_waitcnt lgkmcnt(1)
	v_mfma_f32_16x16x32_bf16 v[12:15], v[152:155], v[192:195], v[12:15]
	v_mfma_f32_16x16x32_bf16 v[8:11], v[160:163], v[192:195], v[8:11]
	v_mfma_f32_16x16x32_bf16 v[60:63], v[156:159], v[172:175], v[60:63]
	s_add_u32 s8, s12, 0x160000
	s_addc_u32 s9, s13, 0
	v_mfma_f32_16x16x32_bf16 v[56:59], v[164:167], v[172:175], v[56:59]
	s_add_i32 s45, s36, s22
	v_mfma_f32_16x16x32_bf16 v[44:47], v[156:159], v[180:183], v[44:47]
	v_mfma_f32_16x16x32_bf16 v[40:43], v[164:167], v[180:183], v[40:43]
	v_mfma_f32_16x16x32_bf16 v[28:31], v[156:159], v[188:191], v[28:31]
	v_mfma_f32_16x16x32_bf16 v[24:27], v[164:167], v[188:191], v[24:27]
	s_waitcnt lgkmcnt(0)
	v_mfma_f32_16x16x32_bf16 v[12:15], v[156:159], v[198:201], v[12:15]
	s_mov_b32 m0, s45
	v_mfma_f32_16x16x32_bf16 v[8:11], v[164:167], v[198:201], v[8:11]
	s_barrier
; #define PG8_STAGE(bufoff, gbase, voff) do { _Pragma("unroll") for (int _i = 0; _i < 2; ++_i) \
;         __builtin_amdgcn_global_load_lds((const unsigned*)((const char*)(gbase) + (voff)[_i]), (LAS unsigned*)(lds + (bufoff) + ldsw + _i * 8192), 16, 0, 0); } while (0)
; #define PG8_LDA(dst, b, h) do { _Pragma("unroll") for (int m = 0; m < 4; ++m) _Pragma("unroll") for (int k = 0; k < 2; ++k) dst[m][k] = *(const LAS bf16x8*)(lds + PG8_SA(b, h) + aoff + m * 2048 + k * 1024); } while (0)
; #define PG8_LDB(dst, b, h) do { _Pragma("unroll") for (int n = 0; n < 2; ++n) _Pragma("unroll") for (int k = 0; k < 2; ++k) dst[n][k] = *(const LAS bf16x8*)(lds + PG8_SB(b, h) + boff + n * 2048 + k * 1024); } while (0)
; #define PG8_MMA(ai, bj, At, Bt) do { __builtin_amdgcn_s_setprio(1); _Pragma("unroll") for (int m = 0; m < 4; ++m) _Pragma("unroll") for (int n = 0; n < 2; ++n) _Pragma("unroll") for (int k = 0; k < 2; ++k) \
;         acc[ai][bj][m][n] = __builtin_amdgcn_mfma_f32_16x16x32_bf16(Bt[n][k], At[m][k], acc[ai][bj][m][n], 0, 0, 0); __builtin_amdgcn_s_setprio(0); } while (0)
; #define PG8_WAIT_V(n) asm volatile("s_waitcnt vmcnt(" #n ")" ::: "memory")
; #define PG8_WAIT_L(n) asm volatile("s_waitcnt lgkmcnt(" #n ")" ::: "memory")
; #define PG8_BAR __builtin_amdgcn_s_barrier()
; #define PG8_SCHED __builtin_amdgcn_sched_barrier(0)
; template <class Map, class Epi>
; DI void gemm_phase(LAS unsigned char* lds, const Map& MP, const Epi& E, const int nM, const int nN, const int K, const int lda, const int ldb) {
;     ...
;             PG8_LDA(At, 0, 1); PG8_STAGE(PG8_SA(0, 0), a2, voffA);
;             PG8_BAR; PG8_WAIT_L(0); PG8_MMA(1, 0, At, B0); PG8_BAR; PG8_SCHED;
;             PG8_STAGE(PG8_SB(0, 1), b2 + hstepB, voffB);
;             PG8_WAIT_V(6); PG8_BAR; PG8_MMA(1, 1, At, B1); PG8_BAR;
;             PG8_LDB(B0, 1, 0); PG8_SCHED; PG8_LDA(At, 1, 0); PG8_STAGE(PG8_SA(0, 1), a2 + hstepA, voffA);
;             PG8_WAIT_L(8); PG8_BAR; PG8_WAIT_L(0); PG8_MMA(0, 0, At, B0); PG8_BAR; PG8_SCHED;
;             PG8_LDB(B1, 1, 1); PG8_STAGE(PG8_SB(1, 0), b3, voffB);
;             PG8_BAR; PG8_WAIT_L(0); PG8_MMA(0, 1, At, B1); PG8_BAR;
;             PG8_LDA(At, 1, 1); PG8_STAGE(PG8_SA(1, 0), a3, voffA);
	s_setprio 0
	global_load_lds_dwordx4 v132, s[8:9]
	s_add_i32 m0, s45, 0x2000
	s_nop 0
	global_load_lds_dwordx4 v128, s[8:9]
	s_waitcnt vmcnt(6)
	s_setprio 1
	s_barrier
	v_mfma_f32_16x16x32_bf16 v[52:55], v[202:205], v[168:171], v[52:55]
	v_mfma_f32_16x16x32_bf16 v[48:51], v[210:213], v[168:171], v[48:51]
	s_add_i32 s45, 0, 0x18000
	v_add_u32_e32 v164, s45, v148
	ds_read_b128 v[152:155], v164
	v_mfma_f32_16x16x32_bf16 v[36:39], v[202:205], v[176:179], v[36:39]
	v_mfma_f32_16x16x32_bf16 v[32:35], v[210:213], v[176:179], v[32:35]
	ds_read_b128 v[156:159], v164 offset:1024
	v_mfma_f32_16x16x32_bf16 v[20:23], v[202:205], v[184:187], v[20:23]
	v_mfma_f32_16x16x32_bf16 v[16:19], v[210:213], v[184:187], v[16:19]
	ds_read_b128 v[160:163], v164 offset:2048
	v_mfma_f32_16x16x32_bf16 v[4:7], v[202:205], v[192:195], v[4:7]
	v_mfma_f32_16x16x32_bf16 v[0:3], v[210:213], v[192:195], v[0:3]
	ds_read_b128 v[164:167], v164 offset:3072
	v_mfma_f32_16x16x32_bf16 v[52:55], v[206:209], v[172:175], v[52:55]
	s_add_u32 s8, s14, 0x160000
	s_addc_u32 s9, s15, 0
	v_mfma_f32_16x16x32_bf16 v[48:51], v[214:217], v[172:175], v[48:51]
	v_mfma_f32_16x16x32_bf16 v[36:39], v[206:209], v[180:183], v[36:39]
	v_mfma_f32_16x16x32_bf16 v[32:35], v[214:217], v[180:183], v[32:35]
	v_mfma_f32_16x16x32_bf16 v[20:23], v[206:209], v[188:191], v[20:23]
	v_mfma_f32_16x16x32_bf16 v[16:19], v[214:217], v[188:191], v[16:19]
	v_mfma_f32_16x16x32_bf16 v[4:7], v[206:209], v[198:201], v[4:7]
	s_mov_b32 m0, s26
	v_mfma_f32_16x16x32_bf16 v[0:3], v[214:217], v[198:201], v[0:3]
	s_barrier
	s_setprio 0
	ds_read_b128 v[168:171], v150 offset:32768
	ds_read_b128 v[172:175], v150 offset:33792
	ds_read_b128 v[176:179], v150 offset:34816
	ds_read_b128 v[180:183], v150 offset:35840
	ds_read_b128 v[184:187], v150 offset:36864
	ds_read_b128 v[188:191], v150 offset:37888
	ds_read_b128 v[192:195], v150 offset:38912
	global_load_lds_dwordx4 v134, s[8:9]
	s_mov_b32 m0, s27
	ds_read_b128 v[198:201], v150 offset:39936
	global_load_lds_dwordx4 v130, s[8:9]
	s_waitcnt lgkmcnt(8)
	s_setprio 1
	s_barrier
	s_waitcnt lgkmcnt(7)
	v_mfma_f32_16x16x32_bf16 v[124:127], v[152:155], v[168:171], v[124:127]
	v_mfma_f32_16x16x32_bf16 v[120:123], v[160:163], v[168:171], v[120:123]
	s_waitcnt lgkmcnt(5)
	v_mfma_f32_16x16x32_bf16 v[108:111], v[152:155], v[176:179], v[108:111]
	v_mfma_f32_16x16x32_bf16 v[104:107], v[160:163], v[176:179], v[104:107]
	s_waitcnt lgkmcnt(3)
	v_mfma_f32_16x16x32_bf16 v[92:95], v[152:155], v[184:187], v[92:95]
	v_mfma_f32_16x16x32_bf16 v[88:91], v[160:163], v[184:187], v[88:91]
	s_waitcnt lgkmcnt(1)
	v_mfma_f32_16x16x32_bf16 v[76:79], v[152:155], v[192:195], v[76:79]
	v_mfma_f32_16x16x32_bf16 v[72:75], v[160:163], v[192:195], v[72:75]
	v_mfma_f32_16x16x32_bf16 v[124:127], v[156:159], v[172:175], v[124:127]
	s_add_i32 s14, 0, 0x1c000
	v_mfma_f32_16x16x32_bf16 v[120:123], v[164:167], v[172:175], v[120:123]
	s_add_i32 s8, s45, s22
	v_mfma_f32_16x16x32_bf16 v[108:111], v[156:159], v[180:183], v[108:111]
	v_add_u32_e32 v196, s14, v148
	v_mfma_f32_16x16x32_bf16 v[104:107], v[164:167], v[180:183], v[104:107]
	v_lshl_add_u64 v[144:145], v[144:145], 0, s[46:47]
	v_mfma_f32_16x16x32_bf16 v[92:95], v[156:159], v[188:191], v[92:95]
	v_mfma_f32_16x16x32_bf16 v[88:91], v[164:167], v[188:191], v[88:91]
	s_waitcnt lgkmcnt(0)
	v_mfma_f32_16x16x32_bf16 v[76:79], v[156:159], v[198:201], v[76:79]
	s_mov_b32 m0, s8
	v_mfma_f32_16x16x32_bf16 v[72:75], v[164:167], v[198:201], v[72:75]
	s_barrier
	s_setprio 0
	ds_read_b128 v[202:205], v196
	ds_read_b128 v[206:209], v196 offset:1024
	ds_read_b128 v[210:213], v196 offset:2048
	global_load_lds_dwordx4 v[144:145], off
	v_lshl_add_u64 v[144:145], v[218:219], 0, s[46:47]
	s_add_i32 m0, s8, 0x2000
	ds_read_b128 v[214:217], v196 offset:3072
	global_load_lds_dwordx4 v[144:145], off
	s_setprio 1
	s_barrier
	s_waitcnt lgkmcnt(3)
	v_mfma_f32_16x16x32_bf16 v[116:119], v[202:205], v[168:171], v[116:119]
	s_waitcnt lgkmcnt(1)
	v_mfma_f32_16x16x32_bf16 v[112:115], v[210:213], v[168:171], v[112:115]
	v_mfma_f32_16x16x32_bf16 v[100:103], v[202:205], v[176:179], v[100:103]
	v_mfma_f32_16x16x32_bf16 v[96:99], v[210:213], v[176:179], v[96:99]
	v_mfma_f32_16x16x32_bf16 v[84:87], v[202:205], v[184:187], v[84:87]
	v_mfma_f32_16x16x32_bf16 v[80:83], v[210:213], v[184:187], v[80:83]
	v_mfma_f32_16x16x32_bf16 v[68:71], v[202:205], v[192:195], v[68:71]
	v_mfma_f32_16x16x32_bf16 v[64:67], v[210:213], v[192:195], v[64:67]
	v_mfma_f32_16x16x32_bf16 v[116:119], v[206:209], v[172:175], v[116:119]
	s_mov_b32 m0, s30
	s_waitcnt lgkmcnt(0)
	v_mfma_f32_16x16x32_bf16 v[112:115], v[214:217], v[172:175], v[112:115]
	v_lshl_add_u64 v[144:145], v[220:221], 0, s[46:47]
	v_mfma_f32_16x16x32_bf16 v[100:103], v[206:209], v[180:183], v[100:103]
	v_mfma_f32_16x16x32_bf16 v[96:99], v[214:217], v[180:183], v[96:99]
	v_mfma_f32_16x16x32_bf16 v[84:87], v[206:209], v[188:191], v[84:87]
	v_mfma_f32_16x16x32_bf16 v[80:83], v[214:217], v[188:191], v[80:83]
	v_mfma_f32_16x16x32_bf16 v[68:71], v[206:209], v[198:201], v[68:71]
	v_mfma_f32_16x16x32_bf16 v[64:67], v[214:217], v[198:201], v[64:67]
	s_barrier
	s_setprio 0
	ds_read_b128 v[168:171], v150 offset:49152
	ds_read_b128 v[172:175], v150 offset:50176
	ds_read_b128 v[176:179], v150 offset:51200
	ds_read_b128 v[180:183], v150 offset:52224
	ds_read_b128 v[184:187], v150 offset:53248
	ds_read_b128 v[188:191], v150 offset:54272
	ds_read_b128 v[192:195], v150 offset:55296
	global_load_lds_dwordx4 v[144:145], off
	v_lshl_add_u64 v[144:145], v[222:223], 0, s[46:47]
	s_mov_b32 m0, s31
	ds_read_b128 v[198:201], v150 offset:56320
	global_load_lds_dwordx4 v[144:145], off
	s_waitcnt vmcnt(10)
	s_setprio 1
	s_barrier
; DI float bflo(unsigned w) { return __uint_as_float(w << 16); }
;     DI void operator()(const f32x4 (&acc)[2][2][4][2], const Unit& u, int wr, int wc, int fr, int fq) const {
;         const int row0 = u.pm * BM + wr * 64 + fr, col0 = u.pn * BM + wc * 32 + 8 * fq;
;         f32x4 sc[2][2];
; #pragma unroll
;         for (int bj = 0; bj < 2; ++bj)
; #pragma unroll
;             for (int n = 0; n < 2; ++n) sc[bj][n] = scale ? *(const f32x4*)(scale + col0 + bj * HALF + 4 * n) : (f32x4){1.f, 1.f, 1.f, 1.f};
; #pragma unroll
;         for (int ai = 0; ai < 2; ++ai)
; #pragma unroll
;             for (int m = 0; m < 4; ++m) { const size_t ro = (size_t)(row0 + ai * HALF + m * 16) * D + col0;
; #pragma unroll
;                 for (int bj = 0; bj < 2; ++bj) {
;                     f32x4 x0, x1;
;                     if constexpr (IB) { const u32x4 w = *(const u32x4*)((const bf16_t*)Xin + ro + bj * HALF);
;                         x0 = (f32x4){bflo(w[0]), bfhi(w[0]), bflo(w[1]), bfhi(w[1])}; x1 = (f32x4){bflo(w[2]), bfhi(w[2]), bflo(w[3]), bfhi(w[3])}; }
;                     else { x0 = *(const f32x4*)((const float*)Xin + ro + bj * HALF); x1 = *(const f32x4*)((const float*)Xin + ro + bj * HALF + 4); }
;                     x0 += acc[ai][bj][m][0] * sc[bj][0]; x1 += acc[ai][bj][m][1] * sc[bj][1];
;                     if constexpr (OB) { u32x4 o; o[0] = pack2(x0[0], x0[1]); o[1] = pack2(x0[2], x0[3]); o[2] = pack2(x1[0], x1[1]); o[3] = pack2(x1[2], x1[3]);
;                         *(u32x4*)((bf16_t*)Xout + ro + bj * HALF) = o; }
;                     else { *(f32x4*)((float*)Xout + ro + bj * HALF) = x0; *(f32x4*)((float*)Xout + ro + bj * HALF + 4) = x1; } } }
;     }
; template <class Map, class Epi>
; DI void gemm_phase(LAS unsigned char* lds, const Map& MP, const Epi& E, const int nM, const int nN, const int K, const int lda, const int ldb) {
;     ...
;             PG8_WAIT_L(8); PG8_BAR; PG8_WAIT_L(0); PG8_MMA(0, 0, At, B0); PG8_BAR; PG8_SCHED;
;             PG8_LDB(B1, 1, 1); PG8_STAGE(PG8_SB(1, 0), b3, voffB);
;             PG8_BAR; PG8_WAIT_L(0); PG8_MMA(0, 1, At, B1); PG8_BAR;
;             PG8_LDA(At, 1, 1); PG8_STAGE(PG8_SA(1, 0), a3, voffA);
;             PG8_BAR; PG8_WAIT_L(0); PG8_MMA(1, 0, At, B0); PG8_BAR; PG8_SCHED;
;             PG8_STAGE(PG8_SB(1, 1), b3 + hstepB, voffB);
;             PG8_WAIT_V(6); PG8_BAR; PG8_MMA(1, 1, At, B1); PG8_BAR;
	s_waitcnt lgkmcnt(7)
	v_mfma_f32_16x16x32_bf16 v[60:63], v[152:155], v[168:171], v[60:63]
	v_mfma_f32_16x16x32_bf16 v[56:59], v[160:163], v[168:171], v[56:59]
	s_waitcnt lgkmcnt(5)
	v_mfma_f32_16x16x32_bf16 v[44:47], v[152:155], v[176:179], v[44:47]
	v_mfma_f32_16x16x32_bf16 v[40:43], v[160:163], v[176:179], v[40:43]
	s_waitcnt lgkmcnt(3)
	v_mfma_f32_16x16x32_bf16 v[28:31], v[152:155], v[184:187], v[28:31]
	v_mfma_f32_16x16x32_bf16 v[24:27], v[160:163], v[184:187], v[24:27]
	s_waitcnt lgkmcnt(1)
	v_mfma_f32_16x16x32_bf16 v[12:15], v[152:155], v[192:195], v[12:15]
	v_mfma_f32_16x16x32_bf16 v[8:11], v[160:163], v[192:195], v[8:11]
	v_mfma_f32_16x16x32_bf16 v[60:63], v[156:159], v[172:175], v[60:63]
	s_add_u32 s8, s12, 0x160080
	s_addc_u32 s9, s13, 0
	v_mfma_f32_16x16x32_bf16 v[56:59], v[164:167], v[172:175], v[56:59]
	s_add_i32 s12, s14, s22
	v_mfma_f32_16x16x32_bf16 v[44:47], v[156:159], v[180:183], v[44:47]
	v_mfma_f32_16x16x32_bf16 v[40:43], v[164:167], v[180:183], v[40:43]
	v_mfma_f32_16x16x32_bf16 v[28:31], v[156:159], v[188:191], v[28:31]
	v_mfma_f32_16x16x32_bf16 v[24:27], v[164:167], v[188:191], v[24:27]
	s_waitcnt lgkmcnt(0)
	v_mfma_f32_16x16x32_bf16 v[12:15], v[156:159], v[198:201], v[12:15]
	s_mov_b32 m0, s12
	v_mfma_f32_16x16x32_bf16 v[8:11], v[164:167], v[198:201], v[8:11]
	s_barrier
	s_setprio 0
	global_load_lds_dwordx4 v132, s[8:9]
	s_add_i32 m0, s12, 0x2000
	s_nop 0
	global_load_lds_dwordx4 v128, s[8:9]
	s_waitcnt vmcnt(6)
	s_setprio 1
	s_barrier
	v_mfma_f32_16x16x32_bf16 v[52:55], v[202:205], v[168:171], v[52:55]
	v_mfma_f32_16x16x32_bf16 v[48:51], v[210:213], v[168:171], v[48:51]
	ds_read_b128 v[152:155], v149
	v_mfma_f32_16x16x32_bf16 v[36:39], v[202:205], v[176:179], v[36:39]
	v_mfma_f32_16x16x32_bf16 v[32:35], v[210:213], v[176:179], v[32:35]
	ds_read_b128 v[156:159], v149 offset:1024
	v_mfma_f32_16x16x32_bf16 v[20:23], v[202:205], v[184:187], v[20:23]
	v_mfma_f32_16x16x32_bf16 v[16:19], v[210:213], v[184:187], v[16:19]
	ds_read_b128 v[160:163], v149 offset:2048
	v_mfma_f32_16x16x32_bf16 v[4:7], v[202:205], v[192:195], v[4:7]
	v_mfma_f32_16x16x32_bf16 v[0:3], v[210:213], v[192:195], v[0:3]
	ds_read_b128 v[164:167], v149 offset:3072
	v_mfma_f32_16x16x32_bf16 v[52:55], v[206:209], v[172:175], v[52:55]
	s_add_i32 s3, s3, 2
	v_mfma_f32_16x16x32_bf16 v[48:51], v[214:217], v[172:175], v[48:51]
	s_add_u32 s39, s39, 0x100
	s_addc_u32 s44, s44, 0
	v_mfma_f32_16x16x32_bf16 v[36:39], v[206:209], v[180:183], v[36:39]
	s_cmpk_gt_u32 s3, 0x55
	v_mfma_f32_16x16x32_bf16 v[32:35], v[214:217], v[180:183], v[32:35]
	s_mov_b64 s[8:9], s[10:11]
	v_mfma_f32_16x16x32_bf16 v[20:23], v[206:209], v[188:191], v[20:23]
	v_mfma_f32_16x16x32_bf16 v[16:19], v[214:217], v[188:191], v[16:19]
	v_mfma_f32_16x16x32_bf16 v[4:7], v[206:209], v[198:201], v[4:7]
	v_mfma_f32_16x16x32_bf16 v[0:3], v[214:217], v[198:201], v[0:3]
	s_barrier
	s_setprio 0
	s_cbranch_scc0 .LBB1_2078
	s_waitcnt lgkmcnt(0)
	v_mov_b32_e32 v152, v147
	v_mov_b32_e32 v144, v146
	s_lshl_b32 s2, s2, 8
	s_add_i32 s2, s2, s29
	s_lshl_b32 s3, s38, 8
	v_add_u32_e32 v152, s2, v152
	s_or_b32 s3, s3, s52
	v_ashrrev_i32_e32 v153, 31, v152
	v_lshl_add_u32 v144, v144, 3, s3
	v_lshlrev_b64 v[152:153], 12, v[152:153]
	v_ashrrev_i32_e32 v145, 31, v144
	v_lshl_add_u64 v[152:153], s[4:5], 0, v[152:153]
	v_lshl_add_u64 v[144:145], v[144:145], 1, v[152:153]
	global_load_dwordx4 v[160:163], v[144:145], off
	global_load_dwordx4 v[164:167], v[144:145], off offset:256
	s_mov_b64 s[98:99], 0x10000
	v_lshl_add_u64 v[154:155], v[144:145], 0, s[98:99]
	global_load_dwordx4 v[168:171], v[154:155], off
	global_load_dwordx4 v[172:175], v[154:155], off offset:256
	s_mov_b64 s[98:99], 0x20000
	v_lshl_add_u64 v[154:155], v[144:145], 0, s[98:99]
	global_load_dwordx4 v[176:179], v[154:155], off
	global_load_dwordx4 v[180:183], v[154:155], off offset:256
	s_mov_b64 s[98:99], 0x30000
	v_lshl_add_u64 v[154:155], v[144:145], 0, s[98:99]
	global_load_dwordx4 v[184:187], v[154:155], off
	global_load_dwordx4 v[188:191], v[154:155], off offset:256
	s_mov_b64 s[98:99], 0x80000
	v_lshl_add_u64 v[154:155], v[144:145], 0, s[98:99]
	global_load_dwordx4 v[192:195], v[154:155], off
	global_load_dwordx4 v[198:201], v[154:155], off offset:256
	s_mov_b64 s[98:99], 0x90000
	v_lshl_add_u64 v[154:155], v[144:145], 0, s[98:99]
	global_load_dwordx4 v[202:205], v[154:155], off
	global_load_dwordx4 v[206:209], v[154:155], off offset:256
	s_mov_b64 s[98:99], 0xa0000
	v_lshl_add_u64 v[154:155], v[144:145], 0, s[98:99]
	global_load_dwordx4 v[210:213], v[154:155], off
	global_load_dwordx4 v[214:217], v[154:155], off offset:256
	s_mov_b64 s[98:99], 0xb0000
	v_lshl_add_u64 v[154:155], v[144:145], 0, s[98:99]
	global_load_dwordx4 v[248:251], v[154:155], off
	global_load_dwordx4 v[252:255], v[154:155], off offset:256
	s_waitcnt vmcnt(15)
	s_nop 1
	v_mov_b32_e32 v152, v160
	v_mov_b32_e32 v153, v161
	v_mov_b32_e32 v154, v162
	v_mov_b32_e32 v155, v163
	s_mov_b64 s[2:3], 0x10000
	s_mov_b32 s38, s37
	s_mov_b64 s[10:11], s[6:7]
	s_mov_b64 s[8:9], s[42:43]
	s_waitcnt lgkmcnt(0)
	v_lshlrev_b32_e32 v156, 16, v152
	v_and_b32_e32 v157, 0xffff0000, v152
	v_lshlrev_b32_e32 v152, 16, v153
	v_and_b32_e32 v153, 0xffff0000, v153
	v_lshlrev_b32_e32 v158, 16, v154
	v_and_b32_e32 v159, 0xffff0000, v154
	v_lshlrev_b32_e32 v154, 16, v155
	v_and_b32_e32 v155, 0xffff0000, v155
	v_pk_add_f32 v[126:127], v[126:127], v[152:153]
	v_pk_add_f32 v[124:125], v[124:125], v[156:157]
	v_pk_add_f32 v[152:153], v[122:123], v[154:155]
	v_pk_add_f32 v[122:123], v[120:121], v[158:159]
	v_cvt_pk_bf16_f32 v120, v124, v125
	v_cvt_pk_bf16_f32 v121, v126, v127
	v_cvt_pk_bf16_f32 v122, v122, v123
	v_cvt_pk_bf16_f32 v123, v152, v153
	global_store_dwordx4 v[144:145], v[120:123], off
	s_waitcnt vmcnt(15)
; DI unsigned pack2(float a, float b) { f32x2 v = {a, b}; hwbf16x2 r = __builtin_convertvector(v, hwbf16x2); return __builtin_bit_cast(unsigned, r); }
; DI float bflo(unsigned w) { return __uint_as_float(w << 16); }
; DI float bfhi(unsigned w) { return __uint_as_float(w & 0xffff0000u); }
;     DI void operator()(const f32x4 (&acc)[2][2][4][2], const Unit& u, int wr, int wc, int fr, int fq) const {
;     ...
;             for (int m = 0; m < 4; ++m) { const size_t ro = (size_t)(row0 + ai * HALF + m * 16) * D + col0;
; #pragma unroll
;                 for (int bj = 0; bj < 2; ++bj) {
;                     f32x4 x0, x1;
;                     if constexpr (IB) { const u32x4 w = *(const u32x4*)((const bf16_t*)Xin + ro + bj * HALF);
;                         x0 = (f32x4){bflo(w[0]), bfhi(w[0]), bflo(w[1]), bfhi(w[1])}; x1 = (f32x4){bflo(w[2]), bfhi(w[2]), bflo(w[3]), bfhi(w[3])}; }
;                     else { x0 = *(const f32x4*)((const float*)Xin + ro + bj * HALF); x1 = *(const f32x4*)((const float*)Xin + ro + bj * HALF + 4); }
;                     x0 += acc[ai][bj][m][0] * sc[bj][0]; x1 += acc[ai][bj][m][1] * sc[bj][1];
;                     if constexpr (OB) { u32x4 o; o[0] = pack2(x0[0], x0[1]); o[1] = pack2(x0[2], x0[3]); o[2] = pack2(x1[0], x1[1]); o[3] = pack2(x1[2], x1[3]);
;                         *(u32x4*)((bf16_t*)Xout + ro + bj * HALF) = o; }
;                     else { *(f32x4*)((float*)Xout + ro + bj * HALF) = x0; *(f32x4*)((float*)Xout + ro + bj * HALF + 4) = x1; } } }
	s_nop 1
	v_mov_b32_e32 v120, v164
	v_mov_b32_e32 v121, v165
	v_mov_b32_e32 v122, v166
	v_mov_b32_e32 v123, v167
	s_waitcnt lgkmcnt(0)
	v_lshlrev_b32_e32 v124, 16, v120
	v_and_b32_e32 v125, 0xffff0000, v120
	v_lshlrev_b32_e32 v120, 16, v121
	v_and_b32_e32 v121, 0xffff0000, v121
	v_lshlrev_b32_e32 v126, 16, v122
	v_and_b32_e32 v127, 0xffff0000, v122
	v_lshlrev_b32_e32 v122, 16, v123
	v_and_b32_e32 v123, 0xffff0000, v123
	v_pk_add_f32 v[116:117], v[116:117], v[124:125]
	v_pk_add_f32 v[118:119], v[118:119], v[120:121]
	v_pk_add_f32 v[120:121], v[114:115], v[122:123]
	v_pk_add_f32 v[114:115], v[112:113], v[126:127]
	v_cvt_pk_bf16_f32 v112, v116, v117
	v_lshl_add_u64 v[116:117], v[144:145], 0, s[2:3]
	s_mov_b32 s2, 0x10000
	v_cvt_pk_bf16_f32 v113, v118, v119
	v_add_co_u32_e32 v118, vcc, s2, v144
	v_cvt_pk_bf16_f32 v114, v114, v115
	v_cvt_pk_bf16_f32 v115, v120, v121
	v_addc_co_u32_e32 v119, vcc, 0, v145, vcc
	global_store_dwordx4 v[144:145], v[112:115], off offset:256
	s_waitcnt vmcnt(15)
	s_nop 1
	v_mov_b32_e32 v112, v168
	v_mov_b32_e32 v113, v169
	v_mov_b32_e32 v114, v170
	v_mov_b32_e32 v115, v171
	s_mov_b64 s[2:3], 0x20000
	s_waitcnt lgkmcnt(0)
	v_lshlrev_b32_e32 v120, 16, v112
	v_and_b32_e32 v121, 0xffff0000, v112
	v_lshlrev_b32_e32 v112, 16, v113
	v_and_b32_e32 v113, 0xffff0000, v113
	v_lshlrev_b32_e32 v122, 16, v114
	v_and_b32_e32 v123, 0xffff0000, v114
	v_lshlrev_b32_e32 v114, 16, v115
	v_and_b32_e32 v115, 0xffff0000, v115
	v_pk_add_f32 v[110:111], v[110:111], v[112:113]
	v_pk_add_f32 v[108:109], v[108:109], v[120:121]
	v_pk_add_f32 v[112:113], v[106:107], v[114:115]
	v_pk_add_f32 v[106:107], v[104:105], v[122:123]
	v_cvt_pk_bf16_f32 v104, v108, v109
	v_cvt_pk_bf16_f32 v105, v110, v111
	v_cvt_pk_bf16_f32 v106, v106, v107
	v_cvt_pk_bf16_f32 v107, v112, v113
	global_store_dwordx4 v[118:119], v[104:107], off
	s_waitcnt vmcnt(15)
	s_nop 1
	v_mov_b32_e32 v104, v172
	v_mov_b32_e32 v105, v173
	v_mov_b32_e32 v106, v174
	v_mov_b32_e32 v107, v175
	s_waitcnt lgkmcnt(0)
	v_lshlrev_b32_e32 v108, 16, v104
	v_and_b32_e32 v109, 0xffff0000, v104
	v_lshlrev_b32_e32 v104, 16, v105
	v_and_b32_e32 v105, 0xffff0000, v105
	v_lshlrev_b32_e32 v110, 16, v106
	v_and_b32_e32 v111, 0xffff0000, v106
	v_lshlrev_b32_e32 v106, 16, v107
	v_and_b32_e32 v107, 0xffff0000, v107
	v_pk_add_f32 v[100:101], v[100:101], v[108:109]
	v_pk_add_f32 v[102:103], v[102:103], v[104:105]
	v_pk_add_f32 v[104:105], v[98:99], v[106:107]
	v_pk_add_f32 v[98:99], v[96:97], v[110:111]
	v_cvt_pk_bf16_f32 v96, v100, v101
	v_lshl_add_u64 v[100:101], v[144:145], 0, s[2:3]
	s_mov_b32 s2, 0x20000
	v_cvt_pk_bf16_f32 v97, v102, v103
	v_add_co_u32_e32 v102, vcc, s2, v144
	v_cvt_pk_bf16_f32 v98, v98, v99
	v_cvt_pk_bf16_f32 v99, v104, v105
	v_addc_co_u32_e32 v103, vcc, 0, v145, vcc
	global_store_dwordx4 v[116:117], v[96:99], off offset:256
	s_waitcnt vmcnt(15)
	s_nop 1
	v_mov_b32_e32 v96, v176
	v_mov_b32_e32 v97, v177
	v_mov_b32_e32 v98, v178
	v_mov_b32_e32 v99, v179
	s_mov_b64 s[2:3], 0x30000
	s_waitcnt lgkmcnt(0)
	v_lshlrev_b32_e32 v104, 16, v96
	v_and_b32_e32 v105, 0xffff0000, v96
	v_lshlrev_b32_e32 v96, 16, v97
	v_and_b32_e32 v97, 0xffff0000, v97
	v_lshlrev_b32_e32 v106, 16, v98
	v_and_b32_e32 v107, 0xffff0000, v98
	v_lshlrev_b32_e32 v98, 16, v99
	v_and_b32_e32 v99, 0xffff0000, v99
	v_pk_add_f32 v[94:95], v[94:95], v[96:97]
	v_pk_add_f32 v[92:93], v[92:93], v[104:105]
	v_pk_add_f32 v[96:97], v[90:91], v[98:99]
	v_pk_add_f32 v[90:91], v[88:89], v[106:107]
	v_cvt_pk_bf16_f32 v88, v92, v93
	v_cvt_pk_bf16_f32 v89, v94, v95
	v_cvt_pk_bf16_f32 v90, v90, v91
	v_cvt_pk_bf16_f32 v91, v96, v97
	global_store_dwordx4 v[102:103], v[88:91], off
	s_waitcnt vmcnt(15)
	s_nop 1
	v_mov_b32_e32 v88, v180
	v_mov_b32_e32 v89, v181
	v_mov_b32_e32 v90, v182
	v_mov_b32_e32 v91, v183
	s_waitcnt lgkmcnt(0)
	v_lshlrev_b32_e32 v92, 16, v88
	v_and_b32_e32 v93, 0xffff0000, v88
	v_lshlrev_b32_e32 v88, 16, v89
	v_and_b32_e32 v89, 0xffff0000, v89
	v_lshlrev_b32_e32 v94, 16, v90
	v_and_b32_e32 v95, 0xffff0000, v90
	v_lshlrev_b32_e32 v90, 16, v91
	v_and_b32_e32 v91, 0xffff0000, v91
	v_pk_add_f32 v[86:87], v[86:87], v[88:89]
	v_pk_add_f32 v[84:85], v[84:85], v[92:93]
	v_pk_add_f32 v[88:89], v[82:83], v[90:91]
	v_pk_add_f32 v[82:83], v[80:81], v[94:95]
	v_cvt_pk_bf16_f32 v80, v84, v85
	v_cvt_pk_bf16_f32 v81, v86, v87
	v_cvt_pk_bf16_f32 v82, v82, v83
	v_cvt_pk_bf16_f32 v83, v88, v89
	global_store_dwordx4 v[100:101], v[80:83], off offset:256
	s_nop 1
	v_lshl_add_u64 v[80:81], v[144:145], 0, s[2:3]
	s_mov_b32 s2, 0x30000
	v_add_co_u32_e32 v86, vcc, s2, v144
	s_mov_b64 s[2:3], 0x80000
	s_nop 0
	v_addc_co_u32_e32 v87, vcc, 0, v145, vcc
	s_waitcnt vmcnt(15)
	s_nop 1
	v_mov_b32_e32 v82, v184
	v_mov_b32_e32 v83, v185
	v_mov_b32_e32 v84, v186
	v_mov_b32_e32 v85, v187
	s_waitcnt lgkmcnt(0)
	v_lshlrev_b32_e32 v88, 16, v82
	v_and_b32_e32 v89, 0xffff0000, v82
	v_lshlrev_b32_e32 v82, 16, v83
	v_and_b32_e32 v83, 0xffff0000, v83
	v_lshlrev_b32_e32 v90, 16, v84
	v_and_b32_e32 v91, 0xffff0000, v84
	v_lshlrev_b32_e32 v84, 16, v85
	v_and_b32_e32 v85, 0xffff0000, v85
	v_pk_add_f32 v[78:79], v[78:79], v[82:83]
	v_pk_add_f32 v[76:77], v[76:77], v[88:89]
	v_pk_add_f32 v[82:83], v[74:75], v[84:85]
	v_pk_add_f32 v[74:75], v[72:73], v[90:91]
	v_cvt_pk_bf16_f32 v72, v76, v77
	v_cvt_pk_bf16_f32 v73, v78, v79
	v_cvt_pk_bf16_f32 v74, v74, v75
	v_cvt_pk_bf16_f32 v75, v82, v83
	global_store_dwordx4 v[86:87], v[72:75], off
	s_waitcnt vmcnt(15)
	s_nop 1
	v_mov_b32_e32 v72, v188
	v_mov_b32_e32 v73, v189
	v_mov_b32_e32 v74, v190
	v_mov_b32_e32 v75, v191
	s_waitcnt lgkmcnt(0)
; DI unsigned pack2(float a, float b) { f32x2 v = {a, b}; hwbf16x2 r = __builtin_convertvector(v, hwbf16x2); return __builtin_bit_cast(unsigned, r); }
; DI float bflo(unsigned w) { return __uint_as_float(w << 16); }
; DI float bfhi(unsigned w) { return __uint_as_float(w & 0xffff0000u); }
;     DI void operator()(const f32x4 (&acc)[2][2][4][2], const Unit& u, int wr, int wc, int fr, int fq) const {
;     ...
;             for (int m = 0; m < 4; ++m) { const size_t ro = (size_t)(row0 + ai * HALF + m * 16) * D + col0;
; #pragma unroll
;                 for (int bj = 0; bj < 2; ++bj) {
;                     f32x4 x0, x1;
;                     if constexpr (IB) { const u32x4 w = *(const u32x4*)((const bf16_t*)Xin + ro + bj * HALF);
;                         x0 = (f32x4){bflo(w[0]), bfhi(w[0]), bflo(w[1]), bfhi(w[1])}; x1 = (f32x4){bflo(w[2]), bfhi(w[2]), bflo(w[3]), bfhi(w[3])}; }
;                     else { x0 = *(const f32x4*)((const float*)Xin + ro + bj * HALF); x1 = *(const f32x4*)((const float*)Xin + ro + bj * HALF + 4); }
;                     x0 += acc[ai][bj][m][0] * sc[bj][0]; x1 += acc[ai][bj][m][1] * sc[bj][1];
;                     if constexpr (OB) { u32x4 o; o[0] = pack2(x0[0], x0[1]); o[1] = pack2(x0[2], x0[3]); o[2] = pack2(x1[0], x1[1]); o[3] = pack2(x1[2], x1[3]);
;                         *(u32x4*)((bf16_t*)Xout + ro + bj * HALF) = o; }
;                     else { *(f32x4*)((float*)Xout + ro + bj * HALF) = x0; *(f32x4*)((float*)Xout + ro + bj * HALF + 4) = x1; } } }
	v_lshlrev_b32_e32 v76, 16, v72
	v_and_b32_e32 v77, 0xffff0000, v72
	v_lshlrev_b32_e32 v72, 16, v73
	v_and_b32_e32 v73, 0xffff0000, v73
	v_lshlrev_b32_e32 v78, 16, v74
	v_and_b32_e32 v79, 0xffff0000, v74
	v_lshlrev_b32_e32 v74, 16, v75
	v_and_b32_e32 v75, 0xffff0000, v75
	v_pk_add_f32 v[70:71], v[70:71], v[72:73]
	v_pk_add_f32 v[68:69], v[68:69], v[76:77]
	v_pk_add_f32 v[72:73], v[66:67], v[74:75]
	v_pk_add_f32 v[66:67], v[64:65], v[78:79]
	v_cvt_pk_bf16_f32 v64, v68, v69
	v_cvt_pk_bf16_f32 v65, v70, v71
	v_cvt_pk_bf16_f32 v66, v66, v67
	v_cvt_pk_bf16_f32 v67, v72, v73
	global_store_dwordx4 v[80:81], v[64:67], off offset:256
	s_nop 1
	v_lshl_add_u64 v[64:65], v[144:145], 0, s[2:3]
	s_mov_b32 s2, 0x80000
	v_add_co_u32_e32 v70, vcc, s2, v144
	s_mov_b64 s[2:3], 0x90000
	s_nop 0
	v_addc_co_u32_e32 v71, vcc, 0, v145, vcc
	s_waitcnt vmcnt(15)
	s_nop 1
	v_mov_b32_e32 v66, v192
	v_mov_b32_e32 v67, v193
	v_mov_b32_e32 v68, v194
	v_mov_b32_e32 v69, v195
	s_waitcnt lgkmcnt(0)
	v_lshlrev_b32_e32 v72, 16, v66
	v_and_b32_e32 v73, 0xffff0000, v66
	v_lshlrev_b32_e32 v66, 16, v67
	v_and_b32_e32 v67, 0xffff0000, v67
	v_lshlrev_b32_e32 v74, 16, v68
	v_and_b32_e32 v75, 0xffff0000, v68
	v_lshlrev_b32_e32 v68, 16, v69
	v_and_b32_e32 v69, 0xffff0000, v69
	v_pk_add_f32 v[62:63], v[62:63], v[66:67]
	v_pk_add_f32 v[60:61], v[60:61], v[72:73]
	v_pk_add_f32 v[66:67], v[58:59], v[68:69]
	v_pk_add_f32 v[58:59], v[56:57], v[74:75]
	v_cvt_pk_bf16_f32 v56, v60, v61
	v_cvt_pk_bf16_f32 v57, v62, v63
	v_cvt_pk_bf16_f32 v58, v58, v59
	v_cvt_pk_bf16_f32 v59, v66, v67
	global_store_dwordx4 v[70:71], v[56:59], off
	s_waitcnt vmcnt(15)
	s_nop 1
	v_mov_b32_e32 v56, v198
	v_mov_b32_e32 v57, v199
	v_mov_b32_e32 v58, v200
	v_mov_b32_e32 v59, v201
	s_waitcnt lgkmcnt(0)
	v_lshlrev_b32_e32 v60, 16, v56
	v_and_b32_e32 v61, 0xffff0000, v56
	v_lshlrev_b32_e32 v56, 16, v57
	v_and_b32_e32 v57, 0xffff0000, v57
	v_lshlrev_b32_e32 v62, 16, v58
	v_and_b32_e32 v63, 0xffff0000, v58
	v_lshlrev_b32_e32 v58, 16, v59
	v_and_b32_e32 v59, 0xffff0000, v59
	v_pk_add_f32 v[54:55], v[54:55], v[56:57]
	v_pk_add_f32 v[52:53], v[52:53], v[60:61]
	v_pk_add_f32 v[56:57], v[50:51], v[58:59]
	v_pk_add_f32 v[50:51], v[48:49], v[62:63]
	v_cvt_pk_bf16_f32 v48, v52, v53
	v_cvt_pk_bf16_f32 v49, v54, v55
	v_cvt_pk_bf16_f32 v50, v50, v51
	v_cvt_pk_bf16_f32 v51, v56, v57
	global_store_dwordx4 v[64:65], v[48:51], off offset:256
	s_nop 1
	v_lshl_add_u64 v[48:49], v[144:145], 0, s[2:3]
	s_mov_b32 s2, 0x90000
	v_add_co_u32_e32 v54, vcc, s2, v144
	s_mov_b64 s[2:3], 0xa0000
	s_nop 0
	v_addc_co_u32_e32 v55, vcc, 0, v145, vcc
	s_waitcnt vmcnt(15)
	s_nop 1
	v_mov_b32_e32 v50, v202
	v_mov_b32_e32 v51, v203
	v_mov_b32_e32 v52, v204
	v_mov_b32_e32 v53, v205
	s_waitcnt lgkmcnt(0)
	v_lshlrev_b32_e32 v56, 16, v50
	v_and_b32_e32 v57, 0xffff0000, v50
	v_lshlrev_b32_e32 v50, 16, v51
	v_and_b32_e32 v51, 0xffff0000, v51
	v_lshlrev_b32_e32 v58, 16, v52
	v_and_b32_e32 v59, 0xffff0000, v52
	v_lshlrev_b32_e32 v52, 16, v53
	v_and_b32_e32 v53, 0xffff0000, v53
	v_pk_add_f32 v[46:47], v[46:47], v[50:51]
	v_pk_add_f32 v[44:45], v[44:45], v[56:57]
	v_pk_add_f32 v[50:51], v[42:43], v[52:53]
	v_pk_add_f32 v[42:43], v[40:41], v[58:59]
	v_cvt_pk_bf16_f32 v40, v44, v45
	v_cvt_pk_bf16_f32 v41, v46, v47
	v_cvt_pk_bf16_f32 v42, v42, v43
	v_cvt_pk_bf16_f32 v43, v50, v51
	global_store_dwordx4 v[54:55], v[40:43], off
	s_waitcnt vmcnt(15)
	s_nop 1
	v_mov_b32_e32 v40, v206
	v_mov_b32_e32 v41, v207
	v_mov_b32_e32 v42, v208
	v_mov_b32_e32 v43, v209
	s_waitcnt lgkmcnt(0)
; DI unsigned pack2(float a, float b) { f32x2 v = {a, b}; hwbf16x2 r = __builtin_convertvector(v, hwbf16x2); return __builtin_bit_cast(unsigned, r); }
; DI float bflo(unsigned w) { return __uint_as_float(w << 16); }
; DI float bfhi(unsigned w) { return __uint_as_float(w & 0xffff0000u); }
;     DI const char* a(const Unit& u) const { return (const char*)(A + (size_t)u.pm * BM * lda); }
; #define PG8_BAR __builtin_amdgcn_s_barrier()
;     DI void operator()(const f32x4 (&acc)[2][2][4][2], const Unit& u, int wr, int wc, int fr, int fq) const {
;     ...
;             for (int m = 0; m < 4; ++m) { const size_t ro = (size_t)(row0 + ai * HALF + m * 16) * D + col0;
; #pragma unroll
;                 for (int bj = 0; bj < 2; ++bj) {
;                     f32x4 x0, x1;
;                     if constexpr (IB) { const u32x4 w = *(const u32x4*)((const bf16_t*)Xin + ro + bj * HALF);
;                         x0 = (f32x4){bflo(w[0]), bfhi(w[0]), bflo(w[1]), bfhi(w[1])}; x1 = (f32x4){bflo(w[2]), bfhi(w[2]), bflo(w[3]), bfhi(w[3])}; }
;                     else { x0 = *(const f32x4*)((const float*)Xin + ro + bj * HALF); x1 = *(const f32x4*)((const float*)Xin + ro + bj * HALF + 4); }
;                     x0 += acc[ai][bj][m][0] * sc[bj][0]; x1 += acc[ai][bj][m][1] * sc[bj][1];
;                     if constexpr (OB) { u32x4 o; o[0] = pack2(x0[0], x0[1]); o[1] = pack2(x0[2], x0[3]); o[2] = pack2(x1[0], x1[1]); o[3] = pack2(x1[2], x1[3]);
;                         *(u32x4*)((bf16_t*)Xout + ro + bj * HALF) = o; }
;                     else { *(f32x4*)((float*)Xout + ro + bj * HALF) = x0; *(f32x4*)((float*)Xout + ro + bj * HALF + 4) = x1; } } }
; template <class Map, class Epi>
; DI void gemm_phase(LAS unsigned char* lds, const Map& MP, const Epi& E, const int nM, const int nN, const int K, const int lda, const int ldb) {
;     ...
;         { int frr = fr, fqq = fq; asm volatile("" : "+v"(frr), "+v"(fqq)); E(acc, cur, wr, wc, frr, fqq); }
;         if (!has_next) break;
; #pragma unroll
;         for (int a = 0; a < 2; ++a)
; #pragma unroll
;             for (int b = 0; b < 2; ++b)
; #pragma unroll
;                 for (int m = 0; m < 4; ++m)
; #pragma unroll
;                     for (int n = 0; n < 2; ++n) acc[a][b][m][n] = (f32x4){0.f, 0.f, 0.f, 0.f};
;         cur = nxt; cA = nA; cB = nB; ++ui;
;     }
;     PG8_WAIT_V(0);
;     if (wr == 0) PG8_BAR;
;     PG8_BAR;
	v_lshlrev_b32_e32 v44, 16, v40
	v_and_b32_e32 v45, 0xffff0000, v40
	v_lshlrev_b32_e32 v40, 16, v41
	v_and_b32_e32 v41, 0xffff0000, v41
	v_lshlrev_b32_e32 v46, 16, v42
	v_and_b32_e32 v47, 0xffff0000, v42
	v_lshlrev_b32_e32 v42, 16, v43
	v_and_b32_e32 v43, 0xffff0000, v43
	v_pk_add_f32 v[38:39], v[38:39], v[40:41]
	v_pk_add_f32 v[36:37], v[36:37], v[44:45]
	v_pk_add_f32 v[40:41], v[34:35], v[42:43]
	v_pk_add_f32 v[34:35], v[32:33], v[46:47]
	v_cvt_pk_bf16_f32 v32, v36, v37
	v_cvt_pk_bf16_f32 v33, v38, v39
	v_cvt_pk_bf16_f32 v34, v34, v35
	v_cvt_pk_bf16_f32 v35, v40, v41
	global_store_dwordx4 v[48:49], v[32:35], off offset:256
	s_nop 1
	v_lshl_add_u64 v[32:33], v[144:145], 0, s[2:3]
	s_mov_b32 s2, 0xa0000
	v_add_co_u32_e32 v38, vcc, s2, v144
	s_mov_b64 s[2:3], 0xb0000
	s_nop 0
	v_addc_co_u32_e32 v39, vcc, 0, v145, vcc
	s_waitcnt vmcnt(15)
	s_nop 1
	v_mov_b32_e32 v34, v210
	v_mov_b32_e32 v35, v211
	v_mov_b32_e32 v36, v212
	v_mov_b32_e32 v37, v213
	s_waitcnt lgkmcnt(0)
	v_lshlrev_b32_e32 v40, 16, v34
	v_and_b32_e32 v41, 0xffff0000, v34
	v_lshlrev_b32_e32 v34, 16, v35
	v_and_b32_e32 v35, 0xffff0000, v35
	v_lshlrev_b32_e32 v42, 16, v36
	v_and_b32_e32 v43, 0xffff0000, v36
	v_lshlrev_b32_e32 v36, 16, v37
	v_and_b32_e32 v37, 0xffff0000, v37
	v_pk_add_f32 v[30:31], v[30:31], v[34:35]
	v_pk_add_f32 v[28:29], v[28:29], v[40:41]
	v_pk_add_f32 v[34:35], v[26:27], v[36:37]
	v_pk_add_f32 v[26:27], v[24:25], v[42:43]
	v_cvt_pk_bf16_f32 v24, v28, v29
	v_cvt_pk_bf16_f32 v25, v30, v31
	v_cvt_pk_bf16_f32 v26, v26, v27
	v_cvt_pk_bf16_f32 v27, v34, v35
	global_store_dwordx4 v[38:39], v[24:27], off
	s_waitcnt vmcnt(15)
	s_nop 1
	v_mov_b32_e32 v24, v214
	v_mov_b32_e32 v25, v215
	v_mov_b32_e32 v26, v216
	v_mov_b32_e32 v27, v217
	s_waitcnt lgkmcnt(0)
	v_lshlrev_b32_e32 v28, 16, v24
	v_and_b32_e32 v29, 0xffff0000, v24
	v_lshlrev_b32_e32 v24, 16, v25
	v_and_b32_e32 v25, 0xffff0000, v25
	v_lshlrev_b32_e32 v30, 16, v26
	v_and_b32_e32 v31, 0xffff0000, v26
	v_lshlrev_b32_e32 v26, 16, v27
	v_and_b32_e32 v27, 0xffff0000, v27
	v_pk_add_f32 v[22:23], v[22:23], v[24:25]
	v_pk_add_f32 v[20:21], v[20:21], v[28:29]
	v_pk_add_f32 v[24:25], v[18:19], v[26:27]
	v_pk_add_f32 v[18:19], v[16:17], v[30:31]
	v_cvt_pk_bf16_f32 v16, v20, v21
	v_cvt_pk_bf16_f32 v17, v22, v23
	v_cvt_pk_bf16_f32 v18, v18, v19
	v_cvt_pk_bf16_f32 v19, v24, v25
	global_store_dwordx4 v[32:33], v[16:19], off offset:256
	s_nop 1
	v_lshl_add_u64 v[16:17], v[144:145], 0, s[2:3]
	s_mov_b32 s2, 0xb0000
	v_add_co_u32_e32 v22, vcc, s2, v144
	s_mov_b32 s2, s53
	s_nop 0
	v_addc_co_u32_e32 v23, vcc, 0, v145, vcc
	s_waitcnt vmcnt(15)
	s_nop 1
	v_mov_b32_e32 v18, v248
	v_mov_b32_e32 v19, v249
	v_mov_b32_e32 v20, v250
	v_mov_b32_e32 v21, v251
	s_and_b64 vcc, exec, s[40:41]
	s_waitcnt lgkmcnt(0)
	v_lshlrev_b32_e32 v24, 16, v18
	v_and_b32_e32 v25, 0xffff0000, v18
	v_lshlrev_b32_e32 v18, 16, v19
	v_and_b32_e32 v19, 0xffff0000, v19
	v_lshlrev_b32_e32 v26, 16, v20
	v_and_b32_e32 v27, 0xffff0000, v20
	v_lshlrev_b32_e32 v20, 16, v21
	v_and_b32_e32 v21, 0xffff0000, v21
	v_pk_add_f32 v[14:15], v[14:15], v[18:19]
	v_pk_add_f32 v[12:13], v[12:13], v[24:25]
	v_pk_add_f32 v[18:19], v[10:11], v[20:21]
	v_pk_add_f32 v[10:11], v[8:9], v[26:27]
	v_cvt_pk_bf16_f32 v8, v12, v13
	v_cvt_pk_bf16_f32 v9, v14, v15
	v_cvt_pk_bf16_f32 v10, v10, v11
	v_cvt_pk_bf16_f32 v11, v18, v19
	global_store_dwordx4 v[22:23], v[8:11], off
	s_waitcnt vmcnt(15)
	s_nop 1
	v_mov_b32_e32 v8, v252
	v_mov_b32_e32 v9, v253
	v_mov_b32_e32 v10, v254
	v_mov_b32_e32 v11, v255
	s_waitcnt lgkmcnt(0)
	v_lshlrev_b32_e32 v12, 16, v8
	v_and_b32_e32 v13, 0xffff0000, v8
	v_lshlrev_b32_e32 v8, 16, v9
	v_and_b32_e32 v9, 0xffff0000, v9
	v_lshlrev_b32_e32 v14, 16, v10
	v_and_b32_e32 v15, 0xffff0000, v10
	v_lshlrev_b32_e32 v10, 16, v11
	v_and_b32_e32 v11, 0xffff0000, v11
	v_pk_add_f32 v[6:7], v[6:7], v[8:9]
	v_pk_add_f32 v[4:5], v[4:5], v[12:13]
	v_pk_add_f32 v[8:9], v[2:3], v[10:11]
	v_pk_add_f32 v[2:3], v[0:1], v[14:15]
	v_cvt_pk_bf16_f32 v0, v4, v5
	v_cvt_pk_bf16_f32 v1, v6, v7
	v_cvt_pk_bf16_f32 v2, v2, v3
	v_cvt_pk_bf16_f32 v3, v8, v9
	global_store_dwordx4 v[16:17], v[0:3], off offset:256
	s_cbranch_vccz .LBB1_2071
	s_waitcnt vmcnt(0)
	s_cmpk_gt_u32 s17, 0xff
	s_cbranch_scc1 .LBB1_2082
	s_barrier

; #define PG8_STAGE(bufoff, gbase, voff) do { _Pragma("unroll") for (int _i = 0; _i < 2; ++_i) \
;         __builtin_amdgcn_global_load_lds((const unsigned*)((const char*)(gbase) + (voff)[_i]), (LAS unsigned*)(lds + (bufoff) + ldsw + _i * 8192), 16, 0, 0); } while (0)
; #define PG8_LDA(dst, b, h) do { _Pragma("unroll") for (int m = 0; m < 4; ++m) _Pragma("unroll") for (int k = 0; k < 2; ++k) dst[m][k] = *(const LAS bf16x8*)(lds + PG8_SA(b, h) + aoff + m * 2048 + k * 1024); } while (0)
; #define PG8_LDB(dst, b, h) do { _Pragma("unroll") for (int n = 0; n < 2; ++n) _Pragma("unroll") for (int k = 0; k < 2; ++k) dst[n][k] = *(const LAS bf16x8*)(lds + PG8_SB(b, h) + boff + n * 2048 + k * 1024); } while (0)
; #define PG8_MMA(ai, bj, At, Bt) do { __builtin_amdgcn_s_setprio(1); _Pragma("unroll") for (int m = 0; m < 4; ++m) _Pragma("unroll") for (int n = 0; n < 2; ++n) _Pragma("unroll") for (int k = 0; k < 2; ++k) \
;         acc[ai][bj][m][n] = __builtin_amdgcn_mfma_f32_16x16x32_bf16(Bt[n][k], At[m][k], acc[ai][bj][m][n], 0, 0, 0); __builtin_amdgcn_s_setprio(0); } while (0)
; #define PG8_WAIT_V(n) asm volatile("s_waitcnt vmcnt(" #n ")" ::: "memory")
; #define PG8_WAIT_L(n) asm volatile("s_waitcnt lgkmcnt(" #n ")" ::: "memory")
; template <class Map, class Epi>
; DI void gemm_phase(LAS unsigned char* lds, const Map& MP, const Epi& E, const int nM, const int nN, const int K, const int lda, const int ldb) {
;     ...
;         for (int t = 0; t < nt; t += 2) {
;             const bool last = (t == nt - 2);
;             const char* a1 = cA + (size_t)(t + 1) * kstep;
;             const char* a2 = last ? nA : cA + (size_t)(t + 2) * kstep; const char* b2 = last ? nB : cB + (size_t)(t + 2) * kstep;
;             const char* a3 = a2 + kstep; const char* b3 = b2 + kstep;
;             PG8_LDB(B0, 0, 0); PG8_SCHED; PG8_LDA(At, 0, 0); PG8_STAGE(PG8_SA(1, 1), a1 + hstepA, voffA);
;             PG8_WAIT_L(8); PG8_BAR; PG8_WAIT_L(0); PG8_MMA(0, 0, At, B0); PG8_BAR; PG8_SCHED;
;             PG8_LDB(B1, 0, 1); PG8_STAGE(PG8_SB(0, 0), b2, voffB);
;             PG8_BAR; PG8_WAIT_L(0); PG8_MMA(0, 1, At, B1); PG8_BAR;
;             PG8_LDA(At, 0, 1); PG8_STAGE(PG8_SA(0, 0), a2, voffA);
;             PG8_BAR; PG8_WAIT_L(0); PG8_MMA(1, 0, At, B0); PG8_BAR; PG8_SCHED;
;             PG8_STAGE(PG8_SB(0, 1), b2 + hstepB, voffB);
;             PG8_WAIT_V(6); PG8_BAR; PG8_MMA(1, 1, At, B1); PG8_BAR;
.LBB1_2339:
	s_add_u32 s12, s10, 0xfff80080
	s_addc_u32 s13, s11, -1
	s_cmp_eq_u32 s3, 4
	s_cselect_b32 s15, s38, s13
	s_cselect_b32 s14, s39, s12
	s_cselect_b32 s13, s48, s56
	s_cselect_b32 s12, s49, s53
	s_add_i32 m0, s9, 0xc000
	ds_read_b128 v[168:171], v166
	ds_read_b128 v[172:175], v166 offset:1024
	ds_read_b128 v[176:179], v166 offset:2048
	ds_read_b128 v[180:183], v166 offset:3072
	ds_read_b128 v[184:187], v166 offset:4096
	ds_read_b128 v[188:191], v166 offset:5120
	ds_read_b128 v[192:195], v166 offset:6144
	ds_read_b128 v[198:201], v166 offset:7168
	global_load_lds_dwordx4 v154, s[10:11]
	s_add_i32 m0, s9, 0xe000
	s_nop 0
	global_load_lds_dwordx4 v152, s[10:11]
	s_waitcnt lgkmcnt(8)
	s_setprio 1
	s_barrier
	s_waitcnt lgkmcnt(7)
	v_mfma_f32_16x16x32_bf16 v[140:143], v[40:43], v[168:171], v[140:143]
	v_mfma_f32_16x16x32_bf16 v[136:139], v[56:59], v[168:171], v[136:139]
	s_waitcnt lgkmcnt(5)
	v_mfma_f32_16x16x32_bf16 v[124:127], v[40:43], v[176:179], v[124:127]
	v_mfma_f32_16x16x32_bf16 v[120:123], v[56:59], v[176:179], v[120:123]
	s_waitcnt lgkmcnt(3)
	v_mfma_f32_16x16x32_bf16 v[108:111], v[40:43], v[184:187], v[108:111]
	v_mfma_f32_16x16x32_bf16 v[104:107], v[56:59], v[184:187], v[104:107]
	s_waitcnt lgkmcnt(1)
	v_mfma_f32_16x16x32_bf16 v[92:95], v[40:43], v[192:195], v[92:95]
	v_mfma_f32_16x16x32_bf16 v[88:91], v[56:59], v[192:195], v[88:91]
	v_mfma_f32_16x16x32_bf16 v[140:143], v[44:47], v[172:175], v[140:143]
	s_add_i32 s57, s35, s22
	v_mfma_f32_16x16x32_bf16 v[136:139], v[60:63], v[172:175], v[136:139]
	v_lshl_add_u64 v[160:161], s[12:13], 0, v[148:149]
	v_mfma_f32_16x16x32_bf16 v[124:127], v[44:47], v[180:183], v[124:127]
	v_lshl_add_u64 v[218:219], s[12:13], 0, v[144:145]
	v_mfma_f32_16x16x32_bf16 v[120:123], v[60:63], v[180:183], v[120:123]
	v_mfma_f32_16x16x32_bf16 v[108:111], v[44:47], v[188:191], v[108:111]
	v_mfma_f32_16x16x32_bf16 v[104:107], v[60:63], v[188:191], v[104:107]
	s_waitcnt lgkmcnt(0)
	v_mfma_f32_16x16x32_bf16 v[92:95], v[44:47], v[198:201], v[92:95]
	s_mov_b32 m0, s57
	v_mfma_f32_16x16x32_bf16 v[88:91], v[60:63], v[198:201], v[88:91]
	s_barrier
	s_setprio 0
	ds_read_b128 v[202:205], v167
	ds_read_b128 v[206:209], v167 offset:1024
	ds_read_b128 v[210:213], v167 offset:2048
	global_load_lds_dwordx4 v[160:161], off
	s_add_i32 m0, s57, 0x2000
	ds_read_b128 v[214:217], v167 offset:3072
	global_load_lds_dwordx4 v[218:219], off
	s_setprio 1
	s_barrier
	s_waitcnt lgkmcnt(3)
	v_mfma_f32_16x16x32_bf16 v[132:135], v[202:205], v[168:171], v[132:135]
	s_waitcnt lgkmcnt(1)
	v_mfma_f32_16x16x32_bf16 v[128:131], v[210:213], v[168:171], v[128:131]
	v_mfma_f32_16x16x32_bf16 v[116:119], v[202:205], v[176:179], v[116:119]
	v_mfma_f32_16x16x32_bf16 v[112:115], v[210:213], v[176:179], v[112:115]
	v_mfma_f32_16x16x32_bf16 v[100:103], v[202:205], v[184:187], v[100:103]
	v_mfma_f32_16x16x32_bf16 v[96:99], v[210:213], v[184:187], v[96:99]
	v_mfma_f32_16x16x32_bf16 v[84:87], v[202:205], v[192:195], v[84:87]
	v_mfma_f32_16x16x32_bf16 v[80:83], v[210:213], v[192:195], v[80:83]
	v_mfma_f32_16x16x32_bf16 v[132:135], v[206:209], v[172:175], v[132:135]
	v_lshl_add_u64 v[222:223], s[14:15], 0, v[146:147]
	s_mov_b32 m0, s9
	s_waitcnt lgkmcnt(0)
	v_mfma_f32_16x16x32_bf16 v[128:131], v[214:217], v[172:175], v[128:131]
	v_lshl_add_u64 v[220:221], s[14:15], 0, v[150:151]
	v_mfma_f32_16x16x32_bf16 v[116:119], v[206:209], v[180:183], v[116:119]
	v_mfma_f32_16x16x32_bf16 v[112:115], v[214:217], v[180:183], v[112:115]
	v_mfma_f32_16x16x32_bf16 v[100:103], v[206:209], v[188:191], v[100:103]
	v_mfma_f32_16x16x32_bf16 v[96:99], v[214:217], v[188:191], v[96:99]
	v_mfma_f32_16x16x32_bf16 v[84:87], v[206:209], v[198:201], v[84:87]
	v_mfma_f32_16x16x32_bf16 v[80:83], v[214:217], v[198:201], v[80:83]
	s_barrier
	s_setprio 0
	ds_read_b128 v[168:171], v166 offset:16384
	ds_read_b128 v[172:175], v166 offset:17408
	ds_read_b128 v[176:179], v166 offset:18432
	ds_read_b128 v[180:183], v166 offset:19456
	ds_read_b128 v[184:187], v166 offset:20480
	ds_read_b128 v[188:191], v166 offset:21504
	ds_read_b128 v[192:195], v166 offset:22528
	global_load_lds_dwordx4 v[220:221], off
	s_mov_b32 m0, s24
	ds_read_b128 v[198:201], v166 offset:23552
	global_load_lds_dwordx4 v[222:223], off
	s_waitcnt vmcnt(10)
	s_setprio 1
	s_barrier
	s_waitcnt lgkmcnt(7)
	v_mfma_f32_16x16x32_bf16 v[76:79], v[40:43], v[168:171], v[76:79]
	v_mfma_f32_16x16x32_bf16 v[72:75], v[56:59], v[168:171], v[72:75]
	s_waitcnt lgkmcnt(5)
	v_mfma_f32_16x16x32_bf16 v[52:55], v[40:43], v[176:179], v[52:55]
	v_mfma_f32_16x16x32_bf16 v[48:51], v[56:59], v[176:179], v[48:51]
	s_waitcnt lgkmcnt(3)
	v_mfma_f32_16x16x32_bf16 v[28:31], v[40:43], v[184:187], v[28:31]
	v_mfma_f32_16x16x32_bf16 v[24:27], v[56:59], v[184:187], v[24:27]
	s_waitcnt lgkmcnt(1)
	v_mfma_f32_16x16x32_bf16 v[12:15], v[40:43], v[192:195], v[12:15]
	v_mfma_f32_16x16x32_bf16 v[8:11], v[56:59], v[192:195], v[8:11]
	v_mfma_f32_16x16x32_bf16 v[76:79], v[44:47], v[172:175], v[76:79]
	s_add_u32 s58, s12, 0x20000
	s_addc_u32 s59, s13, 0
	v_mfma_f32_16x16x32_bf16 v[72:75], v[60:63], v[172:175], v[72:75]
	s_add_i32 s57, s36, s22
	v_mfma_f32_16x16x32_bf16 v[52:55], v[44:47], v[180:183], v[52:55]
	v_mfma_f32_16x16x32_bf16 v[48:51], v[60:63], v[180:183], v[48:51]
	v_mfma_f32_16x16x32_bf16 v[28:31], v[44:47], v[188:191], v[28:31]
	v_mfma_f32_16x16x32_bf16 v[24:27], v[60:63], v[188:191], v[24:27]
	s_waitcnt lgkmcnt(0)
	v_mfma_f32_16x16x32_bf16 v[12:15], v[44:47], v[198:201], v[12:15]
	s_mov_b32 m0, s57
	v_mfma_f32_16x16x32_bf16 v[8:11], v[60:63], v[198:201], v[8:11]
	s_barrier
; #define PG8_STAGE(bufoff, gbase, voff) do { _Pragma("unroll") for (int _i = 0; _i < 2; ++_i) \
;         __builtin_amdgcn_global_load_lds((const unsigned*)((const char*)(gbase) + (voff)[_i]), (LAS unsigned*)(lds + (bufoff) + ldsw + _i * 8192), 16, 0, 0); } while (0)
; #define PG8_LDA(dst, b, h) do { _Pragma("unroll") for (int m = 0; m < 4; ++m) _Pragma("unroll") for (int k = 0; k < 2; ++k) dst[m][k] = *(const LAS bf16x8*)(lds + PG8_SA(b, h) + aoff + m * 2048 + k * 1024); } while (0)
; #define PG8_LDB(dst, b, h) do { _Pragma("unroll") for (int n = 0; n < 2; ++n) _Pragma("unroll") for (int k = 0; k < 2; ++k) dst[n][k] = *(const LAS bf16x8*)(lds + PG8_SB(b, h) + boff + n * 2048 + k * 1024); } while (0)
; #define PG8_MMA(ai, bj, At, Bt) do { __builtin_amdgcn_s_setprio(1); _Pragma("unroll") for (int m = 0; m < 4; ++m) _Pragma("unroll") for (int n = 0; n < 2; ++n) _Pragma("unroll") for (int k = 0; k < 2; ++k) \
;         acc[ai][bj][m][n] = __builtin_amdgcn_mfma_f32_16x16x32_bf16(Bt[n][k], At[m][k], acc[ai][bj][m][n], 0, 0, 0); __builtin_amdgcn_s_setprio(0); } while (0)
; #define PG8_WAIT_V(n) asm volatile("s_waitcnt vmcnt(" #n ")" ::: "memory")
; #define PG8_WAIT_L(n) asm volatile("s_waitcnt lgkmcnt(" #n ")" ::: "memory")
; #define PG8_BAR __builtin_amdgcn_s_barrier()
; #define PG8_SCHED __builtin_amdgcn_sched_barrier(0)
; template <class Map, class Epi>
; DI void gemm_phase(LAS unsigned char* lds, const Map& MP, const Epi& E, const int nM, const int nN, const int K, const int lda, const int ldb) {
;     ...
;             PG8_LDB(B0, 1, 0); PG8_SCHED; PG8_LDA(At, 1, 0); PG8_STAGE(PG8_SA(0, 1), a2 + hstepA, voffA);
;             PG8_WAIT_L(8); PG8_BAR; PG8_WAIT_L(0); PG8_MMA(0, 0, At, B0); PG8_BAR; PG8_SCHED;
;             PG8_LDB(B1, 1, 1); PG8_STAGE(PG8_SB(1, 0), b3, voffB);
;             PG8_BAR; PG8_WAIT_L(0); PG8_MMA(0, 1, At, B1); PG8_BAR;
;             PG8_LDA(At, 1, 1); PG8_STAGE(PG8_SA(1, 0), a3, voffA);
;             PG8_BAR; PG8_WAIT_L(0); PG8_MMA(1, 0, At, B0); PG8_BAR; PG8_SCHED;
;             PG8_STAGE(PG8_SB(1, 1), b3 + hstepB, voffB);
;             PG8_WAIT_V(6); PG8_BAR; PG8_MMA(1, 1, At, B1); PG8_BAR;
	s_setprio 0
	global_load_lds_dwordx4 v148, s[58:59]
	s_add_i32 m0, s57, 0x2000
	s_nop 0
	global_load_lds_dwordx4 v144, s[58:59]
	s_waitcnt vmcnt(6)
	s_setprio 1
	s_barrier
	v_mfma_f32_16x16x32_bf16 v[36:39], v[202:205], v[176:179], v[36:39]
	v_mfma_f32_16x16x32_bf16 v[32:35], v[210:213], v[176:179], v[32:35]
	v_mfma_f32_16x16x32_bf16 v[20:23], v[202:205], v[184:187], v[20:23]
	v_mfma_f32_16x16x32_bf16 v[16:19], v[210:213], v[184:187], v[16:19]
	v_mfma_f32_16x16x32_bf16 v[4:7], v[202:205], v[192:195], v[4:7]
	v_mfma_f32_16x16x32_bf16 v[0:3], v[210:213], v[192:195], v[0:3]
	v_mfma_f32_16x16x32_bf16 v[40:43], v[202:205], v[168:171], v[68:71]
	s_add_i32 s57, 0, 0x18000
	v_add_u32_e32 v68, s57, v164
	ds_read_b128 v[56:59], v68
	ds_read_b128 v[60:63], v68 offset:1024
	v_mfma_f32_16x16x32_bf16 v[44:47], v[210:213], v[168:171], v[64:67]
	ds_read_b128 v[64:67], v68 offset:2048
	ds_read_b128 v[68:71], v68 offset:3072
	v_mfma_f32_16x16x32_bf16 v[36:39], v[206:209], v[180:183], v[36:39]
	s_add_u32 s14, s14, 0x80000
	s_addc_u32 s15, s15, 0
	v_mfma_f32_16x16x32_bf16 v[32:35], v[214:217], v[180:183], v[32:35]
	v_mfma_f32_16x16x32_bf16 v[20:23], v[206:209], v[188:191], v[20:23]
	v_mfma_f32_16x16x32_bf16 v[16:19], v[214:217], v[188:191], v[16:19]
	v_mfma_f32_16x16x32_bf16 v[4:7], v[206:209], v[198:201], v[4:7]
	v_mfma_f32_16x16x32_bf16 v[0:3], v[214:217], v[198:201], v[0:3]
	v_mfma_f32_16x16x32_bf16 v[40:43], v[206:209], v[172:175], v[40:43]
	s_mov_b32 m0, s25
	v_mfma_f32_16x16x32_bf16 v[44:47], v[214:217], v[172:175], v[44:47]
	s_barrier
	s_setprio 0
	ds_read_b128 v[168:171], v166 offset:32768
	ds_read_b128 v[172:175], v166 offset:33792
	ds_read_b128 v[176:179], v166 offset:34816
	ds_read_b128 v[180:183], v166 offset:35840
	ds_read_b128 v[184:187], v166 offset:36864
	ds_read_b128 v[188:191], v166 offset:37888
	ds_read_b128 v[192:195], v166 offset:38912
	global_load_lds_dwordx4 v150, s[14:15]
	s_mov_b32 m0, s26
	ds_read_b128 v[198:201], v166 offset:39936
	global_load_lds_dwordx4 v146, s[14:15]
	s_waitcnt lgkmcnt(8)
	s_setprio 1
	s_barrier
	s_waitcnt lgkmcnt(7)
	v_mfma_f32_16x16x32_bf16 v[140:143], v[56:59], v[168:171], v[140:143]
	v_mfma_f32_16x16x32_bf16 v[136:139], v[64:67], v[168:171], v[136:139]
	s_waitcnt lgkmcnt(5)
	v_mfma_f32_16x16x32_bf16 v[124:127], v[56:59], v[176:179], v[124:127]
	v_mfma_f32_16x16x32_bf16 v[120:123], v[64:67], v[176:179], v[120:123]
	s_waitcnt lgkmcnt(3)
	v_mfma_f32_16x16x32_bf16 v[108:111], v[56:59], v[184:187], v[108:111]
	v_mfma_f32_16x16x32_bf16 v[104:107], v[64:67], v[184:187], v[104:107]
	s_waitcnt lgkmcnt(1)
	v_mfma_f32_16x16x32_bf16 v[92:95], v[56:59], v[192:195], v[92:95]
	v_mfma_f32_16x16x32_bf16 v[88:91], v[64:67], v[192:195], v[88:91]
	v_mfma_f32_16x16x32_bf16 v[140:143], v[60:63], v[172:175], v[140:143]
	s_add_i32 s14, 0, 0x1c000
	v_mfma_f32_16x16x32_bf16 v[136:139], v[68:71], v[172:175], v[136:139]
	s_add_i32 s15, s57, s22
	v_mfma_f32_16x16x32_bf16 v[124:127], v[60:63], v[180:183], v[124:127]
	v_add_u32_e32 v196, s14, v164
	v_mfma_f32_16x16x32_bf16 v[120:123], v[68:71], v[180:183], v[120:123]
	v_lshl_add_u64 v[160:161], v[160:161], 0, s[46:47]
	v_mfma_f32_16x16x32_bf16 v[108:111], v[60:63], v[188:191], v[108:111]
	v_mfma_f32_16x16x32_bf16 v[104:107], v[68:71], v[188:191], v[104:107]
	s_waitcnt lgkmcnt(0)
	v_mfma_f32_16x16x32_bf16 v[92:95], v[60:63], v[198:201], v[92:95]
	s_mov_b32 m0, s15
	v_mfma_f32_16x16x32_bf16 v[88:91], v[68:71], v[198:201], v[88:91]
	s_barrier
	s_setprio 0
	ds_read_b128 v[202:205], v196
	ds_read_b128 v[206:209], v196 offset:1024
	ds_read_b128 v[210:213], v196 offset:2048
	global_load_lds_dwordx4 v[160:161], off
	v_lshl_add_u64 v[160:161], v[218:219], 0, s[46:47]
	s_add_i32 m0, s15, 0x2000
	ds_read_b128 v[214:217], v196 offset:3072
	global_load_lds_dwordx4 v[160:161], off
	s_setprio 1
	s_barrier
	s_waitcnt lgkmcnt(3)
	v_mfma_f32_16x16x32_bf16 v[132:135], v[202:205], v[168:171], v[132:135]
	s_waitcnt lgkmcnt(1)
	v_mfma_f32_16x16x32_bf16 v[128:131], v[210:213], v[168:171], v[128:131]
	v_mfma_f32_16x16x32_bf16 v[116:119], v[202:205], v[176:179], v[116:119]
	v_mfma_f32_16x16x32_bf16 v[112:115], v[210:213], v[176:179], v[112:115]
	v_mfma_f32_16x16x32_bf16 v[100:103], v[202:205], v[184:187], v[100:103]
	v_mfma_f32_16x16x32_bf16 v[96:99], v[210:213], v[184:187], v[96:99]
	v_mfma_f32_16x16x32_bf16 v[84:87], v[202:205], v[192:195], v[84:87]
	v_mfma_f32_16x16x32_bf16 v[80:83], v[210:213], v[192:195], v[80:83]
	v_mfma_f32_16x16x32_bf16 v[132:135], v[206:209], v[172:175], v[132:135]
	s_mov_b32 m0, s30
	s_waitcnt lgkmcnt(0)
	v_mfma_f32_16x16x32_bf16 v[128:131], v[214:217], v[172:175], v[128:131]
	v_lshl_add_u64 v[160:161], v[220:221], 0, s[46:47]
	v_mfma_f32_16x16x32_bf16 v[116:119], v[206:209], v[180:183], v[116:119]
	v_mfma_f32_16x16x32_bf16 v[112:115], v[214:217], v[180:183], v[112:115]
	v_mfma_f32_16x16x32_bf16 v[100:103], v[206:209], v[188:191], v[100:103]
	v_mfma_f32_16x16x32_bf16 v[96:99], v[214:217], v[188:191], v[96:99]
	v_mfma_f32_16x16x32_bf16 v[84:87], v[206:209], v[198:201], v[84:87]
	v_mfma_f32_16x16x32_bf16 v[80:83], v[214:217], v[198:201], v[80:83]
	s_barrier
	s_setprio 0
	ds_read_b128 v[168:171], v166 offset:49152
	ds_read_b128 v[172:175], v166 offset:50176
	ds_read_b128 v[176:179], v166 offset:51200
	ds_read_b128 v[180:183], v166 offset:52224
	ds_read_b128 v[184:187], v166 offset:53248
	ds_read_b128 v[188:191], v166 offset:54272
	ds_read_b128 v[192:195], v166 offset:55296
	global_load_lds_dwordx4 v[160:161], off
	v_lshl_add_u64 v[160:161], v[222:223], 0, s[46:47]
	s_mov_b32 m0, s31
	ds_read_b128 v[198:201], v166 offset:56320
	global_load_lds_dwordx4 v[160:161], off
	s_waitcnt vmcnt(10)
	s_setprio 1
	s_barrier
; DI unsigned pack2(float a, float b) { f32x2 v = {a, b}; hwbf16x2 r = __builtin_convertvector(v, hwbf16x2); return __builtin_bit_cast(unsigned, r); }
; DI float bflo(unsigned w) { return __uint_as_float(w << 16); }
; DI float bfhi(unsigned w) { return __uint_as_float(w & 0xffff0000u); }
; #define PG8_WAIT_V(n) asm volatile("s_waitcnt vmcnt(" #n ")" ::: "memory")
; #define PG8_BAR __builtin_amdgcn_s_barrier()
;     DI void operator()(const f32x4 (&acc)[2][2][4][2], const Unit& u, int wr, int wc, int fr, int fq) const {
;         const int row0 = u.pm * BM + wr * 64 + fr, col0 = u.pn * BM + wc * 32 + 8 * fq;
;         f32x4 sc[2][2];
; #pragma unroll
;         for (int bj = 0; bj < 2; ++bj)
; #pragma unroll
;             for (int n = 0; n < 2; ++n) sc[bj][n] = scale ? *(const f32x4*)(scale + col0 + bj * HALF + 4 * n) : (f32x4){1.f, 1.f, 1.f, 1.f};
; #pragma unroll
;         for (int ai = 0; ai < 2; ++ai)
; #pragma unroll
;             for (int m = 0; m < 4; ++m) { const size_t ro = (size_t)(row0 + ai * HALF + m * 16) * D + col0;
; #pragma unroll
;                 for (int bj = 0; bj < 2; ++bj) {
;                     f32x4 x0, x1;
;                     if constexpr (IB) { const u32x4 w = *(const u32x4*)((const bf16_t*)Xin + ro + bj * HALF);
;                         x0 = (f32x4){bflo(w[0]), bfhi(w[0]), bflo(w[1]), bfhi(w[1])}; x1 = (f32x4){bflo(w[2]), bfhi(w[2]), bflo(w[3]), bfhi(w[3])}; }
;                     else { x0 = *(const f32x4*)((const float*)Xin + ro + bj * HALF); x1 = *(const f32x4*)((const float*)Xin + ro + bj * HALF + 4); }
;                     x0 += acc[ai][bj][m][0] * sc[bj][0]; x1 += acc[ai][bj][m][1] * sc[bj][1];
;                     if constexpr (OB) { u32x4 o; o[0] = pack2(x0[0], x0[1]); o[1] = pack2(x0[2], x0[3]); o[2] = pack2(x1[0], x1[1]); o[3] = pack2(x1[2], x1[3]);
;                         *(u32x4*)((bf16_t*)Xout + ro + bj * HALF) = o; }
;                     else { *(f32x4*)((float*)Xout + ro + bj * HALF) = x0; *(f32x4*)((float*)Xout + ro + bj * HALF + 4) = x1; } } }
; template <class Map, class Epi>
; DI void gemm_phase(LAS unsigned char* lds, const Map& MP, const Epi& E, const int nM, const int nN, const int K, const int lda, const int ldb) {
;     ...
;             PG8_WAIT_V(6); PG8_BAR; PG8_MMA(1, 1, At, B1); PG8_BAR;
	s_waitcnt lgkmcnt(7)
	v_mfma_f32_16x16x32_bf16 v[76:79], v[56:59], v[168:171], v[76:79]
	v_mfma_f32_16x16x32_bf16 v[72:75], v[64:67], v[168:171], v[72:75]
	s_waitcnt lgkmcnt(5)
	v_mfma_f32_16x16x32_bf16 v[52:55], v[56:59], v[176:179], v[52:55]
	v_mfma_f32_16x16x32_bf16 v[48:51], v[64:67], v[176:179], v[48:51]
	s_waitcnt lgkmcnt(3)
	v_mfma_f32_16x16x32_bf16 v[28:31], v[56:59], v[184:187], v[28:31]
	v_mfma_f32_16x16x32_bf16 v[24:27], v[64:67], v[184:187], v[24:27]
	s_waitcnt lgkmcnt(1)
	v_mfma_f32_16x16x32_bf16 v[12:15], v[56:59], v[192:195], v[12:15]
	v_mfma_f32_16x16x32_bf16 v[8:11], v[64:67], v[192:195], v[8:11]
	v_mfma_f32_16x16x32_bf16 v[76:79], v[60:63], v[172:175], v[76:79]
	s_add_u32 s12, s12, 0x20080
	s_addc_u32 s13, s13, 0
	v_mfma_f32_16x16x32_bf16 v[72:75], v[68:71], v[172:175], v[72:75]
	s_add_i32 s14, s14, s22
	v_mfma_f32_16x16x32_bf16 v[52:55], v[60:63], v[180:183], v[52:55]
	v_mfma_f32_16x16x32_bf16 v[48:51], v[68:71], v[180:183], v[48:51]
	v_mfma_f32_16x16x32_bf16 v[28:31], v[60:63], v[188:191], v[28:31]
	v_mfma_f32_16x16x32_bf16 v[24:27], v[68:71], v[188:191], v[24:27]
	s_waitcnt lgkmcnt(0)
	v_mfma_f32_16x16x32_bf16 v[12:15], v[60:63], v[198:201], v[12:15]
	s_mov_b32 m0, s14
	v_mfma_f32_16x16x32_bf16 v[8:11], v[68:71], v[198:201], v[8:11]
	s_barrier
	s_setprio 0
	global_load_lds_dwordx4 v148, s[12:13]
	s_add_i32 m0, s14, 0x2000
	s_nop 0
	global_load_lds_dwordx4 v144, s[12:13]
	s_waitcnt vmcnt(6)
	s_setprio 1
	s_barrier
	v_mfma_f32_16x16x32_bf16 v[40:43], v[202:205], v[168:171], v[40:43]
	v_mfma_f32_16x16x32_bf16 v[68:71], v[206:209], v[172:175], v[40:43]
	v_mfma_f32_16x16x32_bf16 v[40:43], v[210:213], v[168:171], v[44:47]
	v_mfma_f32_16x16x32_bf16 v[36:39], v[202:205], v[176:179], v[36:39]
	v_mfma_f32_16x16x32_bf16 v[32:35], v[210:213], v[176:179], v[32:35]
	v_mfma_f32_16x16x32_bf16 v[20:23], v[202:205], v[184:187], v[20:23]
	v_mfma_f32_16x16x32_bf16 v[16:19], v[210:213], v[184:187], v[16:19]
	v_mfma_f32_16x16x32_bf16 v[4:7], v[202:205], v[192:195], v[4:7]
	v_mfma_f32_16x16x32_bf16 v[0:3], v[210:213], v[192:195], v[0:3]
	s_add_i32 s3, s3, 2
	v_mfma_f32_16x16x32_bf16 v[64:67], v[214:217], v[172:175], v[40:43]
	s_add_u32 s53, s53, 0x100
	s_addc_u32 s56, s56, 0
	ds_read_b128 v[40:43], v165
	ds_read_b128 v[44:47], v165 offset:1024
	ds_read_b128 v[56:59], v165 offset:2048
	ds_read_b128 v[60:63], v165 offset:3072
	v_mfma_f32_16x16x32_bf16 v[36:39], v[206:209], v[180:183], v[36:39]
	s_add_u32 s10, s10, 0x100
	s_addc_u32 s11, s11, 0
	v_mfma_f32_16x16x32_bf16 v[32:35], v[214:217], v[180:183], v[32:35]
	s_cmp_gt_u32 s3, 5
	v_mfma_f32_16x16x32_bf16 v[20:23], v[206:209], v[188:191], v[20:23]
	v_mfma_f32_16x16x32_bf16 v[16:19], v[214:217], v[188:191], v[16:19]
	v_mfma_f32_16x16x32_bf16 v[4:7], v[206:209], v[198:201], v[4:7]
	v_mfma_f32_16x16x32_bf16 v[0:3], v[214:217], v[198:201], v[0:3]
	s_barrier
	s_setprio 0
	s_cbranch_scc0 .LBB1_2339
	s_waitcnt lgkmcnt(0)
	s_lshl_b32 s2, s2, 8
	v_mov_b32_e32 v40, v163
	v_mov_b32_e32 v168, v162
	s_or_b32 s2, s2, s29
	s_and_b64 vcc, exec, s[40:41]
	v_lshl_add_u32 v160, v40, 3, s2
	s_lshl_b32 s2, s8, 8
	s_add_i32 s2, s2, s28
	v_add_u32_e32 v168, s2, v168
	v_ashrrev_i32_e32 v169, 31, v168
	v_ashrrev_i32_e32 v161, 31, v160
	v_lshlrev_b64 v[168:169], 11, v[168:169]
	v_lshl_add_u64 v[44:45], v[160:161], 2, s[44:45]
	v_lshl_add_u64 v[160:161], v[168:169], 0, v[160:161]
	v_lshlrev_b64 v[160:161], 1, v[160:161]
	v_lshl_add_u64 v[172:173], s[4:5], 0, v[160:161]
	global_load_dwordx4 v[56:59], v[44:45], off offset:16
	global_load_dwordx4 v[60:63], v[44:45], off
	global_load_dwordx4 v[40:43], v[44:45], off offset:528
	s_nop 0
	global_load_dwordx4 v[44:47], v[44:45], off offset:512
	s_mov_b64 s[2:3], 0x10000
	global_load_dwordx4 v[178:181], v[172:173], off
	global_load_dwordx4 v[182:185], v[172:173], off offset:256
	s_mov_b64 s[98:99], 0x10000
	v_lshl_add_u64 v[170:171], v[172:173], 0, s[98:99]
	global_load_dwordx4 v[186:189], v[170:171], off
	global_load_dwordx4 v[190:193], v[170:171], off offset:256
	s_mov_b64 s[98:99], 0x20000
	v_lshl_add_u64 v[170:171], v[172:173], 0, s[98:99]
	global_load_dwordx4 v[198:201], v[170:171], off
	global_load_dwordx4 v[202:205], v[170:171], off offset:256
	s_mov_b64 s[98:99], 0x30000
	v_lshl_add_u64 v[170:171], v[172:173], 0, s[98:99]
	global_load_dwordx4 v[206:209], v[170:171], off
	global_load_dwordx4 v[210:213], v[170:171], off offset:256
	s_mov_b64 s[98:99], 0x80000
	v_lshl_add_u64 v[170:171], v[172:173], 0, s[98:99]
	global_load_dwordx4 v[214:217], v[170:171], off
	global_load_dwordx4 v[248:251], v[170:171], off offset:256
	s_mov_b64 s[98:99], 0x90000
	v_lshl_add_u64 v[170:171], v[172:173], 0, s[98:99]
	global_load_dwordx4 v[252:255], v[170:171], off
	s_waitcnt vmcnt(10)
	s_nop 1
	v_mov_b32_e32 v168, v178
	v_mov_b32_e32 v169, v179
	v_mov_b32_e32 v170, v180
	v_mov_b32_e32 v171, v181
	s_mov_b32 s8, s52
	s_mov_b64 s[10:11], s[54:55]
	s_mov_b64 s[12:13], s[6:7]
	s_waitcnt lgkmcnt(0)
	v_lshlrev_b32_e32 v174, 16, v168
	v_and_b32_e32 v175, 0xffff0000, v168
	v_lshlrev_b32_e32 v168, 16, v169
	v_and_b32_e32 v169, 0xffff0000, v169
	v_lshlrev_b32_e32 v176, 16, v170
	v_and_b32_e32 v177, 0xffff0000, v170
	v_lshlrev_b32_e32 v170, 16, v171
	v_and_b32_e32 v171, 0xffff0000, v171
	v_pk_fma_f32 v[142:143], v[142:143], v[62:63], v[168:169]
	v_pk_fma_f32 v[140:141], v[140:141], v[60:61], v[174:175]
	v_pk_fma_f32 v[168:169], v[138:139], v[58:59], v[170:171]
	v_pk_fma_f32 v[138:139], v[136:137], v[56:57], v[176:177]
	v_cvt_pk_bf16_f32 v136, v140, v141
	v_cvt_pk_bf16_f32 v137, v142, v143
	v_cvt_pk_bf16_f32 v138, v138, v139
	v_cvt_pk_bf16_f32 v139, v168, v169
	v_lshl_add_u64 v[140:141], s[42:43], 0, v[160:161]
	global_store_dwordx4 v[140:141], v[136:139], off
	s_waitcnt vmcnt(10)
; DI unsigned pack2(float a, float b) { f32x2 v = {a, b}; hwbf16x2 r = __builtin_convertvector(v, hwbf16x2); return __builtin_bit_cast(unsigned, r); }
; DI float bflo(unsigned w) { return __uint_as_float(w << 16); }
; DI float bfhi(unsigned w) { return __uint_as_float(w & 0xffff0000u); }
;     DI void operator()(const f32x4 (&acc)[2][2][4][2], const Unit& u, int wr, int wc, int fr, int fq) const {
;     ...
;             for (int m = 0; m < 4; ++m) { const size_t ro = (size_t)(row0 + ai * HALF + m * 16) * D + col0;
; #pragma unroll
;                 for (int bj = 0; bj < 2; ++bj) {
;                     f32x4 x0, x1;
;                     if constexpr (IB) { const u32x4 w = *(const u32x4*)((const bf16_t*)Xin + ro + bj * HALF);
;                         x0 = (f32x4){bflo(w[0]), bfhi(w[0]), bflo(w[1]), bfhi(w[1])}; x1 = (f32x4){bflo(w[2]), bfhi(w[2]), bflo(w[3]), bfhi(w[3])}; }
;                     else { x0 = *(const f32x4*)((const float*)Xin + ro + bj * HALF); x1 = *(const f32x4*)((const float*)Xin + ro + bj * HALF + 4); }
;                     x0 += acc[ai][bj][m][0] * sc[bj][0]; x1 += acc[ai][bj][m][1] * sc[bj][1];
;                     if constexpr (OB) { u32x4 o; o[0] = pack2(x0[0], x0[1]); o[1] = pack2(x0[2], x0[3]); o[2] = pack2(x1[0], x1[1]); o[3] = pack2(x1[2], x1[3]);
;                         *(u32x4*)((bf16_t*)Xout + ro + bj * HALF) = o; }
;                     else { *(f32x4*)((float*)Xout + ro + bj * HALF) = x0; *(f32x4*)((float*)Xout + ro + bj * HALF + 4) = x1; } } }
	s_nop 1
	v_mov_b32_e32 v136, v182
	v_mov_b32_e32 v137, v183
	v_mov_b32_e32 v138, v184
	v_mov_b32_e32 v139, v185
	s_waitcnt lgkmcnt(0)
	v_lshlrev_b32_e32 v142, 16, v136
	v_and_b32_e32 v143, 0xffff0000, v136
	v_lshlrev_b32_e32 v136, 16, v137
	v_and_b32_e32 v137, 0xffff0000, v137
	v_lshlrev_b32_e32 v168, 16, v138
	v_and_b32_e32 v169, 0xffff0000, v138
	v_lshlrev_b32_e32 v138, 16, v139
	v_and_b32_e32 v139, 0xffff0000, v139
	v_pk_fma_f32 v[134:135], v[134:135], v[46:47], v[136:137]
	v_pk_fma_f32 v[132:133], v[132:133], v[44:45], v[142:143]
	v_pk_fma_f32 v[136:137], v[130:131], v[42:43], v[138:139]
	v_pk_fma_f32 v[130:131], v[128:129], v[40:41], v[168:169]
	v_cvt_pk_bf16_f32 v128, v132, v133
	v_cvt_pk_bf16_f32 v129, v134, v135
	v_cvt_pk_bf16_f32 v130, v130, v131
	v_cvt_pk_bf16_f32 v131, v136, v137
	v_lshl_add_u64 v[132:133], v[160:161], 0, s[2:3]
	global_store_dwordx4 v[140:141], v[128:131], off offset:256
	v_lshl_add_u64 v[134:135], s[4:5], 0, v[132:133]
	s_waitcnt vmcnt(10)
	s_nop 1
	v_mov_b32_e32 v128, v186
	v_mov_b32_e32 v129, v187
	v_mov_b32_e32 v130, v188
	v_mov_b32_e32 v131, v189
	s_mov_b64 s[2:3], 0x20000
	s_waitcnt lgkmcnt(0)
	v_lshlrev_b32_e32 v136, 16, v128
	v_and_b32_e32 v137, 0xffff0000, v128
	v_lshlrev_b32_e32 v128, 16, v129
	v_and_b32_e32 v129, 0xffff0000, v129
	v_lshlrev_b32_e32 v138, 16, v130
	v_and_b32_e32 v139, 0xffff0000, v130
	v_lshlrev_b32_e32 v130, 16, v131
	v_and_b32_e32 v131, 0xffff0000, v131
	v_pk_fma_f32 v[126:127], v[126:127], v[62:63], v[128:129]
	v_pk_fma_f32 v[124:125], v[124:125], v[60:61], v[136:137]
	v_pk_fma_f32 v[128:129], v[122:123], v[58:59], v[130:131]
	v_pk_fma_f32 v[122:123], v[120:121], v[56:57], v[138:139]
	v_cvt_pk_bf16_f32 v120, v124, v125
	v_cvt_pk_bf16_f32 v121, v126, v127
	v_cvt_pk_bf16_f32 v122, v122, v123
	v_cvt_pk_bf16_f32 v123, v128, v129
	v_lshl_add_u64 v[124:125], s[42:43], 0, v[132:133]
	global_store_dwordx4 v[124:125], v[120:123], off
	s_waitcnt vmcnt(10)
	s_nop 1
	v_mov_b32_e32 v120, v190
	v_mov_b32_e32 v121, v191
	v_mov_b32_e32 v122, v192
	v_mov_b32_e32 v123, v193
	s_waitcnt lgkmcnt(0)
	v_lshlrev_b32_e32 v126, 16, v120
	v_and_b32_e32 v127, 0xffff0000, v120
	v_lshlrev_b32_e32 v120, 16, v121
	v_and_b32_e32 v121, 0xffff0000, v121
	v_lshlrev_b32_e32 v128, 16, v122
	v_and_b32_e32 v129, 0xffff0000, v122
	v_lshlrev_b32_e32 v122, 16, v123
	v_and_b32_e32 v123, 0xffff0000, v123
	v_pk_fma_f32 v[118:119], v[118:119], v[46:47], v[120:121]
	v_pk_fma_f32 v[116:117], v[116:117], v[44:45], v[126:127]
	v_pk_fma_f32 v[120:121], v[114:115], v[42:43], v[122:123]
	v_pk_fma_f32 v[114:115], v[112:113], v[40:41], v[128:129]
	v_cvt_pk_bf16_f32 v112, v116, v117
	v_cvt_pk_bf16_f32 v113, v118, v119
	v_cvt_pk_bf16_f32 v114, v114, v115
	v_cvt_pk_bf16_f32 v115, v120, v121
	v_lshl_add_u64 v[116:117], v[160:161], 0, s[2:3]
	global_store_dwordx4 v[124:125], v[112:115], off offset:256
	v_lshl_add_u64 v[118:119], s[4:5], 0, v[116:117]
	s_waitcnt vmcnt(10)
	s_nop 1
	v_mov_b32_e32 v112, v198
	v_mov_b32_e32 v113, v199
	v_mov_b32_e32 v114, v200
	v_mov_b32_e32 v115, v201
	s_mov_b64 s[2:3], 0x30000
	s_waitcnt lgkmcnt(0)
	v_lshlrev_b32_e32 v120, 16, v112
	v_and_b32_e32 v121, 0xffff0000, v112
	v_lshlrev_b32_e32 v112, 16, v113
	v_and_b32_e32 v113, 0xffff0000, v113
	v_lshlrev_b32_e32 v122, 16, v114
	v_and_b32_e32 v123, 0xffff0000, v114
	v_lshlrev_b32_e32 v114, 16, v115
	v_and_b32_e32 v115, 0xffff0000, v115
	v_pk_fma_f32 v[110:111], v[110:111], v[62:63], v[112:113]
	v_pk_fma_f32 v[108:109], v[108:109], v[60:61], v[120:121]
	v_pk_fma_f32 v[112:113], v[106:107], v[58:59], v[114:115]
	v_pk_fma_f32 v[106:107], v[104:105], v[56:57], v[122:123]
	v_cvt_pk_bf16_f32 v104, v108, v109
	v_cvt_pk_bf16_f32 v105, v110, v111
	v_cvt_pk_bf16_f32 v106, v106, v107
	v_cvt_pk_bf16_f32 v107, v112, v113
	v_lshl_add_u64 v[108:109], s[42:43], 0, v[116:117]
	global_store_dwordx4 v[108:109], v[104:107], off
	s_waitcnt vmcnt(10)
	s_nop 1
	v_mov_b32_e32 v104, v202
	v_mov_b32_e32 v105, v203
	v_mov_b32_e32 v106, v204
	v_mov_b32_e32 v107, v205
	s_waitcnt lgkmcnt(0)
	v_lshlrev_b32_e32 v110, 16, v104
	v_and_b32_e32 v111, 0xffff0000, v104
	v_lshlrev_b32_e32 v104, 16, v105
	v_and_b32_e32 v105, 0xffff0000, v105
	v_lshlrev_b32_e32 v112, 16, v106
	v_and_b32_e32 v113, 0xffff0000, v106
	v_lshlrev_b32_e32 v106, 16, v107
	v_and_b32_e32 v107, 0xffff0000, v107
	v_pk_fma_f32 v[102:103], v[102:103], v[46:47], v[104:105]
	v_pk_fma_f32 v[100:101], v[100:101], v[44:45], v[110:111]
	v_pk_fma_f32 v[104:105], v[98:99], v[42:43], v[106:107]
	v_pk_fma_f32 v[98:99], v[96:97], v[40:41], v[112:113]
	v_cvt_pk_bf16_f32 v96, v100, v101
	v_cvt_pk_bf16_f32 v97, v102, v103
	v_cvt_pk_bf16_f32 v98, v98, v99
	v_cvt_pk_bf16_f32 v99, v104, v105
	v_lshl_add_u64 v[100:101], v[160:161], 0, s[2:3]
	global_store_dwordx4 v[108:109], v[96:99], off offset:256
	v_lshl_add_u64 v[102:103], s[4:5], 0, v[100:101]
	s_waitcnt vmcnt(10)
	s_nop 1
	v_mov_b32_e32 v96, v206
	v_mov_b32_e32 v97, v207
	v_mov_b32_e32 v98, v208
	v_mov_b32_e32 v99, v209
	s_mov_b64 s[2:3], 0x80000
	s_waitcnt lgkmcnt(0)
	v_lshlrev_b32_e32 v104, 16, v96
	v_and_b32_e32 v105, 0xffff0000, v96
	v_lshlrev_b32_e32 v96, 16, v97
	v_and_b32_e32 v97, 0xffff0000, v97
	v_lshlrev_b32_e32 v106, 16, v98
	v_and_b32_e32 v107, 0xffff0000, v98
	v_lshlrev_b32_e32 v98, 16, v99
	v_and_b32_e32 v99, 0xffff0000, v99
	v_pk_fma_f32 v[94:95], v[94:95], v[62:63], v[96:97]
	v_pk_fma_f32 v[92:93], v[92:93], v[60:61], v[104:105]
	v_pk_fma_f32 v[96:97], v[90:91], v[58:59], v[98:99]
	v_pk_fma_f32 v[90:91], v[88:89], v[56:57], v[106:107]
	v_cvt_pk_bf16_f32 v88, v92, v93
	v_cvt_pk_bf16_f32 v89, v94, v95
	v_cvt_pk_bf16_f32 v90, v90, v91
	v_cvt_pk_bf16_f32 v91, v96, v97
	v_lshl_add_u64 v[92:93], s[42:43], 0, v[100:101]
	global_store_dwordx4 v[92:93], v[88:91], off
	s_waitcnt vmcnt(10)
; DI unsigned pack2(float a, float b) { f32x2 v = {a, b}; hwbf16x2 r = __builtin_convertvector(v, hwbf16x2); return __builtin_bit_cast(unsigned, r); }
; DI float bflo(unsigned w) { return __uint_as_float(w << 16); }
; DI float bfhi(unsigned w) { return __uint_as_float(w & 0xffff0000u); }
;     DI void operator()(const f32x4 (&acc)[2][2][4][2], const Unit& u, int wr, int wc, int fr, int fq) const {
;     ...
;             for (int m = 0; m < 4; ++m) { const size_t ro = (size_t)(row0 + ai * HALF + m * 16) * D + col0;
; #pragma unroll
;                 for (int bj = 0; bj < 2; ++bj) {
;                     f32x4 x0, x1;
;                     if constexpr (IB) { const u32x4 w = *(const u32x4*)((const bf16_t*)Xin + ro + bj * HALF);
;                         x0 = (f32x4){bflo(w[0]), bfhi(w[0]), bflo(w[1]), bfhi(w[1])}; x1 = (f32x4){bflo(w[2]), bfhi(w[2]), bflo(w[3]), bfhi(w[3])}; }
;                     else { x0 = *(const f32x4*)((const float*)Xin + ro + bj * HALF); x1 = *(const f32x4*)((const float*)Xin + ro + bj * HALF + 4); }
;                     x0 += acc[ai][bj][m][0] * sc[bj][0]; x1 += acc[ai][bj][m][1] * sc[bj][1];
;                     if constexpr (OB) { u32x4 o; o[0] = pack2(x0[0], x0[1]); o[1] = pack2(x0[2], x0[3]); o[2] = pack2(x1[0], x1[1]); o[3] = pack2(x1[2], x1[3]);
;                         *(u32x4*)((bf16_t*)Xout + ro + bj * HALF) = o; }
;                     else { *(f32x4*)((float*)Xout + ro + bj * HALF) = x0; *(f32x4*)((float*)Xout + ro + bj * HALF + 4) = x1; } } }
	s_nop 1
	v_mov_b32_e32 v88, v210
	v_mov_b32_e32 v89, v211
	v_mov_b32_e32 v90, v212
	v_mov_b32_e32 v91, v213
	s_waitcnt lgkmcnt(0)
	v_lshlrev_b32_e32 v94, 16, v88
	v_and_b32_e32 v95, 0xffff0000, v88
	v_lshlrev_b32_e32 v88, 16, v89
	v_and_b32_e32 v89, 0xffff0000, v89
	v_lshlrev_b32_e32 v96, 16, v90
	v_and_b32_e32 v97, 0xffff0000, v90
	v_lshlrev_b32_e32 v90, 16, v91
	v_and_b32_e32 v91, 0xffff0000, v91
	v_pk_fma_f32 v[86:87], v[86:87], v[46:47], v[88:89]
	v_pk_fma_f32 v[84:85], v[84:85], v[44:45], v[94:95]
	v_pk_fma_f32 v[88:89], v[82:83], v[42:43], v[90:91]
	v_pk_fma_f32 v[82:83], v[80:81], v[40:41], v[96:97]
	v_cvt_pk_bf16_f32 v80, v84, v85
	v_cvt_pk_bf16_f32 v81, v86, v87
	v_cvt_pk_bf16_f32 v82, v82, v83
	v_cvt_pk_bf16_f32 v83, v88, v89
	v_lshl_add_u64 v[84:85], v[160:161], 0, s[2:3]
	global_store_dwordx4 v[92:93], v[80:83], off offset:256
	v_lshl_add_u64 v[86:87], s[4:5], 0, v[84:85]
	s_waitcnt vmcnt(10)
	s_nop 1
	v_mov_b32_e32 v80, v214
	v_mov_b32_e32 v81, v215
	v_mov_b32_e32 v82, v216
	v_mov_b32_e32 v83, v217
	s_mov_b64 s[2:3], 0x90000
	s_waitcnt lgkmcnt(0)
	v_lshlrev_b32_e32 v88, 16, v80
	v_and_b32_e32 v89, 0xffff0000, v80
	v_lshlrev_b32_e32 v80, 16, v81
	v_and_b32_e32 v81, 0xffff0000, v81
	v_lshlrev_b32_e32 v90, 16, v82
	v_and_b32_e32 v91, 0xffff0000, v82
	v_lshlrev_b32_e32 v82, 16, v83
	v_and_b32_e32 v83, 0xffff0000, v83
	v_pk_fma_f32 v[78:79], v[78:79], v[62:63], v[80:81]
	v_pk_fma_f32 v[76:77], v[76:77], v[60:61], v[88:89]
	v_pk_fma_f32 v[80:81], v[74:75], v[58:59], v[82:83]
	v_pk_fma_f32 v[74:75], v[72:73], v[56:57], v[90:91]
	v_cvt_pk_bf16_f32 v72, v76, v77
	v_cvt_pk_bf16_f32 v73, v78, v79
	v_cvt_pk_bf16_f32 v74, v74, v75
	v_cvt_pk_bf16_f32 v75, v80, v81
	v_lshl_add_u64 v[76:77], s[42:43], 0, v[84:85]
	global_store_dwordx4 v[76:77], v[72:75], off
	s_waitcnt vmcnt(10)
	s_nop 1
	v_mov_b32_e32 v72, v248
	v_mov_b32_e32 v73, v249
	v_mov_b32_e32 v74, v250
	v_mov_b32_e32 v75, v251
	s_waitcnt lgkmcnt(0)
	v_lshlrev_b32_e32 v78, 16, v72
	v_and_b32_e32 v79, 0xffff0000, v72
	v_lshlrev_b32_e32 v72, 16, v73
	v_and_b32_e32 v73, 0xffff0000, v73
	v_lshlrev_b32_e32 v80, 16, v74
	v_and_b32_e32 v81, 0xffff0000, v74
	v_lshlrev_b32_e32 v74, 16, v75
	v_and_b32_e32 v75, 0xffff0000, v75
	v_pk_fma_f32 v[70:71], v[70:71], v[46:47], v[72:73]
	v_pk_fma_f32 v[68:69], v[68:69], v[44:45], v[78:79]
	v_pk_fma_f32 v[72:73], v[66:67], v[42:43], v[74:75]
	v_pk_fma_f32 v[66:67], v[64:65], v[40:41], v[80:81]
	v_cvt_pk_bf16_f32 v64, v68, v69
	v_cvt_pk_bf16_f32 v65, v70, v71
	v_cvt_pk_bf16_f32 v66, v66, v67
	v_cvt_pk_bf16_f32 v67, v72, v73
	v_lshl_add_u64 v[68:69], v[160:161], 0, s[2:3]
	global_store_dwordx4 v[76:77], v[64:67], off offset:256
	v_lshl_add_u64 v[70:71], s[4:5], 0, v[68:69]
	s_waitcnt vmcnt(10)
	s_nop 1
	v_mov_b32_e32 v64, v252
	v_mov_b32_e32 v65, v253
	v_mov_b32_e32 v66, v254
	v_mov_b32_e32 v67, v255
	s_mov_b64 s[2:3], 0xa0000
	s_waitcnt lgkmcnt(0)
	v_lshlrev_b32_e32 v72, 16, v64
	v_and_b32_e32 v73, 0xffff0000, v64
	v_lshlrev_b32_e32 v64, 16, v65
	v_and_b32_e32 v65, 0xffff0000, v65
	v_lshlrev_b32_e32 v74, 16, v66
	v_and_b32_e32 v75, 0xffff0000, v66
	v_lshlrev_b32_e32 v66, 16, v67
	v_and_b32_e32 v67, 0xffff0000, v67
	v_pk_fma_f32 v[54:55], v[54:55], v[62:63], v[64:65]
	v_pk_fma_f32 v[52:53], v[52:53], v[60:61], v[72:73]
	v_pk_fma_f32 v[64:65], v[50:51], v[58:59], v[66:67]
	v_pk_fma_f32 v[50:51], v[48:49], v[56:57], v[74:75]
	v_cvt_pk_bf16_f32 v48, v52, v53
	v_cvt_pk_bf16_f32 v49, v54, v55
	v_cvt_pk_bf16_f32 v50, v50, v51
	v_cvt_pk_bf16_f32 v51, v64, v65
	v_lshl_add_u64 v[52:53], s[42:43], 0, v[68:69]
	global_store_dwordx4 v[52:53], v[48:51], off
	global_load_dwordx4 v[48:51], v[70:71], off offset:256
	s_waitcnt vmcnt(0) lgkmcnt(0)
; DI unsigned pack2(float a, float b) { f32x2 v = {a, b}; hwbf16x2 r = __builtin_convertvector(v, hwbf16x2); return __builtin_bit_cast(unsigned, r); }
; DI float bflo(unsigned w) { return __uint_as_float(w << 16); }
; DI float bfhi(unsigned w) { return __uint_as_float(w & 0xffff0000u); }
;     DI const char* a(const Unit& u) const { return (const char*)(A + (size_t)u.pm * BM * lda); }
; #define PG8_BAR __builtin_amdgcn_s_barrier()
;     DI void operator()(const f32x4 (&acc)[2][2][4][2], const Unit& u, int wr, int wc, int fr, int fq) const {
;     ...
;             for (int m = 0; m < 4; ++m) { const size_t ro = (size_t)(row0 + ai * HALF + m * 16) * D + col0;
; #pragma unroll
;                 for (int bj = 0; bj < 2; ++bj) {
;                     f32x4 x0, x1;
;                     if constexpr (IB) { const u32x4 w = *(const u32x4*)((const bf16_t*)Xin + ro + bj * HALF);
;                         x0 = (f32x4){bflo(w[0]), bfhi(w[0]), bflo(w[1]), bfhi(w[1])}; x1 = (f32x4){bflo(w[2]), bfhi(w[2]), bflo(w[3]), bfhi(w[3])}; }
;                     else { x0 = *(const f32x4*)((const float*)Xin + ro + bj * HALF); x1 = *(const f32x4*)((const float*)Xin + ro + bj * HALF + 4); }
;                     x0 += acc[ai][bj][m][0] * sc[bj][0]; x1 += acc[ai][bj][m][1] * sc[bj][1];
;                     if constexpr (OB) { u32x4 o; o[0] = pack2(x0[0], x0[1]); o[1] = pack2(x0[2], x0[3]); o[2] = pack2(x1[0], x1[1]); o[3] = pack2(x1[2], x1[3]);
;                         *(u32x4*)((bf16_t*)Xout + ro + bj * HALF) = o; }
;                     else { *(f32x4*)((float*)Xout + ro + bj * HALF) = x0; *(f32x4*)((float*)Xout + ro + bj * HALF + 4) = x1; } } }
; template <class Map, class Epi>
; DI void gemm_phase(LAS unsigned char* lds, const Map& MP, const Epi& E, const int nM, const int nN, const int K, const int lda, const int ldb) {
;     ...
;         { int frr = fr, fqq = fq; asm volatile("" : "+v"(frr), "+v"(fqq)); E(acc, cur, wr, wc, frr, fqq); }
;         if (!has_next) break;
; #pragma unroll
;         for (int a = 0; a < 2; ++a)
; #pragma unroll
;             for (int b = 0; b < 2; ++b)
; #pragma unroll
;                 for (int m = 0; m < 4; ++m)
; #pragma unroll
;                     for (int n = 0; n < 2; ++n) acc[a][b][m][n] = (f32x4){0.f, 0.f, 0.f, 0.f};
;         cur = nxt; cA = nA; cB = nB; ++ui;
;     }
;     PG8_WAIT_V(0);
;     if (wr == 0) PG8_BAR;
;     PG8_BAR;
	v_lshlrev_b32_e32 v54, 16, v48
	v_and_b32_e32 v55, 0xffff0000, v48
	v_lshlrev_b32_e32 v48, 16, v49
	v_and_b32_e32 v49, 0xffff0000, v49
	v_lshlrev_b32_e32 v64, 16, v50
	v_and_b32_e32 v65, 0xffff0000, v50
	v_lshlrev_b32_e32 v50, 16, v51
	v_and_b32_e32 v51, 0xffff0000, v51
	v_pk_fma_f32 v[38:39], v[38:39], v[46:47], v[48:49]
	v_pk_fma_f32 v[36:37], v[36:37], v[44:45], v[54:55]
	v_pk_fma_f32 v[48:49], v[34:35], v[42:43], v[50:51]
	v_pk_fma_f32 v[34:35], v[32:33], v[40:41], v[64:65]
	v_cvt_pk_bf16_f32 v32, v36, v37
	v_cvt_pk_bf16_f32 v33, v38, v39
	v_cvt_pk_bf16_f32 v34, v34, v35
	v_cvt_pk_bf16_f32 v35, v48, v49
	v_lshl_add_u64 v[36:37], v[160:161], 0, s[2:3]
	global_store_dwordx4 v[52:53], v[32:35], off offset:256
	v_lshl_add_u64 v[38:39], s[4:5], 0, v[36:37]
	global_load_dwordx4 v[32:35], v[38:39], off
	s_mov_b64 s[2:3], 0xb0000
	s_waitcnt vmcnt(0) lgkmcnt(0)
	v_lshlrev_b32_e32 v48, 16, v32
	v_and_b32_e32 v49, 0xffff0000, v32
	v_lshlrev_b32_e32 v32, 16, v33
	v_and_b32_e32 v33, 0xffff0000, v33
	v_lshlrev_b32_e32 v50, 16, v34
	v_and_b32_e32 v51, 0xffff0000, v34
	v_lshlrev_b32_e32 v34, 16, v35
	v_and_b32_e32 v35, 0xffff0000, v35
	v_pk_fma_f32 v[30:31], v[30:31], v[62:63], v[32:33]
	v_pk_fma_f32 v[28:29], v[28:29], v[60:61], v[48:49]
	v_pk_fma_f32 v[32:33], v[26:27], v[58:59], v[34:35]
	v_pk_fma_f32 v[26:27], v[24:25], v[56:57], v[50:51]
	v_cvt_pk_bf16_f32 v24, v28, v29
	v_cvt_pk_bf16_f32 v25, v30, v31
	v_cvt_pk_bf16_f32 v26, v26, v27
	v_cvt_pk_bf16_f32 v27, v32, v33
	v_lshl_add_u64 v[28:29], s[42:43], 0, v[36:37]
	global_store_dwordx4 v[28:29], v[24:27], off
	global_load_dwordx4 v[24:27], v[38:39], off offset:256
	s_waitcnt vmcnt(0) lgkmcnt(0)
	v_lshlrev_b32_e32 v30, 16, v24
	v_and_b32_e32 v31, 0xffff0000, v24
	v_lshlrev_b32_e32 v24, 16, v25
	v_and_b32_e32 v25, 0xffff0000, v25
	v_lshlrev_b32_e32 v32, 16, v26
	v_and_b32_e32 v33, 0xffff0000, v26
	v_lshlrev_b32_e32 v26, 16, v27
	v_and_b32_e32 v27, 0xffff0000, v27
	v_pk_fma_f32 v[22:23], v[22:23], v[46:47], v[24:25]
	v_pk_fma_f32 v[20:21], v[20:21], v[44:45], v[30:31]
	v_pk_fma_f32 v[24:25], v[18:19], v[42:43], v[26:27]
	v_pk_fma_f32 v[18:19], v[16:17], v[40:41], v[32:33]
	v_cvt_pk_bf16_f32 v16, v20, v21
	v_cvt_pk_bf16_f32 v17, v22, v23
	v_cvt_pk_bf16_f32 v18, v18, v19
	v_cvt_pk_bf16_f32 v19, v24, v25
	v_lshl_add_u64 v[20:21], v[160:161], 0, s[2:3]
	global_store_dwordx4 v[28:29], v[16:19], off offset:256
	v_lshl_add_u64 v[22:23], s[4:5], 0, v[20:21]
	global_load_dwordx4 v[16:19], v[22:23], off
	s_mov_b32 s2, s37
	s_waitcnt vmcnt(0) lgkmcnt(0)
	v_lshlrev_b32_e32 v24, 16, v16
	v_and_b32_e32 v25, 0xffff0000, v16
	v_lshlrev_b32_e32 v16, 16, v17
	v_and_b32_e32 v17, 0xffff0000, v17
	v_lshlrev_b32_e32 v26, 16, v18
	v_and_b32_e32 v27, 0xffff0000, v18
	v_lshlrev_b32_e32 v18, 16, v19
	v_and_b32_e32 v19, 0xffff0000, v19
	v_pk_fma_f32 v[14:15], v[14:15], v[62:63], v[16:17]
	v_pk_fma_f32 v[12:13], v[12:13], v[60:61], v[24:25]
	v_pk_fma_f32 v[16:17], v[10:11], v[58:59], v[18:19]
	v_pk_fma_f32 v[10:11], v[8:9], v[56:57], v[26:27]
	v_cvt_pk_bf16_f32 v8, v12, v13
	v_cvt_pk_bf16_f32 v9, v14, v15
	v_cvt_pk_bf16_f32 v10, v10, v11
	v_cvt_pk_bf16_f32 v11, v16, v17
	v_lshl_add_u64 v[12:13], s[42:43], 0, v[20:21]
	global_store_dwordx4 v[12:13], v[8:11], off
	global_load_dwordx4 v[8:11], v[22:23], off offset:256
	s_waitcnt vmcnt(0) lgkmcnt(0)
	v_lshlrev_b32_e32 v14, 16, v8
	v_and_b32_e32 v15, 0xffff0000, v8
	v_lshlrev_b32_e32 v8, 16, v9
	v_and_b32_e32 v9, 0xffff0000, v9
	v_lshlrev_b32_e32 v16, 16, v10
	v_and_b32_e32 v17, 0xffff0000, v10
	v_lshlrev_b32_e32 v10, 16, v11
	v_and_b32_e32 v11, 0xffff0000, v11
	v_pk_fma_f32 v[6:7], v[6:7], v[46:47], v[8:9]
	v_pk_fma_f32 v[4:5], v[4:5], v[44:45], v[14:15]
	v_pk_fma_f32 v[8:9], v[2:3], v[42:43], v[10:11]
	v_pk_fma_f32 v[2:3], v[0:1], v[40:41], v[16:17]
	v_cvt_pk_bf16_f32 v0, v4, v5
	v_cvt_pk_bf16_f32 v1, v6, v7
	v_cvt_pk_bf16_f32 v2, v2, v3
	v_cvt_pk_bf16_f32 v3, v8, v9
	global_store_dwordx4 v[12:13], v[0:3], off offset:256
	s_cbranch_vccz .LBB1_2336
	s_waitcnt vmcnt(0)
	s_cmpk_gt_u32 s17, 0xff
	s_cbranch_scc1 .LBB1_2343
	s_barrier

; #define PG8_STAGE(bufoff, gbase, voff) do { _Pragma("unroll") for (int _i = 0; _i < 2; ++_i) \
;         __builtin_amdgcn_global_load_lds((const unsigned*)((const char*)(gbase) + (voff)[_i]), (LAS unsigned*)(lds + (bufoff) + ldsw + _i * 8192), 16, 0, 0); } while (0)
; #define PG8_LDA(dst, b, h) do { _Pragma("unroll") for (int m = 0; m < 4; ++m) _Pragma("unroll") for (int k = 0; k < 2; ++k) dst[m][k] = *(const LAS bf16x8*)(lds + PG8_SA(b, h) + aoff + m * 2048 + k * 1024); } while (0)
; #define PG8_LDB(dst, b, h) do { _Pragma("unroll") for (int n = 0; n < 2; ++n) _Pragma("unroll") for (int k = 0; k < 2; ++k) dst[n][k] = *(const LAS bf16x8*)(lds + PG8_SB(b, h) + boff + n * 2048 + k * 1024); } while (0)
; #define PG8_MMA(ai, bj, At, Bt) do { __builtin_amdgcn_s_setprio(1); _Pragma("unroll") for (int m = 0; m < 4; ++m) _Pragma("unroll") for (int n = 0; n < 2; ++n) _Pragma("unroll") for (int k = 0; k < 2; ++k) \
;         acc[ai][bj][m][n] = __builtin_amdgcn_mfma_f32_16x16x32_bf16(Bt[n][k], At[m][k], acc[ai][bj][m][n], 0, 0, 0); __builtin_amdgcn_s_setprio(0); } while (0)
; #define PG8_WAIT_V(n) asm volatile("s_waitcnt vmcnt(" #n ")" ::: "memory")
; #define PG8_WAIT_L(n) asm volatile("s_waitcnt lgkmcnt(" #n ")" ::: "memory")
; template <class Map, class Epi>
; DI void gemm_phase(LAS unsigned char* lds, const Map& MP, const Epi& E, const int nM, const int nN, const int K, const int lda, const int ldb) {
;     ...
;         for (int t = 0; t < nt; t += 2) {
;             const bool last = (t == nt - 2);
;             const char* a1 = cA + (size_t)(t + 1) * kstep;
;             const char* a2 = last ? nA : cA + (size_t)(t + 2) * kstep; const char* b2 = last ? nB : cB + (size_t)(t + 2) * kstep;
;             const char* a3 = a2 + kstep; const char* b3 = b2 + kstep;
;             PG8_LDB(B0, 0, 0); PG8_SCHED; PG8_LDA(At, 0, 0); PG8_STAGE(PG8_SA(1, 1), a1 + hstepA, voffA);
;             PG8_WAIT_L(8); PG8_BAR; PG8_WAIT_L(0); PG8_MMA(0, 0, At, B0); PG8_BAR; PG8_SCHED;
;             PG8_LDB(B1, 0, 1); PG8_STAGE(PG8_SB(0, 0), b2, voffB);
;             PG8_BAR; PG8_WAIT_L(0); PG8_MMA(0, 1, At, B1); PG8_BAR;
;             PG8_LDA(At, 0, 1); PG8_STAGE(PG8_SA(0, 0), a2, voffA);
;             PG8_BAR; PG8_WAIT_L(0); PG8_MMA(1, 0, At, B0); PG8_BAR; PG8_SCHED;
;             PG8_STAGE(PG8_SB(0, 1), b2 + hstepB, voffB);
;             PG8_WAIT_V(6); PG8_BAR; PG8_MMA(1, 1, At, B1); PG8_BAR;
.LBB1_2483:
	s_add_u32 s28, s42, 0xfff80080
	s_addc_u32 s29, s43, -1
	s_cmp_eq_u32 s3, 28
	s_cselect_b32 s47, s23, s29
	s_cselect_b32 s46, s58, s28
	s_cselect_b32 s29, s21, vcc_hi
	s_cselect_b32 s28, s59, vcc_lo
	s_add_i32 m0, s38, 0xc000
	ds_read_b128 v[96:99], v190
	ds_read_b128 v[100:103], v190 offset:1024
	ds_read_b128 v[108:111], v190 offset:2048
	ds_read_b128 v[112:115], v190 offset:3072
	ds_read_b128 v[160:163], v190 offset:4096
	ds_read_b128 v[164:167], v190 offset:5120
	ds_read_b128 v[198:201], v190 offset:6144
	ds_read_b128 v[202:205], v190 offset:7168
	global_load_lds_dwordx4 v178, s[42:43]
	s_add_i32 m0, s38, 0xe000
	s_nop 0
	global_load_lds_dwordx4 v176, s[42:43]
	s_waitcnt lgkmcnt(8)
	s_setprio 1
	s_barrier
	s_waitcnt lgkmcnt(7)
	v_mfma_f32_16x16x32_bf16 v[148:151], v[80:83], v[96:99], v[148:151]
	v_mfma_f32_16x16x32_bf16 v[144:147], v[88:91], v[96:99], v[144:147]
	s_waitcnt lgkmcnt(5)
	v_mfma_f32_16x16x32_bf16 v[136:139], v[80:83], v[108:111], v[136:139]
	v_mfma_f32_16x16x32_bf16 v[128:131], v[88:91], v[108:111], v[128:131]
	s_waitcnt lgkmcnt(3)
	v_mfma_f32_16x16x32_bf16 v[120:123], v[80:83], v[160:163], v[120:123]
	v_mfma_f32_16x16x32_bf16 v[104:107], v[88:91], v[160:163], v[104:107]
	s_waitcnt lgkmcnt(1)
	v_mfma_f32_16x16x32_bf16 v[76:79], v[80:83], v[198:201], v[76:79]
	v_mfma_f32_16x16x32_bf16 v[72:75], v[88:91], v[198:201], v[72:75]
	v_mfma_f32_16x16x32_bf16 v[148:151], v[84:87], v[100:103], v[148:151]
	s_add_i32 s68, s2, s37
	v_mfma_f32_16x16x32_bf16 v[144:147], v[92:95], v[100:103], v[144:147]
	v_lshl_add_u64 v[184:185], s[28:29], 0, v[172:173]
	v_mfma_f32_16x16x32_bf16 v[136:139], v[84:87], v[112:115], v[136:139]
	v_lshl_add_u64 v[194:195], s[28:29], 0, v[168:169]
	v_mfma_f32_16x16x32_bf16 v[128:131], v[92:95], v[112:115], v[128:131]
	v_mfma_f32_16x16x32_bf16 v[120:123], v[84:87], v[164:167], v[120:123]
	v_mfma_f32_16x16x32_bf16 v[104:107], v[92:95], v[164:167], v[104:107]
	s_waitcnt lgkmcnt(0)
	v_mfma_f32_16x16x32_bf16 v[76:79], v[84:87], v[202:205], v[76:79]
	s_mov_b32 m0, s68
	v_mfma_f32_16x16x32_bf16 v[72:75], v[92:95], v[202:205], v[72:75]
	s_barrier
	s_setprio 0
	ds_read_b128 v[206:209], v191
	ds_read_b128 v[210:213], v191 offset:1024
	ds_read_b128 v[214:217], v191 offset:2048
	global_load_lds_dwordx4 v[184:185], off
	s_add_i32 m0, s68, 0x2000
	ds_read_b128 v[218:221], v191 offset:3072
	global_load_lds_dwordx4 v[194:195], off
	s_setprio 1
	s_barrier
	s_waitcnt lgkmcnt(3)
	v_mfma_f32_16x16x32_bf16 v[156:159], v[206:209], v[96:99], v[156:159]
	s_waitcnt lgkmcnt(1)
	v_mfma_f32_16x16x32_bf16 v[96:99], v[214:217], v[96:99], v[152:155]
	v_mfma_f32_16x16x32_bf16 v[156:159], v[210:213], v[100:103], v[156:159]
	s_waitcnt lgkmcnt(0)
	v_mfma_f32_16x16x32_bf16 v[96:99], v[218:221], v[100:103], v[96:99]
	v_mfma_f32_16x16x32_bf16 v[100:103], v[206:209], v[108:111], v[140:143]
	v_mfma_f32_16x16x32_bf16 v[108:111], v[214:217], v[108:111], v[132:135]
	v_mfma_f32_16x16x32_bf16 v[116:119], v[214:217], v[160:163], v[116:119]
	v_mfma_f32_16x16x32_bf16 v[68:71], v[206:209], v[198:201], v[68:71]
	v_mfma_f32_16x16x32_bf16 v[64:67], v[214:217], v[198:201], v[64:67]
	v_lshl_add_u64 v[232:233], s[46:47], 0, v[170:171]
	s_mov_b32 m0, s38
	v_mfma_f32_16x16x32_bf16 v[100:103], v[210:213], v[112:115], v[100:103]
	v_lshl_add_u64 v[230:231], s[46:47], 0, v[174:175]
	v_mfma_f32_16x16x32_bf16 v[108:111], v[218:221], v[112:115], v[108:111]
	v_mfma_f32_16x16x32_bf16 v[112:115], v[206:209], v[160:163], v[124:127]
	v_mfma_f32_16x16x32_bf16 v[116:119], v[218:221], v[164:167], v[116:119]
	v_mfma_f32_16x16x32_bf16 v[68:71], v[210:213], v[202:205], v[68:71]
	v_mfma_f32_16x16x32_bf16 v[64:67], v[218:221], v[202:205], v[64:67]
	v_mfma_f32_16x16x32_bf16 v[112:115], v[210:213], v[164:167], v[112:115]
	s_barrier
	s_setprio 0
	ds_read_b128 v[124:127], v190 offset:16384
	ds_read_b128 v[132:135], v190 offset:17408
	ds_read_b128 v[140:143], v190 offset:18432
	ds_read_b128 v[152:155], v190 offset:19456
	ds_read_b128 v[160:163], v190 offset:20480
	ds_read_b128 v[164:167], v190 offset:21504
	ds_read_b128 v[198:201], v190 offset:22528
	global_load_lds_dwordx4 v[230:231], off
	s_mov_b32 m0, s39
	ds_read_b128 v[202:205], v190 offset:23552
	global_load_lds_dwordx4 v[232:233], off
	s_waitcnt vmcnt(10)
	s_setprio 1
	s_barrier
	s_waitcnt lgkmcnt(7)
	v_mfma_f32_16x16x32_bf16 v[60:63], v[80:83], v[124:127], v[60:63]
	v_mfma_f32_16x16x32_bf16 v[48:51], v[88:91], v[124:127], v[48:51]
	s_waitcnt lgkmcnt(5)
	v_mfma_f32_16x16x32_bf16 v[40:43], v[80:83], v[140:143], v[40:43]
	v_mfma_f32_16x16x32_bf16 v[32:35], v[88:91], v[140:143], v[32:35]
	s_waitcnt lgkmcnt(3)
	v_mfma_f32_16x16x32_bf16 v[24:27], v[80:83], v[160:163], v[24:27]
	v_mfma_f32_16x16x32_bf16 v[16:19], v[88:91], v[160:163], v[16:19]
	s_waitcnt lgkmcnt(1)
	v_mfma_f32_16x16x32_bf16 v[12:15], v[80:83], v[198:201], v[12:15]
	v_mfma_f32_16x16x32_bf16 v[8:11], v[88:91], v[198:201], v[8:11]
	v_mfma_f32_16x16x32_bf16 v[60:63], v[84:87], v[132:135], v[60:63]
	s_add_u32 s68, s28, 0x80000
	s_addc_u32 s69, s29, 0
	v_mfma_f32_16x16x32_bf16 v[48:51], v[92:95], v[132:135], v[48:51]
	s_add_i32 s70, s67, s37
	v_mfma_f32_16x16x32_bf16 v[40:43], v[84:87], v[152:155], v[40:43]
	v_mfma_f32_16x16x32_bf16 v[32:35], v[92:95], v[152:155], v[32:35]
	v_mfma_f32_16x16x32_bf16 v[24:27], v[84:87], v[164:167], v[24:27]
	v_mfma_f32_16x16x32_bf16 v[16:19], v[92:95], v[164:167], v[16:19]
	s_waitcnt lgkmcnt(0)
	v_mfma_f32_16x16x32_bf16 v[12:15], v[84:87], v[202:205], v[12:15]
	s_mov_b32 m0, s70
	v_mfma_f32_16x16x32_bf16 v[8:11], v[92:95], v[202:205], v[8:11]
	s_barrier
; #define PG8_STAGE(bufoff, gbase, voff) do { _Pragma("unroll") for (int _i = 0; _i < 2; ++_i) \
;         __builtin_amdgcn_global_load_lds((const unsigned*)((const char*)(gbase) + (voff)[_i]), (LAS unsigned*)(lds + (bufoff) + ldsw + _i * 8192), 16, 0, 0); } while (0)
; #define PG8_LDA(dst, b, h) do { _Pragma("unroll") for (int m = 0; m < 4; ++m) _Pragma("unroll") for (int k = 0; k < 2; ++k) dst[m][k] = *(const LAS bf16x8*)(lds + PG8_SA(b, h) + aoff + m * 2048 + k * 1024); } while (0)
; #define PG8_LDB(dst, b, h) do { _Pragma("unroll") for (int n = 0; n < 2; ++n) _Pragma("unroll") for (int k = 0; k < 2; ++k) dst[n][k] = *(const LAS bf16x8*)(lds + PG8_SB(b, h) + boff + n * 2048 + k * 1024); } while (0)
; #define PG8_MMA(ai, bj, At, Bt) do { __builtin_amdgcn_s_setprio(1); _Pragma("unroll") for (int m = 0; m < 4; ++m) _Pragma("unroll") for (int n = 0; n < 2; ++n) _Pragma("unroll") for (int k = 0; k < 2; ++k) \
;         acc[ai][bj][m][n] = __builtin_amdgcn_mfma_f32_16x16x32_bf16(Bt[n][k], At[m][k], acc[ai][bj][m][n], 0, 0, 0); __builtin_amdgcn_s_setprio(0); } while (0)
; #define PG8_WAIT_L(n) asm volatile("s_waitcnt lgkmcnt(" #n ")" ::: "memory")
; #define PG8_BAR __builtin_amdgcn_s_barrier()
; #define PG8_SCHED __builtin_amdgcn_sched_barrier(0)
; template <class Map, class Epi>
; DI void gemm_phase(LAS unsigned char* lds, const Map& MP, const Epi& E, const int nM, const int nN, const int K, const int lda, const int ldb) {
;     ...
;             PG8_LDB(B0, 1, 0); PG8_SCHED; PG8_LDA(At, 1, 0); PG8_STAGE(PG8_SA(0, 1), a2 + hstepA, voffA);
;             PG8_WAIT_L(8); PG8_BAR; PG8_WAIT_L(0); PG8_MMA(0, 0, At, B0); PG8_BAR; PG8_SCHED;
;             PG8_LDB(B1, 1, 1); PG8_STAGE(PG8_SB(1, 0), b3, voffB);
;             PG8_BAR; PG8_WAIT_L(0); PG8_MMA(0, 1, At, B1); PG8_BAR;
;             PG8_LDA(At, 1, 1); PG8_STAGE(PG8_SA(1, 0), a3, voffA);
;             PG8_BAR; PG8_WAIT_L(0); PG8_MMA(1, 0, At, B0); PG8_BAR; PG8_SCHED;
;             PG8_STAGE(PG8_SB(1, 1), b3 + hstepB, voffB);
	s_setprio 0
	global_load_lds_dwordx4 v172, s[68:69]
	s_add_i32 m0, s70, 0x2000
	s_nop 0
	global_load_lds_dwordx4 v168, s[68:69]
	s_waitcnt vmcnt(6)
	s_setprio 1
	s_barrier
	v_mfma_f32_16x16x32_bf16 v[56:59], v[206:209], v[124:127], v[56:59]
	v_mfma_f32_16x16x32_bf16 v[52:55], v[214:217], v[124:127], v[52:55]
	s_add_i32 s68, 0, 0x18000
	v_add_u32_e32 v92, s68, v188
	ds_read_b128 v[80:83], v92
	v_mfma_f32_16x16x32_bf16 v[44:47], v[206:209], v[140:143], v[44:47]
	v_mfma_f32_16x16x32_bf16 v[36:39], v[214:217], v[140:143], v[36:39]
	ds_read_b128 v[84:87], v92 offset:1024
	v_mfma_f32_16x16x32_bf16 v[28:31], v[206:209], v[160:163], v[28:31]
	v_mfma_f32_16x16x32_bf16 v[20:23], v[214:217], v[160:163], v[20:23]
	ds_read_b128 v[88:91], v92 offset:2048
	v_mfma_f32_16x16x32_bf16 v[4:7], v[206:209], v[198:201], v[4:7]
	v_mfma_f32_16x16x32_bf16 v[0:3], v[214:217], v[198:201], v[0:3]
	ds_read_b128 v[92:95], v92 offset:3072
	v_mfma_f32_16x16x32_bf16 v[56:59], v[210:213], v[132:135], v[56:59]
	s_add_u32 s46, s46, 0x80000
	s_addc_u32 s47, s47, 0
	v_mfma_f32_16x16x32_bf16 v[52:55], v[218:221], v[132:135], v[52:55]
	v_mfma_f32_16x16x32_bf16 v[44:47], v[210:213], v[152:155], v[44:47]
	v_mfma_f32_16x16x32_bf16 v[36:39], v[218:221], v[152:155], v[36:39]
	v_mfma_f32_16x16x32_bf16 v[28:31], v[210:213], v[164:167], v[28:31]
	v_mfma_f32_16x16x32_bf16 v[20:23], v[218:221], v[164:167], v[20:23]
	v_mfma_f32_16x16x32_bf16 v[4:7], v[210:213], v[202:205], v[4:7]
	s_mov_b32 m0, s55
	v_mfma_f32_16x16x32_bf16 v[0:3], v[218:221], v[202:205], v[0:3]
	s_barrier
	s_setprio 0
	ds_read_b128 v[124:127], v190 offset:32768
	ds_read_b128 v[132:135], v190 offset:33792
	ds_read_b128 v[160:163], v190 offset:34816
	ds_read_b128 v[164:167], v190 offset:35840
	ds_read_b128 v[198:201], v190 offset:36864
	ds_read_b128 v[202:205], v190 offset:37888
	ds_read_b128 v[206:209], v190 offset:38912
	global_load_lds_dwordx4 v174, s[46:47]
	s_mov_b32 m0, s56
	ds_read_b128 v[210:213], v190 offset:39936
	global_load_lds_dwordx4 v170, s[46:47]
	s_waitcnt lgkmcnt(8)
	s_setprio 1
	s_barrier
	s_waitcnt lgkmcnt(7)
	v_mfma_f32_16x16x32_bf16 v[140:143], v[80:83], v[124:127], v[148:151]
	s_waitcnt lgkmcnt(6)
	v_mfma_f32_16x16x32_bf16 v[148:151], v[84:87], v[132:135], v[140:143]
	v_mfma_f32_16x16x32_bf16 v[140:143], v[88:91], v[124:127], v[144:147]
	s_waitcnt lgkmcnt(5)
	v_mfma_f32_16x16x32_bf16 v[136:139], v[80:83], v[160:163], v[136:139]
	v_mfma_f32_16x16x32_bf16 v[128:131], v[88:91], v[160:163], v[128:131]
	s_waitcnt lgkmcnt(3)
	v_mfma_f32_16x16x32_bf16 v[120:123], v[80:83], v[198:201], v[120:123]
	v_mfma_f32_16x16x32_bf16 v[104:107], v[88:91], v[198:201], v[104:107]
	s_waitcnt lgkmcnt(1)
	v_mfma_f32_16x16x32_bf16 v[76:79], v[80:83], v[206:209], v[76:79]
	v_mfma_f32_16x16x32_bf16 v[72:75], v[88:91], v[206:209], v[72:75]
	s_add_i32 s46, 0, 0x1c000
	v_mfma_f32_16x16x32_bf16 v[144:147], v[92:95], v[132:135], v[140:143]
	v_add_u32_e32 v140, s46, v188
	v_mfma_f32_16x16x32_bf16 v[136:139], v[84:87], v[164:167], v[136:139]
	s_add_i32 s47, s68, s37
	v_mfma_f32_16x16x32_bf16 v[128:131], v[92:95], v[164:167], v[128:131]
	v_mfma_f32_16x16x32_bf16 v[120:123], v[84:87], v[202:205], v[120:123]
	v_mfma_f32_16x16x32_bf16 v[104:107], v[92:95], v[202:205], v[104:107]
	s_waitcnt lgkmcnt(0)
	v_mfma_f32_16x16x32_bf16 v[76:79], v[84:87], v[210:213], v[76:79]
	s_mov_b32 m0, s47
	v_mfma_f32_16x16x32_bf16 v[72:75], v[92:95], v[210:213], v[72:75]
	s_barrier
	s_setprio 0
	ds_read_b128 v[214:217], v140
	ds_read_b128 v[218:221], v140 offset:1024
	ds_read_b128 v[222:225], v140 offset:2048
	ds_read_b128 v[226:229], v140 offset:3072
	v_lshl_add_u64 v[140:141], v[184:185], 0, s[14:15]
	global_load_lds_dwordx4 v[140:141], off
	v_lshl_add_u64 v[140:141], v[194:195], 0, s[14:15]
	s_add_i32 m0, s47, 0x2000
	s_nop 0
	global_load_lds_dwordx4 v[140:141], off
	s_setprio 1
	s_barrier
	s_waitcnt lgkmcnt(1)
	v_mfma_f32_16x16x32_bf16 v[96:99], v[222:225], v[124:127], v[96:99]
	v_mfma_f32_16x16x32_bf16 v[140:143], v[214:217], v[124:127], v[156:159]
	s_waitcnt lgkmcnt(0)
	v_mfma_f32_16x16x32_bf16 v[152:155], v[226:229], v[132:135], v[96:99]
	v_mfma_f32_16x16x32_bf16 v[96:99], v[214:217], v[160:163], v[100:103]
	v_mfma_f32_16x16x32_bf16 v[156:159], v[218:221], v[132:135], v[140:143]
	v_mfma_f32_16x16x32_bf16 v[140:143], v[218:221], v[164:167], v[96:99]
	v_mfma_f32_16x16x32_bf16 v[96:99], v[222:225], v[160:163], v[108:111]
	v_mfma_f32_16x16x32_bf16 v[132:135], v[226:229], v[164:167], v[96:99]
	v_mfma_f32_16x16x32_bf16 v[96:99], v[214:217], v[198:201], v[112:115]
	s_mov_b32 m0, s62
	v_mfma_f32_16x16x32_bf16 v[124:127], v[218:221], v[202:205], v[96:99]
	v_lshl_add_u64 v[184:185], v[230:231], 0, s[14:15]
	v_mfma_f32_16x16x32_bf16 v[96:99], v[222:225], v[198:201], v[116:119]
	v_mfma_f32_16x16x32_bf16 v[68:71], v[214:217], v[206:209], v[68:71]
	v_mfma_f32_16x16x32_bf16 v[64:67], v[222:225], v[206:209], v[64:67]
	v_mfma_f32_16x16x32_bf16 v[116:119], v[226:229], v[202:205], v[96:99]
	v_mfma_f32_16x16x32_bf16 v[68:71], v[218:221], v[210:213], v[68:71]
	v_mfma_f32_16x16x32_bf16 v[64:67], v[226:229], v[210:213], v[64:67]
	s_barrier
	s_setprio 0
	ds_read_b128 v[96:99], v190 offset:49152
	ds_read_b128 v[100:103], v190 offset:50176
	ds_read_b128 v[108:111], v190 offset:51200
	ds_read_b128 v[112:115], v190 offset:52224
	ds_read_b128 v[160:163], v190 offset:53248
	ds_read_b128 v[164:167], v190 offset:54272
	ds_read_b128 v[198:201], v190 offset:55296
	global_load_lds_dwordx4 v[184:185], off
	v_lshl_add_u64 v[184:185], v[232:233], 0, s[14:15]
	s_mov_b32 m0, s63
	ds_read_b128 v[202:205], v190 offset:56320
	global_load_lds_dwordx4 v[184:185], off
	s_waitcnt vmcnt(10)
	s_setprio 1
	s_barrier
; #define PG8_STAGE(bufoff, gbase, voff) do { _Pragma("unroll") for (int _i = 0; _i < 2; ++_i) \
;         __builtin_amdgcn_global_load_lds((const unsigned*)((const char*)(gbase) + (voff)[_i]), (LAS unsigned*)(lds + (bufoff) + ldsw + _i * 8192), 16, 0, 0); } while (0)
; #define PG8_LDA(dst, b, h) do { _Pragma("unroll") for (int m = 0; m < 4; ++m) _Pragma("unroll") for (int k = 0; k < 2; ++k) dst[m][k] = *(const LAS bf16x8*)(lds + PG8_SA(b, h) + aoff + m * 2048 + k * 1024); } while (0)
; #define PG8_MMA(ai, bj, At, Bt) do { __builtin_amdgcn_s_setprio(1); _Pragma("unroll") for (int m = 0; m < 4; ++m) _Pragma("unroll") for (int n = 0; n < 2; ++n) _Pragma("unroll") for (int k = 0; k < 2; ++k) \
;         acc[ai][bj][m][n] = __builtin_amdgcn_mfma_f32_16x16x32_bf16(Bt[n][k], At[m][k], acc[ai][bj][m][n], 0, 0, 0); __builtin_amdgcn_s_setprio(0); } while (0)
; #define PG8_WAIT_V(n) asm volatile("s_waitcnt vmcnt(" #n ")" ::: "memory")
; #define PG8_WAIT_L(n) asm volatile("s_waitcnt lgkmcnt(" #n ")" ::: "memory")
; #define PG8_BAR __builtin_amdgcn_s_barrier()
; #define PG8_SCHED __builtin_amdgcn_sched_barrier(0)
; template <class Map, class Epi>
; DI void gemm_phase(LAS unsigned char* lds, const Map& MP, const Epi& E, const int nM, const int nN, const int K, const int lda, const int ldb) {
;     ...
;             PG8_LDA(At, 1, 1); PG8_STAGE(PG8_SA(1, 0), a3, voffA);
;             PG8_BAR; PG8_WAIT_L(0); PG8_MMA(1, 0, At, B0); PG8_BAR; PG8_SCHED;
;             PG8_STAGE(PG8_SB(1, 1), b3 + hstepB, voffB);
;             PG8_WAIT_V(6); PG8_BAR; PG8_MMA(1, 1, At, B1); PG8_BAR;
	s_waitcnt lgkmcnt(7)
	v_mfma_f32_16x16x32_bf16 v[60:63], v[80:83], v[96:99], v[60:63]
	v_mfma_f32_16x16x32_bf16 v[48:51], v[88:91], v[96:99], v[48:51]
	s_waitcnt lgkmcnt(5)
	v_mfma_f32_16x16x32_bf16 v[40:43], v[80:83], v[108:111], v[40:43]
	v_mfma_f32_16x16x32_bf16 v[32:35], v[88:91], v[108:111], v[32:35]
	s_waitcnt lgkmcnt(3)
	v_mfma_f32_16x16x32_bf16 v[24:27], v[80:83], v[160:163], v[24:27]
	v_mfma_f32_16x16x32_bf16 v[16:19], v[88:91], v[160:163], v[16:19]
	s_waitcnt lgkmcnt(1)
	v_mfma_f32_16x16x32_bf16 v[12:15], v[80:83], v[198:201], v[12:15]
	v_mfma_f32_16x16x32_bf16 v[8:11], v[88:91], v[198:201], v[8:11]
	v_mfma_f32_16x16x32_bf16 v[60:63], v[84:87], v[100:103], v[60:63]
	s_add_u32 s28, s28, 0x80080
	s_addc_u32 s29, s29, 0
	v_mfma_f32_16x16x32_bf16 v[48:51], v[92:95], v[100:103], v[48:51]
	s_add_i32 s46, s46, s37
	v_mfma_f32_16x16x32_bf16 v[40:43], v[84:87], v[112:115], v[40:43]
	v_mfma_f32_16x16x32_bf16 v[32:35], v[92:95], v[112:115], v[32:35]
	v_mfma_f32_16x16x32_bf16 v[24:27], v[84:87], v[164:167], v[24:27]
	v_mfma_f32_16x16x32_bf16 v[16:19], v[92:95], v[164:167], v[16:19]
	s_waitcnt lgkmcnt(0)
	v_mfma_f32_16x16x32_bf16 v[12:15], v[84:87], v[202:205], v[12:15]
	s_mov_b32 m0, s46
	v_mfma_f32_16x16x32_bf16 v[8:11], v[92:95], v[202:205], v[8:11]
	s_barrier
	s_setprio 0
	global_load_lds_dwordx4 v172, s[28:29]
	s_add_i32 m0, s46, 0x2000
	s_nop 0
	global_load_lds_dwordx4 v168, s[28:29]
	s_waitcnt vmcnt(6)
	s_setprio 1
	s_barrier
	v_mfma_f32_16x16x32_bf16 v[56:59], v[214:217], v[96:99], v[56:59]
	v_mfma_f32_16x16x32_bf16 v[52:55], v[222:225], v[96:99], v[52:55]
	ds_read_b128 v[80:83], v189
	v_mfma_f32_16x16x32_bf16 v[44:47], v[214:217], v[108:111], v[44:47]
	v_mfma_f32_16x16x32_bf16 v[36:39], v[222:225], v[108:111], v[36:39]
	ds_read_b128 v[84:87], v189 offset:1024
	v_mfma_f32_16x16x32_bf16 v[28:31], v[214:217], v[160:163], v[28:31]
	v_mfma_f32_16x16x32_bf16 v[20:23], v[222:225], v[160:163], v[20:23]
	ds_read_b128 v[88:91], v189 offset:2048
	v_mfma_f32_16x16x32_bf16 v[4:7], v[214:217], v[198:201], v[4:7]
	v_mfma_f32_16x16x32_bf16 v[0:3], v[222:225], v[198:201], v[0:3]
	ds_read_b128 v[92:95], v189 offset:3072
	v_mfma_f32_16x16x32_bf16 v[56:59], v[218:221], v[100:103], v[56:59]
	s_add_i32 s3, s3, 2
	v_mfma_f32_16x16x32_bf16 v[52:55], v[226:229], v[100:103], v[52:55]
	s_add_u32 vcc_lo, vcc_lo, 0x100
	s_addc_u32 vcc_hi, vcc_hi, 0
	v_mfma_f32_16x16x32_bf16 v[44:47], v[218:221], v[112:115], v[44:47]
	s_add_u32 s42, s42, 0x100
	s_addc_u32 s43, s43, 0
	v_mfma_f32_16x16x32_bf16 v[36:39], v[226:229], v[112:115], v[36:39]
	s_cmp_gt_u32 s3, 29
	v_mfma_f32_16x16x32_bf16 v[28:31], v[218:221], v[164:167], v[28:31]
	v_mfma_f32_16x16x32_bf16 v[20:23], v[226:229], v[164:167], v[20:23]
	v_mfma_f32_16x16x32_bf16 v[4:7], v[218:221], v[202:205], v[4:7]
	v_mfma_f32_16x16x32_bf16 v[0:3], v[226:229], v[202:205], v[0:3]
	s_barrier
	s_setprio 0
	s_cbranch_scc0 .LBB1_2483
; DI float silu_mul(float g, float v) { return g * v * __builtin_amdgcn_rcpf(1.0f + __builtin_amdgcn_exp2f(-LOG2E * g)); }
;     DI void operator()(const f32x4 (&acc)[2][2][4][2], const Unit& u, int wr, int wc, int fr, int fq) const {
;         const int row0 = u.pm * BM + wr * 64 + fr, ch0 = u.pn * 128 + wc * 32 + 8 * fq;
;         f32x4 w0[2], w1[2], w2[2], bb[2];
; #pragma unroll
;         for (int n = 0; n < 2; ++n) { w0[n] = *(const f32x4*)(cw + ch0 + 4 * n); w1[n] = *(const f32x4*)(cw + DFF + ch0 + 4 * n); w2[n] = *(const f32x4*)(cw + 2 * DFF + ch0 + 4 * n); bb[n] = *(const f32x4*)(cb + ch0 + 4 * n); }
; #pragma unroll
;         for (int ai = 0; ai < 2; ++ai)
; #pragma unroll
;             for (int m = 0; m < 4; ++m) {
;                 const bool efirst = (m == 0) && (fr == 0), elast = (m == 3) && (fr == 15);
;                 const int row = row0 + ai * HALF + m * 16;
;                 f32x4 gc[2];
; #pragma unroll
;                 for (int n = 0; n < 2; ++n) {
;                     const f32x4 g = acc[ai][0][m][n];
;                     const f32x4 gprev = acc[ai][0][m > 0 ? m - 1 : 0][n], gnext = acc[ai][0][m < 3 ? m + 1 : 3][n];
;                     f32x4 up, dn;
; #pragma unroll
;                     for (int e = 0; e < 4; ++e) {
;                         const float pu = (m > 0 && fr == 15) ? gprev[e] : g[e];
;                         const float pd = (m < 3 && fr == 0) ? gnext[e] : g[e];
;                         up[e] = dpp_ror1(pu); dn[e] = dpp_ror15(pd);
;                     }
;                     if (efirst) up = (f32x4){0.f, 0.f, 0.f, 0.f};
;                     if (elast) dn = (f32x4){0.f, 0.f, 0.f, 0.f};
;                     gc[n] = w0[n] * up + w1[n] * g + w2[n] * dn + bb[n];
;                 }
;                 if (efirst || elast) {
;                     const size_t eo = (size_t)((row >> 6) * 2 + (elast ? 1 : 0)) * DFF + ch0;
; #pragma unroll
;                     for (int n = 0; n < 2; ++n) { *(f32x4*)(EP + eo + 4 * n) = gc[n]; *(f32x4*)(ER + eo + 4 * n) = acc[ai][0][m][n]; *(f32x4*)(EV + eo + 4 * n) = acc[ai][1][m][n]; }
;                 } else {
;                     const f32x4 v0 = acc[ai][1][m][0], v1 = acc[ai][1][m][1];
;                     u32x4 o;
;                     o[0] = pack2(silu_mul(gc[0][0], v0[0]), silu_mul(gc[0][1], v0[1])); o[1] = pack2(silu_mul(gc[0][2], v0[2]), silu_mul(gc[0][3], v0[3]));
	s_waitcnt lgkmcnt(0)
	s_lshl_b32 s21, s45, 7
	v_mov_b32_e32 v80, v187
	v_mov_b32_e32 v194, v186
	s_or_b32 s21, s21, s57
	v_lshl_add_u32 v184, v80, 3, s21
	v_ashrrev_i32_e32 v185, 31, v184
	v_lshlrev_b64 v[80:81], 2, v[184:185]
	v_lshl_add_u64 v[84:85], s[4:5], 0, v[80:81]
	v_lshl_add_u64 v[88:89], s[16:17], 0, v[80:81]
	v_lshl_add_u64 v[92:93], s[18:19], 0, v[80:81]
	v_lshl_add_u64 v[112:113], s[6:7], 0, v[80:81]
	global_load_dwordx4 v[80:83], v[84:85], off offset:16
	global_load_dwordx4 v[96:99], v[84:85], off
	s_nop 0
	global_load_dwordx4 v[84:87], v[88:89], off offset:16
	global_load_dwordx4 v[100:103], v[88:89], off
	s_nop 0
	global_load_dwordx4 v[88:91], v[92:93], off offset:16
	global_load_dwordx4 v[108:111], v[92:93], off
	s_nop 0
	global_load_dwordx4 v[92:95], v[112:113], off offset:16
	s_nop 0
	global_load_dwordx4 v[112:115], v[112:113], off
	v_cmp_eq_u32_e32 vcc, 0, v194
	s_nop 0
	s_nop 0
	v_cndmask_b32_e32 v161, v148, v136, vcc
	v_cndmask_b32_e32 v162, v149, v137, vcc
	v_cndmask_b32_e32 v163, v150, v138, vcc
	v_mov_b32_dpp v160, v161 row_ror:15 row_mask:0xf bank_mask:0xf
	s_nop 0
	s_nop 0
	v_mov_b32_dpp v161, v162 row_ror:15 row_mask:0xf bank_mask:0xf
	v_mov_b32_dpp v164, v150 row_ror:1 row_mask:0xf bank_mask:0xf
	v_cndmask_b32_e32 v165, v151, v139, vcc
	v_mov_b32_dpp v162, v163 row_ror:15 row_mask:0xf bank_mask:0xf
	v_mov_b32_dpp v195, v151 row_ror:1 row_mask:0xf bank_mask:0xf
	v_mov_b32_dpp v166, v148 row_ror:1 row_mask:0xf bank_mask:0xf
	v_mov_b32_dpp v167, v149 row_ror:1 row_mask:0xf bank_mask:0xf
	v_mov_b32_dpp v163, v165 row_ror:15 row_mask:0xf bank_mask:0xf
	v_cndmask_b32_e64 v165, v195, 0, vcc
	v_cndmask_b32_e64 v164, v164, 0, vcc
	v_cndmask_b32_e64 v167, v167, 0, vcc
	v_cndmask_b32_e64 v166, v166, 0, vcc
	s_nop 0
	s_nop 0
	v_mov_b32_dpp v195, v144 row_ror:1 row_mask:0xf bank_mask:0xf
	v_mov_b32_dpp v196, v145 row_ror:1 row_mask:0xf bank_mask:0xf
	v_mov_b32_dpp v198, v146 row_ror:1 row_mask:0xf bank_mask:0xf
	v_cndmask_b32_e32 v199, v147, v131, vcc
	v_mov_b32_dpp v200, v147 row_ror:1 row_mask:0xf bank_mask:0xf
	v_cndmask_b32_e64 v198, v198, 0, vcc
	v_cndmask_b32_e64 v201, v196, 0, vcc
	s_lshl_b32 s3, s44, 8
	s_add_i32 s3, s3, s49
	v_add_u32_e32 v193, s3, v194
	v_cmp_ne_u32_e64 s[46:47], 0, v194
	s_waitcnt vmcnt(0)
	v_pk_mul_f32 v[164:165], v[98:99], v[164:165]
	v_pk_mul_f32 v[166:167], v[96:97], v[166:167]
	v_pk_fma_f32 v[164:165], v[150:151], v[102:103], v[164:165]
	v_pk_fma_f32 v[166:167], v[148:149], v[100:101], v[166:167]
	v_pk_fma_f32 v[162:163], v[110:111], v[162:163], v[164:165]
	v_cndmask_b32_e32 v165, v144, v128, vcc
	v_pk_fma_f32 v[160:161], v[108:109], v[160:161], v[166:167]
	v_cndmask_b32_e32 v166, v145, v129, vcc
	v_mov_b32_dpp v164, v165 row_ror:15 row_mask:0xf bank_mask:0xf
	v_cndmask_b32_e32 v167, v146, v130, vcc
	v_pk_add_f32 v[162:163], v[114:115], v[162:163]
	v_mov_b32_dpp v165, v166 row_ror:15 row_mask:0xf bank_mask:0xf
	v_pk_add_f32 v[160:161], v[112:113], v[160:161]
	s_nop 0
	v_mov_b32_dpp v166, v167 row_ror:15 row_mask:0xf bank_mask:0xf
	s_nop 1
	v_mov_b32_dpp v167, v199 row_ror:15 row_mask:0xf bank_mask:0xf
	v_cndmask_b32_e64 v199, v200, 0, vcc
	v_cndmask_b32_e64 v200, v195, 0, vcc
	v_pk_mul_f32 v[200:201], v[80:81], v[200:201]
	v_pk_mul_f32 v[198:199], v[82:83], v[198:199]
	v_pk_fma_f32 v[200:201], v[144:145], v[84:85], v[200:201]
	v_pk_fma_f32 v[198:199], v[146:147], v[86:87], v[198:199]
	v_pk_fma_f32 v[164:165], v[88:89], v[164:165], v[200:201]
	v_pk_fma_f32 v[166:167], v[90:91], v[166:167], v[198:199]
	v_pk_add_f32 v[164:165], v[92:93], v[164:165]
	v_pk_add_f32 v[166:167], v[94:95], v[166:167]
	s_and_saveexec_b64 s[28:29], s[46:47]
	s_xor_b64 s[28:29], exec, s[28:29]
	s_cbranch_execz .LBB1_2486
	v_mul_f32_e32 v195, 0xbfb8aa3b, v160
	v_exp_f32_e32 v195, v195
	v_mul_f32_e32 v196, 0xbfb8aa3b, v161
	v_exp_f32_e32 v196, v196
	v_pk_mul_f32 v[160:161], v[156:157], v[160:161]
	v_add_f32_e32 v195, 1.0, v195
	v_rcp_f32_e32 v198, v195
	v_add_f32_e32 v196, 1.0, v196
	v_mul_f32_e32 v195, 0xbfb8aa3b, v162
	v_rcp_f32_e32 v199, v196
	v_exp_f32_e32 v195, v195
	v_mul_f32_e32 v196, 0xbfb8aa3b, v163
	v_exp_f32_e32 v196, v196
	v_pk_mul_f32 v[160:161], v[160:161], v[198:199]
	v_add_f32_e32 v195, 1.0, v195
	v_rcp_f32_e32 v200, v195
	v_add_f32_e32 v195, 1.0, v196
	v_rcp_f32_e32 v201, v195
	v_cvt_pk_bf16_f32 v160, v160, v161
	v_mul_f32_e32 v161, 0xbfb8aa3b, v164
	v_exp_f32_e32 v195, v161
	v_mul_f32_e32 v161, 0xbfb8aa3b, v165
	v_exp_f32_e32 v196, v161
	v_pk_mul_f32 v[162:163], v[158:159], v[162:163]
	v_pk_mul_f32 v[164:165], v[152:153], v[164:165]
	v_pk_mul_f32 v[162:163], v[162:163], v[200:201]
	s_nop 0
	v_cvt_pk_bf16_f32 v161, v162, v163
	v_add_f32_e32 v162, 1.0, v195
	v_mul_f32_e32 v195, 0xbfb8aa3b, v166
	v_add_f32_e32 v163, 1.0, v196
	v_exp_f32_e32 v195, v195
	v_mul_f32_e32 v196, 0xbfb8aa3b, v167
	v_exp_f32_e32 v196, v196
	v_rcp_f32_e32 v162, v162
	v_add_f32_e32 v195, 1.0, v195
	v_rcp_f32_e32 v198, v195
	v_add_f32_e32 v195, 1.0, v196
	v_rcp_f32_e32 v163, v163
	v_rcp_f32_e32 v199, v195
	v_pk_mul_f32 v[166:167], v[154:155], v[166:167]
	v_pk_mul_f32 v[162:163], v[164:165], v[162:163]
	v_pk_mul_f32 v[164:165], v[166:167], v[198:199]
	v_cvt_pk_bf16_f32 v162, v162, v163
	v_cvt_pk_bf16_f32 v163, v164, v165
	v_mov_b64_e32 v[164:165], s[52:53]
	v_mad_i64_i32 v[164:165], s[42:43], v193, s60, v[164:165]
	v_lshl_add_u64 v[164:165], v[184:185], 1, v[164:165]
	global_store_dwordx4 v[164:165], v[160:163], off

; #define PG8_STAGE(bufoff, gbase, voff) do { _Pragma("unroll") for (int _i = 0; _i < 2; ++_i) \
;         __builtin_amdgcn_global_load_lds((const unsigned*)((const char*)(gbase) + (voff)[_i]), (LAS unsigned*)(lds + (bufoff) + ldsw + _i * 8192), 16, 0, 0); } while (0)
; #define PG8_LDA(dst, b, h) do { _Pragma("unroll") for (int m = 0; m < 4; ++m) _Pragma("unroll") for (int k = 0; k < 2; ++k) dst[m][k] = *(const LAS bf16x8*)(lds + PG8_SA(b, h) + aoff + m * 2048 + k * 1024); } while (0)
; #define PG8_LDB(dst, b, h) do { _Pragma("unroll") for (int n = 0; n < 2; ++n) _Pragma("unroll") for (int k = 0; k < 2; ++k) dst[n][k] = *(const LAS bf16x8*)(lds + PG8_SB(b, h) + boff + n * 2048 + k * 1024); } while (0)
; #define PG8_MMA(ai, bj, At, Bt) do { __builtin_amdgcn_s_setprio(1); _Pragma("unroll") for (int m = 0; m < 4; ++m) _Pragma("unroll") for (int n = 0; n < 2; ++n) _Pragma("unroll") for (int k = 0; k < 2; ++k) \
;         acc[ai][bj][m][n] = __builtin_amdgcn_mfma_f32_16x16x32_bf16(Bt[n][k], At[m][k], acc[ai][bj][m][n], 0, 0, 0); __builtin_amdgcn_s_setprio(0); } while (0)
; #define PG8_WAIT_V(n) asm volatile("s_waitcnt vmcnt(" #n ")" ::: "memory")
; #define PG8_WAIT_L(n) asm volatile("s_waitcnt lgkmcnt(" #n ")" ::: "memory")
; template <class Map, class Epi>
; DI void gemm_phase(LAS unsigned char* lds, const Map& MP, const Epi& E, const int nM, const int nN, const int K, const int lda, const int ldb) {
;     ...
;         for (int t = 0; t < nt; t += 2) {
;             const bool last = (t == nt - 2);
;             const char* a1 = cA + (size_t)(t + 1) * kstep;
;             const char* a2 = last ? nA : cA + (size_t)(t + 2) * kstep; const char* b2 = last ? nB : cB + (size_t)(t + 2) * kstep;
;             const char* a3 = a2 + kstep; const char* b3 = b2 + kstep;
;             PG8_LDB(B0, 0, 0); PG8_SCHED; PG8_LDA(At, 0, 0); PG8_STAGE(PG8_SA(1, 1), a1 + hstepA, voffA);
;             PG8_WAIT_L(8); PG8_BAR; PG8_WAIT_L(0); PG8_MMA(0, 0, At, B0); PG8_BAR; PG8_SCHED;
;             PG8_LDB(B1, 0, 1); PG8_STAGE(PG8_SB(0, 0), b2, voffB);
;             PG8_BAR; PG8_WAIT_L(0); PG8_MMA(0, 1, At, B1); PG8_BAR;
;             PG8_LDA(At, 0, 1); PG8_STAGE(PG8_SA(0, 0), a2, voffA);
;             PG8_BAR; PG8_WAIT_L(0); PG8_MMA(1, 0, At, B0); PG8_BAR; PG8_SCHED;
;             PG8_STAGE(PG8_SB(0, 1), b2 + hstepB, voffB);
;             PG8_WAIT_V(6); PG8_BAR; PG8_MMA(1, 1, At, B1); PG8_BAR;
.LBB1_2653:
	s_add_u32 s10, s8, 0x100
	s_addc_u32 s11, s9, 0
	s_cmpk_eq_i32 s48, 0x54
	s_cselect_b32 s15, s43, s11
	s_cselect_b32 s14, s42, s10
	s_cselect_b32 s13, s45, s39
	s_cselect_b32 s12, s44, s38
	s_add_i32 m0, s22, 0xc000
	ds_read_b128 v[168:171], v150
	ds_read_b128 v[172:175], v150 offset:1024
	ds_read_b128 v[176:179], v150 offset:2048
	ds_read_b128 v[180:183], v150 offset:3072
	ds_read_b128 v[184:187], v150 offset:4096
	ds_read_b128 v[188:191], v150 offset:5120
	ds_read_b128 v[192:195], v150 offset:6144
	ds_read_b128 v[196:199], v150 offset:7168
	global_load_lds_dwordx4 v138, s[8:9]
	s_add_i32 m0, s22, 0xe000
	s_nop 0
	global_load_lds_dwordx4 v136, s[8:9]
	s_waitcnt lgkmcnt(8)
	s_setprio 1
	s_barrier
	s_waitcnt lgkmcnt(7)
	v_mfma_f32_16x16x32_bf16 v[124:127], v[152:155], v[168:171], v[124:127]
	v_mfma_f32_16x16x32_bf16 v[120:123], v[160:163], v[168:171], v[120:123]
	s_waitcnt lgkmcnt(5)
	v_mfma_f32_16x16x32_bf16 v[108:111], v[152:155], v[176:179], v[108:111]
	v_mfma_f32_16x16x32_bf16 v[104:107], v[160:163], v[176:179], v[104:107]
	s_waitcnt lgkmcnt(3)
	v_mfma_f32_16x16x32_bf16 v[92:95], v[152:155], v[184:187], v[92:95]
	v_mfma_f32_16x16x32_bf16 v[88:91], v[160:163], v[184:187], v[88:91]
	s_waitcnt lgkmcnt(1)
	v_mfma_f32_16x16x32_bf16 v[76:79], v[152:155], v[192:195], v[76:79]
	v_mfma_f32_16x16x32_bf16 v[72:75], v[160:163], v[192:195], v[72:75]
	v_mfma_f32_16x16x32_bf16 v[124:127], v[156:159], v[172:175], v[124:127]
	s_add_i32 s8, s33, s20
	v_mfma_f32_16x16x32_bf16 v[120:123], v[164:167], v[172:175], v[120:123]
	v_lshl_add_u64 v[144:145], s[12:13], 0, v[132:133]
	v_mfma_f32_16x16x32_bf16 v[108:111], v[156:159], v[180:183], v[108:111]
	v_lshl_add_u64 v[216:217], s[12:13], 0, v[128:129]
	v_mfma_f32_16x16x32_bf16 v[104:107], v[164:167], v[180:183], v[104:107]
	v_mfma_f32_16x16x32_bf16 v[92:95], v[156:159], v[188:191], v[92:95]
	v_mfma_f32_16x16x32_bf16 v[88:91], v[164:167], v[188:191], v[88:91]
	s_waitcnt lgkmcnt(0)
	v_mfma_f32_16x16x32_bf16 v[76:79], v[156:159], v[196:199], v[76:79]
	s_mov_b32 m0, s8
	v_mfma_f32_16x16x32_bf16 v[72:75], v[164:167], v[196:199], v[72:75]
	s_barrier
	s_setprio 0
	ds_read_b128 v[200:203], v151
	ds_read_b128 v[204:207], v151 offset:1024
	ds_read_b128 v[208:211], v151 offset:2048
	global_load_lds_dwordx4 v[144:145], off
	s_add_i32 m0, s8, 0x2000
	ds_read_b128 v[212:215], v151 offset:3072
	global_load_lds_dwordx4 v[216:217], off
	s_setprio 1
	s_barrier
	s_waitcnt lgkmcnt(3)
	v_mfma_f32_16x16x32_bf16 v[116:119], v[200:203], v[168:171], v[116:119]
	s_waitcnt lgkmcnt(1)
	v_mfma_f32_16x16x32_bf16 v[112:115], v[208:211], v[168:171], v[112:115]
	v_mfma_f32_16x16x32_bf16 v[100:103], v[200:203], v[176:179], v[100:103]
	v_mfma_f32_16x16x32_bf16 v[96:99], v[208:211], v[176:179], v[96:99]
	v_mfma_f32_16x16x32_bf16 v[84:87], v[200:203], v[184:187], v[84:87]
	v_mfma_f32_16x16x32_bf16 v[80:83], v[208:211], v[184:187], v[80:83]
	v_mfma_f32_16x16x32_bf16 v[68:71], v[200:203], v[192:195], v[68:71]
	v_mfma_f32_16x16x32_bf16 v[64:67], v[208:211], v[192:195], v[64:67]
	v_mfma_f32_16x16x32_bf16 v[116:119], v[204:207], v[172:175], v[116:119]
	v_lshl_add_u64 v[220:221], s[14:15], 0, v[130:131]
	s_mov_b32 m0, s22
	s_waitcnt lgkmcnt(0)
	v_mfma_f32_16x16x32_bf16 v[112:115], v[212:215], v[172:175], v[112:115]
	v_lshl_add_u64 v[218:219], s[14:15], 0, v[134:135]
	v_mfma_f32_16x16x32_bf16 v[100:103], v[204:207], v[180:183], v[100:103]
	v_mfma_f32_16x16x32_bf16 v[96:99], v[212:215], v[180:183], v[96:99]
	v_mfma_f32_16x16x32_bf16 v[84:87], v[204:207], v[188:191], v[84:87]
	v_mfma_f32_16x16x32_bf16 v[80:83], v[212:215], v[188:191], v[80:83]
	v_mfma_f32_16x16x32_bf16 v[68:71], v[204:207], v[196:199], v[68:71]
	v_mfma_f32_16x16x32_bf16 v[64:67], v[212:215], v[196:199], v[64:67]
	s_barrier
	s_setprio 0
	ds_read_b128 v[168:171], v150 offset:16384
	ds_read_b128 v[172:175], v150 offset:17408
	ds_read_b128 v[176:179], v150 offset:18432
	ds_read_b128 v[180:183], v150 offset:19456
	ds_read_b128 v[184:187], v150 offset:20480
	ds_read_b128 v[188:191], v150 offset:21504
	ds_read_b128 v[192:195], v150 offset:22528
	global_load_lds_dwordx4 v[218:219], off
	s_mov_b32 m0, s23
	ds_read_b128 v[196:199], v150 offset:23552
	global_load_lds_dwordx4 v[220:221], off
	s_waitcnt vmcnt(10)
	s_setprio 1
	s_barrier
	s_waitcnt lgkmcnt(7)
	v_mfma_f32_16x16x32_bf16 v[60:63], v[152:155], v[168:171], v[60:63]
	v_mfma_f32_16x16x32_bf16 v[56:59], v[160:163], v[168:171], v[56:59]
	s_waitcnt lgkmcnt(5)
	v_mfma_f32_16x16x32_bf16 v[44:47], v[152:155], v[176:179], v[44:47]
	v_mfma_f32_16x16x32_bf16 v[40:43], v[160:163], v[176:179], v[40:43]
	s_waitcnt lgkmcnt(3)
	v_mfma_f32_16x16x32_bf16 v[28:31], v[152:155], v[184:187], v[28:31]
	v_mfma_f32_16x16x32_bf16 v[24:27], v[160:163], v[184:187], v[24:27]
	s_waitcnt lgkmcnt(1)
	v_mfma_f32_16x16x32_bf16 v[12:15], v[152:155], v[192:195], v[12:15]
	v_mfma_f32_16x16x32_bf16 v[8:11], v[160:163], v[192:195], v[8:11]
	v_mfma_f32_16x16x32_bf16 v[60:63], v[156:159], v[172:175], v[60:63]
	s_add_u32 s8, s12, 0x160000
	s_addc_u32 s9, s13, 0
	v_mfma_f32_16x16x32_bf16 v[56:59], v[164:167], v[172:175], v[56:59]
	s_add_i32 s49, s34, s20
	v_mfma_f32_16x16x32_bf16 v[44:47], v[156:159], v[180:183], v[44:47]
	v_mfma_f32_16x16x32_bf16 v[40:43], v[164:167], v[180:183], v[40:43]
	v_mfma_f32_16x16x32_bf16 v[28:31], v[156:159], v[188:191], v[28:31]
	v_mfma_f32_16x16x32_bf16 v[24:27], v[164:167], v[188:191], v[24:27]
	s_waitcnt lgkmcnt(0)
	v_mfma_f32_16x16x32_bf16 v[12:15], v[156:159], v[196:199], v[12:15]
	s_mov_b32 m0, s49
	v_mfma_f32_16x16x32_bf16 v[8:11], v[164:167], v[196:199], v[8:11]
	s_barrier
; #define PG8_STAGE(bufoff, gbase, voff) do { _Pragma("unroll") for (int _i = 0; _i < 2; ++_i) \
;         __builtin_amdgcn_global_load_lds((const unsigned*)((const char*)(gbase) + (voff)[_i]), (LAS unsigned*)(lds + (bufoff) + ldsw + _i * 8192), 16, 0, 0); } while (0)
; #define PG8_LDA(dst, b, h) do { _Pragma("unroll") for (int m = 0; m < 4; ++m) _Pragma("unroll") for (int k = 0; k < 2; ++k) dst[m][k] = *(const LAS bf16x8*)(lds + PG8_SA(b, h) + aoff + m * 2048 + k * 1024); } while (0)
; #define PG8_LDB(dst, b, h) do { _Pragma("unroll") for (int n = 0; n < 2; ++n) _Pragma("unroll") for (int k = 0; k < 2; ++k) dst[n][k] = *(const LAS bf16x8*)(lds + PG8_SB(b, h) + boff + n * 2048 + k * 1024); } while (0)
; #define PG8_MMA(ai, bj, At, Bt) do { __builtin_amdgcn_s_setprio(1); _Pragma("unroll") for (int m = 0; m < 4; ++m) _Pragma("unroll") for (int n = 0; n < 2; ++n) _Pragma("unroll") for (int k = 0; k < 2; ++k) \
;         acc[ai][bj][m][n] = __builtin_amdgcn_mfma_f32_16x16x32_bf16(Bt[n][k], At[m][k], acc[ai][bj][m][n], 0, 0, 0); __builtin_amdgcn_s_setprio(0); } while (0)
; #define PG8_WAIT_L(n) asm volatile("s_waitcnt lgkmcnt(" #n ")" ::: "memory")
; #define PG8_BAR __builtin_amdgcn_s_barrier()
; #define PG8_SCHED __builtin_amdgcn_sched_barrier(0)
; template <class Map, class Epi>
; DI void gemm_phase(LAS unsigned char* lds, const Map& MP, const Epi& E, const int nM, const int nN, const int K, const int lda, const int ldb) {
;     ...
;             PG8_LDB(B0, 1, 0); PG8_SCHED; PG8_LDA(At, 1, 0); PG8_STAGE(PG8_SA(0, 1), a2 + hstepA, voffA);
;             PG8_WAIT_L(8); PG8_BAR; PG8_WAIT_L(0); PG8_MMA(0, 0, At, B0); PG8_BAR; PG8_SCHED;
;             PG8_LDB(B1, 1, 1); PG8_STAGE(PG8_SB(1, 0), b3, voffB);
;             PG8_BAR; PG8_WAIT_L(0); PG8_MMA(0, 1, At, B1); PG8_BAR;
;             PG8_LDA(At, 1, 1); PG8_STAGE(PG8_SA(1, 0), a3, voffA);
;             PG8_BAR; PG8_WAIT_L(0); PG8_MMA(1, 0, At, B0); PG8_BAR; PG8_SCHED;
;             PG8_STAGE(PG8_SB(1, 1), b3 + hstepB, voffB);
	s_setprio 0
	global_load_lds_dwordx4 v132, s[8:9]
	s_add_i32 m0, s49, 0x2000
	s_nop 0
	global_load_lds_dwordx4 v128, s[8:9]
	s_waitcnt vmcnt(6)
	s_setprio 1
	s_barrier
	v_mfma_f32_16x16x32_bf16 v[52:55], v[200:203], v[168:171], v[52:55]
	v_mfma_f32_16x16x32_bf16 v[48:51], v[208:211], v[168:171], v[48:51]
	s_add_i32 s49, 0, 0x18000
	v_add_u32_e32 v164, s49, v148
	ds_read_b128 v[152:155], v164
	v_mfma_f32_16x16x32_bf16 v[36:39], v[200:203], v[176:179], v[36:39]
	v_mfma_f32_16x16x32_bf16 v[32:35], v[208:211], v[176:179], v[32:35]
	ds_read_b128 v[156:159], v164 offset:1024
	v_mfma_f32_16x16x32_bf16 v[20:23], v[200:203], v[184:187], v[20:23]
	v_mfma_f32_16x16x32_bf16 v[16:19], v[208:211], v[184:187], v[16:19]
	ds_read_b128 v[160:163], v164 offset:2048
	v_mfma_f32_16x16x32_bf16 v[4:7], v[200:203], v[192:195], v[4:7]
	v_mfma_f32_16x16x32_bf16 v[0:3], v[208:211], v[192:195], v[0:3]
	ds_read_b128 v[164:167], v164 offset:3072
	v_mfma_f32_16x16x32_bf16 v[52:55], v[204:207], v[172:175], v[52:55]
	s_add_u32 s8, s14, 0x160000
	s_addc_u32 s9, s15, 0
	v_mfma_f32_16x16x32_bf16 v[48:51], v[212:215], v[172:175], v[48:51]
	v_mfma_f32_16x16x32_bf16 v[36:39], v[204:207], v[180:183], v[36:39]
	v_mfma_f32_16x16x32_bf16 v[32:35], v[212:215], v[180:183], v[32:35]
	v_mfma_f32_16x16x32_bf16 v[20:23], v[204:207], v[188:191], v[20:23]
	v_mfma_f32_16x16x32_bf16 v[16:19], v[212:215], v[188:191], v[16:19]
	v_mfma_f32_16x16x32_bf16 v[4:7], v[204:207], v[196:199], v[4:7]
	s_mov_b32 m0, s24
	v_mfma_f32_16x16x32_bf16 v[0:3], v[212:215], v[196:199], v[0:3]
	s_barrier
	s_setprio 0
	ds_read_b128 v[168:171], v150 offset:32768
	ds_read_b128 v[172:175], v150 offset:33792
	ds_read_b128 v[176:179], v150 offset:34816
	ds_read_b128 v[180:183], v150 offset:35840
	ds_read_b128 v[184:187], v150 offset:36864
	ds_read_b128 v[188:191], v150 offset:37888
	ds_read_b128 v[192:195], v150 offset:38912
	global_load_lds_dwordx4 v134, s[8:9]
	s_mov_b32 m0, s25
	ds_read_b128 v[196:199], v150 offset:39936
	global_load_lds_dwordx4 v130, s[8:9]
	s_waitcnt lgkmcnt(8)
	s_setprio 1
	s_barrier
	s_waitcnt lgkmcnt(7)
	v_mfma_f32_16x16x32_bf16 v[124:127], v[152:155], v[168:171], v[124:127]
	v_mfma_f32_16x16x32_bf16 v[120:123], v[160:163], v[168:171], v[120:123]
	s_waitcnt lgkmcnt(5)
	v_mfma_f32_16x16x32_bf16 v[108:111], v[152:155], v[176:179], v[108:111]
	v_mfma_f32_16x16x32_bf16 v[104:107], v[160:163], v[176:179], v[104:107]
	s_waitcnt lgkmcnt(3)
	v_mfma_f32_16x16x32_bf16 v[92:95], v[152:155], v[184:187], v[92:95]
	v_mfma_f32_16x16x32_bf16 v[88:91], v[160:163], v[184:187], v[88:91]
	s_waitcnt lgkmcnt(1)
	v_mfma_f32_16x16x32_bf16 v[76:79], v[152:155], v[192:195], v[76:79]
	v_mfma_f32_16x16x32_bf16 v[72:75], v[160:163], v[192:195], v[72:75]
	v_mfma_f32_16x16x32_bf16 v[124:127], v[156:159], v[172:175], v[124:127]
	s_add_i32 s14, 0, 0x1c000
	v_mfma_f32_16x16x32_bf16 v[120:123], v[164:167], v[172:175], v[120:123]
	s_add_i32 s8, s49, s20
	v_mfma_f32_16x16x32_bf16 v[108:111], v[156:159], v[180:183], v[108:111]
	v_add_u32_e32 v212, s14, v148
	v_mfma_f32_16x16x32_bf16 v[104:107], v[164:167], v[180:183], v[104:107]
	v_lshl_add_u64 v[144:145], v[144:145], 0, s[46:47]
	v_mfma_f32_16x16x32_bf16 v[92:95], v[156:159], v[188:191], v[92:95]
	v_mfma_f32_16x16x32_bf16 v[88:91], v[164:167], v[188:191], v[88:91]
	s_waitcnt lgkmcnt(0)
	v_mfma_f32_16x16x32_bf16 v[76:79], v[156:159], v[196:199], v[76:79]
	s_mov_b32 m0, s8
	v_mfma_f32_16x16x32_bf16 v[72:75], v[164:167], v[196:199], v[72:75]
	s_barrier
	s_setprio 0
	ds_read_b128 v[200:203], v212
	ds_read_b128 v[204:207], v212 offset:1024
	ds_read_b128 v[208:211], v212 offset:2048
	global_load_lds_dwordx4 v[144:145], off
	v_lshl_add_u64 v[144:145], v[216:217], 0, s[46:47]
	s_add_i32 m0, s8, 0x2000
	ds_read_b128 v[212:215], v212 offset:3072
	global_load_lds_dwordx4 v[144:145], off
	s_setprio 1
	s_barrier
	s_waitcnt lgkmcnt(3)
	v_mfma_f32_16x16x32_bf16 v[116:119], v[200:203], v[168:171], v[116:119]
	s_waitcnt lgkmcnt(1)
	v_mfma_f32_16x16x32_bf16 v[112:115], v[208:211], v[168:171], v[112:115]
	v_mfma_f32_16x16x32_bf16 v[100:103], v[200:203], v[176:179], v[100:103]
	v_mfma_f32_16x16x32_bf16 v[96:99], v[208:211], v[176:179], v[96:99]
	v_mfma_f32_16x16x32_bf16 v[84:87], v[200:203], v[184:187], v[84:87]
	v_mfma_f32_16x16x32_bf16 v[80:83], v[208:211], v[184:187], v[80:83]
	v_mfma_f32_16x16x32_bf16 v[68:71], v[200:203], v[192:195], v[68:71]
	v_mfma_f32_16x16x32_bf16 v[64:67], v[208:211], v[192:195], v[64:67]
	v_mfma_f32_16x16x32_bf16 v[116:119], v[204:207], v[172:175], v[116:119]
	s_mov_b32 m0, s29
	s_waitcnt lgkmcnt(0)
	v_mfma_f32_16x16x32_bf16 v[112:115], v[212:215], v[172:175], v[112:115]
	v_lshl_add_u64 v[144:145], v[218:219], 0, s[46:47]
	v_mfma_f32_16x16x32_bf16 v[100:103], v[204:207], v[180:183], v[100:103]
	v_mfma_f32_16x16x32_bf16 v[96:99], v[212:215], v[180:183], v[96:99]
	v_mfma_f32_16x16x32_bf16 v[84:87], v[204:207], v[188:191], v[84:87]
	v_mfma_f32_16x16x32_bf16 v[80:83], v[212:215], v[188:191], v[80:83]
	v_mfma_f32_16x16x32_bf16 v[68:71], v[204:207], v[196:199], v[68:71]
	v_mfma_f32_16x16x32_bf16 v[64:67], v[212:215], v[196:199], v[64:67]
	s_barrier
	s_setprio 0
	ds_read_b128 v[168:171], v150 offset:49152
	ds_read_b128 v[172:175], v150 offset:50176
	ds_read_b128 v[176:179], v150 offset:51200
	ds_read_b128 v[180:183], v150 offset:52224
	ds_read_b128 v[184:187], v150 offset:53248
	ds_read_b128 v[188:191], v150 offset:54272
	ds_read_b128 v[192:195], v150 offset:55296
	global_load_lds_dwordx4 v[144:145], off
	v_lshl_add_u64 v[144:145], v[220:221], 0, s[46:47]
	s_mov_b32 m0, s30
	ds_read_b128 v[196:199], v150 offset:56320
	global_load_lds_dwordx4 v[144:145], off
	s_waitcnt vmcnt(10)
	s_setprio 1
	s_barrier
; DI unsigned pack2(float a, float b) { f32x2 v = {a, b}; hwbf16x2 r = __builtin_convertvector(v, hwbf16x2); return __builtin_bit_cast(unsigned, r); }
; DI float bflo(unsigned w) { return __uint_as_float(w << 16); }
; DI float bfhi(unsigned w) { return __uint_as_float(w & 0xffff0000u); }
; #define PG8_STAGE(bufoff, gbase, voff) do { _Pragma("unroll") for (int _i = 0; _i < 2; ++_i) \
;         __builtin_amdgcn_global_load_lds((const unsigned*)((const char*)(gbase) + (voff)[_i]), (LAS unsigned*)(lds + (bufoff) + ldsw + _i * 8192), 16, 0, 0); } while (0)
; #define PG8_WAIT_V(n) asm volatile("s_waitcnt vmcnt(" #n ")" ::: "memory")
; #define PG8_WAIT_L(n) asm volatile("s_waitcnt lgkmcnt(" #n ")" ::: "memory")
;     DI void operator()(const f32x4 (&acc)[2][2][4][2], const Unit& u, int wr, int wc, int fr, int fq) const {
;     ...
;             for (int m = 0; m < 4; ++m) { const size_t ro = (size_t)(row0 + ai * HALF + m * 16) * D + col0;
; #pragma unroll
;                 for (int bj = 0; bj < 2; ++bj) {
;                     f32x4 x0, x1;
;                     if constexpr (IB) { const u32x4 w = *(const u32x4*)((const bf16_t*)Xin + ro + bj * HALF);
;                         x0 = (f32x4){bflo(w[0]), bfhi(w[0]), bflo(w[1]), bfhi(w[1])}; x1 = (f32x4){bflo(w[2]), bfhi(w[2]), bflo(w[3]), bfhi(w[3])}; }
;                     else { x0 = *(const f32x4*)((const float*)Xin + ro + bj * HALF); x1 = *(const f32x4*)((const float*)Xin + ro + bj * HALF + 4); }
;                     x0 += acc[ai][bj][m][0] * sc[bj][0]; x1 += acc[ai][bj][m][1] * sc[bj][1];
;                     if constexpr (OB) { u32x4 o; o[0] = pack2(x0[0], x0[1]); o[1] = pack2(x0[2], x0[3]); o[2] = pack2(x1[0], x1[1]); o[3] = pack2(x1[2], x1[3]);
;                         *(u32x4*)((bf16_t*)Xout + ro + bj * HALF) = o; }
;                     else { *(f32x4*)((float*)Xout + ro + bj * HALF) = x0; *(f32x4*)((float*)Xout + ro + bj * HALF + 4) = x1; } } }
; template <class Map, class Epi>
; DI void gemm_phase(LAS unsigned char* lds, const Map& MP, const Epi& E, const int nM, const int nN, const int K, const int lda, const int ldb) {
;     ...
;             PG8_LDA(At, 1, 1); PG8_STAGE(PG8_SA(1, 0), a3, voffA);
;             PG8_BAR; PG8_WAIT_L(0); PG8_MMA(1, 0, At, B0); PG8_BAR; PG8_SCHED;
;             PG8_STAGE(PG8_SB(1, 1), b3 + hstepB, voffB);
;             PG8_WAIT_V(6); PG8_BAR; PG8_MMA(1, 1, At, B1); PG8_BAR;
	s_waitcnt lgkmcnt(7)
	v_mfma_f32_16x16x32_bf16 v[60:63], v[152:155], v[168:171], v[60:63]
	v_mfma_f32_16x16x32_bf16 v[56:59], v[160:163], v[168:171], v[56:59]
	s_waitcnt lgkmcnt(5)
	v_mfma_f32_16x16x32_bf16 v[44:47], v[152:155], v[176:179], v[44:47]
	v_mfma_f32_16x16x32_bf16 v[40:43], v[160:163], v[176:179], v[40:43]
	s_waitcnt lgkmcnt(3)
	v_mfma_f32_16x16x32_bf16 v[28:31], v[152:155], v[184:187], v[28:31]
	v_mfma_f32_16x16x32_bf16 v[24:27], v[160:163], v[184:187], v[24:27]
	s_waitcnt lgkmcnt(1)
	v_mfma_f32_16x16x32_bf16 v[12:15], v[152:155], v[192:195], v[12:15]
	v_mfma_f32_16x16x32_bf16 v[8:11], v[160:163], v[192:195], v[8:11]
	v_mfma_f32_16x16x32_bf16 v[60:63], v[156:159], v[172:175], v[60:63]
	s_add_u32 s8, s12, 0x160080
	s_addc_u32 s9, s13, 0
	v_mfma_f32_16x16x32_bf16 v[56:59], v[164:167], v[172:175], v[56:59]
	s_add_i32 s12, s14, s20
	v_mfma_f32_16x16x32_bf16 v[44:47], v[156:159], v[180:183], v[44:47]
	v_mfma_f32_16x16x32_bf16 v[40:43], v[164:167], v[180:183], v[40:43]
	v_mfma_f32_16x16x32_bf16 v[28:31], v[156:159], v[188:191], v[28:31]
	v_mfma_f32_16x16x32_bf16 v[24:27], v[164:167], v[188:191], v[24:27]
	s_waitcnt lgkmcnt(0)
	v_mfma_f32_16x16x32_bf16 v[12:15], v[156:159], v[196:199], v[12:15]
	s_mov_b32 m0, s12
	v_mfma_f32_16x16x32_bf16 v[8:11], v[164:167], v[196:199], v[8:11]
	s_barrier
	s_setprio 0
	global_load_lds_dwordx4 v132, s[8:9]
	s_add_i32 m0, s12, 0x2000
	s_nop 0
	global_load_lds_dwordx4 v128, s[8:9]
	s_waitcnt vmcnt(6)
	s_setprio 1
	s_barrier
	v_mfma_f32_16x16x32_bf16 v[52:55], v[200:203], v[168:171], v[52:55]
	v_mfma_f32_16x16x32_bf16 v[48:51], v[208:211], v[168:171], v[48:51]
	ds_read_b128 v[152:155], v149
	v_mfma_f32_16x16x32_bf16 v[36:39], v[200:203], v[176:179], v[36:39]
	v_mfma_f32_16x16x32_bf16 v[32:35], v[208:211], v[176:179], v[32:35]
	ds_read_b128 v[156:159], v149 offset:1024
	v_mfma_f32_16x16x32_bf16 v[20:23], v[200:203], v[184:187], v[20:23]
	v_mfma_f32_16x16x32_bf16 v[16:19], v[208:211], v[184:187], v[16:19]
	ds_read_b128 v[160:163], v149 offset:2048
	v_mfma_f32_16x16x32_bf16 v[4:7], v[200:203], v[192:195], v[4:7]
	v_mfma_f32_16x16x32_bf16 v[0:3], v[208:211], v[192:195], v[0:3]
	ds_read_b128 v[164:167], v149 offset:3072
	v_mfma_f32_16x16x32_bf16 v[52:55], v[204:207], v[172:175], v[52:55]
	s_add_i32 s48, s48, 2
	v_mfma_f32_16x16x32_bf16 v[48:51], v[212:215], v[172:175], v[48:51]
	s_add_u32 s38, s38, 0x100
	s_addc_u32 s39, s39, 0
	v_mfma_f32_16x16x32_bf16 v[36:39], v[204:207], v[180:183], v[36:39]
	s_cmpk_gt_u32 s48, 0x55
	v_mfma_f32_16x16x32_bf16 v[32:35], v[212:215], v[180:183], v[32:35]
	s_mov_b64 s[8:9], s[10:11]
	v_mfma_f32_16x16x32_bf16 v[20:23], v[204:207], v[188:191], v[20:23]
	v_mfma_f32_16x16x32_bf16 v[16:19], v[212:215], v[188:191], v[16:19]
	v_mfma_f32_16x16x32_bf16 v[4:7], v[204:207], v[196:199], v[4:7]
	v_mfma_f32_16x16x32_bf16 v[0:3], v[212:215], v[196:199], v[0:3]
	s_barrier
	s_setprio 0
	s_cbranch_scc0 .LBB1_2653
	s_waitcnt lgkmcnt(0)
	v_mov_b32_e32 v144, v147
	v_mov_b32_e32 v152, v146
	s_lshl_b32 s2, s2, 8
	s_lshl_b32 s8, s37, 8
	s_add_i32 s2, s2, s27
	s_or_b32 s8, s8, s28
	v_add_u32_e32 v152, s2, v152
	v_lshl_add_u32 v144, v144, 3, s8
	v_ashrrev_i32_e32 v153, 31, v152
	v_ashrrev_i32_e32 v145, 31, v144
	v_lshlrev_b64 v[152:153], 11, v[152:153]
	v_lshl_add_u64 v[144:145], v[152:153], 0, v[144:145]
	v_lshl_add_u64 v[156:157], v[144:145], 1, s[6:7]
	global_load_dwordx4 v[162:165], v[156:157], off
	global_load_dwordx4 v[166:169], v[156:157], off offset:256
	s_mov_b64 s[98:99], 0x10000
	v_lshl_add_u64 v[154:155], v[156:157], 0, s[98:99]
	global_load_dwordx4 v[170:173], v[154:155], off
	global_load_dwordx4 v[174:177], v[154:155], off offset:256
	s_mov_b64 s[98:99], 0x20000
	v_lshl_add_u64 v[154:155], v[156:157], 0, s[98:99]
	global_load_dwordx4 v[178:181], v[154:155], off
	global_load_dwordx4 v[182:185], v[154:155], off offset:256
	s_mov_b64 s[98:99], 0x30000
	v_lshl_add_u64 v[154:155], v[156:157], 0, s[98:99]
	global_load_dwordx4 v[186:189], v[154:155], off
	global_load_dwordx4 v[190:193], v[154:155], off offset:256
	s_mov_b64 s[98:99], 0x80000
	v_lshl_add_u64 v[154:155], v[156:157], 0, s[98:99]
	global_load_dwordx4 v[194:197], v[154:155], off
	global_load_dwordx4 v[198:201], v[154:155], off offset:256
	s_mov_b64 s[98:99], 0x90000
	v_lshl_add_u64 v[154:155], v[156:157], 0, s[98:99]
	global_load_dwordx4 v[202:205], v[154:155], off
	global_load_dwordx4 v[206:209], v[154:155], off offset:256
	s_mov_b64 s[98:99], 0xa0000
	v_lshl_add_u64 v[154:155], v[156:157], 0, s[98:99]
	global_load_dwordx4 v[210:213], v[154:155], off
	global_load_dwordx4 v[248:251], v[154:155], off offset:256
	s_mov_b64 s[98:99], 0xb0000
	v_lshl_add_u64 v[154:155], v[156:157], 0, s[98:99]
	global_load_dwordx4 v[252:255], v[154:155], off
	s_waitcnt vmcnt(14)
	s_nop 1
	v_mov_b32_e32 v152, v162
	v_mov_b32_e32 v153, v163
	v_mov_b32_e32 v154, v164
	v_mov_b32_e32 v155, v165
	s_mov_b64 s[8:9], 0x8000
	s_and_b64 vcc, exec, s[40:41]
	s_mov_b32 s37, s35
	s_mov_b32 s2, s36
	s_mov_b64 s[10:11], s[44:45]
	s_waitcnt lgkmcnt(0)
	v_lshlrev_b32_e32 v158, 16, v152
	v_and_b32_e32 v159, 0xffff0000, v152
	v_lshlrev_b32_e32 v152, 16, v153
	v_and_b32_e32 v153, 0xffff0000, v153
	v_lshlrev_b32_e32 v160, 16, v154
	v_and_b32_e32 v161, 0xffff0000, v154
	v_lshlrev_b32_e32 v154, 16, v155
	v_and_b32_e32 v155, 0xffff0000, v155
	v_pk_add_f32 v[126:127], v[126:127], v[152:153]
	v_pk_add_f32 v[124:125], v[124:125], v[158:159]
	v_lshl_add_u64 v[152:153], v[144:145], 2, s[4:5]
	v_pk_add_f32 v[122:123], v[122:123], v[154:155]
	v_pk_add_f32 v[120:121], v[120:121], v[160:161]
	global_store_dwordx4 v[152:153], v[124:127], off
	global_store_dwordx4 v[152:153], v[120:123], off offset:16
	s_waitcnt vmcnt(15)
; DI unsigned pack2(float a, float b) { f32x2 v = {a, b}; hwbf16x2 r = __builtin_convertvector(v, hwbf16x2); return __builtin_bit_cast(unsigned, r); }
; DI float bflo(unsigned w) { return __uint_as_float(w << 16); }
; DI float bfhi(unsigned w) { return __uint_as_float(w & 0xffff0000u); }
;     DI void operator()(const f32x4 (&acc)[2][2][4][2], const Unit& u, int wr, int wc, int fr, int fq) const {
;     ...
;             for (int m = 0; m < 4; ++m) { const size_t ro = (size_t)(row0 + ai * HALF + m * 16) * D + col0;
; #pragma unroll
;                 for (int bj = 0; bj < 2; ++bj) {
;                     f32x4 x0, x1;
;                     if constexpr (IB) { const u32x4 w = *(const u32x4*)((const bf16_t*)Xin + ro + bj * HALF);
;                         x0 = (f32x4){bflo(w[0]), bfhi(w[0]), bflo(w[1]), bfhi(w[1])}; x1 = (f32x4){bflo(w[2]), bfhi(w[2]), bflo(w[3]), bfhi(w[3])}; }
;                     else { x0 = *(const f32x4*)((const float*)Xin + ro + bj * HALF); x1 = *(const f32x4*)((const float*)Xin + ro + bj * HALF + 4); }
;                     x0 += acc[ai][bj][m][0] * sc[bj][0]; x1 += acc[ai][bj][m][1] * sc[bj][1];
;                     if constexpr (OB) { u32x4 o; o[0] = pack2(x0[0], x0[1]); o[1] = pack2(x0[2], x0[3]); o[2] = pack2(x1[0], x1[1]); o[3] = pack2(x1[2], x1[3]);
;                         *(u32x4*)((bf16_t*)Xout + ro + bj * HALF) = o; }
;                     else { *(f32x4*)((float*)Xout + ro + bj * HALF) = x0; *(f32x4*)((float*)Xout + ro + bj * HALF + 4) = x1; } } }
	s_nop 1
	v_mov_b32_e32 v120, v166
	v_mov_b32_e32 v121, v167
	v_mov_b32_e32 v122, v168
	v_mov_b32_e32 v123, v169
	s_waitcnt lgkmcnt(0)
	v_lshlrev_b32_e32 v124, 16, v120
	v_and_b32_e32 v125, 0xffff0000, v120
	v_lshlrev_b32_e32 v120, 16, v121
	v_and_b32_e32 v121, 0xffff0000, v121
	v_lshlrev_b32_e32 v126, 16, v122
	v_and_b32_e32 v127, 0xffff0000, v122
	v_lshlrev_b32_e32 v122, 16, v123
	v_and_b32_e32 v123, 0xffff0000, v123
	v_pk_add_f32 v[118:119], v[118:119], v[120:121]
	v_pk_add_f32 v[116:117], v[116:117], v[124:125]
	v_pk_add_f32 v[114:115], v[114:115], v[122:123]
	v_pk_add_f32 v[112:113], v[112:113], v[126:127]
	global_store_dwordx4 v[152:153], v[116:119], off offset:512
	global_store_dwordx4 v[152:153], v[112:115], off offset:528
	s_nop 0
	v_lshl_add_u64 v[116:117], v[144:145], 0, s[8:9]
	v_lshl_add_u64 v[118:119], v[116:117], 1, s[6:7]
	s_waitcnt vmcnt(16)
	s_nop 1
	v_mov_b32_e32 v112, v170
	v_mov_b32_e32 v113, v171
	v_mov_b32_e32 v114, v172
	v_mov_b32_e32 v115, v173
	s_mov_b64 s[8:9], 0x10000
	s_waitcnt lgkmcnt(0)
	v_lshlrev_b32_e32 v120, 16, v112
	v_and_b32_e32 v121, 0xffff0000, v112
	v_lshlrev_b32_e32 v112, 16, v113
	v_and_b32_e32 v113, 0xffff0000, v113
	v_lshlrev_b32_e32 v122, 16, v114
	v_and_b32_e32 v123, 0xffff0000, v114
	v_lshlrev_b32_e32 v114, 16, v115
	v_and_b32_e32 v115, 0xffff0000, v115
	v_pk_add_f32 v[110:111], v[110:111], v[112:113]
	v_pk_add_f32 v[108:109], v[108:109], v[120:121]
	v_lshl_add_u64 v[112:113], v[116:117], 2, s[4:5]
	v_pk_add_f32 v[106:107], v[106:107], v[114:115]
	v_pk_add_f32 v[104:105], v[104:105], v[122:123]
	global_store_dwordx4 v[112:113], v[108:111], off
	global_store_dwordx4 v[112:113], v[104:107], off offset:16
	s_waitcnt vmcnt(17)
	s_nop 1
	v_mov_b32_e32 v104, v174
	v_mov_b32_e32 v105, v175
	v_mov_b32_e32 v106, v176
	v_mov_b32_e32 v107, v177
	s_waitcnt lgkmcnt(0)
	v_lshlrev_b32_e32 v108, 16, v104
	v_and_b32_e32 v109, 0xffff0000, v104
	v_lshlrev_b32_e32 v104, 16, v105
	v_and_b32_e32 v105, 0xffff0000, v105
	v_lshlrev_b32_e32 v110, 16, v106
	v_and_b32_e32 v111, 0xffff0000, v106
	v_lshlrev_b32_e32 v106, 16, v107
	v_and_b32_e32 v107, 0xffff0000, v107
	v_pk_add_f32 v[102:103], v[102:103], v[104:105]
	v_pk_add_f32 v[100:101], v[100:101], v[108:109]
	v_pk_add_f32 v[98:99], v[98:99], v[106:107]
	v_pk_add_f32 v[96:97], v[96:97], v[110:111]
	global_store_dwordx4 v[112:113], v[100:103], off offset:512
	global_store_dwordx4 v[112:113], v[96:99], off offset:528
	s_nop 0
	v_lshl_add_u64 v[100:101], v[144:145], 0, s[8:9]
	v_lshl_add_u64 v[102:103], v[100:101], 1, s[6:7]
	s_waitcnt vmcnt(18)
	s_nop 1
	v_mov_b32_e32 v96, v178
	v_mov_b32_e32 v97, v179
	v_mov_b32_e32 v98, v180
	v_mov_b32_e32 v99, v181
	s_mov_b64 s[8:9], 0x18000
	s_waitcnt lgkmcnt(0)
	v_lshlrev_b32_e32 v104, 16, v96
	v_and_b32_e32 v105, 0xffff0000, v96
	v_lshlrev_b32_e32 v96, 16, v97
	v_and_b32_e32 v97, 0xffff0000, v97
	v_lshlrev_b32_e32 v106, 16, v98
	v_and_b32_e32 v107, 0xffff0000, v98
	v_lshlrev_b32_e32 v98, 16, v99
	v_and_b32_e32 v99, 0xffff0000, v99
	v_pk_add_f32 v[94:95], v[94:95], v[96:97]
	v_pk_add_f32 v[92:93], v[92:93], v[104:105]
	v_lshl_add_u64 v[96:97], v[100:101], 2, s[4:5]
	v_pk_add_f32 v[90:91], v[90:91], v[98:99]
	v_pk_add_f32 v[88:89], v[88:89], v[106:107]
	global_store_dwordx4 v[96:97], v[92:95], off
	global_store_dwordx4 v[96:97], v[88:91], off offset:16
	s_waitcnt vmcnt(19)
	s_nop 1
	v_mov_b32_e32 v88, v182
	v_mov_b32_e32 v89, v183
	v_mov_b32_e32 v90, v184
	v_mov_b32_e32 v91, v185
	s_waitcnt lgkmcnt(0)
	v_lshlrev_b32_e32 v92, 16, v88
	v_and_b32_e32 v93, 0xffff0000, v88
	v_lshlrev_b32_e32 v88, 16, v89
	v_and_b32_e32 v89, 0xffff0000, v89
	v_lshlrev_b32_e32 v94, 16, v90
	v_and_b32_e32 v95, 0xffff0000, v90
	v_lshlrev_b32_e32 v90, 16, v91
	v_and_b32_e32 v91, 0xffff0000, v91
	v_pk_add_f32 v[86:87], v[86:87], v[88:89]
	v_pk_add_f32 v[84:85], v[84:85], v[92:93]
	v_pk_add_f32 v[82:83], v[82:83], v[90:91]
	v_pk_add_f32 v[80:81], v[80:81], v[94:95]
	global_store_dwordx4 v[96:97], v[84:87], off offset:512
	global_store_dwordx4 v[96:97], v[80:83], off offset:528
	s_nop 0
	v_lshl_add_u64 v[84:85], v[144:145], 0, s[8:9]
	v_lshl_add_u64 v[86:87], v[84:85], 1, s[6:7]
	s_waitcnt vmcnt(20)
	s_nop 1
	v_mov_b32_e32 v80, v186
	v_mov_b32_e32 v81, v187
	v_mov_b32_e32 v82, v188
	v_mov_b32_e32 v83, v189
	s_mov_b64 s[8:9], 0x40000
	s_waitcnt lgkmcnt(0)
	v_lshlrev_b32_e32 v88, 16, v80
	v_and_b32_e32 v89, 0xffff0000, v80
	v_lshlrev_b32_e32 v80, 16, v81
	v_and_b32_e32 v81, 0xffff0000, v81
	v_lshlrev_b32_e32 v90, 16, v82
	v_and_b32_e32 v91, 0xffff0000, v82
	v_lshlrev_b32_e32 v82, 16, v83
	v_and_b32_e32 v83, 0xffff0000, v83
	v_pk_add_f32 v[78:79], v[78:79], v[80:81]
	v_pk_add_f32 v[76:77], v[76:77], v[88:89]
	v_lshl_add_u64 v[80:81], v[84:85], 2, s[4:5]
	v_pk_add_f32 v[74:75], v[74:75], v[82:83]
	v_pk_add_f32 v[72:73], v[72:73], v[90:91]
	global_store_dwordx4 v[80:81], v[76:79], off
	global_store_dwordx4 v[80:81], v[72:75], off offset:16
	s_waitcnt vmcnt(21)
	s_nop 1
	v_mov_b32_e32 v72, v190
	v_mov_b32_e32 v73, v191
	v_mov_b32_e32 v74, v192
	v_mov_b32_e32 v75, v193
	s_waitcnt lgkmcnt(0)
	v_lshlrev_b32_e32 v76, 16, v72
	v_and_b32_e32 v77, 0xffff0000, v72
	v_lshlrev_b32_e32 v72, 16, v73
	v_and_b32_e32 v73, 0xffff0000, v73
	v_lshlrev_b32_e32 v78, 16, v74
	v_and_b32_e32 v79, 0xffff0000, v74
	v_lshlrev_b32_e32 v74, 16, v75
	v_and_b32_e32 v75, 0xffff0000, v75
	v_pk_add_f32 v[70:71], v[70:71], v[72:73]
	v_pk_add_f32 v[68:69], v[68:69], v[76:77]
	v_pk_add_f32 v[66:67], v[66:67], v[74:75]
	v_pk_add_f32 v[64:65], v[64:65], v[78:79]
	global_store_dwordx4 v[80:81], v[68:71], off offset:512
	global_store_dwordx4 v[80:81], v[64:67], off offset:528
	s_nop 0
	v_lshl_add_u64 v[68:69], v[144:145], 0, s[8:9]
	v_lshl_add_u64 v[70:71], v[68:69], 1, s[6:7]
	s_waitcnt vmcnt(22)
; DI unsigned pack2(float a, float b) { f32x2 v = {a, b}; hwbf16x2 r = __builtin_convertvector(v, hwbf16x2); return __builtin_bit_cast(unsigned, r); }
; DI float bflo(unsigned w) { return __uint_as_float(w << 16); }
; DI float bfhi(unsigned w) { return __uint_as_float(w & 0xffff0000u); }
;     DI const char* a(const Unit& u) const { return (const char*)(A + (size_t)u.pm * BM * lda); }
; #define PG8_BAR __builtin_amdgcn_s_barrier()
;     DI void operator()(const f32x4 (&acc)[2][2][4][2], const Unit& u, int wr, int wc, int fr, int fq) const {
;     ...
;             for (int m = 0; m < 4; ++m) { const size_t ro = (size_t)(row0 + ai * HALF + m * 16) * D + col0;
; #pragma unroll
;                 for (int bj = 0; bj < 2; ++bj) {
;                     f32x4 x0, x1;
;                     if constexpr (IB) { const u32x4 w = *(const u32x4*)((const bf16_t*)Xin + ro + bj * HALF);
;                         x0 = (f32x4){bflo(w[0]), bfhi(w[0]), bflo(w[1]), bfhi(w[1])}; x1 = (f32x4){bflo(w[2]), bfhi(w[2]), bflo(w[3]), bfhi(w[3])}; }
;                     else { x0 = *(const f32x4*)((const float*)Xin + ro + bj * HALF); x1 = *(const f32x4*)((const float*)Xin + ro + bj * HALF + 4); }
;                     x0 += acc[ai][bj][m][0] * sc[bj][0]; x1 += acc[ai][bj][m][1] * sc[bj][1];
;                     if constexpr (OB) { u32x4 o; o[0] = pack2(x0[0], x0[1]); o[1] = pack2(x0[2], x0[3]); o[2] = pack2(x1[0], x1[1]); o[3] = pack2(x1[2], x1[3]);
;                         *(u32x4*)((bf16_t*)Xout + ro + bj * HALF) = o; }
;                     else { *(f32x4*)((float*)Xout + ro + bj * HALF) = x0; *(f32x4*)((float*)Xout + ro + bj * HALF + 4) = x1; } } }
; template <class Map, class Epi>
; DI void gemm_phase(LAS unsigned char* lds, const Map& MP, const Epi& E, const int nM, const int nN, const int K, const int lda, const int ldb) {
;     ...
;         { int frr = fr, fqq = fq; asm volatile("" : "+v"(frr), "+v"(fqq)); E(acc, cur, wr, wc, frr, fqq); }
;         if (!has_next) break;
; #pragma unroll
;         for (int a = 0; a < 2; ++a)
; #pragma unroll
;             for (int b = 0; b < 2; ++b)
; #pragma unroll
;                 for (int m = 0; m < 4; ++m)
; #pragma unroll
;                     for (int n = 0; n < 2; ++n) acc[a][b][m][n] = (f32x4){0.f, 0.f, 0.f, 0.f};
;         cur = nxt; cA = nA; cB = nB; ++ui;
;     }
;     PG8_WAIT_V(0);
;     if (wr == 0) PG8_BAR;
;     PG8_BAR;
	s_nop 1
	v_mov_b32_e32 v64, v194
	v_mov_b32_e32 v65, v195
	v_mov_b32_e32 v66, v196
	v_mov_b32_e32 v67, v197
	s_mov_b64 s[8:9], 0x48000
	s_waitcnt lgkmcnt(0)
	v_lshlrev_b32_e32 v72, 16, v64
	v_and_b32_e32 v73, 0xffff0000, v64
	v_lshlrev_b32_e32 v64, 16, v65
	v_and_b32_e32 v65, 0xffff0000, v65
	v_lshlrev_b32_e32 v74, 16, v66
	v_and_b32_e32 v75, 0xffff0000, v66
	v_lshlrev_b32_e32 v66, 16, v67
	v_and_b32_e32 v67, 0xffff0000, v67
	v_pk_add_f32 v[62:63], v[62:63], v[64:65]
	v_pk_add_f32 v[60:61], v[60:61], v[72:73]
	v_lshl_add_u64 v[64:65], v[68:69], 2, s[4:5]
	v_pk_add_f32 v[58:59], v[58:59], v[66:67]
	v_pk_add_f32 v[56:57], v[56:57], v[74:75]
	global_store_dwordx4 v[64:65], v[60:63], off
	global_store_dwordx4 v[64:65], v[56:59], off offset:16
	s_waitcnt vmcnt(23)
	s_nop 1
	v_mov_b32_e32 v56, v198
	v_mov_b32_e32 v57, v199
	v_mov_b32_e32 v58, v200
	v_mov_b32_e32 v59, v201
	s_waitcnt lgkmcnt(0)
	v_lshlrev_b32_e32 v60, 16, v56
	v_and_b32_e32 v61, 0xffff0000, v56
	v_lshlrev_b32_e32 v56, 16, v57
	v_and_b32_e32 v57, 0xffff0000, v57
	v_lshlrev_b32_e32 v62, 16, v58
	v_and_b32_e32 v63, 0xffff0000, v58
	v_lshlrev_b32_e32 v58, 16, v59
	v_and_b32_e32 v59, 0xffff0000, v59
	v_pk_add_f32 v[54:55], v[54:55], v[56:57]
	v_pk_add_f32 v[52:53], v[52:53], v[60:61]
	v_pk_add_f32 v[50:51], v[50:51], v[58:59]
	v_pk_add_f32 v[48:49], v[48:49], v[62:63]
	global_store_dwordx4 v[64:65], v[52:55], off offset:512
	global_store_dwordx4 v[64:65], v[48:51], off offset:528
	s_nop 0
	v_lshl_add_u64 v[52:53], v[144:145], 0, s[8:9]
	v_lshl_add_u64 v[54:55], v[52:53], 1, s[6:7]
	s_waitcnt vmcnt(24)
	s_nop 1
	v_mov_b32_e32 v48, v202
	v_mov_b32_e32 v49, v203
	v_mov_b32_e32 v50, v204
	v_mov_b32_e32 v51, v205
	s_mov_b64 s[8:9], 0x50000
	s_waitcnt lgkmcnt(0)
	v_lshlrev_b32_e32 v56, 16, v48
	v_and_b32_e32 v57, 0xffff0000, v48
	v_lshlrev_b32_e32 v48, 16, v49
	v_and_b32_e32 v49, 0xffff0000, v49
	v_lshlrev_b32_e32 v58, 16, v50
	v_and_b32_e32 v59, 0xffff0000, v50
	v_lshlrev_b32_e32 v50, 16, v51
	v_and_b32_e32 v51, 0xffff0000, v51
	v_pk_add_f32 v[46:47], v[46:47], v[48:49]
	v_pk_add_f32 v[44:45], v[44:45], v[56:57]
	v_lshl_add_u64 v[48:49], v[52:53], 2, s[4:5]
	v_pk_add_f32 v[42:43], v[42:43], v[50:51]
	v_pk_add_f32 v[40:41], v[40:41], v[58:59]
	global_store_dwordx4 v[48:49], v[44:47], off
	global_store_dwordx4 v[48:49], v[40:43], off offset:16
	s_waitcnt vmcnt(25)
	s_nop 1
	v_mov_b32_e32 v40, v206
	v_mov_b32_e32 v41, v207
	v_mov_b32_e32 v42, v208
	v_mov_b32_e32 v43, v209
	s_waitcnt lgkmcnt(0)
	v_lshlrev_b32_e32 v44, 16, v40
	v_and_b32_e32 v45, 0xffff0000, v40
	v_lshlrev_b32_e32 v40, 16, v41
	v_and_b32_e32 v41, 0xffff0000, v41
	v_lshlrev_b32_e32 v46, 16, v42
	v_and_b32_e32 v47, 0xffff0000, v42
	v_lshlrev_b32_e32 v42, 16, v43
	v_and_b32_e32 v43, 0xffff0000, v43
	v_pk_add_f32 v[38:39], v[38:39], v[40:41]
	v_pk_add_f32 v[36:37], v[36:37], v[44:45]
	v_pk_add_f32 v[34:35], v[34:35], v[42:43]
	v_pk_add_f32 v[32:33], v[32:33], v[46:47]
	global_store_dwordx4 v[48:49], v[36:39], off offset:512
	global_store_dwordx4 v[48:49], v[32:35], off offset:528
	s_nop 0
	v_lshl_add_u64 v[36:37], v[144:145], 0, s[8:9]
	v_lshl_add_u64 v[38:39], v[36:37], 1, s[6:7]
	s_waitcnt vmcnt(26)
	s_nop 1
	v_mov_b32_e32 v32, v210
	v_mov_b32_e32 v33, v211
	v_mov_b32_e32 v34, v212
	v_mov_b32_e32 v35, v213
	s_mov_b64 s[8:9], 0x58000
	s_waitcnt lgkmcnt(0)
	v_lshlrev_b32_e32 v40, 16, v32
	v_and_b32_e32 v41, 0xffff0000, v32
	v_lshlrev_b32_e32 v32, 16, v33
	v_and_b32_e32 v33, 0xffff0000, v33
	v_lshlrev_b32_e32 v42, 16, v34
	v_and_b32_e32 v43, 0xffff0000, v34
	v_lshlrev_b32_e32 v34, 16, v35
	v_and_b32_e32 v35, 0xffff0000, v35
	v_pk_add_f32 v[30:31], v[30:31], v[32:33]
	v_pk_add_f32 v[28:29], v[28:29], v[40:41]
	v_lshl_add_u64 v[32:33], v[36:37], 2, s[4:5]
	v_pk_add_f32 v[26:27], v[26:27], v[34:35]
	v_pk_add_f32 v[24:25], v[24:25], v[42:43]
	global_store_dwordx4 v[32:33], v[28:31], off
	global_store_dwordx4 v[32:33], v[24:27], off offset:16
	s_waitcnt vmcnt(27)
	s_nop 1
	v_mov_b32_e32 v24, v248
	v_mov_b32_e32 v25, v249
	v_mov_b32_e32 v26, v250
	v_mov_b32_e32 v27, v251
	s_waitcnt lgkmcnt(0)
	v_lshlrev_b32_e32 v28, 16, v24
	v_and_b32_e32 v29, 0xffff0000, v24
	v_lshlrev_b32_e32 v24, 16, v25
	v_and_b32_e32 v25, 0xffff0000, v25
	v_lshlrev_b32_e32 v30, 16, v26
	v_and_b32_e32 v31, 0xffff0000, v26
	v_lshlrev_b32_e32 v26, 16, v27
	v_and_b32_e32 v27, 0xffff0000, v27
	v_pk_add_f32 v[22:23], v[22:23], v[24:25]
	v_pk_add_f32 v[20:21], v[20:21], v[28:29]
	v_pk_add_f32 v[18:19], v[18:19], v[26:27]
	v_pk_add_f32 v[16:17], v[16:17], v[30:31]
	global_store_dwordx4 v[32:33], v[20:23], off offset:512
	global_store_dwordx4 v[32:33], v[16:19], off offset:528
	s_nop 0
	v_lshl_add_u64 v[20:21], v[144:145], 0, s[8:9]
	v_lshl_add_u64 v[22:23], v[20:21], 1, s[6:7]
	s_waitcnt vmcnt(28)
	s_nop 1
	v_mov_b32_e32 v16, v252
	v_mov_b32_e32 v17, v253
	v_mov_b32_e32 v18, v254
	v_mov_b32_e32 v19, v255
	s_mov_b64 s[8:9], s[42:43]
	s_waitcnt lgkmcnt(0)
	v_lshlrev_b32_e32 v24, 16, v16
	v_and_b32_e32 v25, 0xffff0000, v16
	v_lshlrev_b32_e32 v16, 16, v17
	v_and_b32_e32 v17, 0xffff0000, v17
	v_lshlrev_b32_e32 v26, 16, v18
	v_and_b32_e32 v27, 0xffff0000, v18
	v_lshlrev_b32_e32 v18, 16, v19
	v_and_b32_e32 v19, 0xffff0000, v19
	v_pk_add_f32 v[14:15], v[14:15], v[16:17]
	v_pk_add_f32 v[12:13], v[12:13], v[24:25]
	v_lshl_add_u64 v[16:17], v[20:21], 2, s[4:5]
	v_pk_add_f32 v[10:11], v[10:11], v[18:19]
	v_pk_add_f32 v[8:9], v[8:9], v[26:27]
	global_store_dwordx4 v[16:17], v[12:15], off
	global_store_dwordx4 v[16:17], v[8:11], off offset:16
	global_load_dwordx4 v[8:11], v[22:23], off offset:256
	s_waitcnt vmcnt(0) lgkmcnt(0)
	v_lshlrev_b32_e32 v12, 16, v8
	v_and_b32_e32 v13, 0xffff0000, v8
	v_lshlrev_b32_e32 v8, 16, v9
	v_and_b32_e32 v9, 0xffff0000, v9
	v_lshlrev_b32_e32 v14, 16, v10
	v_and_b32_e32 v15, 0xffff0000, v10
	v_lshlrev_b32_e32 v10, 16, v11
	v_and_b32_e32 v11, 0xffff0000, v11
	v_pk_add_f32 v[6:7], v[6:7], v[8:9]
	v_pk_add_f32 v[4:5], v[4:5], v[12:13]
	v_pk_add_f32 v[2:3], v[2:3], v[10:11]
	v_pk_add_f32 v[0:1], v[0:1], v[14:15]
	global_store_dwordx4 v[16:17], v[4:7], off offset:512
	global_store_dwordx4 v[16:17], v[0:3], off offset:528
	s_cbranch_vccz .LBB1_2646
	s_waitcnt vmcnt(0)
	s_cmpk_gt_u32 s3, 0xff
	s_cbranch_scc1 .LBB1_2657
	s_barrier
